# flat to global memory ops, skip 5 independent grid barriers, sc1 write-through stores in swiglu epilogue
# speedup vs baseline: 1.0068x; 1.0068x over previous
.Lskip_gridbar:
.LBB0_9:
	s_mov_b64 s[4:5], 0
	s_waitcnt lgkmcnt(0)

.LBB0_173:
	v_lshl_add_u64 v[0:1], s[10:11], 0, v[58:59]
	v_add_co_u32_e32 v4, vcc, 0x18800000, v0
	ds_read_b128 v[74:77], v71
	s_nop 0
	v_addc_co_u32_e32 v5, vcc, 0, v1, vcc
	global_load_dwordx4 v[0:3], v[4:5], off
	global_load_dwordx4 v[40:43], v[4:5], off offset:32
	global_load_dwordx4 v[36:39], v[4:5], off offset:64
	global_load_dwordx4 v[32:35], v[4:5], off offset:96
	global_load_dwordx4 v[28:31], v[4:5], off offset:128
	global_load_dwordx4 v[24:27], v[4:5], off offset:160
	global_load_dwordx4 v[20:23], v[4:5], off offset:192
	global_load_dwordx4 v[16:19], v[4:5], off offset:224
	s_mov_b64 s[4:5], -1
	s_and_b64 vcc, exec, s[8:9]
	v_lshl_add_u64 v[60:61], s[10:11], 0, v[56:57]
	s_waitcnt vmcnt(0) lgkmcnt(0)
	v_lshlrev_b32_e32 v4, 16, v0
	v_and_b32_e32 v0, 0xffff0000, v0
	v_lshlrev_b32_e32 v5, 16, v1
	v_and_b32_e32 v1, 0xffff0000, v1
	v_lshlrev_b32_e32 v6, 16, v2
	v_and_b32_e32 v2, 0xffff0000, v2
	v_lshlrev_b32_e32 v7, 16, v3
	v_and_b32_e32 v3, 0xffff0000, v3
	v_mul_f32_e32 v8, 0x3d372713, v4
	v_mul_f32_e32 v9, 0x3d372713, v0
	v_mul_f32_e32 v10, 0x3d372713, v5
	v_mul_f32_e32 v11, 0x3d372713, v1
	v_mul_f32_e32 v12, 0x3d372713, v6
	v_mul_f32_e32 v13, 0x3d372713, v2
	v_mul_f32_e32 v14, 0x3d372713, v7
	v_mul_f32_e32 v15, 0x3d372713, v3
	v_mul_f32_e32 v8, v8, v4
	v_mul_f32_e32 v9, v9, v0
	v_mul_f32_e32 v10, v10, v5
	v_mul_f32_e32 v11, v11, v1
	v_mul_f32_e32 v12, v12, v6
	v_mul_f32_e32 v13, v13, v2
	v_mul_f32_e32 v14, v14, v7
	v_mul_f32_e32 v15, v15, v3
	v_fma_f32 v8, v8, v4, v4
	v_fma_f32 v9, v9, v0, v0
	v_fma_f32 v10, v10, v5, v5
	v_fma_f32 v11, v11, v1, v1
	v_fma_f32 v12, v12, v6, v6
	v_fma_f32 v13, v13, v2, v2
	v_fma_f32 v14, v14, v7, v7
	v_fma_f32 v15, v15, v3, v3
	v_mul_f32_e32 v8, 0x3fcc422a, v8
	v_mul_f32_e32 v9, 0x3fcc422a, v9
	v_mul_f32_e32 v10, 0x3fcc422a, v10
	v_mul_f32_e32 v11, 0x3fcc422a, v11
	v_mul_f32_e32 v12, 0x3fcc422a, v12
	v_mul_f32_e32 v13, 0x3fcc422a, v13
	v_mul_f32_e32 v14, 0x3fcc422a, v14
	v_mul_f32_e32 v15, 0x3fcc422a, v15
	v_mul_f32_e32 v8, 0xbfb8aa3b, v8
	v_mul_f32_e32 v9, 0xbfb8aa3b, v9
	v_mul_f32_e32 v10, 0xbfb8aa3b, v10
	v_mul_f32_e32 v11, 0xbfb8aa3b, v11
	v_mul_f32_e32 v12, 0xbfb8aa3b, v12
	v_mul_f32_e32 v13, 0xbfb8aa3b, v13
	v_mul_f32_e32 v14, 0xbfb8aa3b, v14
	v_mul_f32_e32 v15, 0xbfb8aa3b, v15
	v_exp_f32_e32 v8, v8
	v_exp_f32_e32 v9, v9
	v_exp_f32_e32 v10, v10
	v_exp_f32_e32 v11, v11
	v_exp_f32_e32 v12, v12
	v_exp_f32_e32 v13, v13
	v_exp_f32_e32 v14, v14
	v_exp_f32_e32 v15, v15
	v_add_f32_e32 v8, 1.0, v8
	v_add_f32_e32 v9, 1.0, v9
	v_add_f32_e32 v10, 1.0, v10
	v_add_f32_e32 v11, 1.0, v11
	v_add_f32_e32 v12, 1.0, v12
	v_add_f32_e32 v13, 1.0, v13
	v_add_f32_e32 v14, 1.0, v14
	v_add_f32_e32 v15, 1.0, v15
	v_rcp_f32_e32 v8, v8
	v_rcp_f32_e32 v9, v9
	v_rcp_f32_e32 v10, v10
	v_rcp_f32_e32 v11, v11
	v_rcp_f32_e32 v12, v12
	v_rcp_f32_e32 v13, v13
	v_rcp_f32_e32 v14, v14
	v_rcp_f32_e32 v15, v15
	v_mul_f32_e32 v4, v8, v4
	v_mul_f32_e32 v0, v9, v0
	v_mul_f32_e32 v5, v10, v5
	v_mul_f32_e32 v1, v11, v1
	v_mul_f32_e32 v6, v12, v6
	v_mul_f32_e32 v2, v13, v2
	v_mul_f32_e32 v7, v14, v7
	v_mul_f32_e32 v3, v15, v3
	v_cvt_pk_bf16_f32 v78, v4, v0
	v_cvt_pk_bf16_f32 v79, v5, v1
	v_cvt_pk_bf16_f32 v80, v6, v2
	v_cvt_pk_bf16_f32 v81, v7, v3
	ds_read_b128 v[0:3], v72
	ds_read_b128 v[4:7], v72 offset:32
	ds_read_b128 v[8:11], v72 offset:64
	ds_read_b128 v[12:15], v72 offset:96
	s_nop 4
	s_waitcnt lgkmcnt(0)
	v_mfma_f32_32x32x16_bf16 v[0:15], v[74:77], v[78:81], v[0:15]
	s_nop 11
	v_mul_f32_e32 v11, 0xbfb8aa3b, v11
	v_mul_f32_e32 v8, 0xbfb8aa3b, v8
	v_mul_f32_e32 v9, 0xbfb8aa3b, v9
	v_mul_f32_e32 v10, 0xbfb8aa3b, v10
	v_exp_f32_e32 v11, v11
	v_exp_f32_e32 v8, v8
	v_exp_f32_e32 v9, v9
	v_exp_f32_e32 v10, v10
	v_add_f32_e32 v11, 1.0, v11
	v_add_f32_e32 v8, 1.0, v8
	v_add_f32_e32 v9, 1.0, v9
	v_add_f32_e32 v10, 1.0, v10
	v_rcp_f32_e32 v11, v11
	v_rcp_f32_e32 v8, v8
	v_rcp_f32_e32 v9, v9
	v_rcp_f32_e32 v10, v10
	v_mul_f32_e32 v3, v3, v11
	v_mul_f32_e32 v0, v0, v8
	v_mul_f32_e32 v1, v1, v9
	v_mul_f32_e32 v2, v2, v10
	v_cvt_pk_bf16_f32 v8, v0, v1
	v_cvt_pk_bf16_f32 v3, v2, v3
	s_nop 0
	v_lshlrev_b32_e32 v0, 16, v8
	v_lshlrev_b32_e32 v1, 16, v3
	v_and_b32_e32 v2, 0xffff0000, v8
	v_and_b32_e32 v3, 0xffff0000, v3
	s_cbranch_vccz .LBB0_175
	ds_read_b128 v[8:11], v73
	v_mul_f32_e32 v74, v70, v0
	s_mov_b64 s[4:5], 0
	s_waitcnt lgkmcnt(0)
	v_mul_f32_e32 v8, v74, v8
	v_mul_f32_e32 v74, v70, v2
	v_mul_f32_e32 v9, v74, v9
	v_cvt_pk_bf16_f32 v8, v8, v9
	v_mul_f32_e32 v9, v70, v1
	v_mul_f32_e32 v9, v9, v10
	v_mul_f32_e32 v10, v70, v3
	v_mul_f32_e32 v10, v10, v11
	v_cvt_pk_bf16_f32 v9, v9, v10
	v_add_co_u32_e32 v10, vcc, 0x10800000, v60
	s_nop 1
	v_addc_co_u32_e32 v11, vcc, 0, v61, vcc
	global_store_dwordx2 v[10:11], v[8:9], off

.LBB0_177:
	v_mul_f32_e32 v0, 0xbfb8aa3b, v12
	v_mul_f32_e32 v3, 0xbfb8aa3b, v15
	v_exp_f32_e32 v0, v0
	v_mul_f32_e32 v1, 0xbfb8aa3b, v13
	v_mul_f32_e32 v2, 0xbfb8aa3b, v14
	v_exp_f32_e32 v3, v3
	v_exp_f32_e32 v1, v1
	v_exp_f32_e32 v2, v2
	v_add_f32_e32 v0, 1.0, v0
	v_add_f32_e32 v3, 1.0, v3
	v_add_f32_e32 v1, 1.0, v1
	v_rcp_f32_e32 v0, v0
	v_add_f32_e32 v2, 1.0, v2
	v_rcp_f32_e32 v3, v3
	v_rcp_f32_e32 v1, v1
	v_rcp_f32_e32 v2, v2
	v_mul_f32_e32 v0, v4, v0
	v_mul_f32_e32 v3, v7, v3
	v_mul_f32_e32 v1, v5, v1
	v_mul_f32_e32 v2, v6, v2
	v_cvt_pk_bf16_f32 v4, v0, v1
	v_cvt_pk_bf16_f32 v3, v2, v3
	v_cndmask_b32_e64 v0, 0, 1, s[8:9]
	s_mov_b64 s[26:27], -1
	v_cmp_ne_u32_e64 s[4:5], 1, v0
	s_andn2_b64 vcc, exec, s[8:9]
	v_lshlrev_b32_e32 v0, 16, v4
	v_lshlrev_b32_e32 v1, 16, v3
	v_and_b32_e32 v2, 0xffff0000, v4
	v_and_b32_e32 v3, 0xffff0000, v3
	s_cbranch_vccnz .LBB0_179
	ds_read_b128 v[4:7], v73 offset:32
	v_mul_f32_e32 v8, v70, v0
	s_mov_b64 s[26:27], 0
	s_waitcnt lgkmcnt(0)
	v_mul_f32_e32 v4, v8, v4
	v_mul_f32_e32 v8, v70, v2
	v_mul_f32_e32 v5, v8, v5
	v_cvt_pk_bf16_f32 v4, v4, v5
	v_mul_f32_e32 v5, v70, v1
	v_mul_f32_e32 v5, v5, v6
	v_mul_f32_e32 v6, v70, v3
	v_mul_f32_e32 v6, v6, v7
	v_cvt_pk_bf16_f32 v5, v5, v6
	v_add_co_u32_e32 v6, vcc, 0x10800000, v60
	s_nop 1
	v_addc_co_u32_e32 v7, vcc, 0, v61, vcc
	global_store_dwordx2 v[6:7], v[4:5], off offset:16

.LBB0_181:
	v_lshlrev_b32_e32 v0, 16, v40
	v_and_b32_e32 v2, 0xffff0000, v40
	v_mul_f32_e32 v1, 0x3d372713, v0
	v_mul_f32_e32 v3, 0x3d372713, v2
	v_mul_f32_e32 v1, v1, v0
	v_mul_f32_e32 v3, v3, v2
	v_fma_f32 v1, v1, v0, v0
	v_fma_f32 v3, v3, v2, v2
	v_mul_f32_e32 v1, 0x3fcc422a, v1
	v_mul_f32_e32 v3, 0x3fcc422a, v3
	v_mul_f32_e32 v1, 0xbfb8aa3b, v1
	v_mul_f32_e32 v3, 0xbfb8aa3b, v3
	v_exp_f32_e32 v1, v1
	v_exp_f32_e32 v3, v3
	v_lshlrev_b32_e32 v4, 16, v41
	v_mul_f32_e32 v5, 0x3d372713, v4
	v_mul_f32_e32 v5, v5, v4
	v_fma_f32 v5, v5, v4, v4
	v_add_f32_e32 v1, 1.0, v1
	v_add_f32_e32 v3, 1.0, v3
	v_mul_f32_e32 v5, 0x3fcc422a, v5
	v_rcp_f32_e32 v1, v1
	v_rcp_f32_e32 v3, v3
	v_mul_f32_e32 v5, 0xbfb8aa3b, v5
	v_exp_f32_e32 v5, v5
	v_mul_f32_e32 v0, v1, v0
	v_mul_f32_e32 v1, v3, v2
	v_lshlrev_b32_e32 v3, 16, v42
	ds_read_b128 v[74:77], v71 offset:1024
	v_cvt_pk_bf16_f32 v40, v0, v1
	v_add_f32_e32 v0, 1.0, v5
	v_mul_f32_e32 v5, 0x3d372713, v3
	v_mul_f32_e32 v5, v5, v3
	v_fma_f32 v5, v5, v3, v3
	v_and_b32_e32 v1, 0xffff0000, v41
	v_mul_f32_e32 v5, 0x3fcc422a, v5
	v_mul_f32_e32 v2, 0x3d372713, v1
	v_mul_f32_e32 v5, 0xbfb8aa3b, v5
	v_rcp_f32_e32 v0, v0
	v_mul_f32_e32 v2, v2, v1
	v_exp_f32_e32 v5, v5
	v_fma_f32 v2, v2, v1, v1
	v_mul_f32_e32 v2, 0x3fcc422a, v2
	v_mul_f32_e32 v2, 0xbfb8aa3b, v2
	v_exp_f32_e32 v2, v2
	v_mul_f32_e32 v0, v0, v4
	v_add_f32_e32 v4, 1.0, v5
	v_and_b32_e32 v5, 0xffff0000, v42
	v_mul_f32_e32 v6, 0x3d372713, v5
	v_mul_f32_e32 v6, v6, v5
	v_fma_f32 v6, v6, v5, v5
	v_add_f32_e32 v2, 1.0, v2
	v_mul_f32_e32 v6, 0x3fcc422a, v6
	v_rcp_f32_e32 v2, v2
	v_rcp_f32_e32 v4, v4
	v_mul_f32_e32 v6, 0xbfb8aa3b, v6
	v_exp_f32_e32 v6, v6
	v_mul_f32_e32 v1, v2, v1
	v_cvt_pk_bf16_f32 v41, v0, v1
	v_mul_f32_e32 v0, v4, v3
	v_lshlrev_b32_e32 v2, 16, v43
	v_and_b32_e32 v4, 0xffff0000, v43
	v_add_f32_e32 v1, 1.0, v6
	v_mul_f32_e32 v3, 0x3d372713, v2
	v_mul_f32_e32 v6, 0x3d372713, v4
	v_mul_f32_e32 v3, v3, v2
	v_mul_f32_e32 v6, v6, v4
	v_fma_f32 v3, v3, v2, v2
	v_fma_f32 v6, v6, v4, v4
	v_mul_f32_e32 v3, 0x3fcc422a, v3
	v_mul_f32_e32 v6, 0x3fcc422a, v6
	v_mul_f32_e32 v3, 0xbfb8aa3b, v3
	v_mul_f32_e32 v6, 0xbfb8aa3b, v6
	v_exp_f32_e32 v3, v3
	v_exp_f32_e32 v6, v6
	v_rcp_f32_e32 v1, v1
	s_mov_b64 s[26:27], -1
	v_add_f32_e32 v3, 1.0, v3
	v_add_f32_e32 v6, 1.0, v6
	v_rcp_f32_e32 v3, v3
	v_rcp_f32_e32 v6, v6
	v_mul_f32_e32 v1, v1, v5
	v_cvt_pk_bf16_f32 v42, v0, v1
	v_mul_f32_e32 v0, v3, v2
	v_mul_f32_e32 v1, v6, v4
	v_cvt_pk_bf16_f32 v43, v0, v1
	ds_read_b128 v[0:3], v72 offset:128
	ds_read_b128 v[4:7], v72 offset:160
	ds_read_b128 v[8:11], v72 offset:192
	ds_read_b128 v[12:15], v72 offset:224
	s_waitcnt lgkmcnt(0)
	s_nop 4
	s_and_b64 vcc, exec, s[4:5]
	v_mfma_f32_32x32x16_bf16 v[0:15], v[74:77], v[40:43], v[0:15]
	s_nop 11
	v_mul_f32_e32 v11, 0xbfb8aa3b, v11
	v_mul_f32_e32 v8, 0xbfb8aa3b, v8
	v_mul_f32_e32 v9, 0xbfb8aa3b, v9
	v_mul_f32_e32 v10, 0xbfb8aa3b, v10
	v_exp_f32_e32 v11, v11
	v_exp_f32_e32 v8, v8
	v_exp_f32_e32 v9, v9
	v_exp_f32_e32 v10, v10
	v_add_f32_e32 v11, 1.0, v11
	v_add_f32_e32 v8, 1.0, v8
	v_add_f32_e32 v9, 1.0, v9
	v_add_f32_e32 v10, 1.0, v10
	v_rcp_f32_e32 v11, v11
	v_rcp_f32_e32 v8, v8
	v_rcp_f32_e32 v9, v9
	v_rcp_f32_e32 v10, v10
	v_mul_f32_e32 v3, v3, v11
	v_mul_f32_e32 v0, v0, v8
	v_mul_f32_e32 v1, v1, v9
	v_mul_f32_e32 v2, v2, v10
	v_cvt_pk_bf16_f32 v8, v0, v1
	v_cvt_pk_bf16_f32 v3, v2, v3
	s_nop 0
	v_lshlrev_b32_e32 v0, 16, v8
	v_lshlrev_b32_e32 v1, 16, v3
	v_and_b32_e32 v2, 0xffff0000, v8
	v_and_b32_e32 v3, 0xffff0000, v3
	s_cbranch_vccnz .LBB0_183
	ds_read_b128 v[8:11], v73 offset:64
	v_mul_f32_e32 v40, v70, v0
	s_mov_b64 s[26:27], 0
	s_waitcnt lgkmcnt(0)
	v_mul_f32_e32 v8, v40, v8
	v_mul_f32_e32 v40, v70, v2
	v_mul_f32_e32 v9, v40, v9
	v_cvt_pk_bf16_f32 v8, v8, v9
	v_mul_f32_e32 v9, v70, v1
	v_mul_f32_e32 v9, v9, v10
	v_mul_f32_e32 v10, v70, v3
	v_mul_f32_e32 v10, v10, v11
	v_cvt_pk_bf16_f32 v9, v9, v10
	v_add_co_u32_e32 v10, vcc, 0x10800000, v60
	s_nop 1
	v_addc_co_u32_e32 v11, vcc, 0, v61, vcc
	global_store_dwordx2 v[10:11], v[8:9], off offset:32

.LBB0_185:
	v_mul_f32_e32 v3, 0xbfb8aa3b, v15
	v_mul_f32_e32 v0, 0xbfb8aa3b, v12
	v_mul_f32_e32 v1, 0xbfb8aa3b, v13
	v_mul_f32_e32 v2, 0xbfb8aa3b, v14
	v_exp_f32_e32 v3, v3
	v_exp_f32_e32 v0, v0
	v_exp_f32_e32 v1, v1
	v_exp_f32_e32 v2, v2
	v_add_f32_e32 v3, 1.0, v3
	v_add_f32_e32 v0, 1.0, v0
	v_add_f32_e32 v1, 1.0, v1
	v_add_f32_e32 v2, 1.0, v2
	v_rcp_f32_e32 v3, v3
	v_rcp_f32_e32 v0, v0
	v_rcp_f32_e32 v1, v1
	v_rcp_f32_e32 v2, v2
	v_mul_f32_e32 v3, v7, v3
	v_mul_f32_e32 v0, v4, v0
	v_mul_f32_e32 v1, v5, v1
	v_mul_f32_e32 v2, v6, v2
	v_cvt_pk_bf16_f32 v4, v0, v1
	v_cvt_pk_bf16_f32 v3, v2, v3
	s_mov_b64 s[26:27], -1
	s_and_b64 vcc, exec, s[4:5]
	v_lshlrev_b32_e32 v0, 16, v4
	v_lshlrev_b32_e32 v1, 16, v3
	v_and_b32_e32 v2, 0xffff0000, v4
	v_and_b32_e32 v3, 0xffff0000, v3
	s_cbranch_vccnz .LBB0_187
	ds_read_b128 v[4:7], v73 offset:96
	v_mul_f32_e32 v8, v70, v0
	s_mov_b64 s[26:27], 0
	s_waitcnt lgkmcnt(0)
	v_mul_f32_e32 v4, v8, v4
	v_mul_f32_e32 v8, v70, v2
	v_mul_f32_e32 v5, v8, v5
	v_cvt_pk_bf16_f32 v4, v4, v5
	v_mul_f32_e32 v5, v70, v1
	v_mul_f32_e32 v5, v5, v6
	v_mul_f32_e32 v6, v70, v3
	v_mul_f32_e32 v6, v6, v7
	v_cvt_pk_bf16_f32 v5, v5, v6
	v_add_co_u32_e32 v6, vcc, 0x10800000, v60
	s_nop 1
	v_addc_co_u32_e32 v7, vcc, 0, v61, vcc
	global_store_dwordx2 v[6:7], v[4:5], off offset:48

.LBB0_189:
	v_lshlrev_b32_e32 v0, 16, v36
	v_and_b32_e32 v2, 0xffff0000, v36
	v_mul_f32_e32 v1, 0x3d372713, v0
	v_mul_f32_e32 v3, 0x3d372713, v2
	v_mul_f32_e32 v1, v1, v0
	v_mul_f32_e32 v3, v3, v2
	v_fma_f32 v1, v1, v0, v0
	v_fma_f32 v3, v3, v2, v2
	v_mul_f32_e32 v1, 0x3fcc422a, v1
	v_mul_f32_e32 v3, 0x3fcc422a, v3
	v_mul_f32_e32 v1, 0xbfb8aa3b, v1
	v_mul_f32_e32 v3, 0xbfb8aa3b, v3
	v_exp_f32_e32 v1, v1
	v_exp_f32_e32 v3, v3
	v_lshlrev_b32_e32 v4, 16, v37
	v_mul_f32_e32 v5, 0x3d372713, v4
	v_mul_f32_e32 v5, v5, v4
	v_fma_f32 v5, v5, v4, v4
	v_add_f32_e32 v1, 1.0, v1
	v_add_f32_e32 v3, 1.0, v3
	v_mul_f32_e32 v5, 0x3fcc422a, v5
	v_rcp_f32_e32 v1, v1
	v_rcp_f32_e32 v3, v3
	v_mul_f32_e32 v5, 0xbfb8aa3b, v5
	v_exp_f32_e32 v5, v5
	v_mul_f32_e32 v0, v1, v0
	v_mul_f32_e32 v1, v3, v2
	v_lshlrev_b32_e32 v3, 16, v38
	ds_read_b128 v[40:43], v71 offset:2048
	v_cvt_pk_bf16_f32 v36, v0, v1
	v_add_f32_e32 v0, 1.0, v5
	v_mul_f32_e32 v5, 0x3d372713, v3
	v_mul_f32_e32 v5, v5, v3
	v_fma_f32 v5, v5, v3, v3
	v_and_b32_e32 v1, 0xffff0000, v37
	v_mul_f32_e32 v5, 0x3fcc422a, v5
	v_mul_f32_e32 v2, 0x3d372713, v1
	v_mul_f32_e32 v5, 0xbfb8aa3b, v5
	v_rcp_f32_e32 v0, v0
	v_mul_f32_e32 v2, v2, v1
	v_exp_f32_e32 v5, v5
	v_fma_f32 v2, v2, v1, v1
	v_mul_f32_e32 v2, 0x3fcc422a, v2
	v_mul_f32_e32 v2, 0xbfb8aa3b, v2
	v_exp_f32_e32 v2, v2
	v_mul_f32_e32 v0, v0, v4
	v_add_f32_e32 v4, 1.0, v5
	v_and_b32_e32 v5, 0xffff0000, v38
	v_mul_f32_e32 v6, 0x3d372713, v5
	v_mul_f32_e32 v6, v6, v5
	v_fma_f32 v6, v6, v5, v5
	v_add_f32_e32 v2, 1.0, v2
	v_mul_f32_e32 v6, 0x3fcc422a, v6
	v_rcp_f32_e32 v2, v2
	v_rcp_f32_e32 v4, v4
	v_mul_f32_e32 v6, 0xbfb8aa3b, v6
	v_exp_f32_e32 v6, v6
	v_mul_f32_e32 v1, v2, v1
	v_cvt_pk_bf16_f32 v37, v0, v1
	v_mul_f32_e32 v0, v4, v3
	v_lshlrev_b32_e32 v2, 16, v39
	v_and_b32_e32 v4, 0xffff0000, v39
	v_add_f32_e32 v1, 1.0, v6
	v_mul_f32_e32 v3, 0x3d372713, v2
	v_mul_f32_e32 v6, 0x3d372713, v4
	v_mul_f32_e32 v3, v3, v2
	v_mul_f32_e32 v6, v6, v4
	v_fma_f32 v3, v3, v2, v2
	v_fma_f32 v6, v6, v4, v4
	v_mul_f32_e32 v3, 0x3fcc422a, v3
	v_mul_f32_e32 v6, 0x3fcc422a, v6
	v_mul_f32_e32 v3, 0xbfb8aa3b, v3
	v_mul_f32_e32 v6, 0xbfb8aa3b, v6
	v_exp_f32_e32 v3, v3
	v_exp_f32_e32 v6, v6
	v_rcp_f32_e32 v1, v1
	s_mov_b64 s[26:27], -1
	v_add_f32_e32 v3, 1.0, v3
	v_add_f32_e32 v6, 1.0, v6
	v_rcp_f32_e32 v3, v3
	v_rcp_f32_e32 v6, v6
	v_mul_f32_e32 v1, v1, v5
	v_cvt_pk_bf16_f32 v38, v0, v1
	v_mul_f32_e32 v0, v3, v2
	v_mul_f32_e32 v1, v6, v4
	v_cvt_pk_bf16_f32 v39, v0, v1
	ds_read_b128 v[0:3], v72 offset:256
	ds_read_b128 v[4:7], v72 offset:288
	ds_read_b128 v[8:11], v72 offset:320
	ds_read_b128 v[12:15], v72 offset:352
	s_waitcnt lgkmcnt(0)
	s_nop 4
	s_and_b64 vcc, exec, s[4:5]
	v_mfma_f32_32x32x16_bf16 v[0:15], v[40:43], v[36:39], v[0:15]
	s_nop 11
	v_mul_f32_e32 v11, 0xbfb8aa3b, v11
	v_mul_f32_e32 v8, 0xbfb8aa3b, v8
	v_mul_f32_e32 v9, 0xbfb8aa3b, v9
	v_mul_f32_e32 v10, 0xbfb8aa3b, v10
	v_exp_f32_e32 v11, v11
	v_exp_f32_e32 v8, v8
	v_exp_f32_e32 v9, v9
	v_exp_f32_e32 v10, v10
	v_add_f32_e32 v11, 1.0, v11
	v_add_f32_e32 v8, 1.0, v8
	v_add_f32_e32 v9, 1.0, v9
	v_add_f32_e32 v10, 1.0, v10
	v_rcp_f32_e32 v11, v11
	v_rcp_f32_e32 v8, v8
	v_rcp_f32_e32 v9, v9
	v_rcp_f32_e32 v10, v10
	v_mul_f32_e32 v3, v3, v11
	v_mul_f32_e32 v0, v0, v8
	v_mul_f32_e32 v1, v1, v9
	v_mul_f32_e32 v2, v2, v10
	v_cvt_pk_bf16_f32 v8, v0, v1
	v_cvt_pk_bf16_f32 v3, v2, v3
	s_nop 0
	v_lshlrev_b32_e32 v0, 16, v8
	v_lshlrev_b32_e32 v1, 16, v3
	v_and_b32_e32 v2, 0xffff0000, v8
	v_and_b32_e32 v3, 0xffff0000, v3
	s_cbranch_vccnz .LBB0_191
	ds_read_b128 v[8:11], v73 offset:128
	v_mul_f32_e32 v36, v70, v0
	s_mov_b64 s[26:27], 0
	s_waitcnt lgkmcnt(0)
	v_mul_f32_e32 v8, v36, v8
	v_mul_f32_e32 v36, v70, v2
	v_mul_f32_e32 v9, v36, v9
	v_cvt_pk_bf16_f32 v8, v8, v9
	v_mul_f32_e32 v9, v70, v1
	v_mul_f32_e32 v9, v9, v10
	v_mul_f32_e32 v10, v70, v3
	v_mul_f32_e32 v10, v10, v11
	v_cvt_pk_bf16_f32 v9, v9, v10
	v_add_co_u32_e32 v10, vcc, 0x10800000, v60
	s_nop 1
	v_addc_co_u32_e32 v11, vcc, 0, v61, vcc
	global_store_dwordx2 v[10:11], v[8:9], off offset:64

.LBB0_193:
	v_mul_f32_e32 v3, 0xbfb8aa3b, v15
	v_mul_f32_e32 v0, 0xbfb8aa3b, v12
	v_mul_f32_e32 v1, 0xbfb8aa3b, v13
	v_mul_f32_e32 v2, 0xbfb8aa3b, v14
	v_exp_f32_e32 v3, v3
	v_exp_f32_e32 v0, v0
	v_exp_f32_e32 v1, v1
	v_exp_f32_e32 v2, v2
	v_add_f32_e32 v3, 1.0, v3
	v_add_f32_e32 v0, 1.0, v0
	v_add_f32_e32 v1, 1.0, v1
	v_add_f32_e32 v2, 1.0, v2
	v_rcp_f32_e32 v3, v3
	v_rcp_f32_e32 v0, v0
	v_rcp_f32_e32 v1, v1
	v_rcp_f32_e32 v2, v2
	v_mul_f32_e32 v3, v7, v3
	v_mul_f32_e32 v0, v4, v0
	v_mul_f32_e32 v1, v5, v1
	v_mul_f32_e32 v2, v6, v2
	v_cvt_pk_bf16_f32 v4, v0, v1
	v_cvt_pk_bf16_f32 v3, v2, v3
	s_mov_b64 s[26:27], -1
	s_and_b64 vcc, exec, s[4:5]
	v_lshlrev_b32_e32 v0, 16, v4
	v_lshlrev_b32_e32 v1, 16, v3
	v_and_b32_e32 v2, 0xffff0000, v4
	v_and_b32_e32 v3, 0xffff0000, v3
	s_cbranch_vccnz .LBB0_195
	ds_read_b128 v[4:7], v73 offset:160
	v_mul_f32_e32 v8, v70, v0
	s_mov_b64 s[26:27], 0
	s_waitcnt lgkmcnt(0)
	v_mul_f32_e32 v4, v8, v4
	v_mul_f32_e32 v8, v70, v2
	v_mul_f32_e32 v5, v8, v5
	v_cvt_pk_bf16_f32 v4, v4, v5
	v_mul_f32_e32 v5, v70, v1
	v_mul_f32_e32 v5, v5, v6
	v_mul_f32_e32 v6, v70, v3
	v_mul_f32_e32 v6, v6, v7
	v_cvt_pk_bf16_f32 v5, v5, v6
	v_add_co_u32_e32 v6, vcc, 0x10800000, v60
	s_nop 1
	v_addc_co_u32_e32 v7, vcc, 0, v61, vcc
	global_store_dwordx2 v[6:7], v[4:5], off offset:80

.LBB0_197:
	v_lshlrev_b32_e32 v0, 16, v32
	v_and_b32_e32 v2, 0xffff0000, v32
	v_mul_f32_e32 v1, 0x3d372713, v0
	v_mul_f32_e32 v3, 0x3d372713, v2
	v_mul_f32_e32 v1, v1, v0
	v_mul_f32_e32 v3, v3, v2
	v_fma_f32 v1, v1, v0, v0
	v_fma_f32 v3, v3, v2, v2
	v_mul_f32_e32 v1, 0x3fcc422a, v1
	v_mul_f32_e32 v3, 0x3fcc422a, v3
	v_mul_f32_e32 v1, 0xbfb8aa3b, v1
	v_mul_f32_e32 v3, 0xbfb8aa3b, v3
	v_exp_f32_e32 v1, v1
	v_exp_f32_e32 v3, v3
	v_lshlrev_b32_e32 v4, 16, v33
	v_mul_f32_e32 v5, 0x3d372713, v4
	v_mul_f32_e32 v5, v5, v4
	v_fma_f32 v5, v5, v4, v4
	v_add_f32_e32 v1, 1.0, v1
	v_add_f32_e32 v3, 1.0, v3
	v_mul_f32_e32 v5, 0x3fcc422a, v5
	v_rcp_f32_e32 v1, v1
	v_rcp_f32_e32 v3, v3
	v_mul_f32_e32 v5, 0xbfb8aa3b, v5
	v_exp_f32_e32 v5, v5
	v_mul_f32_e32 v0, v1, v0
	v_mul_f32_e32 v1, v3, v2
	v_lshlrev_b32_e32 v3, 16, v34
	ds_read_b128 v[36:39], v71 offset:3072
	v_cvt_pk_bf16_f32 v32, v0, v1
	v_add_f32_e32 v0, 1.0, v5
	v_mul_f32_e32 v5, 0x3d372713, v3
	v_mul_f32_e32 v5, v5, v3
	v_fma_f32 v5, v5, v3, v3
	v_and_b32_e32 v1, 0xffff0000, v33
	v_mul_f32_e32 v5, 0x3fcc422a, v5
	v_mul_f32_e32 v2, 0x3d372713, v1
	v_mul_f32_e32 v5, 0xbfb8aa3b, v5
	v_rcp_f32_e32 v0, v0
	v_mul_f32_e32 v2, v2, v1
	v_exp_f32_e32 v5, v5
	v_fma_f32 v2, v2, v1, v1
	v_mul_f32_e32 v2, 0x3fcc422a, v2
	v_mul_f32_e32 v2, 0xbfb8aa3b, v2
	v_exp_f32_e32 v2, v2
	v_mul_f32_e32 v0, v0, v4
	v_add_f32_e32 v4, 1.0, v5
	v_and_b32_e32 v5, 0xffff0000, v34
	v_mul_f32_e32 v6, 0x3d372713, v5
	v_mul_f32_e32 v6, v6, v5
	v_fma_f32 v6, v6, v5, v5
	v_add_f32_e32 v2, 1.0, v2
	v_mul_f32_e32 v6, 0x3fcc422a, v6
	v_rcp_f32_e32 v2, v2
	v_rcp_f32_e32 v4, v4
	v_mul_f32_e32 v6, 0xbfb8aa3b, v6
	v_exp_f32_e32 v6, v6
	v_mul_f32_e32 v1, v2, v1
	v_cvt_pk_bf16_f32 v33, v0, v1
	v_mul_f32_e32 v0, v4, v3
	v_lshlrev_b32_e32 v2, 16, v35
	v_and_b32_e32 v4, 0xffff0000, v35
	v_add_f32_e32 v1, 1.0, v6
	v_mul_f32_e32 v3, 0x3d372713, v2
	v_mul_f32_e32 v6, 0x3d372713, v4
	v_mul_f32_e32 v3, v3, v2
	v_mul_f32_e32 v6, v6, v4
	v_fma_f32 v3, v3, v2, v2
	v_fma_f32 v6, v6, v4, v4
	v_mul_f32_e32 v3, 0x3fcc422a, v3
	v_mul_f32_e32 v6, 0x3fcc422a, v6
	v_mul_f32_e32 v3, 0xbfb8aa3b, v3
	v_mul_f32_e32 v6, 0xbfb8aa3b, v6
	v_exp_f32_e32 v3, v3
	v_exp_f32_e32 v6, v6
	v_rcp_f32_e32 v1, v1
	s_mov_b64 s[26:27], -1
	v_add_f32_e32 v3, 1.0, v3
	v_add_f32_e32 v6, 1.0, v6
	v_rcp_f32_e32 v3, v3
	v_rcp_f32_e32 v6, v6
	v_mul_f32_e32 v1, v1, v5
	v_cvt_pk_bf16_f32 v34, v0, v1
	v_mul_f32_e32 v0, v3, v2
	v_mul_f32_e32 v1, v6, v4
	v_cvt_pk_bf16_f32 v35, v0, v1
	ds_read_b128 v[0:3], v72 offset:384
	ds_read_b128 v[4:7], v72 offset:416
	ds_read_b128 v[8:11], v72 offset:448
	ds_read_b128 v[12:15], v72 offset:480
	s_waitcnt lgkmcnt(0)
	s_nop 4
	s_and_b64 vcc, exec, s[4:5]
	v_mfma_f32_32x32x16_bf16 v[0:15], v[36:39], v[32:35], v[0:15]
	s_nop 11
	v_mul_f32_e32 v11, 0xbfb8aa3b, v11
	v_mul_f32_e32 v8, 0xbfb8aa3b, v8
	v_mul_f32_e32 v9, 0xbfb8aa3b, v9
	v_mul_f32_e32 v10, 0xbfb8aa3b, v10
	v_exp_f32_e32 v11, v11
	v_exp_f32_e32 v8, v8
	v_exp_f32_e32 v9, v9
	v_exp_f32_e32 v10, v10
	v_add_f32_e32 v11, 1.0, v11
	v_add_f32_e32 v8, 1.0, v8
	v_add_f32_e32 v9, 1.0, v9
	v_add_f32_e32 v10, 1.0, v10
	v_rcp_f32_e32 v11, v11
	v_rcp_f32_e32 v8, v8
	v_rcp_f32_e32 v9, v9
	v_rcp_f32_e32 v10, v10
	v_mul_f32_e32 v3, v3, v11
	v_mul_f32_e32 v0, v0, v8
	v_mul_f32_e32 v1, v1, v9
	v_mul_f32_e32 v2, v2, v10
	v_cvt_pk_bf16_f32 v8, v0, v1
	v_cvt_pk_bf16_f32 v3, v2, v3
	s_nop 0
	v_lshlrev_b32_e32 v0, 16, v8
	v_lshlrev_b32_e32 v1, 16, v3
	v_and_b32_e32 v2, 0xffff0000, v8
	v_and_b32_e32 v3, 0xffff0000, v3
	s_cbranch_vccnz .LBB0_199
	ds_read_b128 v[8:11], v73 offset:192
	v_mul_f32_e32 v32, v70, v0
	s_mov_b64 s[26:27], 0
	s_waitcnt lgkmcnt(0)
	v_mul_f32_e32 v8, v32, v8
	v_mul_f32_e32 v32, v70, v2
	v_mul_f32_e32 v9, v32, v9
	v_cvt_pk_bf16_f32 v8, v8, v9
	v_mul_f32_e32 v9, v70, v1
	v_mul_f32_e32 v9, v9, v10
	v_mul_f32_e32 v10, v70, v3
	v_mul_f32_e32 v10, v10, v11
	v_cvt_pk_bf16_f32 v9, v9, v10
	v_add_co_u32_e32 v10, vcc, 0x10800000, v60
	s_nop 1
	v_addc_co_u32_e32 v11, vcc, 0, v61, vcc
	global_store_dwordx2 v[10:11], v[8:9], off offset:96

.LBB0_201:
	v_mul_f32_e32 v3, 0xbfb8aa3b, v15
	v_mul_f32_e32 v0, 0xbfb8aa3b, v12
	v_mul_f32_e32 v1, 0xbfb8aa3b, v13
	v_mul_f32_e32 v2, 0xbfb8aa3b, v14
	v_exp_f32_e32 v3, v3
	v_exp_f32_e32 v0, v0
	v_exp_f32_e32 v1, v1
	v_exp_f32_e32 v2, v2
	v_add_f32_e32 v3, 1.0, v3
	v_add_f32_e32 v0, 1.0, v0
	v_add_f32_e32 v1, 1.0, v1
	v_add_f32_e32 v2, 1.0, v2
	v_rcp_f32_e32 v3, v3
	v_rcp_f32_e32 v0, v0
	v_rcp_f32_e32 v1, v1
	v_rcp_f32_e32 v2, v2
	v_mul_f32_e32 v3, v7, v3
	v_mul_f32_e32 v0, v4, v0
	v_mul_f32_e32 v1, v5, v1
	v_mul_f32_e32 v2, v6, v2
	v_cvt_pk_bf16_f32 v4, v0, v1
	v_cvt_pk_bf16_f32 v3, v2, v3
	s_mov_b64 s[26:27], -1
	s_and_b64 vcc, exec, s[4:5]
	v_lshlrev_b32_e32 v0, 16, v4
	v_lshlrev_b32_e32 v1, 16, v3
	v_and_b32_e32 v2, 0xffff0000, v4
	v_and_b32_e32 v3, 0xffff0000, v3
	s_cbranch_vccnz .LBB0_203
	ds_read_b128 v[4:7], v73 offset:224
	v_mul_f32_e32 v8, v70, v0
	s_mov_b64 s[26:27], 0
	s_waitcnt lgkmcnt(0)
	v_mul_f32_e32 v4, v8, v4
	v_mul_f32_e32 v8, v70, v2
	v_mul_f32_e32 v5, v8, v5
	v_cvt_pk_bf16_f32 v4, v4, v5
	v_mul_f32_e32 v5, v70, v1
	v_mul_f32_e32 v5, v5, v6
	v_mul_f32_e32 v6, v70, v3
	v_mul_f32_e32 v6, v6, v7
	v_cvt_pk_bf16_f32 v5, v5, v6
	v_add_co_u32_e32 v6, vcc, 0x10800000, v60
	s_nop 1
	v_addc_co_u32_e32 v7, vcc, 0, v61, vcc
	global_store_dwordx2 v[6:7], v[4:5], off offset:112

.LBB0_205:
	v_lshlrev_b32_e32 v0, 16, v28
	v_and_b32_e32 v2, 0xffff0000, v28
	v_mul_f32_e32 v1, 0x3d372713, v0
	v_mul_f32_e32 v3, 0x3d372713, v2
	v_mul_f32_e32 v1, v1, v0
	v_mul_f32_e32 v3, v3, v2
	v_fma_f32 v1, v1, v0, v0
	v_fma_f32 v3, v3, v2, v2
	v_mul_f32_e32 v1, 0x3fcc422a, v1
	v_mul_f32_e32 v3, 0x3fcc422a, v3
	v_mul_f32_e32 v1, 0xbfb8aa3b, v1
	v_mul_f32_e32 v3, 0xbfb8aa3b, v3
	v_exp_f32_e32 v1, v1
	v_exp_f32_e32 v3, v3
	v_lshlrev_b32_e32 v4, 16, v29
	v_mul_f32_e32 v5, 0x3d372713, v4
	v_mul_f32_e32 v5, v5, v4
	v_fma_f32 v5, v5, v4, v4
	v_add_f32_e32 v1, 1.0, v1
	v_add_f32_e32 v3, 1.0, v3
	v_mul_f32_e32 v5, 0x3fcc422a, v5
	v_rcp_f32_e32 v1, v1
	v_rcp_f32_e32 v3, v3
	v_mul_f32_e32 v5, 0xbfb8aa3b, v5
	v_exp_f32_e32 v5, v5
	v_mul_f32_e32 v0, v1, v0
	v_mul_f32_e32 v1, v3, v2
	v_lshlrev_b32_e32 v3, 16, v30
	ds_read_b128 v[32:35], v71 offset:4096
	v_cvt_pk_bf16_f32 v28, v0, v1
	v_add_f32_e32 v0, 1.0, v5
	v_mul_f32_e32 v5, 0x3d372713, v3
	v_mul_f32_e32 v5, v5, v3
	v_fma_f32 v5, v5, v3, v3
	v_and_b32_e32 v1, 0xffff0000, v29
	v_mul_f32_e32 v5, 0x3fcc422a, v5
	v_mul_f32_e32 v2, 0x3d372713, v1
	v_mul_f32_e32 v5, 0xbfb8aa3b, v5
	v_rcp_f32_e32 v0, v0
	v_mul_f32_e32 v2, v2, v1
	v_exp_f32_e32 v5, v5
	v_fma_f32 v2, v2, v1, v1
	v_mul_f32_e32 v2, 0x3fcc422a, v2
	v_mul_f32_e32 v2, 0xbfb8aa3b, v2
	v_exp_f32_e32 v2, v2
	v_mul_f32_e32 v0, v0, v4
	v_add_f32_e32 v4, 1.0, v5
	v_and_b32_e32 v5, 0xffff0000, v30
	v_mul_f32_e32 v6, 0x3d372713, v5
	v_mul_f32_e32 v6, v6, v5
	v_fma_f32 v6, v6, v5, v5
	v_add_f32_e32 v2, 1.0, v2
	v_mul_f32_e32 v6, 0x3fcc422a, v6
	v_rcp_f32_e32 v2, v2
	v_rcp_f32_e32 v4, v4
	v_mul_f32_e32 v6, 0xbfb8aa3b, v6
	v_exp_f32_e32 v6, v6
	v_mul_f32_e32 v1, v2, v1
	v_cvt_pk_bf16_f32 v29, v0, v1
	v_mul_f32_e32 v0, v4, v3
	v_lshlrev_b32_e32 v2, 16, v31
	v_and_b32_e32 v4, 0xffff0000, v31
	v_add_f32_e32 v1, 1.0, v6
	v_mul_f32_e32 v3, 0x3d372713, v2
	v_mul_f32_e32 v6, 0x3d372713, v4
	v_mul_f32_e32 v3, v3, v2
	v_mul_f32_e32 v6, v6, v4
	v_fma_f32 v3, v3, v2, v2
	v_fma_f32 v6, v6, v4, v4
	v_mul_f32_e32 v3, 0x3fcc422a, v3
	v_mul_f32_e32 v6, 0x3fcc422a, v6
	v_mul_f32_e32 v3, 0xbfb8aa3b, v3
	v_mul_f32_e32 v6, 0xbfb8aa3b, v6
	v_exp_f32_e32 v3, v3
	v_exp_f32_e32 v6, v6
	v_rcp_f32_e32 v1, v1
	s_mov_b64 s[26:27], -1
	v_add_f32_e32 v3, 1.0, v3
	v_add_f32_e32 v6, 1.0, v6
	v_rcp_f32_e32 v3, v3
	v_rcp_f32_e32 v6, v6
	v_mul_f32_e32 v1, v1, v5
	v_cvt_pk_bf16_f32 v30, v0, v1
	v_mul_f32_e32 v0, v3, v2
	v_mul_f32_e32 v1, v6, v4
	v_cvt_pk_bf16_f32 v31, v0, v1
	ds_read_b128 v[0:3], v72 offset:512
	ds_read_b128 v[4:7], v72 offset:544
	ds_read_b128 v[8:11], v72 offset:576
	ds_read_b128 v[12:15], v72 offset:608
	s_waitcnt lgkmcnt(0)
	s_nop 4
	s_and_b64 vcc, exec, s[4:5]
	v_mfma_f32_32x32x16_bf16 v[0:15], v[32:35], v[28:31], v[0:15]
	s_nop 11
	v_mul_f32_e32 v11, 0xbfb8aa3b, v11
	v_mul_f32_e32 v8, 0xbfb8aa3b, v8
	v_mul_f32_e32 v9, 0xbfb8aa3b, v9
	v_mul_f32_e32 v10, 0xbfb8aa3b, v10
	v_exp_f32_e32 v11, v11
	v_exp_f32_e32 v8, v8
	v_exp_f32_e32 v9, v9
	v_exp_f32_e32 v10, v10
	v_add_f32_e32 v11, 1.0, v11
	v_add_f32_e32 v8, 1.0, v8
	v_add_f32_e32 v9, 1.0, v9
	v_add_f32_e32 v10, 1.0, v10
	v_rcp_f32_e32 v11, v11
	v_rcp_f32_e32 v8, v8
	v_rcp_f32_e32 v9, v9
	v_rcp_f32_e32 v10, v10
	v_mul_f32_e32 v3, v3, v11
	v_mul_f32_e32 v0, v0, v8
	v_mul_f32_e32 v1, v1, v9
	v_mul_f32_e32 v2, v2, v10
	v_cvt_pk_bf16_f32 v8, v0, v1
	v_cvt_pk_bf16_f32 v3, v2, v3
	s_nop 0
	v_lshlrev_b32_e32 v0, 16, v8
	v_lshlrev_b32_e32 v1, 16, v3
	v_and_b32_e32 v2, 0xffff0000, v8
	v_and_b32_e32 v3, 0xffff0000, v3
	s_cbranch_vccnz .LBB0_207
	ds_read_b128 v[8:11], v73 offset:256
	v_mul_f32_e32 v28, v70, v0
	s_mov_b64 s[26:27], 0
	s_waitcnt lgkmcnt(0)
	v_mul_f32_e32 v8, v28, v8
	v_mul_f32_e32 v28, v70, v2
	v_mul_f32_e32 v9, v28, v9
	v_cvt_pk_bf16_f32 v8, v8, v9
	v_mul_f32_e32 v9, v70, v1
	v_mul_f32_e32 v9, v9, v10
	v_mul_f32_e32 v10, v70, v3
	v_mul_f32_e32 v10, v10, v11
	v_cvt_pk_bf16_f32 v9, v9, v10
	v_add_co_u32_e32 v10, vcc, 0x10800000, v60
	s_nop 1
	v_addc_co_u32_e32 v11, vcc, 0, v61, vcc
	global_store_dwordx2 v[10:11], v[8:9], off offset:128

.LBB0_209:
	v_mul_f32_e32 v3, 0xbfb8aa3b, v15
	v_mul_f32_e32 v0, 0xbfb8aa3b, v12
	v_mul_f32_e32 v1, 0xbfb8aa3b, v13
	v_mul_f32_e32 v2, 0xbfb8aa3b, v14
	v_exp_f32_e32 v3, v3
	v_exp_f32_e32 v0, v0
	v_exp_f32_e32 v1, v1
	v_exp_f32_e32 v2, v2
	v_add_f32_e32 v3, 1.0, v3
	v_add_f32_e32 v0, 1.0, v0
	v_add_f32_e32 v1, 1.0, v1
	v_add_f32_e32 v2, 1.0, v2
	v_rcp_f32_e32 v3, v3
	v_rcp_f32_e32 v0, v0
	v_rcp_f32_e32 v1, v1
	v_rcp_f32_e32 v2, v2
	v_mul_f32_e32 v3, v7, v3
	v_mul_f32_e32 v0, v4, v0
	v_mul_f32_e32 v1, v5, v1
	v_mul_f32_e32 v2, v6, v2
	v_cvt_pk_bf16_f32 v4, v0, v1
	v_cvt_pk_bf16_f32 v3, v2, v3
	s_mov_b64 s[26:27], -1
	s_and_b64 vcc, exec, s[4:5]
	v_lshlrev_b32_e32 v0, 16, v4
	v_lshlrev_b32_e32 v1, 16, v3
	v_and_b32_e32 v2, 0xffff0000, v4
	v_and_b32_e32 v3, 0xffff0000, v3
	s_cbranch_vccnz .LBB0_211
	ds_read_b128 v[4:7], v73 offset:288
	v_mul_f32_e32 v8, v70, v0
	s_mov_b64 s[26:27], 0
	s_waitcnt lgkmcnt(0)
	v_mul_f32_e32 v4, v8, v4
	v_mul_f32_e32 v8, v70, v2
	v_mul_f32_e32 v5, v8, v5
	v_cvt_pk_bf16_f32 v4, v4, v5
	v_mul_f32_e32 v5, v70, v1
	v_mul_f32_e32 v5, v5, v6
	v_mul_f32_e32 v6, v70, v3
	v_mul_f32_e32 v6, v6, v7
	v_cvt_pk_bf16_f32 v5, v5, v6
	v_add_co_u32_e32 v6, vcc, 0x10800000, v60
	s_nop 1
	v_addc_co_u32_e32 v7, vcc, 0, v61, vcc
	global_store_dwordx2 v[6:7], v[4:5], off offset:144

.LBB0_213:
	v_lshlrev_b32_e32 v0, 16, v24
	v_and_b32_e32 v2, 0xffff0000, v24
	v_mul_f32_e32 v1, 0x3d372713, v0
	v_mul_f32_e32 v3, 0x3d372713, v2
	v_mul_f32_e32 v1, v1, v0
	v_mul_f32_e32 v3, v3, v2
	v_fma_f32 v1, v1, v0, v0
	v_fma_f32 v3, v3, v2, v2
	v_mul_f32_e32 v1, 0x3fcc422a, v1
	v_mul_f32_e32 v3, 0x3fcc422a, v3
	v_mul_f32_e32 v1, 0xbfb8aa3b, v1
	v_mul_f32_e32 v3, 0xbfb8aa3b, v3
	v_exp_f32_e32 v1, v1
	v_exp_f32_e32 v3, v3
	v_lshlrev_b32_e32 v4, 16, v25
	v_mul_f32_e32 v5, 0x3d372713, v4
	v_mul_f32_e32 v5, v5, v4
	v_fma_f32 v5, v5, v4, v4
	v_add_f32_e32 v1, 1.0, v1
	v_add_f32_e32 v3, 1.0, v3
	v_mul_f32_e32 v5, 0x3fcc422a, v5
	v_rcp_f32_e32 v1, v1
	v_rcp_f32_e32 v3, v3
	v_mul_f32_e32 v5, 0xbfb8aa3b, v5
	v_exp_f32_e32 v5, v5
	v_mul_f32_e32 v0, v1, v0
	v_mul_f32_e32 v1, v3, v2
	v_lshlrev_b32_e32 v3, 16, v26
	ds_read_b128 v[28:31], v71 offset:5120
	v_cvt_pk_bf16_f32 v24, v0, v1
	v_add_f32_e32 v0, 1.0, v5
	v_mul_f32_e32 v5, 0x3d372713, v3
	v_mul_f32_e32 v5, v5, v3
	v_fma_f32 v5, v5, v3, v3
	v_and_b32_e32 v1, 0xffff0000, v25
	v_mul_f32_e32 v5, 0x3fcc422a, v5
	v_mul_f32_e32 v2, 0x3d372713, v1
	v_mul_f32_e32 v5, 0xbfb8aa3b, v5
	v_rcp_f32_e32 v0, v0
	v_mul_f32_e32 v2, v2, v1
	v_exp_f32_e32 v5, v5
	v_fma_f32 v2, v2, v1, v1
	v_mul_f32_e32 v2, 0x3fcc422a, v2
	v_mul_f32_e32 v2, 0xbfb8aa3b, v2
	v_exp_f32_e32 v2, v2
	v_mul_f32_e32 v0, v0, v4
	v_add_f32_e32 v4, 1.0, v5
	v_and_b32_e32 v5, 0xffff0000, v26
	v_mul_f32_e32 v6, 0x3d372713, v5
	v_mul_f32_e32 v6, v6, v5
	v_fma_f32 v6, v6, v5, v5
	v_add_f32_e32 v2, 1.0, v2
	v_mul_f32_e32 v6, 0x3fcc422a, v6
	v_rcp_f32_e32 v2, v2
	v_rcp_f32_e32 v4, v4
	v_mul_f32_e32 v6, 0xbfb8aa3b, v6
	v_exp_f32_e32 v6, v6
	v_mul_f32_e32 v1, v2, v1
	v_cvt_pk_bf16_f32 v25, v0, v1
	v_mul_f32_e32 v0, v4, v3
	v_lshlrev_b32_e32 v2, 16, v27
	v_and_b32_e32 v4, 0xffff0000, v27
	v_add_f32_e32 v1, 1.0, v6
	v_mul_f32_e32 v3, 0x3d372713, v2
	v_mul_f32_e32 v6, 0x3d372713, v4
	v_mul_f32_e32 v3, v3, v2
	v_mul_f32_e32 v6, v6, v4
	v_fma_f32 v3, v3, v2, v2
	v_fma_f32 v6, v6, v4, v4
	v_mul_f32_e32 v3, 0x3fcc422a, v3
	v_mul_f32_e32 v6, 0x3fcc422a, v6
	v_mul_f32_e32 v3, 0xbfb8aa3b, v3
	v_mul_f32_e32 v6, 0xbfb8aa3b, v6
	v_exp_f32_e32 v3, v3
	v_exp_f32_e32 v6, v6
	v_rcp_f32_e32 v1, v1
	s_mov_b64 s[26:27], -1
	v_add_f32_e32 v3, 1.0, v3
	v_add_f32_e32 v6, 1.0, v6
	v_rcp_f32_e32 v3, v3
	v_rcp_f32_e32 v6, v6
	v_mul_f32_e32 v1, v1, v5
	v_cvt_pk_bf16_f32 v26, v0, v1
	v_mul_f32_e32 v0, v3, v2
	v_mul_f32_e32 v1, v6, v4
	v_cvt_pk_bf16_f32 v27, v0, v1
	ds_read_b128 v[0:3], v72 offset:640
	ds_read_b128 v[4:7], v72 offset:672
	ds_read_b128 v[8:11], v72 offset:704
	ds_read_b128 v[12:15], v72 offset:736
	s_waitcnt lgkmcnt(0)
	s_nop 4
	s_and_b64 vcc, exec, s[4:5]
	v_mfma_f32_32x32x16_bf16 v[0:15], v[28:31], v[24:27], v[0:15]
	s_nop 11
	v_mul_f32_e32 v11, 0xbfb8aa3b, v11
	v_mul_f32_e32 v8, 0xbfb8aa3b, v8
	v_mul_f32_e32 v9, 0xbfb8aa3b, v9
	v_mul_f32_e32 v10, 0xbfb8aa3b, v10
	v_exp_f32_e32 v11, v11
	v_exp_f32_e32 v8, v8
	v_exp_f32_e32 v9, v9
	v_exp_f32_e32 v10, v10
	v_add_f32_e32 v11, 1.0, v11
	v_add_f32_e32 v8, 1.0, v8
	v_add_f32_e32 v9, 1.0, v9
	v_add_f32_e32 v10, 1.0, v10
	v_rcp_f32_e32 v11, v11
	v_rcp_f32_e32 v8, v8
	v_rcp_f32_e32 v9, v9
	v_rcp_f32_e32 v10, v10
	v_mul_f32_e32 v3, v3, v11
	v_mul_f32_e32 v0, v0, v8
	v_mul_f32_e32 v1, v1, v9
	v_mul_f32_e32 v2, v2, v10
	v_cvt_pk_bf16_f32 v8, v0, v1
	v_cvt_pk_bf16_f32 v3, v2, v3
	s_nop 0
	v_lshlrev_b32_e32 v0, 16, v8
	v_lshlrev_b32_e32 v1, 16, v3
	v_and_b32_e32 v2, 0xffff0000, v8
	v_and_b32_e32 v3, 0xffff0000, v3
	s_cbranch_vccnz .LBB0_215
	ds_read_b128 v[8:11], v73 offset:320
	v_mul_f32_e32 v24, v70, v0
	s_mov_b64 s[26:27], 0
	s_waitcnt lgkmcnt(0)
	v_mul_f32_e32 v8, v24, v8
	v_mul_f32_e32 v24, v70, v2
	v_mul_f32_e32 v9, v24, v9
	v_cvt_pk_bf16_f32 v8, v8, v9
	v_mul_f32_e32 v9, v70, v1
	v_mul_f32_e32 v9, v9, v10
	v_mul_f32_e32 v10, v70, v3
	v_mul_f32_e32 v10, v10, v11
	v_cvt_pk_bf16_f32 v9, v9, v10
	v_add_co_u32_e32 v10, vcc, 0x10800000, v60
	s_nop 1
	v_addc_co_u32_e32 v11, vcc, 0, v61, vcc
	global_store_dwordx2 v[10:11], v[8:9], off offset:160

.LBB0_217:
	v_mul_f32_e32 v3, 0xbfb8aa3b, v15
	v_mul_f32_e32 v0, 0xbfb8aa3b, v12
	v_mul_f32_e32 v1, 0xbfb8aa3b, v13
	v_mul_f32_e32 v2, 0xbfb8aa3b, v14
	v_exp_f32_e32 v3, v3
	v_exp_f32_e32 v0, v0
	v_exp_f32_e32 v1, v1
	v_exp_f32_e32 v2, v2
	v_add_f32_e32 v3, 1.0, v3
	v_add_f32_e32 v0, 1.0, v0
	v_add_f32_e32 v1, 1.0, v1
	v_add_f32_e32 v2, 1.0, v2
	v_rcp_f32_e32 v3, v3
	v_rcp_f32_e32 v0, v0
	v_rcp_f32_e32 v1, v1
	v_rcp_f32_e32 v2, v2
	v_mul_f32_e32 v3, v7, v3
	v_mul_f32_e32 v0, v4, v0
	v_mul_f32_e32 v1, v5, v1
	v_mul_f32_e32 v2, v6, v2
	v_cvt_pk_bf16_f32 v4, v0, v1
	v_cvt_pk_bf16_f32 v3, v2, v3
	s_mov_b64 s[26:27], -1
	s_and_b64 vcc, exec, s[4:5]
	v_lshlrev_b32_e32 v0, 16, v4
	v_lshlrev_b32_e32 v1, 16, v3
	v_and_b32_e32 v2, 0xffff0000, v4
	v_and_b32_e32 v3, 0xffff0000, v3
	s_cbranch_vccnz .LBB0_219
	ds_read_b128 v[4:7], v73 offset:352
	v_mul_f32_e32 v8, v70, v0
	s_mov_b64 s[26:27], 0
	s_waitcnt lgkmcnt(0)
	v_mul_f32_e32 v4, v8, v4
	v_mul_f32_e32 v8, v70, v2
	v_mul_f32_e32 v5, v8, v5
	v_cvt_pk_bf16_f32 v4, v4, v5
	v_mul_f32_e32 v5, v70, v1
	v_mul_f32_e32 v5, v5, v6
	v_mul_f32_e32 v6, v70, v3
	v_mul_f32_e32 v6, v6, v7
	v_cvt_pk_bf16_f32 v5, v5, v6
	v_add_co_u32_e32 v6, vcc, 0x10800000, v60
	s_nop 1
	v_addc_co_u32_e32 v7, vcc, 0, v61, vcc
	global_store_dwordx2 v[6:7], v[4:5], off offset:176

.LBB0_221:
	v_lshlrev_b32_e32 v0, 16, v20
	v_and_b32_e32 v2, 0xffff0000, v20
	v_mul_f32_e32 v1, 0x3d372713, v0
	v_mul_f32_e32 v3, 0x3d372713, v2
	v_mul_f32_e32 v1, v1, v0
	v_mul_f32_e32 v3, v3, v2
	v_fma_f32 v1, v1, v0, v0
	v_fma_f32 v3, v3, v2, v2
	v_mul_f32_e32 v1, 0x3fcc422a, v1
	v_mul_f32_e32 v3, 0x3fcc422a, v3
	v_mul_f32_e32 v1, 0xbfb8aa3b, v1
	v_mul_f32_e32 v3, 0xbfb8aa3b, v3
	v_exp_f32_e32 v1, v1
	v_exp_f32_e32 v3, v3
	v_lshlrev_b32_e32 v4, 16, v21
	v_mul_f32_e32 v5, 0x3d372713, v4
	v_mul_f32_e32 v5, v5, v4
	v_fma_f32 v5, v5, v4, v4
	v_add_f32_e32 v1, 1.0, v1
	v_add_f32_e32 v3, 1.0, v3
	v_mul_f32_e32 v5, 0x3fcc422a, v5
	v_rcp_f32_e32 v1, v1
	v_rcp_f32_e32 v3, v3
	v_mul_f32_e32 v5, 0xbfb8aa3b, v5
	v_exp_f32_e32 v5, v5
	v_mul_f32_e32 v0, v1, v0
	v_mul_f32_e32 v1, v3, v2
	v_lshlrev_b32_e32 v3, 16, v22
	ds_read_b128 v[24:27], v71 offset:6144
	v_cvt_pk_bf16_f32 v20, v0, v1
	v_add_f32_e32 v0, 1.0, v5
	v_mul_f32_e32 v5, 0x3d372713, v3
	v_mul_f32_e32 v5, v5, v3
	v_fma_f32 v5, v5, v3, v3
	v_and_b32_e32 v1, 0xffff0000, v21
	v_mul_f32_e32 v5, 0x3fcc422a, v5
	v_mul_f32_e32 v2, 0x3d372713, v1
	v_mul_f32_e32 v5, 0xbfb8aa3b, v5
	v_rcp_f32_e32 v0, v0
	v_mul_f32_e32 v2, v2, v1
	v_exp_f32_e32 v5, v5
	v_fma_f32 v2, v2, v1, v1
	v_mul_f32_e32 v2, 0x3fcc422a, v2
	v_mul_f32_e32 v2, 0xbfb8aa3b, v2
	v_exp_f32_e32 v2, v2
	v_mul_f32_e32 v0, v0, v4
	v_add_f32_e32 v4, 1.0, v5
	v_and_b32_e32 v5, 0xffff0000, v22
	v_mul_f32_e32 v6, 0x3d372713, v5
	v_mul_f32_e32 v6, v6, v5
	v_fma_f32 v6, v6, v5, v5
	v_add_f32_e32 v2, 1.0, v2
	v_mul_f32_e32 v6, 0x3fcc422a, v6
	v_rcp_f32_e32 v2, v2
	v_rcp_f32_e32 v4, v4
	v_mul_f32_e32 v6, 0xbfb8aa3b, v6
	v_exp_f32_e32 v6, v6
	v_mul_f32_e32 v1, v2, v1
	v_cvt_pk_bf16_f32 v21, v0, v1
	v_mul_f32_e32 v0, v4, v3
	v_lshlrev_b32_e32 v2, 16, v23
	v_and_b32_e32 v4, 0xffff0000, v23
	v_add_f32_e32 v1, 1.0, v6
	v_mul_f32_e32 v3, 0x3d372713, v2
	v_mul_f32_e32 v6, 0x3d372713, v4
	v_mul_f32_e32 v3, v3, v2
	v_mul_f32_e32 v6, v6, v4
	v_fma_f32 v3, v3, v2, v2
	v_fma_f32 v6, v6, v4, v4
	v_mul_f32_e32 v3, 0x3fcc422a, v3
	v_mul_f32_e32 v6, 0x3fcc422a, v6
	v_mul_f32_e32 v3, 0xbfb8aa3b, v3
	v_mul_f32_e32 v6, 0xbfb8aa3b, v6
	v_exp_f32_e32 v3, v3
	v_exp_f32_e32 v6, v6
	v_rcp_f32_e32 v1, v1
	s_mov_b64 s[26:27], -1
	v_add_f32_e32 v3, 1.0, v3
	v_add_f32_e32 v6, 1.0, v6
	v_rcp_f32_e32 v3, v3
	v_rcp_f32_e32 v6, v6
	v_mul_f32_e32 v1, v1, v5
	v_cvt_pk_bf16_f32 v22, v0, v1
	v_mul_f32_e32 v0, v3, v2
	v_mul_f32_e32 v1, v6, v4
	v_cvt_pk_bf16_f32 v23, v0, v1
	ds_read_b128 v[0:3], v72 offset:768
	ds_read_b128 v[4:7], v72 offset:800
	ds_read_b128 v[8:11], v72 offset:832
	ds_read_b128 v[12:15], v72 offset:864
	s_waitcnt lgkmcnt(0)
	s_nop 4
	s_and_b64 vcc, exec, s[4:5]
	v_mfma_f32_32x32x16_bf16 v[0:15], v[24:27], v[20:23], v[0:15]
	s_nop 11
	v_mul_f32_e32 v11, 0xbfb8aa3b, v11
	v_mul_f32_e32 v8, 0xbfb8aa3b, v8
	v_mul_f32_e32 v9, 0xbfb8aa3b, v9
	v_mul_f32_e32 v10, 0xbfb8aa3b, v10
	v_exp_f32_e32 v11, v11
	v_exp_f32_e32 v8, v8
	v_exp_f32_e32 v9, v9
	v_exp_f32_e32 v10, v10
	v_add_f32_e32 v11, 1.0, v11
	v_add_f32_e32 v8, 1.0, v8
	v_add_f32_e32 v9, 1.0, v9
	v_add_f32_e32 v10, 1.0, v10
	v_rcp_f32_e32 v11, v11
	v_rcp_f32_e32 v8, v8
	v_rcp_f32_e32 v9, v9
	v_rcp_f32_e32 v10, v10
	v_mul_f32_e32 v3, v3, v11
	v_mul_f32_e32 v0, v0, v8
	v_mul_f32_e32 v1, v1, v9
	v_mul_f32_e32 v2, v2, v10
	v_cvt_pk_bf16_f32 v8, v0, v1
	v_cvt_pk_bf16_f32 v3, v2, v3
	s_nop 0
	v_lshlrev_b32_e32 v0, 16, v8
	v_lshlrev_b32_e32 v1, 16, v3
	v_and_b32_e32 v2, 0xffff0000, v8
	v_and_b32_e32 v3, 0xffff0000, v3
	s_cbranch_vccnz .LBB0_223
	ds_read_b128 v[8:11], v73 offset:384
	v_mul_f32_e32 v20, v70, v0
	s_mov_b64 s[26:27], 0
	s_waitcnt lgkmcnt(0)
	v_mul_f32_e32 v8, v20, v8
	v_mul_f32_e32 v20, v70, v2
	v_mul_f32_e32 v9, v20, v9
	v_cvt_pk_bf16_f32 v8, v8, v9
	v_mul_f32_e32 v9, v70, v1
	v_mul_f32_e32 v9, v9, v10
	v_mul_f32_e32 v10, v70, v3
	v_mul_f32_e32 v10, v10, v11
	v_cvt_pk_bf16_f32 v9, v9, v10
	v_add_co_u32_e32 v10, vcc, 0x10800000, v60
	s_nop 1
	v_addc_co_u32_e32 v11, vcc, 0, v61, vcc
	global_store_dwordx2 v[10:11], v[8:9], off offset:192

.LBB0_225:
	v_mul_f32_e32 v3, 0xbfb8aa3b, v15
	v_mul_f32_e32 v0, 0xbfb8aa3b, v12
	v_mul_f32_e32 v1, 0xbfb8aa3b, v13
	v_mul_f32_e32 v2, 0xbfb8aa3b, v14
	v_exp_f32_e32 v3, v3
	v_exp_f32_e32 v0, v0
	v_exp_f32_e32 v1, v1
	v_exp_f32_e32 v2, v2
	v_add_f32_e32 v3, 1.0, v3
	v_add_f32_e32 v0, 1.0, v0
	v_add_f32_e32 v1, 1.0, v1
	v_add_f32_e32 v2, 1.0, v2
	v_rcp_f32_e32 v3, v3
	v_rcp_f32_e32 v0, v0
	v_rcp_f32_e32 v1, v1
	v_rcp_f32_e32 v2, v2
	v_mul_f32_e32 v3, v7, v3
	v_mul_f32_e32 v0, v4, v0
	v_mul_f32_e32 v1, v5, v1
	v_mul_f32_e32 v2, v6, v2
	v_cvt_pk_bf16_f32 v4, v0, v1
	v_cvt_pk_bf16_f32 v3, v2, v3
	s_mov_b64 s[26:27], -1
	s_and_b64 vcc, exec, s[4:5]
	v_lshlrev_b32_e32 v0, 16, v4
	v_lshlrev_b32_e32 v1, 16, v3
	v_and_b32_e32 v2, 0xffff0000, v4
	v_and_b32_e32 v3, 0xffff0000, v3
	s_cbranch_vccnz .LBB0_227
	ds_read_b128 v[4:7], v73 offset:416
	v_mul_f32_e32 v8, v70, v0
	s_mov_b64 s[26:27], 0
	s_waitcnt lgkmcnt(0)
	v_mul_f32_e32 v4, v8, v4
	v_mul_f32_e32 v8, v70, v2
	v_mul_f32_e32 v5, v8, v5
	v_cvt_pk_bf16_f32 v4, v4, v5
	v_mul_f32_e32 v5, v70, v1
	v_mul_f32_e32 v5, v5, v6
	v_mul_f32_e32 v6, v70, v3
	v_mul_f32_e32 v6, v6, v7
	v_cvt_pk_bf16_f32 v5, v5, v6
	v_add_co_u32_e32 v6, vcc, 0x10800000, v60
	s_nop 1
	v_addc_co_u32_e32 v7, vcc, 0, v61, vcc
	global_store_dwordx2 v[6:7], v[4:5], off offset:208

.LBB0_229:
	v_lshlrev_b32_e32 v0, 16, v16
	v_and_b32_e32 v2, 0xffff0000, v16
	v_mul_f32_e32 v1, 0x3d372713, v0
	v_mul_f32_e32 v3, 0x3d372713, v2
	v_mul_f32_e32 v1, v1, v0
	v_mul_f32_e32 v3, v3, v2
	v_fma_f32 v1, v1, v0, v0
	v_fma_f32 v3, v3, v2, v2
	v_mul_f32_e32 v1, 0x3fcc422a, v1
	v_mul_f32_e32 v3, 0x3fcc422a, v3
	v_mul_f32_e32 v1, 0xbfb8aa3b, v1
	v_mul_f32_e32 v3, 0xbfb8aa3b, v3
	v_exp_f32_e32 v1, v1
	v_exp_f32_e32 v3, v3
	v_lshlrev_b32_e32 v4, 16, v17
	v_mul_f32_e32 v5, 0x3d372713, v4
	v_mul_f32_e32 v5, v5, v4
	v_fma_f32 v5, v5, v4, v4
	v_add_f32_e32 v1, 1.0, v1
	v_add_f32_e32 v3, 1.0, v3
	v_mul_f32_e32 v5, 0x3fcc422a, v5
	v_rcp_f32_e32 v1, v1
	v_rcp_f32_e32 v3, v3
	v_mul_f32_e32 v5, 0xbfb8aa3b, v5
	v_exp_f32_e32 v5, v5
	v_mul_f32_e32 v0, v1, v0
	v_mul_f32_e32 v1, v3, v2
	v_lshlrev_b32_e32 v3, 16, v18
	ds_read_b128 v[20:23], v71 offset:7168
	v_cvt_pk_bf16_f32 v16, v0, v1
	v_add_f32_e32 v0, 1.0, v5
	v_mul_f32_e32 v5, 0x3d372713, v3
	v_mul_f32_e32 v5, v5, v3
	v_fma_f32 v5, v5, v3, v3
	v_and_b32_e32 v1, 0xffff0000, v17
	v_mul_f32_e32 v5, 0x3fcc422a, v5
	v_mul_f32_e32 v2, 0x3d372713, v1
	v_mul_f32_e32 v5, 0xbfb8aa3b, v5
	v_rcp_f32_e32 v0, v0
	v_mul_f32_e32 v2, v2, v1
	v_exp_f32_e32 v5, v5
	v_fma_f32 v2, v2, v1, v1
	v_mul_f32_e32 v2, 0x3fcc422a, v2
	v_mul_f32_e32 v2, 0xbfb8aa3b, v2
	v_exp_f32_e32 v2, v2
	v_mul_f32_e32 v0, v0, v4
	v_add_f32_e32 v4, 1.0, v5
	v_and_b32_e32 v5, 0xffff0000, v18
	v_mul_f32_e32 v6, 0x3d372713, v5
	v_mul_f32_e32 v6, v6, v5
	v_fma_f32 v6, v6, v5, v5
	v_add_f32_e32 v2, 1.0, v2
	v_mul_f32_e32 v6, 0x3fcc422a, v6
	v_rcp_f32_e32 v2, v2
	v_rcp_f32_e32 v4, v4
	v_mul_f32_e32 v6, 0xbfb8aa3b, v6
	v_exp_f32_e32 v6, v6
	v_mul_f32_e32 v1, v2, v1
	v_cvt_pk_bf16_f32 v17, v0, v1
	v_mul_f32_e32 v0, v4, v3
	v_lshlrev_b32_e32 v2, 16, v19
	v_and_b32_e32 v4, 0xffff0000, v19
	v_add_f32_e32 v1, 1.0, v6
	v_mul_f32_e32 v3, 0x3d372713, v2
	v_mul_f32_e32 v6, 0x3d372713, v4
	v_mul_f32_e32 v3, v3, v2
	v_mul_f32_e32 v6, v6, v4
	v_fma_f32 v3, v3, v2, v2
	v_fma_f32 v6, v6, v4, v4
	v_mul_f32_e32 v3, 0x3fcc422a, v3
	v_mul_f32_e32 v6, 0x3fcc422a, v6
	v_mul_f32_e32 v3, 0xbfb8aa3b, v3
	v_mul_f32_e32 v6, 0xbfb8aa3b, v6
	v_exp_f32_e32 v3, v3
	v_exp_f32_e32 v6, v6
	v_rcp_f32_e32 v1, v1
	s_mov_b64 s[26:27], -1
	v_add_f32_e32 v3, 1.0, v3
	v_add_f32_e32 v6, 1.0, v6
	v_rcp_f32_e32 v3, v3
	v_rcp_f32_e32 v6, v6
	v_mul_f32_e32 v1, v1, v5
	v_cvt_pk_bf16_f32 v18, v0, v1
	v_mul_f32_e32 v0, v3, v2
	v_mul_f32_e32 v1, v6, v4
	v_cvt_pk_bf16_f32 v19, v0, v1
	ds_read_b128 v[0:3], v72 offset:896
	ds_read_b128 v[4:7], v72 offset:928
	ds_read_b128 v[8:11], v72 offset:960
	ds_read_b128 v[12:15], v72 offset:992
	s_waitcnt lgkmcnt(0)
	s_nop 4
	s_and_b64 vcc, exec, s[4:5]
	v_mfma_f32_32x32x16_bf16 v[0:15], v[20:23], v[16:19], v[0:15]
	s_nop 11
	v_mul_f32_e32 v11, 0xbfb8aa3b, v11
	v_mul_f32_e32 v8, 0xbfb8aa3b, v8
	v_mul_f32_e32 v9, 0xbfb8aa3b, v9
	v_mul_f32_e32 v10, 0xbfb8aa3b, v10
	v_exp_f32_e32 v11, v11
	v_exp_f32_e32 v8, v8
	v_exp_f32_e32 v9, v9
	v_exp_f32_e32 v10, v10
	v_add_f32_e32 v11, 1.0, v11
	v_add_f32_e32 v8, 1.0, v8
	v_add_f32_e32 v9, 1.0, v9
	v_add_f32_e32 v10, 1.0, v10
	v_rcp_f32_e32 v11, v11
	v_rcp_f32_e32 v8, v8
	v_rcp_f32_e32 v9, v9
	v_rcp_f32_e32 v10, v10
	v_mul_f32_e32 v3, v3, v11
	v_mul_f32_e32 v0, v0, v8
	v_mul_f32_e32 v1, v1, v9
	v_mul_f32_e32 v2, v2, v10
	v_cvt_pk_bf16_f32 v8, v0, v1
	v_cvt_pk_bf16_f32 v3, v2, v3
	s_nop 0
	v_lshlrev_b32_e32 v0, 16, v8
	v_lshlrev_b32_e32 v1, 16, v3
	v_and_b32_e32 v2, 0xffff0000, v8
	v_and_b32_e32 v3, 0xffff0000, v3
	s_cbranch_vccnz .LBB0_231
	ds_read_b128 v[8:11], v73 offset:448
	v_mul_f32_e32 v16, v70, v0
	s_mov_b64 s[26:27], 0
	s_waitcnt lgkmcnt(0)
	v_mul_f32_e32 v8, v16, v8
	v_mul_f32_e32 v16, v70, v2
	v_mul_f32_e32 v9, v16, v9
	v_cvt_pk_bf16_f32 v8, v8, v9
	v_mul_f32_e32 v9, v70, v1
	v_mul_f32_e32 v9, v9, v10
	v_mul_f32_e32 v10, v70, v3
	v_mul_f32_e32 v10, v10, v11
	v_cvt_pk_bf16_f32 v9, v9, v10
	v_add_co_u32_e32 v10, vcc, 0x10800000, v60
	s_nop 1
	v_addc_co_u32_e32 v11, vcc, 0, v61, vcc
	global_store_dwordx2 v[10:11], v[8:9], off offset:224

.LBB0_233:
	v_mul_f32_e32 v3, 0xbfb8aa3b, v15
	v_mul_f32_e32 v0, 0xbfb8aa3b, v12
	v_mul_f32_e32 v1, 0xbfb8aa3b, v13
	v_mul_f32_e32 v2, 0xbfb8aa3b, v14
	v_exp_f32_e32 v3, v3
	v_exp_f32_e32 v0, v0
	v_exp_f32_e32 v1, v1
	v_exp_f32_e32 v2, v2
	v_add_f32_e32 v3, 1.0, v3
	v_add_f32_e32 v0, 1.0, v0
	v_add_f32_e32 v1, 1.0, v1
	v_add_f32_e32 v2, 1.0, v2
	v_rcp_f32_e32 v3, v3
	v_rcp_f32_e32 v0, v0
	v_rcp_f32_e32 v1, v1
	v_rcp_f32_e32 v2, v2
	v_mul_f32_e32 v3, v7, v3
	v_mul_f32_e32 v0, v4, v0
	v_mul_f32_e32 v1, v5, v1
	v_mul_f32_e32 v2, v6, v2
	v_cvt_pk_bf16_f32 v4, v0, v1
	v_cvt_pk_bf16_f32 v3, v2, v3
	s_mov_b64 s[26:27], -1
	s_and_b64 vcc, exec, s[4:5]
	v_lshlrev_b32_e32 v0, 16, v4
	v_lshlrev_b32_e32 v1, 16, v3
	v_and_b32_e32 v2, 0xffff0000, v4
	v_and_b32_e32 v3, 0xffff0000, v3
	s_cbranch_vccnz .LBB0_235
	ds_read_b128 v[4:7], v73 offset:480
	v_mul_f32_e32 v8, v70, v0
	s_mov_b64 s[26:27], 0
	s_waitcnt lgkmcnt(0)
	v_mul_f32_e32 v4, v8, v4
	v_mul_f32_e32 v8, v70, v2
	v_mul_f32_e32 v5, v8, v5
	v_cvt_pk_bf16_f32 v4, v4, v5
	v_mul_f32_e32 v5, v70, v1
	v_mul_f32_e32 v5, v5, v6
	v_mul_f32_e32 v6, v70, v3
	v_mul_f32_e32 v6, v6, v7
	v_cvt_pk_bf16_f32 v5, v5, v6
	v_add_co_u32_e32 v6, vcc, 0x10800000, v60
	s_nop 1
	v_addc_co_u32_e32 v7, vcc, 0, v61, vcc
	global_store_dwordx2 v[6:7], v[4:5], off offset:240

.LBB0_240:
	s_nop 0
	v_add_u32_e32 v10, s4, v67
	v_add_u32_e32 v60, 8, v10
	v_ashrrev_i32_e32 v61, 31, v60
	v_lshlrev_b64 v[8:9], 10, v[60:61]
	v_lshl_add_u64 v[8:9], v[48:49], 0, v[8:9]
	global_load_dwordx4 v[28:31], v[8:9], off
	v_add_u32_e32 v70, 9, v10
	v_ashrrev_i32_e32 v71, 31, v70
	v_lshlrev_b64 v[8:9], 10, v[70:71]
	v_lshl_add_u64 v[8:9], v[48:49], 0, v[8:9]
	global_load_dwordx4 v[32:35], v[8:9], off
	v_add_u32_e32 v72, 10, v10
	v_ashrrev_i32_e32 v73, 31, v72
	v_lshlrev_b64 v[8:9], 10, v[72:73]
	v_lshl_add_u64 v[8:9], v[48:49], 0, v[8:9]
	global_load_dwordx4 v[36:39], v[8:9], off
	v_add_u32_e32 v74, 11, v10
	v_ashrrev_i32_e32 v75, 31, v74
	v_lshlrev_b64 v[8:9], 10, v[74:75]
	v_add_u32_e32 v26, 12, v10
	v_lshl_add_u64 v[8:9], v[48:49], 0, v[8:9]
	v_ashrrev_i32_e32 v27, 31, v26
	global_load_dwordx4 v[40:43], v[8:9], off
	v_lshlrev_b64 v[8:9], 10, v[26:27]
	v_add_u32_e32 v24, 13, v10
	v_lshl_add_u64 v[8:9], v[48:49], 0, v[8:9]
	v_ashrrev_i32_e32 v25, 31, v24
	global_load_dwordx4 v[56:59], v[8:9], off
	v_lshlrev_b64 v[8:9], 10, v[24:25]
	v_add_u32_e32 v22, 14, v10
	v_lshl_add_u64 v[8:9], v[48:49], 0, v[8:9]
	v_ashrrev_i32_e32 v23, 31, v22
	global_load_dwordx4 v[16:19], v[8:9], off
	v_lshlrev_b64 v[8:9], 10, v[22:23]
	v_add_u32_e32 v20, 15, v10
	v_lshl_add_u64 v[8:9], v[48:49], 0, v[8:9]
	v_ashrrev_i32_e32 v21, 31, v20
	global_load_dwordx4 v[12:15], v[8:9], off
	v_lshlrev_b64 v[8:9], 10, v[20:21]
	v_lshl_add_u64 v[8:9], v[48:49], 0, v[8:9]
	global_load_dwordx4 v[8:11], v[8:9], off
	v_lshlrev_b64 v[60:61], 11, v[60:61]
	v_lshl_add_u64 v[60:61], v[50:51], 0, v[60:61]
	v_lshlrev_b64 v[26:27], 11, v[26:27]
	v_lshl_add_u64 v[26:27], v[50:51], 0, v[26:27]
	v_lshlrev_b64 v[24:25], 11, v[24:25]
	v_lshl_add_u64 v[24:25], v[50:51], 0, v[24:25]
	s_add_i32 s4, s4, 8
	s_cmp_gt_u32 s4, 23
	s_waitcnt vmcnt(0) lgkmcnt(0)
	v_lshlrev_b32_e32 v53, 16, v28
	v_and_b32_e32 v28, 0xffff0000, v28
	v_mul_f32_e32 v79, v28, v28
	v_lshlrev_b32_e32 v76, 16, v29
	v_fmac_f32_e32 v79, v53, v53
	v_and_b32_e32 v29, 0xffff0000, v29
	v_fmac_f32_e32 v79, v76, v76
	v_lshlrev_b32_e32 v77, 16, v30
	v_fmac_f32_e32 v79, v29, v29
	v_and_b32_e32 v30, 0xffff0000, v30
	v_fmac_f32_e32 v79, v77, v77
	v_lshlrev_b32_e32 v78, 16, v31
	v_fmac_f32_e32 v79, v30, v30
	v_and_b32_e32 v31, 0xffff0000, v31
	v_fmac_f32_e32 v79, v78, v78
	v_fmac_f32_e32 v79, v31, v31
	ds_bpermute_b32 v80, v62, v79
	s_waitcnt lgkmcnt(0)
	v_add_f32_e32 v79, v79, v80
	ds_bpermute_b32 v80, v63, v79
	s_waitcnt lgkmcnt(0)
	v_add_f32_e32 v79, v79, v80
	ds_bpermute_b32 v80, v64, v79
	s_waitcnt lgkmcnt(0)
	v_add_f32_e32 v79, v79, v80
	ds_bpermute_b32 v80, v65, v79
	s_waitcnt lgkmcnt(0)
	v_add_f32_e32 v79, v79, v80
	ds_bpermute_b32 v80, v66, v79
	s_waitcnt lgkmcnt(0)
	v_add_f32_e32 v79, v79, v80
	ds_bpermute_b32 v80, v55, v79
	s_waitcnt lgkmcnt(0)
	v_add_f32_e32 v79, v79, v80
	v_fmamk_f32 v79, v79, 0x3b000000, v229
	v_rsq_f32_e32 v79, v79
	s_nop 0
	v_mul_f32_e32 v53, v79, v53
	v_mul_f32_e32 v28, v79, v28
	v_mul_f32_e32 v53, v0, v53
	v_mul_f32_e32 v28, v1, v28
	v_cvt_pk_bf16_f32 v28, v53, v28
	v_mul_f32_e32 v53, v79, v76
	v_mul_f32_e32 v29, v79, v29
	v_mul_f32_e32 v53, v2, v53
	v_mul_f32_e32 v29, v3, v29
	v_cvt_pk_bf16_f32 v29, v53, v29
	v_mul_f32_e32 v53, v79, v77
	v_mul_f32_e32 v30, v79, v30
	v_mul_f32_e32 v53, v4, v53
	v_mul_f32_e32 v30, v5, v30
	v_mul_f32_e32 v31, v79, v31
	v_cvt_pk_bf16_f32 v30, v53, v30
	v_mul_f32_e32 v53, v79, v78
	v_mul_f32_e32 v31, v7, v31
	v_mul_f32_e32 v53, v6, v53
	v_cvt_pk_bf16_f32 v31, v53, v31
	global_store_dwordx4 v[60:61], v[28:31], off offset:1024
	s_nop 1
	v_and_b32_e32 v29, 0xffff0000, v32
	v_lshlrev_b32_e32 v28, 16, v32
	v_mul_f32_e32 v53, v29, v29
	v_lshlrev_b32_e32 v30, 16, v33
	v_fmac_f32_e32 v53, v28, v28
	v_and_b32_e32 v31, 0xffff0000, v33
	v_fmac_f32_e32 v53, v30, v30
	v_lshlrev_b32_e32 v32, 16, v34
	v_fmac_f32_e32 v53, v31, v31
	v_and_b32_e32 v33, 0xffff0000, v34
	v_fmac_f32_e32 v53, v32, v32
	v_lshlrev_b32_e32 v34, 16, v35
	v_fmac_f32_e32 v53, v33, v33
	v_and_b32_e32 v35, 0xffff0000, v35
	v_fmac_f32_e32 v53, v34, v34
	v_fmac_f32_e32 v53, v35, v35
	ds_bpermute_b32 v60, v62, v53
	s_waitcnt lgkmcnt(0)
	v_add_f32_e32 v53, v53, v60
	ds_bpermute_b32 v60, v63, v53
	s_waitcnt lgkmcnt(0)
	v_add_f32_e32 v53, v53, v60
	ds_bpermute_b32 v60, v64, v53
	s_waitcnt lgkmcnt(0)
	v_add_f32_e32 v53, v53, v60
	ds_bpermute_b32 v60, v65, v53
	s_waitcnt lgkmcnt(0)
	v_add_f32_e32 v53, v53, v60
	ds_bpermute_b32 v60, v66, v53
	s_waitcnt lgkmcnt(0)
	v_add_f32_e32 v53, v53, v60
	ds_bpermute_b32 v60, v55, v53
	s_waitcnt lgkmcnt(0)
	v_add_f32_e32 v53, v53, v60
	v_fmamk_f32 v53, v53, 0x3b000000, v229
	v_rsq_f32_e32 v53, v53
	s_nop 0
	v_mul_f32_e32 v28, v53, v28
	v_mul_f32_e32 v29, v53, v29
	v_mul_f32_e32 v28, v0, v28
	v_mul_f32_e32 v29, v1, v29
	v_cvt_pk_bf16_f32 v28, v28, v29
	v_mul_f32_e32 v29, v53, v30
	v_mul_f32_e32 v30, v53, v31
	v_mul_f32_e32 v29, v2, v29
	v_mul_f32_e32 v30, v3, v30
	v_cvt_pk_bf16_f32 v29, v29, v30
	v_mul_f32_e32 v30, v53, v32
	v_mul_f32_e32 v31, v53, v33
	v_mul_f32_e32 v30, v4, v30
	v_mul_f32_e32 v31, v5, v31
	v_cvt_pk_bf16_f32 v30, v30, v31
	v_mul_f32_e32 v31, v53, v34
	v_mul_f32_e32 v32, v53, v35
	v_mul_f32_e32 v31, v6, v31
	v_mul_f32_e32 v32, v7, v32
	v_cvt_pk_bf16_f32 v31, v31, v32
	v_lshlrev_b64 v[32:33], 11, v[70:71]
	v_lshl_add_u64 v[32:33], v[50:51], 0, v[32:33]
	global_store_dwordx4 v[32:33], v[28:31], off offset:1024
	v_lshlrev_b32_e32 v32, 16, v38
	v_and_b32_e32 v33, 0xffff0000, v38
	v_and_b32_e32 v29, 0xffff0000, v36
	v_lshlrev_b32_e32 v28, 16, v36
	v_mul_f32_e32 v36, v29, v29
	v_lshlrev_b32_e32 v30, 16, v37
	v_fmac_f32_e32 v36, v28, v28
	v_and_b32_e32 v31, 0xffff0000, v37
	v_fmac_f32_e32 v36, v30, v30
	v_fmac_f32_e32 v36, v31, v31
	v_fmac_f32_e32 v36, v32, v32
	v_lshlrev_b32_e32 v34, 16, v39
	v_fmac_f32_e32 v36, v33, v33
	v_and_b32_e32 v35, 0xffff0000, v39
	v_fmac_f32_e32 v36, v34, v34
	v_fmac_f32_e32 v36, v35, v35
	ds_bpermute_b32 v37, v62, v36
	s_waitcnt lgkmcnt(0)
	v_add_f32_e32 v36, v36, v37
	ds_bpermute_b32 v37, v63, v36
	s_waitcnt lgkmcnt(0)
	v_add_f32_e32 v36, v36, v37
	ds_bpermute_b32 v37, v64, v36
	s_waitcnt lgkmcnt(0)
	v_add_f32_e32 v36, v36, v37
	ds_bpermute_b32 v37, v65, v36
	s_waitcnt lgkmcnt(0)
	v_add_f32_e32 v36, v36, v37
	ds_bpermute_b32 v37, v66, v36
	s_waitcnt lgkmcnt(0)
	v_add_f32_e32 v36, v36, v37
	ds_bpermute_b32 v37, v55, v36
	s_waitcnt lgkmcnt(0)
	v_add_f32_e32 v36, v36, v37
	v_fmamk_f32 v36, v36, 0x3b000000, v229
	v_rsq_f32_e32 v36, v36
	s_nop 0
	v_mul_f32_e32 v28, v36, v28
	v_mul_f32_e32 v29, v36, v29
	v_mul_f32_e32 v28, v0, v28
	v_mul_f32_e32 v29, v1, v29
	v_cvt_pk_bf16_f32 v28, v28, v29
	v_mul_f32_e32 v29, v36, v30
	v_mul_f32_e32 v30, v36, v31
	v_mul_f32_e32 v29, v2, v29
	v_mul_f32_e32 v30, v3, v30
	v_cvt_pk_bf16_f32 v29, v29, v30
	v_mul_f32_e32 v30, v36, v32
	v_mul_f32_e32 v31, v36, v33
	v_mul_f32_e32 v30, v4, v30
	v_mul_f32_e32 v31, v5, v31
	v_cvt_pk_bf16_f32 v30, v30, v31
	v_mul_f32_e32 v31, v36, v34
	v_mul_f32_e32 v32, v36, v35
	v_mul_f32_e32 v31, v6, v31
	v_mul_f32_e32 v32, v7, v32
	v_cvt_pk_bf16_f32 v31, v31, v32
	v_lshlrev_b64 v[32:33], 11, v[72:73]
	v_lshl_add_u64 v[32:33], v[50:51], 0, v[32:33]
	global_store_dwordx4 v[32:33], v[28:31], off offset:1024
	v_lshlrev_b32_e32 v32, 16, v42
	v_and_b32_e32 v33, 0xffff0000, v42
	v_and_b32_e32 v29, 0xffff0000, v40
	v_lshlrev_b32_e32 v28, 16, v40
	v_mul_f32_e32 v36, v29, v29
	v_lshlrev_b32_e32 v30, 16, v41
	v_fmac_f32_e32 v36, v28, v28
	v_and_b32_e32 v31, 0xffff0000, v41
	v_fmac_f32_e32 v36, v30, v30
	v_fmac_f32_e32 v36, v31, v31
	v_fmac_f32_e32 v36, v32, v32
	v_lshlrev_b32_e32 v34, 16, v43
	v_fmac_f32_e32 v36, v33, v33
	v_and_b32_e32 v35, 0xffff0000, v43
	v_fmac_f32_e32 v36, v34, v34
	v_fmac_f32_e32 v36, v35, v35
	ds_bpermute_b32 v37, v62, v36
	s_waitcnt lgkmcnt(0)
	v_add_f32_e32 v36, v36, v37
	ds_bpermute_b32 v37, v63, v36
	s_waitcnt lgkmcnt(0)
	v_add_f32_e32 v36, v36, v37
	ds_bpermute_b32 v37, v64, v36
	s_waitcnt lgkmcnt(0)
	v_add_f32_e32 v36, v36, v37
	ds_bpermute_b32 v37, v65, v36
	s_waitcnt lgkmcnt(0)
	v_add_f32_e32 v36, v36, v37
	ds_bpermute_b32 v37, v66, v36
	s_waitcnt lgkmcnt(0)
	v_add_f32_e32 v36, v36, v37
	ds_bpermute_b32 v37, v55, v36
	s_waitcnt lgkmcnt(0)
	v_add_f32_e32 v36, v36, v37
	v_fmamk_f32 v36, v36, 0x3b000000, v229
	v_rsq_f32_e32 v36, v36
	s_nop 0
	v_mul_f32_e32 v28, v36, v28
	v_mul_f32_e32 v29, v36, v29
	v_mul_f32_e32 v28, v0, v28
	v_mul_f32_e32 v29, v1, v29
	v_cvt_pk_bf16_f32 v28, v28, v29
	v_mul_f32_e32 v29, v36, v30
	v_mul_f32_e32 v30, v36, v31
	v_mul_f32_e32 v29, v2, v29
	v_mul_f32_e32 v30, v3, v30
	v_cvt_pk_bf16_f32 v29, v29, v30
	v_mul_f32_e32 v30, v36, v32
	v_mul_f32_e32 v31, v36, v33
	v_mul_f32_e32 v30, v4, v30
	v_mul_f32_e32 v31, v5, v31
	v_cvt_pk_bf16_f32 v30, v30, v31
	v_mul_f32_e32 v31, v36, v34
	v_mul_f32_e32 v32, v36, v35
	v_mul_f32_e32 v31, v6, v31
	v_mul_f32_e32 v32, v7, v32
	v_cvt_pk_bf16_f32 v31, v31, v32
	v_lshlrev_b64 v[32:33], 11, v[74:75]
	v_lshl_add_u64 v[32:33], v[50:51], 0, v[32:33]
	global_store_dwordx4 v[32:33], v[28:31], off offset:1024
	v_lshlrev_b32_e32 v32, 16, v58
	v_and_b32_e32 v33, 0xffff0000, v58
	v_and_b32_e32 v29, 0xffff0000, v56
	v_lshlrev_b32_e32 v28, 16, v56
	v_mul_f32_e32 v36, v29, v29
	v_lshlrev_b32_e32 v30, 16, v57
	v_fmac_f32_e32 v36, v28, v28
	v_and_b32_e32 v31, 0xffff0000, v57
	v_fmac_f32_e32 v36, v30, v30
	v_fmac_f32_e32 v36, v31, v31
	v_fmac_f32_e32 v36, v32, v32
	v_lshlrev_b32_e32 v34, 16, v59
	v_fmac_f32_e32 v36, v33, v33
	v_and_b32_e32 v35, 0xffff0000, v59
	v_fmac_f32_e32 v36, v34, v34
	v_fmac_f32_e32 v36, v35, v35
	ds_bpermute_b32 v37, v62, v36
	s_waitcnt lgkmcnt(0)
	v_add_f32_e32 v36, v36, v37
	ds_bpermute_b32 v37, v63, v36
	s_waitcnt lgkmcnt(0)
	v_add_f32_e32 v36, v36, v37
	ds_bpermute_b32 v37, v64, v36
	s_waitcnt lgkmcnt(0)
	v_add_f32_e32 v36, v36, v37
	ds_bpermute_b32 v37, v65, v36
	s_waitcnt lgkmcnt(0)
	v_add_f32_e32 v36, v36, v37
	ds_bpermute_b32 v37, v66, v36
	s_waitcnt lgkmcnt(0)
	v_add_f32_e32 v36, v36, v37
	ds_bpermute_b32 v37, v55, v36
	s_waitcnt lgkmcnt(0)
	v_add_f32_e32 v36, v36, v37
	v_fmamk_f32 v36, v36, 0x3b000000, v229
	v_rsq_f32_e32 v36, v36
	s_nop 0
	v_mul_f32_e32 v28, v36, v28
	v_mul_f32_e32 v29, v36, v29
	v_mul_f32_e32 v28, v0, v28
	v_mul_f32_e32 v29, v1, v29
	v_cvt_pk_bf16_f32 v28, v28, v29
	v_mul_f32_e32 v29, v36, v30
	v_mul_f32_e32 v30, v36, v31
	v_mul_f32_e32 v29, v2, v29
	v_mul_f32_e32 v30, v3, v30
	v_cvt_pk_bf16_f32 v29, v29, v30
	v_mul_f32_e32 v30, v36, v32
	v_mul_f32_e32 v31, v36, v33
	v_mul_f32_e32 v30, v4, v30
	v_mul_f32_e32 v31, v5, v31
	v_cvt_pk_bf16_f32 v30, v30, v31
	v_mul_f32_e32 v31, v36, v34
	v_mul_f32_e32 v31, v6, v31
	v_mul_f32_e32 v32, v36, v35
	v_mul_f32_e32 v32, v7, v32
	v_cvt_pk_bf16_f32 v31, v31, v32
	global_store_dwordx4 v[26:27], v[28:31], off offset:1024
	v_lshlrev_b32_e32 v26, 16, v16
	v_and_b32_e32 v16, 0xffff0000, v16
	v_mul_f32_e32 v30, v16, v16
	v_lshlrev_b32_e32 v27, 16, v17
	v_fmac_f32_e32 v30, v26, v26
	v_and_b32_e32 v17, 0xffff0000, v17
	v_fmac_f32_e32 v30, v27, v27
	v_lshlrev_b32_e32 v28, 16, v18
	v_fmac_f32_e32 v30, v17, v17
	v_and_b32_e32 v18, 0xffff0000, v18
	v_fmac_f32_e32 v30, v28, v28
	v_lshlrev_b32_e32 v29, 16, v19
	v_fmac_f32_e32 v30, v18, v18
	v_and_b32_e32 v19, 0xffff0000, v19
	v_fmac_f32_e32 v30, v29, v29
	v_fmac_f32_e32 v30, v19, v19
	ds_bpermute_b32 v31, v62, v30
	s_waitcnt lgkmcnt(0)
	v_add_f32_e32 v30, v30, v31
	ds_bpermute_b32 v31, v63, v30
	s_waitcnt lgkmcnt(0)
	v_add_f32_e32 v30, v30, v31
	ds_bpermute_b32 v31, v64, v30
	s_waitcnt lgkmcnt(0)
	v_add_f32_e32 v30, v30, v31
	ds_bpermute_b32 v31, v65, v30
	s_waitcnt lgkmcnt(0)
	v_add_f32_e32 v30, v30, v31
	ds_bpermute_b32 v31, v66, v30
	s_waitcnt lgkmcnt(0)
	v_add_f32_e32 v30, v30, v31
	ds_bpermute_b32 v31, v55, v30
	s_waitcnt lgkmcnt(0)
	v_add_f32_e32 v30, v30, v31
	v_fmamk_f32 v30, v30, 0x3b000000, v229
	v_rsq_f32_e32 v30, v30
	s_nop 0
	v_mul_f32_e32 v26, v30, v26
	v_mul_f32_e32 v16, v30, v16
	v_mul_f32_e32 v26, v0, v26
	v_mul_f32_e32 v16, v1, v16
	v_cvt_pk_bf16_f32 v16, v26, v16
	v_mul_f32_e32 v26, v30, v27
	v_mul_f32_e32 v17, v30, v17
	v_mul_f32_e32 v26, v2, v26
	v_mul_f32_e32 v17, v3, v17
	v_cvt_pk_bf16_f32 v17, v26, v17
	v_mul_f32_e32 v26, v30, v28
	v_mul_f32_e32 v18, v30, v18
	v_mul_f32_e32 v26, v4, v26
	v_mul_f32_e32 v18, v5, v18
	v_mul_f32_e32 v19, v30, v19
	v_cvt_pk_bf16_f32 v18, v26, v18
	v_mul_f32_e32 v26, v30, v29
	v_mul_f32_e32 v19, v7, v19
	v_mul_f32_e32 v26, v6, v26
	v_cvt_pk_bf16_f32 v19, v26, v19
	global_store_dwordx4 v[24:25], v[16:19], off offset:1024
	s_nop 1
	v_lshlrev_b32_e32 v16, 16, v12
	v_and_b32_e32 v12, 0xffff0000, v12
	v_mul_f32_e32 v24, v12, v12
	v_lshlrev_b32_e32 v17, 16, v13
	v_fmac_f32_e32 v24, v16, v16
	v_and_b32_e32 v13, 0xffff0000, v13
	v_fmac_f32_e32 v24, v17, v17
	v_lshlrev_b32_e32 v18, 16, v14
	v_fmac_f32_e32 v24, v13, v13
	v_and_b32_e32 v14, 0xffff0000, v14
	v_fmac_f32_e32 v24, v18, v18
	v_lshlrev_b32_e32 v19, 16, v15
	v_fmac_f32_e32 v24, v14, v14
	v_and_b32_e32 v15, 0xffff0000, v15
	v_fmac_f32_e32 v24, v19, v19
	v_fmac_f32_e32 v24, v15, v15
	ds_bpermute_b32 v25, v62, v24
	s_waitcnt lgkmcnt(0)
	v_add_f32_e32 v24, v24, v25
	ds_bpermute_b32 v25, v63, v24
	s_waitcnt lgkmcnt(0)
	v_add_f32_e32 v24, v24, v25
	ds_bpermute_b32 v25, v64, v24
	s_waitcnt lgkmcnt(0)
	v_add_f32_e32 v24, v24, v25
	ds_bpermute_b32 v25, v65, v24
	s_waitcnt lgkmcnt(0)
	v_add_f32_e32 v24, v24, v25
	ds_bpermute_b32 v25, v66, v24
	s_waitcnt lgkmcnt(0)
	v_add_f32_e32 v24, v24, v25
	ds_bpermute_b32 v25, v55, v24
	s_waitcnt lgkmcnt(0)
	v_add_f32_e32 v24, v24, v25
	v_fmamk_f32 v24, v24, 0x3b000000, v229
	v_rsq_f32_e32 v24, v24
	s_nop 0
	v_mul_f32_e32 v16, v24, v16
	v_mul_f32_e32 v12, v24, v12
	v_mul_f32_e32 v16, v0, v16
	v_mul_f32_e32 v12, v1, v12
	v_cvt_pk_bf16_f32 v12, v16, v12
	v_mul_f32_e32 v16, v24, v17
	v_mul_f32_e32 v13, v24, v13
	v_mul_f32_e32 v16, v2, v16
	v_mul_f32_e32 v13, v3, v13
	v_cvt_pk_bf16_f32 v13, v16, v13
	v_mul_f32_e32 v16, v24, v18
	v_mul_f32_e32 v14, v24, v14
	v_mul_f32_e32 v16, v4, v16
	v_mul_f32_e32 v14, v5, v14
	v_cvt_pk_bf16_f32 v14, v16, v14
	v_mul_f32_e32 v16, v24, v19
	v_mul_f32_e32 v15, v24, v15
	v_mul_f32_e32 v16, v6, v16
	v_mul_f32_e32 v15, v7, v15
	v_cvt_pk_bf16_f32 v15, v16, v15
	v_lshlrev_b64 v[16:17], 11, v[22:23]
	v_lshl_add_u64 v[16:17], v[50:51], 0, v[16:17]
	global_store_dwordx4 v[16:17], v[12:15], off offset:1024
	s_nop 1
	v_lshlrev_b32_e32 v12, 16, v8
	v_and_b32_e32 v8, 0xffff0000, v8
	v_mul_f32_e32 v16, v8, v8
	v_lshlrev_b32_e32 v13, 16, v9
	v_fmac_f32_e32 v16, v12, v12
	v_and_b32_e32 v9, 0xffff0000, v9
	v_fmac_f32_e32 v16, v13, v13
	v_lshlrev_b32_e32 v14, 16, v10
	v_fmac_f32_e32 v16, v9, v9
	v_and_b32_e32 v10, 0xffff0000, v10
	v_fmac_f32_e32 v16, v14, v14
	v_lshlrev_b32_e32 v15, 16, v11
	v_fmac_f32_e32 v16, v10, v10
	v_and_b32_e32 v11, 0xffff0000, v11
	v_fmac_f32_e32 v16, v15, v15
	v_fmac_f32_e32 v16, v11, v11
	ds_bpermute_b32 v17, v62, v16
	s_waitcnt lgkmcnt(0)
	v_add_f32_e32 v16, v16, v17
	ds_bpermute_b32 v17, v63, v16
	s_waitcnt lgkmcnt(0)
	v_add_f32_e32 v16, v16, v17
	ds_bpermute_b32 v17, v64, v16
	s_waitcnt lgkmcnt(0)
	v_add_f32_e32 v16, v16, v17
	ds_bpermute_b32 v17, v65, v16
	s_waitcnt lgkmcnt(0)
	v_add_f32_e32 v16, v16, v17
	ds_bpermute_b32 v17, v66, v16
	s_waitcnt lgkmcnt(0)
	v_add_f32_e32 v16, v16, v17
	ds_bpermute_b32 v17, v55, v16
	s_waitcnt lgkmcnt(0)
	v_add_f32_e32 v16, v16, v17
	v_fmamk_f32 v16, v16, 0x3b000000, v229
	v_rsq_f32_e32 v16, v16
	s_nop 0
	v_mul_f32_e32 v12, v16, v12
	v_mul_f32_e32 v8, v16, v8
	v_mul_f32_e32 v12, v0, v12
	v_mul_f32_e32 v8, v1, v8
	v_cvt_pk_bf16_f32 v8, v12, v8
	v_mul_f32_e32 v12, v16, v13
	v_mul_f32_e32 v9, v16, v9
	v_mul_f32_e32 v12, v2, v12
	v_mul_f32_e32 v9, v3, v9
	v_cvt_pk_bf16_f32 v9, v12, v9
	v_mul_f32_e32 v12, v16, v14
	v_mul_f32_e32 v10, v16, v10
	v_mul_f32_e32 v12, v4, v12
	v_mul_f32_e32 v10, v5, v10
	v_cvt_pk_bf16_f32 v10, v12, v10
	v_mul_f32_e32 v12, v16, v15
	v_mul_f32_e32 v11, v16, v11
	v_mul_f32_e32 v12, v6, v12
	v_mul_f32_e32 v11, v7, v11
	v_cvt_pk_bf16_f32 v11, v12, v11
	v_lshlrev_b64 v[12:13], 11, v[20:21]
	v_lshl_add_u64 v[12:13], v[50:51], 0, v[12:13]
	global_store_dwordx4 v[12:13], v[8:11], off offset:1024
	s_cbranch_scc0 .LBB0_240
	s_add_i32 s29, s29, s70
	v_add_u32_e32 v52, s28, v52
	s_cmpk_gt_i32 s29, 0xff
	v_add_u32_e32 v67, s28, v67
	s_cbranch_scc0 .LBB0_169

.LBB0_260:
	s_lshl_b32 s3, s96, 8
	s_lshl_b32 s0, s97, 8
	s_and_b32 s3, s3, 0x300
	s_and_b32 s0, s0, 0x300
	v_or_b32_e32 v140, s3, v138
	v_lshrrev_b32_e32 v140, 4, v140
	v_add_lshl_u32 v141, s0, v136, 6
	s_lshl_b32 s3, s96, 2
	v_cvt_pk_bf16_f32 v124, v124, v125
	v_cvt_pk_bf16_f32 v125, v126, v127
	v_cvt_pk_bf16_f32 v126, v120, v121
	v_or_b32_e32 v120, v141, v140
	s_and_b32 s34, s3, -16
	v_ashrrev_i32_e32 v121, 31, v120
	s_ashr_i32 s35, s34, 31
	v_lshlrev_b64 v[120:121], 10, v[120:121]
	v_lshl_add_u64 v[120:121], s[10:11], 0, v[120:121]
	s_lshl_b64 s[34:35], s[34:35], 1
	v_lshl_add_u64 v[120:121], v[120:121], 0, s[34:35]
	v_lshl_add_u64 v[120:121], v[120:121], 0, v[188:189]
	v_cvt_pk_bf16_f32 v127, v122, v123
	global_store_dwordx4 v[120:121], v[124:127], off
	v_or_b32_e32 v120, 8, v140
	v_cvt_pk_bf16_f32 v116, v116, v117
	v_cvt_pk_bf16_f32 v117, v118, v119
	v_cvt_pk_bf16_f32 v118, v108, v109
	v_or_b32_e32 v108, v120, v141
	v_ashrrev_i32_e32 v109, 31, v108
	v_lshlrev_b64 v[108:109], 10, v[108:109]
	v_lshl_add_u64 v[108:109], s[10:11], 0, v[108:109]
	v_lshl_add_u64 v[108:109], v[108:109], 0, s[34:35]
	v_lshl_add_u64 v[108:109], v[108:109], 0, v[188:189]
	v_cvt_pk_bf16_f32 v119, v110, v111
	global_store_dwordx4 v[108:109], v[116:119], off
	v_cvt_pk_bf16_f32 v108, v112, v113
	v_cvt_pk_bf16_f32 v109, v114, v115
	v_cvt_pk_bf16_f32 v110, v104, v105
	v_cvt_pk_bf16_f32 v111, v106, v107
	s_and_b64 vcc, exec, s[4:5]
	s_nop 0
	v_or_b32_e32 v116, 0x400, v141
	v_or_b32_e32 v104, v116, v140
	v_ashrrev_i32_e32 v105, 31, v104
	v_lshlrev_b64 v[104:105], 10, v[104:105]
	v_lshl_add_u64 v[104:105], s[10:11], 0, v[104:105]
	v_lshl_add_u64 v[104:105], v[104:105], 0, s[34:35]
	v_lshl_add_u64 v[104:105], v[104:105], 0, v[188:189]
	global_store_dwordx4 v[104:105], v[108:111], off
	v_cvt_pk_bf16_f32 v100, v100, v101
	v_cvt_pk_bf16_f32 v101, v102, v103
	v_cvt_pk_bf16_f32 v102, v92, v93
	v_or_b32_e32 v92, v116, v120
	v_ashrrev_i32_e32 v93, 31, v92
	v_lshlrev_b64 v[92:93], 10, v[92:93]
	v_lshl_add_u64 v[92:93], s[10:11], 0, v[92:93]
	v_lshl_add_u64 v[92:93], v[92:93], 0, s[34:35]
	v_lshl_add_u64 v[92:93], v[92:93], 0, v[188:189]
	v_cvt_pk_bf16_f32 v103, v94, v95
	global_store_dwordx4 v[92:93], v[100:103], off
	v_cvt_pk_bf16_f32 v92, v96, v97
	v_cvt_pk_bf16_f32 v93, v98, v99
	v_cvt_pk_bf16_f32 v94, v88, v89
	v_cvt_pk_bf16_f32 v95, v90, v91
	s_mov_b64 s[4:5], -1
	s_nop 0
	v_or_b32_e32 v100, 0x800, v141
	v_or_b32_e32 v88, v100, v140
	v_ashrrev_i32_e32 v89, 31, v88
	v_lshlrev_b64 v[88:89], 10, v[88:89]
	v_lshl_add_u64 v[88:89], s[10:11], 0, v[88:89]
	v_lshl_add_u64 v[88:89], v[88:89], 0, s[34:35]
	v_lshl_add_u64 v[88:89], v[88:89], 0, v[188:189]
	global_store_dwordx4 v[88:89], v[92:95], off
	v_cvt_pk_bf16_f32 v84, v84, v85
	v_cvt_pk_bf16_f32 v85, v86, v87
	v_cvt_pk_bf16_f32 v86, v76, v77
	v_or_b32_e32 v76, v100, v120
	v_ashrrev_i32_e32 v77, 31, v76
	v_lshlrev_b64 v[76:77], 10, v[76:77]
	v_lshl_add_u64 v[76:77], s[10:11], 0, v[76:77]
	v_lshl_add_u64 v[76:77], v[76:77], 0, s[34:35]
	v_lshl_add_u64 v[76:77], v[76:77], 0, v[188:189]
	v_cvt_pk_bf16_f32 v87, v78, v79
	global_store_dwordx4 v[76:77], v[84:87], off
	v_cvt_pk_bf16_f32 v76, v80, v81
	v_cvt_pk_bf16_f32 v77, v82, v83
	v_cvt_pk_bf16_f32 v78, v72, v73
	v_cvt_pk_bf16_f32 v79, v74, v75
	s_nop 1
	v_or_b32_e32 v84, 0xc00, v141
	v_or_b32_e32 v72, v84, v140
	v_ashrrev_i32_e32 v73, 31, v72
	v_lshlrev_b64 v[72:73], 10, v[72:73]
	v_lshl_add_u64 v[72:73], s[10:11], 0, v[72:73]
	v_lshl_add_u64 v[72:73], v[72:73], 0, s[34:35]
	v_lshl_add_u64 v[72:73], v[72:73], 0, v[188:189]
	global_store_dwordx4 v[72:73], v[76:79], off
	v_cvt_pk_bf16_f32 v68, v68, v69
	v_cvt_pk_bf16_f32 v69, v70, v71
	v_cvt_pk_bf16_f32 v70, v64, v65
	v_or_b32_e32 v64, v84, v120
	v_ashrrev_i32_e32 v65, 31, v64
	v_lshlrev_b64 v[64:65], 10, v[64:65]
	v_lshl_add_u64 v[64:65], s[10:11], 0, v[64:65]
	v_lshl_add_u64 v[64:65], v[64:65], 0, s[34:35]
	v_lshl_add_u64 v[64:65], v[64:65], 0, v[188:189]
	v_cvt_pk_bf16_f32 v71, v66, v67
	global_store_dwordx4 v[64:65], v[68:71], off
	v_add_u32_e32 v64, 0x2000, v141
	v_cvt_pk_bf16_f32 v60, v60, v61
	v_cvt_pk_bf16_f32 v61, v62, v63
	v_cvt_pk_bf16_f32 v62, v56, v57
	v_or_b32_e32 v56, v64, v140
	v_ashrrev_i32_e32 v57, 31, v56
	v_lshlrev_b64 v[56:57], 10, v[56:57]
	v_lshl_add_u64 v[56:57], s[10:11], 0, v[56:57]
	v_lshl_add_u64 v[56:57], v[56:57], 0, s[34:35]
	v_lshl_add_u64 v[56:57], v[56:57], 0, v[188:189]
	v_cvt_pk_bf16_f32 v63, v58, v59
	global_store_dwordx4 v[56:57], v[60:63], off
	v_cvt_pk_bf16_f32 v52, v52, v53
	v_cvt_pk_bf16_f32 v53, v54, v55
	v_cvt_pk_bf16_f32 v54, v44, v45
	v_or_b32_e32 v44, v64, v120
	v_ashrrev_i32_e32 v45, 31, v44
	v_lshlrev_b64 v[44:45], 10, v[44:45]
	v_lshl_add_u64 v[44:45], s[10:11], 0, v[44:45]
	v_lshl_add_u64 v[44:45], v[44:45], 0, s[34:35]
	v_lshl_add_u64 v[44:45], v[44:45], 0, v[188:189]
	v_cvt_pk_bf16_f32 v55, v46, v47
	global_store_dwordx4 v[44:45], v[52:55], off
	v_cvt_pk_bf16_f32 v44, v48, v49
	v_cvt_pk_bf16_f32 v45, v50, v51
	v_cvt_pk_bf16_f32 v46, v40, v41
	v_cvt_pk_bf16_f32 v47, v42, v43
	s_nop 1
	v_add_u32_e32 v52, 0x2400, v141
	v_or_b32_e32 v40, v52, v140
	v_ashrrev_i32_e32 v41, 31, v40
	v_lshlrev_b64 v[40:41], 10, v[40:41]
	v_lshl_add_u64 v[40:41], s[10:11], 0, v[40:41]
	v_lshl_add_u64 v[40:41], v[40:41], 0, s[34:35]
	v_lshl_add_u64 v[40:41], v[40:41], 0, v[188:189]
	global_store_dwordx4 v[40:41], v[44:47], off
	v_cvt_pk_bf16_f32 v36, v36, v37
	v_cvt_pk_bf16_f32 v37, v38, v39
	v_cvt_pk_bf16_f32 v38, v28, v29
	v_or_b32_e32 v28, v52, v120
	v_ashrrev_i32_e32 v29, 31, v28
	v_lshlrev_b64 v[28:29], 10, v[28:29]
	v_lshl_add_u64 v[28:29], s[10:11], 0, v[28:29]
	v_lshl_add_u64 v[28:29], v[28:29], 0, s[34:35]
	v_lshl_add_u64 v[28:29], v[28:29], 0, v[188:189]
	v_cvt_pk_bf16_f32 v39, v30, v31
	global_store_dwordx4 v[28:29], v[36:39], off
	v_cvt_pk_bf16_f32 v28, v32, v33
	v_cvt_pk_bf16_f32 v29, v34, v35
	v_cvt_pk_bf16_f32 v30, v24, v25
	v_cvt_pk_bf16_f32 v31, v26, v27
	s_nop 1
	v_add_u32_e32 v36, 0x2800, v141
	v_or_b32_e32 v24, v36, v140
	v_ashrrev_i32_e32 v25, 31, v24
	v_lshlrev_b64 v[24:25], 10, v[24:25]
	v_lshl_add_u64 v[24:25], s[10:11], 0, v[24:25]
	v_lshl_add_u64 v[24:25], v[24:25], 0, s[34:35]
	v_lshl_add_u64 v[24:25], v[24:25], 0, v[188:189]
	global_store_dwordx4 v[24:25], v[28:31], off
	v_cvt_pk_bf16_f32 v20, v20, v21
	v_cvt_pk_bf16_f32 v21, v22, v23
	v_cvt_pk_bf16_f32 v22, v12, v13
	v_or_b32_e32 v12, v36, v120
	v_ashrrev_i32_e32 v13, 31, v12
	v_lshlrev_b64 v[12:13], 10, v[12:13]
	v_lshl_add_u64 v[12:13], s[10:11], 0, v[12:13]
	v_lshl_add_u64 v[12:13], v[12:13], 0, s[34:35]
	v_lshl_add_u64 v[12:13], v[12:13], 0, v[188:189]
	v_cvt_pk_bf16_f32 v23, v14, v15
	global_store_dwordx4 v[12:13], v[20:23], off
	v_cvt_pk_bf16_f32 v12, v16, v17
	v_cvt_pk_bf16_f32 v13, v18, v19
	v_cvt_pk_bf16_f32 v14, v8, v9
	v_cvt_pk_bf16_f32 v15, v10, v11
	s_nop 1
	v_add_u32_e32 v20, 0x2c00, v141
	v_or_b32_e32 v8, v20, v140
	v_ashrrev_i32_e32 v9, 31, v8
	v_lshlrev_b64 v[8:9], 10, v[8:9]
	v_lshl_add_u64 v[8:9], s[10:11], 0, v[8:9]
	v_lshl_add_u64 v[8:9], v[8:9], 0, s[34:35]
	v_lshl_add_u64 v[8:9], v[8:9], 0, v[188:189]
	global_store_dwordx4 v[8:9], v[12:15], off
	v_cvt_pk_bf16_f32 v4, v4, v5
	v_cvt_pk_bf16_f32 v5, v6, v7
	v_cvt_pk_bf16_f32 v6, v0, v1
	v_or_b32_e32 v0, v20, v120
	v_ashrrev_i32_e32 v1, 31, v0
	v_lshlrev_b64 v[0:1], 10, v[0:1]
	v_lshl_add_u64 v[0:1], s[10:11], 0, v[0:1]
	v_lshl_add_u64 v[0:1], v[0:1], 0, s[34:35]
	v_lshl_add_u64 v[0:1], v[0:1], 0, v[188:189]
	v_cvt_pk_bf16_f32 v7, v2, v3
	global_store_dwordx4 v[0:1], v[4:7], off
	s_cbranch_vccnz .LBB0_249
	s_andn2_b64 vcc, exec, s[8:9]
	s_cbranch_vccnz .LBB0_248
	s_barrier
	s_branch .LBB0_248

.LBB0_275:
	s_lshl_b32 s0, s90, 9
	s_lshl_b32 s38, s38, 7
	s_and_b32 s0, s0, 0xfe00
	s_ashr_i32 s39, s38, 31
	v_add_u32_e32 v178, s0, v183
	s_lshl_b64 s[36:37], s[38:39], 1
	v_or_b32_e32 v136, s38, v187
	v_ashrrev_i32_e32 v179, 31, v178
	v_lshl_add_u64 v[176:177], v[174:175], 0, s[36:37]
	v_ashrrev_i32_e32 v137, 31, v136
	v_lshlrev_b64 v[206:207], 10, v[178:179]
	v_lshl_add_u64 v[132:133], s[38:39], 2, v[172:173]
	v_lshl_add_u64 v[180:181], v[136:137], 2, s[10:11]
	v_lshl_add_u64 v[136:137], v[176:177], 0, v[206:207]
	global_load_dwordx4 v[128:131], v[132:133], off offset:16
	s_nop 0
	global_load_dwordx4 v[132:135], v[132:133], off
	s_mov_b64 s[4:5], 0x40000
	global_load_dword v204, v[180:181], off
	global_load_dwordx4 v[220:223], v[136:137], off
	v_lshl_add_u64 v[202:203], v[206:207], 0, s[4:5]
	v_lshl_add_u64 v[136:137], v[176:177], 0, v[202:203]
	global_load_dwordx4 v[160:163], v[136:137], off
	v_or_b32_e32 v136, s38, v208
	v_or_b32_e32 v148, s38, v212
	v_ashrrev_i32_e32 v137, 31, v136
	v_ashrrev_i32_e32 v149, 31, v148
	v_lshl_add_u64 v[136:137], v[136:137], 2, s[10:11]
	v_lshl_add_u64 v[148:149], v[148:149], 2, s[10:11]
	global_load_dword v186, v[136:137], off
	global_load_dword v182, v[148:149], off
	v_add_u32_e32 v136, s0, v205
	v_ashrrev_i32_e32 v137, 31, v136
	v_lshlrev_b64 v[136:137], 10, v[136:137]
	v_lshl_add_u64 v[136:137], v[176:177], 0, v[136:137]
	global_load_dwordx4 v[152:155], v[136:137], off
	v_add_u32_e32 v148, s0, v211
	v_ashrrev_i32_e32 v149, 31, v148
	v_lshlrev_b64 v[148:149], 10, v[148:149]
	v_lshl_add_u64 v[148:149], v[176:177], 0, v[148:149]
	global_load_dwordx4 v[156:159], v[148:149], off
	v_add_co_u32_e32 v136, vcc, s2, v136
	s_mov_b32 s3, 0x44000
	s_nop 0
	v_addc_co_u32_e32 v137, vcc, 0, v137, vcc
	global_load_dwordx4 v[140:143], v[136:137], off
	v_or_b32_e32 v136, s38, v210
	v_ashrrev_i32_e32 v137, 31, v136
	v_lshl_add_u64 v[136:137], v[136:137], 2, s[10:11]
	global_load_dword v184, v[136:137], off
	v_add_u32_e32 v136, s0, v209
	v_ashrrev_i32_e32 v137, 31, v136
	v_lshlrev_b64 v[136:137], 10, v[136:137]
	v_lshl_add_u64 v[136:137], v[176:177], 0, v[136:137]
	global_load_dwordx4 v[144:147], v[136:137], off
	v_add_co_u32_e32 v136, vcc, s2, v136
	s_waitcnt vmcnt(0)
	v_pk_fma_f32 v[120:121], v[120:121], v[132:133], v[204:205] op_sel_hi:[1,1,0]
	v_addc_co_u32_e32 v137, vcc, 0, v137, vcc
	global_load_dwordx4 v[136:139], v[136:137], off
	s_waitcnt lgkmcnt(0)
	v_lshlrev_b32_e32 v179, 16, v220
	v_add_co_u32_e32 v148, vcc, s2, v148
	v_mul_f32_e32 v120, v120, v179
	v_and_b32_e32 v179, 0xffff0000, v220
	v_addc_co_u32_e32 v149, vcc, 0, v149, vcc
	v_mul_f32_e32 v121, v121, v179
	global_load_dwordx4 v[148:151], v[148:149], off
	v_pk_fma_f32 v[122:123], v[122:123], v[134:135], v[204:205] op_sel_hi:[1,1,0]
	v_cvt_pk_bf16_f32 v120, v120, v121
	v_lshlrev_b32_e32 v121, 16, v221
	v_mul_f32_e32 v121, v122, v121
	v_and_b32_e32 v122, 0xffff0000, v221
	v_mul_f32_e32 v122, v123, v122
	v_pk_fma_f32 v[124:125], v[124:125], v[128:129], v[204:205] op_sel_hi:[1,1,0]
	v_cvt_pk_bf16_f32 v121, v121, v122
	v_lshlrev_b32_e32 v122, 16, v222
	v_and_b32_e32 v123, 0xffff0000, v222
	v_mul_f32_e32 v122, v124, v122
	v_mul_f32_e32 v123, v125, v123
	v_pk_fma_f32 v[126:127], v[126:127], v[130:131], v[204:205] op_sel_hi:[1,1,0]
	v_cvt_pk_bf16_f32 v122, v122, v123
	v_lshlrev_b32_e32 v123, 16, v223
	v_and_b32_e32 v124, 0xffff0000, v223
	v_mul_f32_e32 v123, v126, v123
	v_mul_f32_e32 v124, v127, v124
	v_cvt_pk_bf16_f32 v123, v123, v124
	v_lshl_add_u64 v[124:125], s[22:23], 0, v[206:207]
	v_lshl_add_u64 v[124:125], v[124:125], 0, s[36:37]
	v_lshl_add_u64 v[124:125], v[124:125], 0, v[188:189]
	global_store_dwordx4 v[124:125], v[120:123], off
	v_pk_fma_f32 v[116:117], v[116:117], v[132:133], v[204:205] op_sel_hi:[1,1,0]
	v_pk_fma_f32 v[118:119], v[118:119], v[134:135], v[204:205] op_sel_hi:[1,1,0]
	v_pk_fma_f32 v[120:121], v[114:115], v[130:131], v[204:205] op_sel_hi:[1,1,0]
	v_pk_fma_f32 v[114:115], v[112:113], v[128:129], v[204:205] op_sel_hi:[1,1,0]
	v_lshlrev_b32_e32 v112, 16, v160
	v_and_b32_e32 v113, 0xffff0000, v160
	v_mul_f32_e32 v112, v116, v112
	v_mul_f32_e32 v113, v117, v113
	v_cvt_pk_bf16_f32 v112, v112, v113
	v_lshlrev_b32_e32 v113, 16, v161
	v_and_b32_e32 v116, 0xffff0000, v161
	v_mul_f32_e32 v113, v118, v113
	v_mul_f32_e32 v116, v119, v116
	v_cvt_pk_bf16_f32 v113, v113, v116
	v_lshlrev_b32_e32 v116, 16, v162
	v_mul_f32_e32 v114, v114, v116
	v_and_b32_e32 v116, 0xffff0000, v162
	v_mul_f32_e32 v115, v115, v116
	v_cvt_pk_bf16_f32 v114, v114, v115
	v_lshlrev_b32_e32 v115, 16, v163
	v_and_b32_e32 v116, 0xffff0000, v163
	v_mul_f32_e32 v115, v120, v115
	v_mul_f32_e32 v116, v121, v116
	v_cvt_pk_bf16_f32 v115, v115, v116
	v_lshl_add_u64 v[116:117], s[22:23], 0, v[202:203]
	v_lshl_add_u64 v[116:117], v[116:117], 0, s[36:37]
	v_lshl_add_u64 v[116:117], v[116:117], 0, v[188:189]
	global_store_dwordx4 v[116:117], v[112:115], off
	v_pk_fma_f32 v[108:109], v[108:109], v[132:133], v[186:187] op_sel_hi:[1,1,0]
	v_pk_fma_f32 v[110:111], v[110:111], v[134:135], v[186:187] op_sel_hi:[1,1,0]
	v_pk_fma_f32 v[114:115], v[106:107], v[130:131], v[186:187] op_sel_hi:[1,1,0]
	v_pk_fma_f32 v[106:107], v[104:105], v[128:129], v[186:187] op_sel_hi:[1,1,0]
	v_lshlrev_b32_e32 v104, 16, v152
	v_and_b32_e32 v105, 0xffff0000, v152
	v_mul_f32_e32 v104, v108, v104
	v_mul_f32_e32 v105, v109, v105
	v_cvt_pk_bf16_f32 v104, v104, v105
	v_lshlrev_b32_e32 v105, 16, v153
	v_and_b32_e32 v108, 0xffff0000, v153
	v_mul_f32_e32 v105, v110, v105
	v_mul_f32_e32 v108, v111, v108
	v_cvt_pk_bf16_f32 v105, v105, v108
	v_lshlrev_b32_e32 v108, 16, v154
	v_mul_f32_e32 v106, v106, v108
	v_and_b32_e32 v108, 0xffff0000, v154
	v_mul_f32_e32 v107, v107, v108
	v_or_b32_e32 v112, 16, v178
	v_cvt_pk_bf16_f32 v106, v106, v107
	v_lshlrev_b32_e32 v107, 16, v155
	v_and_b32_e32 v108, 0xffff0000, v155
	v_ashrrev_i32_e32 v113, 31, v112
	v_mul_f32_e32 v107, v114, v107
	v_mul_f32_e32 v108, v115, v108
	v_cvt_pk_bf16_f32 v107, v107, v108
	v_lshlrev_b64 v[108:109], 10, v[112:113]
	v_lshl_add_u64 v[108:109], s[22:23], 0, v[108:109]
	v_lshl_add_u64 v[108:109], v[108:109], 0, s[36:37]
	v_lshl_add_u64 v[108:109], v[108:109], 0, v[188:189]
	global_store_dwordx4 v[108:109], v[104:107], off
	v_pk_fma_f32 v[100:101], v[100:101], v[132:133], v[186:187] op_sel_hi:[1,1,0]
	v_pk_fma_f32 v[102:103], v[102:103], v[134:135], v[186:187] op_sel_hi:[1,1,0]
	v_pk_fma_f32 v[104:105], v[98:99], v[130:131], v[186:187] op_sel_hi:[1,1,0]
	v_pk_fma_f32 v[98:99], v[96:97], v[128:129], v[186:187] op_sel_hi:[1,1,0]
	v_lshlrev_b32_e32 v96, 16, v140
	v_and_b32_e32 v97, 0xffff0000, v140
	v_mul_f32_e32 v96, v100, v96
	v_mul_f32_e32 v97, v101, v97
	v_cvt_pk_bf16_f32 v96, v96, v97
	v_lshlrev_b32_e32 v97, 16, v141
	v_and_b32_e32 v100, 0xffff0000, v141
	v_mul_f32_e32 v97, v102, v97
	v_mul_f32_e32 v100, v103, v100
	v_cvt_pk_bf16_f32 v97, v97, v100
	v_lshlrev_b32_e32 v100, 16, v142
	v_mul_f32_e32 v98, v98, v100
	v_and_b32_e32 v100, 0xffff0000, v142
	v_mul_f32_e32 v99, v99, v100
	v_cvt_pk_bf16_f32 v98, v98, v99
	v_lshlrev_b32_e32 v99, 16, v143
	v_and_b32_e32 v100, 0xffff0000, v143
	v_mul_f32_e32 v99, v104, v99
	v_mul_f32_e32 v100, v105, v100
	v_cvt_pk_bf16_f32 v99, v99, v100
	v_add_co_u32_e32 v100, vcc, s3, v124
	v_pk_fma_f32 v[92:93], v[92:93], v[132:133], v[184:185] op_sel_hi:[1,1,0]
	s_nop 0
	v_addc_co_u32_e32 v101, vcc, 0, v125, vcc
	global_store_dwordx4 v[100:101], v[96:99], off
	v_pk_fma_f32 v[94:95], v[94:95], v[134:135], v[184:185] op_sel_hi:[1,1,0]
	v_pk_fma_f32 v[84:85], v[84:85], v[132:133], v[184:185] op_sel_hi:[1,1,0]
	v_pk_fma_f32 v[98:99], v[90:91], v[130:131], v[184:185] op_sel_hi:[1,1,0]
	v_pk_fma_f32 v[90:91], v[88:89], v[128:129], v[184:185] op_sel_hi:[1,1,0]
	v_lshlrev_b32_e32 v88, 16, v144
	v_and_b32_e32 v89, 0xffff0000, v144
	v_mul_f32_e32 v88, v92, v88
	v_mul_f32_e32 v89, v93, v89
	v_cvt_pk_bf16_f32 v88, v88, v89
	v_lshlrev_b32_e32 v89, 16, v145
	v_and_b32_e32 v92, 0xffff0000, v145
	v_mul_f32_e32 v89, v94, v89
	v_mul_f32_e32 v92, v95, v92
	v_cvt_pk_bf16_f32 v89, v89, v92
	v_lshlrev_b32_e32 v92, 16, v146
	v_mul_f32_e32 v90, v90, v92
	v_and_b32_e32 v92, 0xffff0000, v146
	v_mul_f32_e32 v91, v91, v92
	v_or_b32_e32 v96, 32, v178
	v_cvt_pk_bf16_f32 v90, v90, v91
	v_lshlrev_b32_e32 v91, 16, v147
	v_and_b32_e32 v92, 0xffff0000, v147
	v_ashrrev_i32_e32 v97, 31, v96
	v_mul_f32_e32 v91, v98, v91
	v_mul_f32_e32 v92, v99, v92
	v_cvt_pk_bf16_f32 v91, v91, v92
	v_lshlrev_b64 v[92:93], 10, v[96:97]
	v_lshl_add_u64 v[92:93], s[22:23], 0, v[92:93]
	v_lshl_add_u64 v[92:93], v[92:93], 0, s[36:37]
	v_lshl_add_u64 v[92:93], v[92:93], 0, v[188:189]
	global_store_dwordx4 v[92:93], v[88:91], off
	v_pk_fma_f32 v[86:87], v[86:87], v[134:135], v[184:185] op_sel_hi:[1,1,0]
	s_mov_b32 s3, 0x48000
	v_pk_fma_f32 v[88:89], v[82:83], v[130:131], v[184:185] op_sel_hi:[1,1,0]
	v_pk_fma_f32 v[82:83], v[80:81], v[128:129], v[184:185] op_sel_hi:[1,1,0]
	s_waitcnt vmcnt(0)
	v_lshlrev_b32_e32 v80, 16, v136
	v_and_b32_e32 v81, 0xffff0000, v136
	v_mul_f32_e32 v80, v84, v80
	v_mul_f32_e32 v81, v85, v81
	v_cvt_pk_bf16_f32 v80, v80, v81
	v_lshlrev_b32_e32 v81, 16, v137
	v_and_b32_e32 v84, 0xffff0000, v137
	v_mul_f32_e32 v81, v86, v81
	v_mul_f32_e32 v84, v87, v84
	v_cvt_pk_bf16_f32 v81, v81, v84
	v_lshlrev_b32_e32 v84, 16, v138
	v_mul_f32_e32 v82, v82, v84
	v_and_b32_e32 v84, 0xffff0000, v138
	v_mul_f32_e32 v83, v83, v84
	v_cvt_pk_bf16_f32 v82, v82, v83
	v_lshlrev_b32_e32 v83, 16, v139
	v_and_b32_e32 v84, 0xffff0000, v139
	v_mul_f32_e32 v83, v88, v83
	v_mul_f32_e32 v84, v89, v84
	v_cvt_pk_bf16_f32 v83, v83, v84
	v_add_co_u32_e32 v84, vcc, s3, v124
	v_pk_fma_f32 v[76:77], v[76:77], v[132:133], v[182:183] op_sel_hi:[1,1,0]
	s_nop 0
	v_addc_co_u32_e32 v85, vcc, 0, v125, vcc
	global_store_dwordx4 v[84:85], v[80:83], off
	v_pk_fma_f32 v[78:79], v[78:79], v[134:135], v[182:183] op_sel_hi:[1,1,0]
	v_pk_fma_f32 v[68:69], v[68:69], v[132:133], v[182:183] op_sel_hi:[1,1,0]
	v_pk_fma_f32 v[82:83], v[74:75], v[130:131], v[182:183] op_sel_hi:[1,1,0]
	v_pk_fma_f32 v[74:75], v[72:73], v[128:129], v[182:183] op_sel_hi:[1,1,0]
	v_lshlrev_b32_e32 v72, 16, v156
	v_and_b32_e32 v73, 0xffff0000, v156
	v_mul_f32_e32 v72, v76, v72
	v_mul_f32_e32 v73, v77, v73
	v_cvt_pk_bf16_f32 v72, v72, v73
	v_lshlrev_b32_e32 v73, 16, v157
	v_and_b32_e32 v76, 0xffff0000, v157
	v_mul_f32_e32 v73, v78, v73
	v_mul_f32_e32 v76, v79, v76
	v_cvt_pk_bf16_f32 v73, v73, v76
	v_lshlrev_b32_e32 v76, 16, v158
	v_mul_f32_e32 v74, v74, v76
	v_and_b32_e32 v76, 0xffff0000, v158
	v_mul_f32_e32 v75, v75, v76
	v_or_b32_e32 v80, 48, v178
	v_cvt_pk_bf16_f32 v74, v74, v75
	v_lshlrev_b32_e32 v75, 16, v159
	v_and_b32_e32 v76, 0xffff0000, v159
	v_ashrrev_i32_e32 v81, 31, v80
	v_mul_f32_e32 v75, v82, v75
	v_mul_f32_e32 v76, v83, v76
	v_cvt_pk_bf16_f32 v75, v75, v76
	v_lshlrev_b64 v[76:77], 10, v[80:81]
	v_lshl_add_u64 v[76:77], s[22:23], 0, v[76:77]
	v_lshl_add_u64 v[76:77], v[76:77], 0, s[36:37]
	v_lshl_add_u64 v[76:77], v[76:77], 0, v[188:189]
	global_store_dwordx4 v[76:77], v[72:75], off
	v_pk_fma_f32 v[70:71], v[70:71], v[134:135], v[182:183] op_sel_hi:[1,1,0]
	s_mov_b32 s3, 0x4c000
	v_pk_fma_f32 v[72:73], v[66:67], v[130:131], v[182:183] op_sel_hi:[1,1,0]
	v_pk_fma_f32 v[66:67], v[64:65], v[128:129], v[182:183] op_sel_hi:[1,1,0]
	s_waitcnt lgkmcnt(0)
	v_lshlrev_b32_e32 v64, 16, v148
	v_and_b32_e32 v65, 0xffff0000, v148
	v_mul_f32_e32 v64, v68, v64
	v_mul_f32_e32 v65, v69, v65
	v_cvt_pk_bf16_f32 v64, v64, v65
	v_lshlrev_b32_e32 v65, 16, v149
	v_and_b32_e32 v68, 0xffff0000, v149
	v_mul_f32_e32 v65, v70, v65
	v_mul_f32_e32 v68, v71, v68
	v_cvt_pk_bf16_f32 v65, v65, v68
	v_lshlrev_b32_e32 v68, 16, v150
	v_mul_f32_e32 v66, v66, v68
	v_and_b32_e32 v68, 0xffff0000, v150
	v_mul_f32_e32 v67, v67, v68
	v_cvt_pk_bf16_f32 v66, v66, v67
	v_lshlrev_b32_e32 v67, 16, v151
	v_and_b32_e32 v68, 0xffff0000, v151
	v_mul_f32_e32 v67, v72, v67
	v_mul_f32_e32 v68, v73, v68
	v_cvt_pk_bf16_f32 v67, v67, v68
	v_add_co_u32_e32 v68, vcc, s3, v124
	s_nop 1
	v_addc_co_u32_e32 v69, vcc, 0, v125, vcc
	global_store_dwordx4 v[68:69], v[64:67], off
	global_load_dword v100, v[180:181], off
	s_nop 0
	v_add_u32_e32 v64, 0x80, v178
	v_ashrrev_i32_e32 v65, 31, v64
	v_lshlrev_b64 v[102:103], 10, v[64:65]
	v_lshl_add_u64 v[64:65], v[176:177], 0, v[102:103]
	global_load_dwordx4 v[80:83], v[64:65], off
	v_add_u32_e32 v64, 0x180, v178
	v_ashrrev_i32_e32 v65, 31, v64
	v_lshlrev_b64 v[64:65], 10, v[64:65]
	v_lshl_add_u64 v[64:65], v[176:177], 0, v[64:65]
	global_load_dwordx4 v[84:87], v[64:65], off
	v_or_b32_e32 v64, s38, v214
	v_ashrrev_i32_e32 v65, 31, v64
	v_lshl_add_u64 v[64:65], v[64:65], 2, s[10:11]
	global_load_dword v104, v[64:65], off
	v_add_u32_e32 v64, s0, v213
	v_ashrrev_i32_e32 v65, 31, v64
	v_lshlrev_b64 v[66:67], 10, v[64:65]
	v_lshl_add_u64 v[66:67], v[176:177], 0, v[66:67]
	global_load_dwordx4 v[88:91], v[66:67], off
	v_add_u32_e32 v64, 0x100, v64
	v_ashrrev_i32_e32 v65, 31, v64
	v_lshlrev_b64 v[64:65], 10, v[64:65]
	v_lshl_add_u64 v[64:65], v[176:177], 0, v[64:65]
	global_load_dwordx4 v[92:95], v[64:65], off
	v_or_b32_e32 v64, s38, v216
	v_ashrrev_i32_e32 v65, 31, v64
	v_lshl_add_u64 v[64:65], v[64:65], 2, s[10:11]
	global_load_dword v78, v[64:65], off
	v_add_u32_e32 v64, s0, v215
	v_ashrrev_i32_e32 v65, 31, v64
	v_lshlrev_b64 v[66:67], 10, v[64:65]
	v_lshl_add_u64 v[66:67], v[176:177], 0, v[66:67]
	global_load_dwordx4 v[96:99], v[66:67], off
	v_add_u32_e32 v64, 0x100, v64
	v_ashrrev_i32_e32 v65, 31, v64
	v_lshlrev_b64 v[64:65], 10, v[64:65]
	v_lshl_add_u64 v[64:65], v[176:177], 0, v[64:65]
	global_load_dwordx4 v[72:75], v[64:65], off
	v_or_b32_e32 v64, s38, v218
	v_ashrrev_i32_e32 v65, 31, v64
	v_lshl_add_u64 v[64:65], v[64:65], 2, s[10:11]
	global_load_dword v76, v[64:65], off
	v_add_u32_e32 v64, s0, v217
	v_ashrrev_i32_e32 v65, 31, v64
	v_lshlrev_b64 v[66:67], 10, v[64:65]
	v_lshl_add_u64 v[66:67], v[176:177], 0, v[66:67]
	global_load_dwordx4 v[68:71], v[66:67], off
	v_add_u32_e32 v64, 0x100, v64
	v_ashrrev_i32_e32 v65, 31, v64
	v_lshlrev_b64 v[64:65], 10, v[64:65]
	v_lshl_add_u64 v[64:65], v[176:177], 0, v[64:65]
	global_load_dwordx4 v[64:67], v[64:65], off
	s_mov_b32 s0, 0x60000
	s_waitcnt vmcnt(0)
	v_pk_fma_f32 v[60:61], v[60:61], v[132:133], v[100:101] op_sel_hi:[1,1,0]
	v_pk_fma_f32 v[106:107], v[58:59], v[130:131], v[100:101] op_sel_hi:[1,1,0]
	v_pk_fma_f32 v[58:59], v[56:57], v[128:129], v[100:101] op_sel_hi:[1,1,0]
	v_pk_fma_f32 v[62:63], v[62:63], v[134:135], v[100:101] op_sel_hi:[1,1,0]
	v_pk_fma_f32 v[52:53], v[52:53], v[132:133], v[100:101] op_sel_hi:[1,1,0]
	v_pk_fma_f32 v[54:55], v[54:55], v[134:135], v[100:101] op_sel_hi:[1,1,0]
	s_waitcnt lgkmcnt(0)
	v_lshlrev_b32_e32 v56, 16, v80
	v_and_b32_e32 v57, 0xffff0000, v80
	v_mul_f32_e32 v56, v60, v56
	v_mul_f32_e32 v57, v61, v57
	v_cvt_pk_bf16_f32 v56, v56, v57
	v_lshlrev_b32_e32 v57, 16, v81
	v_and_b32_e32 v60, 0xffff0000, v81
	v_mul_f32_e32 v57, v62, v57
	v_mul_f32_e32 v60, v63, v60
	v_cvt_pk_bf16_f32 v57, v57, v60
	v_lshlrev_b32_e32 v60, 16, v82
	v_mul_f32_e32 v58, v58, v60
	v_and_b32_e32 v60, 0xffff0000, v82
	v_mul_f32_e32 v59, v59, v60
	v_cvt_pk_bf16_f32 v58, v58, v59
	v_lshlrev_b32_e32 v59, 16, v83
	v_and_b32_e32 v60, 0xffff0000, v83
	v_mul_f32_e32 v59, v106, v59
	v_mul_f32_e32 v60, v107, v60
	v_cvt_pk_bf16_f32 v59, v59, v60
	v_lshl_add_u64 v[60:61], s[22:23], 0, v[102:103]
	v_lshl_add_u64 v[60:61], v[60:61], 0, s[36:37]
	v_lshl_add_u64 v[60:61], v[60:61], 0, v[188:189]
	global_store_dwordx4 v[60:61], v[56:59], off
	v_pk_fma_f32 v[44:45], v[44:45], v[132:133], v[104:105] op_sel_hi:[1,1,0]
	v_pk_fma_f32 v[46:47], v[46:47], v[134:135], v[104:105] op_sel_hi:[1,1,0]
	v_pk_fma_f32 v[56:57], v[50:51], v[130:131], v[100:101] op_sel_hi:[1,1,0]
	v_pk_fma_f32 v[50:51], v[48:49], v[128:129], v[100:101] op_sel_hi:[1,1,0]
	v_lshlrev_b32_e32 v48, 16, v84
	v_and_b32_e32 v49, 0xffff0000, v84
	v_mul_f32_e32 v48, v52, v48
	v_mul_f32_e32 v49, v53, v49
	v_cvt_pk_bf16_f32 v48, v48, v49
	v_lshlrev_b32_e32 v49, 16, v85
	v_and_b32_e32 v52, 0xffff0000, v85
	v_mul_f32_e32 v49, v54, v49
	v_mul_f32_e32 v52, v55, v52
	v_cvt_pk_bf16_f32 v49, v49, v52
	v_lshlrev_b32_e32 v52, 16, v86
	v_mul_f32_e32 v50, v50, v52
	v_and_b32_e32 v52, 0xffff0000, v86
	v_mul_f32_e32 v51, v51, v52
	v_cvt_pk_bf16_f32 v50, v50, v51
	v_lshlrev_b32_e32 v51, 16, v87
	v_and_b32_e32 v52, 0xffff0000, v87
	v_mul_f32_e32 v51, v56, v51
	v_mul_f32_e32 v52, v57, v52
	v_cvt_pk_bf16_f32 v51, v51, v52
	v_add_co_u32_e32 v52, vcc, s0, v124
	s_mov_b32 s0, 0x24000
	s_nop 0
	v_addc_co_u32_e32 v53, vcc, 0, v125, vcc
	global_store_dwordx4 v[52:53], v[48:51], off
	v_pk_fma_f32 v[36:37], v[36:37], v[132:133], v[104:105] op_sel_hi:[1,1,0]
	v_pk_fma_f32 v[38:39], v[38:39], v[134:135], v[104:105] op_sel_hi:[1,1,0]
	v_pk_fma_f32 v[48:49], v[42:43], v[130:131], v[104:105] op_sel_hi:[1,1,0]
	v_pk_fma_f32 v[42:43], v[40:41], v[128:129], v[104:105] op_sel_hi:[1,1,0]
	v_lshlrev_b32_e32 v40, 16, v88
	v_and_b32_e32 v41, 0xffff0000, v88
	v_mul_f32_e32 v40, v44, v40
	v_mul_f32_e32 v41, v45, v41
	v_cvt_pk_bf16_f32 v40, v40, v41
	v_lshlrev_b32_e32 v41, 16, v89
	v_and_b32_e32 v44, 0xffff0000, v89
	v_mul_f32_e32 v41, v46, v41
	v_mul_f32_e32 v44, v47, v44
	v_cvt_pk_bf16_f32 v41, v41, v44
	v_lshlrev_b32_e32 v44, 16, v90
	v_mul_f32_e32 v42, v42, v44
	v_and_b32_e32 v44, 0xffff0000, v90
	v_mul_f32_e32 v43, v43, v44
	v_cvt_pk_bf16_f32 v42, v42, v43
	v_lshlrev_b32_e32 v43, 16, v91
	v_and_b32_e32 v44, 0xffff0000, v91
	v_mul_f32_e32 v43, v48, v43
	v_mul_f32_e32 v44, v49, v44
	v_cvt_pk_bf16_f32 v43, v43, v44
	v_add_co_u32_e32 v44, vcc, s0, v124
	s_mov_b32 s0, 0x64000
	s_nop 0
	v_addc_co_u32_e32 v45, vcc, 0, v125, vcc
	global_store_dwordx4 v[44:45], v[40:43], off
	v_pk_fma_f32 v[28:29], v[28:29], v[132:133], v[78:79] op_sel_hi:[1,1,0]
	v_pk_fma_f32 v[30:31], v[30:31], v[134:135], v[78:79] op_sel_hi:[1,1,0]
	v_pk_fma_f32 v[40:41], v[34:35], v[130:131], v[104:105] op_sel_hi:[1,1,0]
	v_pk_fma_f32 v[34:35], v[32:33], v[128:129], v[104:105] op_sel_hi:[1,1,0]
	v_lshlrev_b32_e32 v32, 16, v92
	v_and_b32_e32 v33, 0xffff0000, v92
	v_mul_f32_e32 v32, v36, v32
	v_mul_f32_e32 v33, v37, v33
	v_cvt_pk_bf16_f32 v32, v32, v33
	v_lshlrev_b32_e32 v33, 16, v93
	v_and_b32_e32 v36, 0xffff0000, v93
	v_mul_f32_e32 v33, v38, v33
	v_mul_f32_e32 v36, v39, v36
	v_cvt_pk_bf16_f32 v33, v33, v36
	v_lshlrev_b32_e32 v36, 16, v94
	v_mul_f32_e32 v34, v34, v36
	v_and_b32_e32 v36, 0xffff0000, v94
	v_mul_f32_e32 v35, v35, v36
	v_cvt_pk_bf16_f32 v34, v34, v35
	v_lshlrev_b32_e32 v35, 16, v95
	v_and_b32_e32 v36, 0xffff0000, v95
	v_mul_f32_e32 v35, v40, v35
	v_mul_f32_e32 v36, v41, v36
	v_cvt_pk_bf16_f32 v35, v35, v36
	v_add_co_u32_e32 v36, vcc, s0, v124
	s_mov_b32 s0, 0x28000
	s_nop 0
	v_addc_co_u32_e32 v37, vcc, 0, v125, vcc
	global_store_dwordx4 v[36:37], v[32:35], off
	v_pk_fma_f32 v[20:21], v[20:21], v[132:133], v[78:79] op_sel_hi:[1,1,0]
	v_pk_fma_f32 v[22:23], v[22:23], v[134:135], v[78:79] op_sel_hi:[1,1,0]
	v_pk_fma_f32 v[32:33], v[26:27], v[130:131], v[78:79] op_sel_hi:[1,1,0]
	v_pk_fma_f32 v[26:27], v[24:25], v[128:129], v[78:79] op_sel_hi:[1,1,0]
	v_lshlrev_b32_e32 v24, 16, v96
	v_and_b32_e32 v25, 0xffff0000, v96
	v_mul_f32_e32 v24, v28, v24
	v_mul_f32_e32 v25, v29, v25
	v_cvt_pk_bf16_f32 v24, v24, v25
	v_lshlrev_b32_e32 v25, 16, v97
	v_and_b32_e32 v28, 0xffff0000, v97
	v_mul_f32_e32 v25, v30, v25
	v_mul_f32_e32 v28, v31, v28
	v_cvt_pk_bf16_f32 v25, v25, v28
	v_lshlrev_b32_e32 v28, 16, v98
	v_mul_f32_e32 v26, v26, v28
	v_and_b32_e32 v28, 0xffff0000, v98
	v_mul_f32_e32 v27, v27, v28
	v_cvt_pk_bf16_f32 v26, v26, v27
	v_lshlrev_b32_e32 v27, 16, v99
	v_and_b32_e32 v28, 0xffff0000, v99
	v_mul_f32_e32 v27, v32, v27
	v_mul_f32_e32 v28, v33, v28
	v_cvt_pk_bf16_f32 v27, v27, v28
	v_add_co_u32_e32 v28, vcc, s0, v124
	s_mov_b32 s0, 0x68000
	s_nop 0
	v_addc_co_u32_e32 v29, vcc, 0, v125, vcc
	global_store_dwordx4 v[28:29], v[24:27], off
	v_pk_fma_f32 v[12:13], v[12:13], v[132:133], v[76:77] op_sel_hi:[1,1,0]
	v_pk_fma_f32 v[14:15], v[14:15], v[134:135], v[76:77] op_sel_hi:[1,1,0]
	v_pk_fma_f32 v[24:25], v[18:19], v[130:131], v[78:79] op_sel_hi:[1,1,0]
	v_pk_fma_f32 v[18:19], v[16:17], v[128:129], v[78:79] op_sel_hi:[1,1,0]
	v_lshlrev_b32_e32 v16, 16, v72
	v_and_b32_e32 v17, 0xffff0000, v72
	v_mul_f32_e32 v16, v20, v16
	v_mul_f32_e32 v17, v21, v17
	v_cvt_pk_bf16_f32 v16, v16, v17
	v_lshlrev_b32_e32 v17, 16, v73
	v_and_b32_e32 v20, 0xffff0000, v73
	v_mul_f32_e32 v17, v22, v17
	v_mul_f32_e32 v20, v23, v20
	v_cvt_pk_bf16_f32 v17, v17, v20
	v_lshlrev_b32_e32 v20, 16, v74
	v_mul_f32_e32 v18, v18, v20
	v_and_b32_e32 v20, 0xffff0000, v74
	v_mul_f32_e32 v19, v19, v20
	v_cvt_pk_bf16_f32 v18, v18, v19
	v_lshlrev_b32_e32 v19, 16, v75
	v_and_b32_e32 v20, 0xffff0000, v75
	v_mul_f32_e32 v19, v24, v19
	v_mul_f32_e32 v20, v25, v20
	v_cvt_pk_bf16_f32 v19, v19, v20
	v_add_co_u32_e32 v20, vcc, s0, v124
	s_mov_b32 s0, 0x2c000
	s_nop 0
	v_addc_co_u32_e32 v21, vcc, 0, v125, vcc
	global_store_dwordx4 v[20:21], v[16:19], off
	v_pk_fma_f32 v[4:5], v[4:5], v[132:133], v[76:77] op_sel_hi:[1,1,0]
	v_pk_fma_f32 v[6:7], v[6:7], v[134:135], v[76:77] op_sel_hi:[1,1,0]
	v_pk_fma_f32 v[16:17], v[10:11], v[130:131], v[76:77] op_sel_hi:[1,1,0]
	v_pk_fma_f32 v[10:11], v[8:9], v[128:129], v[76:77] op_sel_hi:[1,1,0]
	v_lshlrev_b32_e32 v8, 16, v68
	v_and_b32_e32 v9, 0xffff0000, v68
	v_mul_f32_e32 v8, v12, v8
	v_mul_f32_e32 v9, v13, v9
	v_cvt_pk_bf16_f32 v8, v8, v9
	v_lshlrev_b32_e32 v9, 16, v69
	v_and_b32_e32 v12, 0xffff0000, v69
	v_mul_f32_e32 v9, v14, v9
	v_mul_f32_e32 v12, v15, v12
	v_cvt_pk_bf16_f32 v9, v9, v12
	v_lshlrev_b32_e32 v12, 16, v70
	v_mul_f32_e32 v10, v10, v12
	v_and_b32_e32 v12, 0xffff0000, v70
	v_mul_f32_e32 v11, v11, v12
	v_cvt_pk_bf16_f32 v10, v10, v11
	v_lshlrev_b32_e32 v11, 16, v71
	v_and_b32_e32 v12, 0xffff0000, v71
	v_mul_f32_e32 v11, v16, v11
	v_mul_f32_e32 v12, v17, v12
	v_cvt_pk_bf16_f32 v11, v11, v12
	v_add_co_u32_e32 v12, vcc, s0, v124
	s_mov_b64 s[36:37], -1
	s_nop 0
	v_addc_co_u32_e32 v13, vcc, 0, v125, vcc
	global_store_dwordx4 v[12:13], v[8:11], off
	s_nop 1
	v_pk_fma_f32 v[8:9], v[2:3], v[130:131], v[76:77] op_sel_hi:[1,1,0]
	v_pk_fma_f32 v[2:3], v[0:1], v[128:129], v[76:77] op_sel_hi:[1,1,0]
	v_lshlrev_b32_e32 v0, 16, v64
	v_and_b32_e32 v1, 0xffff0000, v64
	v_mul_f32_e32 v0, v4, v0
	v_mul_f32_e32 v1, v5, v1
	v_cvt_pk_bf16_f32 v0, v0, v1
	v_lshlrev_b32_e32 v1, 16, v65
	v_and_b32_e32 v4, 0xffff0000, v65
	v_mul_f32_e32 v1, v6, v1
	v_mul_f32_e32 v4, v7, v4
	v_cvt_pk_bf16_f32 v1, v1, v4
	v_lshlrev_b32_e32 v4, 16, v66
	v_mul_f32_e32 v2, v2, v4
	v_and_b32_e32 v4, 0xffff0000, v66
	v_mul_f32_e32 v3, v3, v4
	v_cvt_pk_bf16_f32 v2, v2, v3
	v_lshlrev_b32_e32 v3, 16, v67
	v_and_b32_e32 v4, 0xffff0000, v67
	v_mul_f32_e32 v3, v8, v3
	v_mul_f32_e32 v4, v9, v4
	v_cvt_pk_bf16_f32 v3, v3, v4
	v_add_co_u32_e32 v4, vcc, 0x6c000, v124
	s_nop 1
	v_addc_co_u32_e32 v5, vcc, 0, v125, vcc
	global_store_dwordx4 v[4:5], v[0:3], off
	s_andn2_b64 vcc, exec, s[34:35]
	s_cbranch_vccnz .LBB0_269
	v_readlane_b32 s4, v255, 32
	v_readlane_b32 s5, v255, 33
	s_andn2_b64 vcc, exec, s[4:5]
	s_cbranch_vccnz .LBB0_268
	s_barrier
	s_branch .LBB0_268

.LBB0_295:
	s_mul_i32 s0, s16, s15
	s_add_i32 s0, s0, s1
	s_ashr_i32 s4, s0, 2
	s_and_b32 s3, s0, 3
	v_lshl_add_u32 v4, s4, 8, v7
	s_lshl_b32 s60, s3, 8
	v_ashrrev_i32_e32 v5, 31, v4
	v_lshl_add_u64 v[2:3], v[0:1], 0, s[60:61]
	v_lshlrev_b64 v[14:15], 10, v[4:5]
	v_lshl_add_u64 v[14:15], v[2:3], 0, v[14:15]
	global_load_dwordx4 v[14:17], v[14:15], off
	s_waitcnt vmcnt(0) lgkmcnt(0)
	v_lshlrev_b32_e32 v5, 16, v14
	v_and_b32_e32 v14, 0xffff0000, v14
	v_mul_f32_e32 v21, v14, v14
	v_lshlrev_b32_e32 v18, 16, v15
	v_fmac_f32_e32 v21, v5, v5
	v_and_b32_e32 v15, 0xffff0000, v15
	v_fmac_f32_e32 v21, v18, v18
	v_lshlrev_b32_e32 v19, 16, v16
	v_fmac_f32_e32 v21, v15, v15
	v_and_b32_e32 v16, 0xffff0000, v16
	v_fmac_f32_e32 v21, v19, v19
	v_lshlrev_b32_e32 v20, 16, v17
	v_fmac_f32_e32 v21, v16, v16
	v_and_b32_e32 v17, 0xffff0000, v17
	v_fmac_f32_e32 v21, v20, v20
	v_fmac_f32_e32 v21, v17, v17
	ds_bpermute_b32 v22, v9, v21
	s_waitcnt lgkmcnt(0)
	v_add_f32_e32 v21, v21, v22
	ds_bpermute_b32 v22, v10, v21
	s_waitcnt lgkmcnt(0)
	v_add_f32_e32 v21, v21, v22
	ds_bpermute_b32 v22, v11, v21
	s_waitcnt lgkmcnt(0)
	v_add_f32_e32 v21, v21, v22
	ds_bpermute_b32 v22, v12, v21
	s_waitcnt lgkmcnt(0)
	v_add_f32_e32 v21, v21, v22
	v_fmamk_f32 v21, v21, 0x3c000000, v229
	v_rsq_f32_e32 v21, v21
	s_nop 0
	v_mul_f32_e32 v5, v21, v5
	v_mul_f32_e32 v14, v21, v14
	v_cvt_pk_bf16_f32 v5, v5, v14
	ds_write_b16 v13, v5
	ds_write_b16_d16_hi v13, v5 offset:528
	v_mul_f32_e32 v5, v21, v18
	v_mul_f32_e32 v14, v21, v15
	v_cvt_pk_bf16_f32 v5, v5, v14
	ds_write_b16 v13, v5 offset:1056
	ds_write_b16_d16_hi v13, v5 offset:1584
	v_mul_f32_e32 v5, v21, v19
	v_mul_f32_e32 v14, v21, v16
	v_cvt_pk_bf16_f32 v5, v5, v14
	ds_write_b16 v13, v5 offset:2112
	ds_write_b16_d16_hi v13, v5 offset:2640
	v_mul_f32_e32 v5, v21, v20
	v_mul_f32_e32 v14, v21, v17
	v_cvt_pk_bf16_f32 v5, v5, v14
	v_add_u32_e32 v14, 32, v4
	v_ashrrev_i32_e32 v15, 31, v14
	v_lshlrev_b64 v[14:15], 10, v[14:15]
	ds_write_b16 v13, v5 offset:3168
	ds_write_b16_d16_hi v13, v5 offset:3696
	v_lshl_add_u64 v[14:15], v[2:3], 0, v[14:15]
	global_load_dwordx4 v[14:17], v[14:15], off
	s_waitcnt vmcnt(0) lgkmcnt(0)
	v_lshlrev_b32_e32 v5, 16, v14
	v_and_b32_e32 v14, 0xffff0000, v14
	v_mul_f32_e32 v21, v14, v14
	v_lshlrev_b32_e32 v18, 16, v15
	v_fmac_f32_e32 v21, v5, v5
	v_and_b32_e32 v15, 0xffff0000, v15
	v_fmac_f32_e32 v21, v18, v18
	v_lshlrev_b32_e32 v19, 16, v16
	v_fmac_f32_e32 v21, v15, v15
	v_and_b32_e32 v16, 0xffff0000, v16
	v_fmac_f32_e32 v21, v19, v19
	v_lshlrev_b32_e32 v20, 16, v17
	v_fmac_f32_e32 v21, v16, v16
	v_and_b32_e32 v17, 0xffff0000, v17
	v_fmac_f32_e32 v21, v20, v20
	v_fmac_f32_e32 v21, v17, v17
	ds_bpermute_b32 v22, v9, v21
	s_waitcnt lgkmcnt(0)
	v_add_f32_e32 v21, v21, v22
	ds_bpermute_b32 v22, v10, v21
	s_waitcnt lgkmcnt(0)
	v_add_f32_e32 v21, v21, v22
	ds_bpermute_b32 v22, v11, v21
	s_waitcnt lgkmcnt(0)
	v_add_f32_e32 v21, v21, v22
	ds_bpermute_b32 v22, v12, v21
	s_waitcnt lgkmcnt(0)
	v_add_f32_e32 v21, v21, v22
	v_fmamk_f32 v21, v21, 0x3c000000, v229
	v_rsq_f32_e32 v21, v21
	s_nop 0
	v_mul_f32_e32 v5, v21, v5
	v_mul_f32_e32 v14, v21, v14
	v_cvt_pk_bf16_f32 v5, v5, v14
	ds_write_b16 v13, v5 offset:64
	ds_write_b16_d16_hi v13, v5 offset:592
	v_mul_f32_e32 v5, v21, v18
	v_mul_f32_e32 v14, v21, v15
	v_cvt_pk_bf16_f32 v5, v5, v14
	ds_write_b16 v13, v5 offset:1120
	ds_write_b16_d16_hi v13, v5 offset:1648
	v_mul_f32_e32 v5, v21, v19
	v_mul_f32_e32 v14, v21, v16
	v_cvt_pk_bf16_f32 v5, v5, v14
	ds_write_b16 v13, v5 offset:2176
	ds_write_b16_d16_hi v13, v5 offset:2704
	v_mul_f32_e32 v5, v21, v20
	v_mul_f32_e32 v14, v21, v17
	v_cvt_pk_bf16_f32 v5, v5, v14
	v_add_u32_e32 v14, 64, v4
	v_ashrrev_i32_e32 v15, 31, v14
	v_lshlrev_b64 v[14:15], 10, v[14:15]
	ds_write_b16 v13, v5 offset:3232
	ds_write_b16_d16_hi v13, v5 offset:3760
	v_lshl_add_u64 v[14:15], v[2:3], 0, v[14:15]
	global_load_dwordx4 v[14:17], v[14:15], off
	s_waitcnt vmcnt(0) lgkmcnt(0)
	v_lshlrev_b32_e32 v5, 16, v14
	v_and_b32_e32 v14, 0xffff0000, v14
	v_mul_f32_e32 v21, v14, v14
	v_lshlrev_b32_e32 v18, 16, v15
	v_fmac_f32_e32 v21, v5, v5
	v_and_b32_e32 v15, 0xffff0000, v15
	v_fmac_f32_e32 v21, v18, v18
	v_lshlrev_b32_e32 v19, 16, v16
	v_fmac_f32_e32 v21, v15, v15
	v_and_b32_e32 v16, 0xffff0000, v16
	v_fmac_f32_e32 v21, v19, v19
	v_lshlrev_b32_e32 v20, 16, v17
	v_fmac_f32_e32 v21, v16, v16
	v_and_b32_e32 v17, 0xffff0000, v17
	v_fmac_f32_e32 v21, v20, v20
	v_fmac_f32_e32 v21, v17, v17
	ds_bpermute_b32 v22, v9, v21
	s_waitcnt lgkmcnt(0)
	v_add_f32_e32 v21, v21, v22
	ds_bpermute_b32 v22, v10, v21
	s_waitcnt lgkmcnt(0)
	v_add_f32_e32 v21, v21, v22
	ds_bpermute_b32 v22, v11, v21
	s_waitcnt lgkmcnt(0)
	v_add_f32_e32 v21, v21, v22
	ds_bpermute_b32 v22, v12, v21
	s_waitcnt lgkmcnt(0)
	v_add_f32_e32 v21, v21, v22
	v_fmamk_f32 v21, v21, 0x3c000000, v229
	v_rsq_f32_e32 v21, v21
	s_nop 0
	v_mul_f32_e32 v5, v21, v5
	v_mul_f32_e32 v14, v21, v14
	v_cvt_pk_bf16_f32 v5, v5, v14
	ds_write_b16 v13, v5 offset:128
	ds_write_b16_d16_hi v13, v5 offset:656
	v_mul_f32_e32 v5, v21, v18
	v_mul_f32_e32 v14, v21, v15
	v_cvt_pk_bf16_f32 v5, v5, v14
	ds_write_b16 v13, v5 offset:1184
	ds_write_b16_d16_hi v13, v5 offset:1712
	v_mul_f32_e32 v5, v21, v19
	v_mul_f32_e32 v14, v21, v16
	v_cvt_pk_bf16_f32 v5, v5, v14
	ds_write_b16 v13, v5 offset:2240
	ds_write_b16_d16_hi v13, v5 offset:2768
	v_mul_f32_e32 v5, v21, v20
	v_mul_f32_e32 v14, v21, v17
	v_cvt_pk_bf16_f32 v5, v5, v14
	v_add_u32_e32 v14, 0x60, v4
	v_ashrrev_i32_e32 v15, 31, v14
	v_lshlrev_b64 v[14:15], 10, v[14:15]
	ds_write_b16 v13, v5 offset:3296
	ds_write_b16_d16_hi v13, v5 offset:3824
	v_lshl_add_u64 v[14:15], v[2:3], 0, v[14:15]
	global_load_dwordx4 v[14:17], v[14:15], off
	s_waitcnt vmcnt(0) lgkmcnt(0)
	v_lshlrev_b32_e32 v5, 16, v14
	v_and_b32_e32 v14, 0xffff0000, v14
	v_mul_f32_e32 v21, v14, v14
	v_lshlrev_b32_e32 v18, 16, v15
	v_fmac_f32_e32 v21, v5, v5
	v_and_b32_e32 v15, 0xffff0000, v15
	v_fmac_f32_e32 v21, v18, v18
	v_lshlrev_b32_e32 v19, 16, v16
	v_fmac_f32_e32 v21, v15, v15
	v_and_b32_e32 v16, 0xffff0000, v16
	v_fmac_f32_e32 v21, v19, v19
	v_lshlrev_b32_e32 v20, 16, v17
	v_fmac_f32_e32 v21, v16, v16
	v_and_b32_e32 v17, 0xffff0000, v17
	v_fmac_f32_e32 v21, v20, v20
	v_fmac_f32_e32 v21, v17, v17
	ds_bpermute_b32 v22, v9, v21
	s_waitcnt lgkmcnt(0)
	v_add_f32_e32 v21, v21, v22
	ds_bpermute_b32 v22, v10, v21
	s_waitcnt lgkmcnt(0)
	v_add_f32_e32 v21, v21, v22
	ds_bpermute_b32 v22, v11, v21
	s_waitcnt lgkmcnt(0)
	v_add_f32_e32 v21, v21, v22
	ds_bpermute_b32 v22, v12, v21
	s_waitcnt lgkmcnt(0)
	v_add_f32_e32 v21, v21, v22
	v_fmamk_f32 v21, v21, 0x3c000000, v229
	v_rsq_f32_e32 v21, v21
	s_nop 0
	v_mul_f32_e32 v5, v21, v5
	v_mul_f32_e32 v14, v21, v14
	v_cvt_pk_bf16_f32 v5, v5, v14
	ds_write_b16 v13, v5 offset:192
	ds_write_b16_d16_hi v13, v5 offset:720
	v_mul_f32_e32 v5, v21, v18
	v_mul_f32_e32 v14, v21, v15
	v_cvt_pk_bf16_f32 v5, v5, v14
	ds_write_b16 v13, v5 offset:1248
	ds_write_b16_d16_hi v13, v5 offset:1776
	v_mul_f32_e32 v5, v21, v19
	v_mul_f32_e32 v14, v21, v16
	v_cvt_pk_bf16_f32 v5, v5, v14
	ds_write_b16 v13, v5 offset:2304
	ds_write_b16_d16_hi v13, v5 offset:2832
	v_mul_f32_e32 v5, v21, v20
	v_mul_f32_e32 v14, v21, v17
	v_cvt_pk_bf16_f32 v5, v5, v14
	v_add_u32_e32 v14, 0x80, v4
	v_ashrrev_i32_e32 v15, 31, v14
	v_lshlrev_b64 v[14:15], 10, v[14:15]
	ds_write_b16 v13, v5 offset:3360
	ds_write_b16_d16_hi v13, v5 offset:3888
	v_lshl_add_u64 v[14:15], v[2:3], 0, v[14:15]
	global_load_dwordx4 v[14:17], v[14:15], off
	s_waitcnt vmcnt(0) lgkmcnt(0)
	v_lshlrev_b32_e32 v5, 16, v14
	v_and_b32_e32 v14, 0xffff0000, v14
	v_mul_f32_e32 v21, v14, v14
	v_lshlrev_b32_e32 v18, 16, v15
	v_fmac_f32_e32 v21, v5, v5
	v_and_b32_e32 v15, 0xffff0000, v15
	v_fmac_f32_e32 v21, v18, v18
	v_lshlrev_b32_e32 v19, 16, v16
	v_fmac_f32_e32 v21, v15, v15
	v_and_b32_e32 v16, 0xffff0000, v16
	v_fmac_f32_e32 v21, v19, v19
	v_lshlrev_b32_e32 v20, 16, v17
	v_fmac_f32_e32 v21, v16, v16
	v_and_b32_e32 v17, 0xffff0000, v17
	v_fmac_f32_e32 v21, v20, v20
	v_fmac_f32_e32 v21, v17, v17
	ds_bpermute_b32 v22, v9, v21
	s_waitcnt lgkmcnt(0)
	v_add_f32_e32 v21, v21, v22
	ds_bpermute_b32 v22, v10, v21
	s_waitcnt lgkmcnt(0)
	v_add_f32_e32 v21, v21, v22
	ds_bpermute_b32 v22, v11, v21
	s_waitcnt lgkmcnt(0)
	v_add_f32_e32 v21, v21, v22
	ds_bpermute_b32 v22, v12, v21
	s_waitcnt lgkmcnt(0)
	v_add_f32_e32 v21, v21, v22
	v_fmamk_f32 v21, v21, 0x3c000000, v229
	v_rsq_f32_e32 v21, v21
	s_nop 0
	v_mul_f32_e32 v5, v21, v5
	v_mul_f32_e32 v14, v21, v14
	v_cvt_pk_bf16_f32 v5, v5, v14
	ds_write_b16 v13, v5 offset:256
	ds_write_b16_d16_hi v13, v5 offset:784
	v_mul_f32_e32 v5, v21, v18
	v_mul_f32_e32 v14, v21, v15
	v_cvt_pk_bf16_f32 v5, v5, v14
	ds_write_b16 v13, v5 offset:1312
	ds_write_b16_d16_hi v13, v5 offset:1840
	v_mul_f32_e32 v5, v21, v19
	v_mul_f32_e32 v14, v21, v16
	v_cvt_pk_bf16_f32 v5, v5, v14
	ds_write_b16 v13, v5 offset:2368
	ds_write_b16_d16_hi v13, v5 offset:2896
	v_mul_f32_e32 v5, v21, v20
	v_mul_f32_e32 v14, v21, v17
	v_cvt_pk_bf16_f32 v5, v5, v14
	v_add_u32_e32 v14, 0xa0, v4
	v_ashrrev_i32_e32 v15, 31, v14
	v_lshlrev_b64 v[14:15], 10, v[14:15]
	ds_write_b16 v13, v5 offset:3424
	ds_write_b16_d16_hi v13, v5 offset:3952
	v_lshl_add_u64 v[14:15], v[2:3], 0, v[14:15]
	global_load_dwordx4 v[14:17], v[14:15], off
	s_waitcnt vmcnt(0) lgkmcnt(0)
	v_lshlrev_b32_e32 v5, 16, v14
	v_and_b32_e32 v14, 0xffff0000, v14
	v_mul_f32_e32 v21, v14, v14
	v_lshlrev_b32_e32 v18, 16, v15
	v_fmac_f32_e32 v21, v5, v5
	v_and_b32_e32 v15, 0xffff0000, v15
	v_fmac_f32_e32 v21, v18, v18
	v_lshlrev_b32_e32 v19, 16, v16
	v_fmac_f32_e32 v21, v15, v15
	v_and_b32_e32 v16, 0xffff0000, v16
	v_fmac_f32_e32 v21, v19, v19
	v_lshlrev_b32_e32 v20, 16, v17
	v_fmac_f32_e32 v21, v16, v16
	v_and_b32_e32 v17, 0xffff0000, v17
	v_fmac_f32_e32 v21, v20, v20
	v_fmac_f32_e32 v21, v17, v17
	ds_bpermute_b32 v22, v9, v21
	s_waitcnt lgkmcnt(0)
	v_add_f32_e32 v21, v21, v22
	ds_bpermute_b32 v22, v10, v21
	s_waitcnt lgkmcnt(0)
	v_add_f32_e32 v21, v21, v22
	ds_bpermute_b32 v22, v11, v21
	s_waitcnt lgkmcnt(0)
	v_add_f32_e32 v21, v21, v22
	ds_bpermute_b32 v22, v12, v21
	s_waitcnt lgkmcnt(0)
	v_add_f32_e32 v21, v21, v22
	v_fmamk_f32 v21, v21, 0x3c000000, v229
	v_rsq_f32_e32 v21, v21
	s_nop 0
	v_mul_f32_e32 v5, v21, v5
	v_mul_f32_e32 v14, v21, v14
	v_cvt_pk_bf16_f32 v5, v5, v14
	ds_write_b16 v13, v5 offset:320
	ds_write_b16_d16_hi v13, v5 offset:848
	v_mul_f32_e32 v5, v21, v18
	v_mul_f32_e32 v14, v21, v15
	v_cvt_pk_bf16_f32 v5, v5, v14
	ds_write_b16 v13, v5 offset:1376
	ds_write_b16_d16_hi v13, v5 offset:1904
	v_mul_f32_e32 v5, v21, v19
	v_mul_f32_e32 v14, v21, v16
	v_cvt_pk_bf16_f32 v5, v5, v14
	ds_write_b16 v13, v5 offset:2432
	ds_write_b16_d16_hi v13, v5 offset:2960
	v_mul_f32_e32 v5, v21, v20
	v_mul_f32_e32 v14, v21, v17
	v_cvt_pk_bf16_f32 v5, v5, v14
	v_add_u32_e32 v14, 0xc0, v4
	v_ashrrev_i32_e32 v15, 31, v14
	v_lshlrev_b64 v[14:15], 10, v[14:15]
	ds_write_b16 v13, v5 offset:3488
	ds_write_b16_d16_hi v13, v5 offset:4016
	v_lshl_add_u64 v[14:15], v[2:3], 0, v[14:15]
	global_load_dwordx4 v[14:17], v[14:15], off
	v_add_u32_e32 v4, 0xe0, v4
	s_waitcnt vmcnt(0) lgkmcnt(0)
	v_lshlrev_b32_e32 v5, 16, v14
	v_and_b32_e32 v14, 0xffff0000, v14
	v_mul_f32_e32 v21, v14, v14
	v_lshlrev_b32_e32 v18, 16, v15
	v_fmac_f32_e32 v21, v5, v5
	v_and_b32_e32 v15, 0xffff0000, v15
	v_fmac_f32_e32 v21, v18, v18
	v_lshlrev_b32_e32 v19, 16, v16
	v_fmac_f32_e32 v21, v15, v15
	v_and_b32_e32 v16, 0xffff0000, v16
	v_fmac_f32_e32 v21, v19, v19
	v_lshlrev_b32_e32 v20, 16, v17
	v_fmac_f32_e32 v21, v16, v16
	v_and_b32_e32 v17, 0xffff0000, v17
	v_fmac_f32_e32 v21, v20, v20
	v_fmac_f32_e32 v21, v17, v17
	ds_bpermute_b32 v22, v9, v21
	s_waitcnt lgkmcnt(0)
	v_add_f32_e32 v21, v21, v22
	ds_bpermute_b32 v22, v10, v21
	s_waitcnt lgkmcnt(0)
	v_add_f32_e32 v21, v21, v22
	ds_bpermute_b32 v22, v11, v21
	s_waitcnt lgkmcnt(0)
	v_add_f32_e32 v21, v21, v22
	ds_bpermute_b32 v22, v12, v21
	s_waitcnt lgkmcnt(0)
	v_add_f32_e32 v21, v21, v22
	v_fmamk_f32 v21, v21, 0x3c000000, v229
	v_rsq_f32_e32 v21, v21
	s_nop 0
	v_mul_f32_e32 v5, v21, v5
	v_mul_f32_e32 v14, v21, v14
	v_cvt_pk_bf16_f32 v5, v5, v14
	ds_write_b16 v13, v5 offset:384
	ds_write_b16_d16_hi v13, v5 offset:912
	v_mul_f32_e32 v5, v21, v18
	v_mul_f32_e32 v14, v21, v15
	v_cvt_pk_bf16_f32 v5, v5, v14
	ds_write_b16 v13, v5 offset:1440
	ds_write_b16_d16_hi v13, v5 offset:1968
	v_mul_f32_e32 v5, v21, v19
	v_mul_f32_e32 v14, v21, v16
	v_cvt_pk_bf16_f32 v5, v5, v14
	ds_write_b16 v13, v5 offset:2496
	ds_write_b16_d16_hi v13, v5 offset:3024
	v_mul_f32_e32 v5, v21, v20
	v_mul_f32_e32 v14, v21, v17
	v_cvt_pk_bf16_f32 v5, v5, v14
	ds_write_b16 v13, v5 offset:3552
	ds_write_b16_d16_hi v13, v5 offset:4080
	v_ashrrev_i32_e32 v5, 31, v4
	v_lshlrev_b64 v[4:5], 10, v[4:5]
	v_lshl_add_u64 v[2:3], v[2:3], 0, v[4:5]
	global_load_dwordx4 v[2:5], v[2:3], off
	s_waitcnt vmcnt(0) lgkmcnt(0)
	v_lshlrev_b32_e32 v14, 16, v2
	v_and_b32_e32 v2, 0xffff0000, v2
	v_mul_f32_e32 v18, v2, v2
	v_lshlrev_b32_e32 v15, 16, v3
	v_fmac_f32_e32 v18, v14, v14
	v_and_b32_e32 v3, 0xffff0000, v3
	v_fmac_f32_e32 v18, v15, v15
	v_lshlrev_b32_e32 v16, 16, v4
	v_fmac_f32_e32 v18, v3, v3
	v_and_b32_e32 v4, 0xffff0000, v4
	v_fmac_f32_e32 v18, v16, v16
	v_lshlrev_b32_e32 v17, 16, v5
	v_fmac_f32_e32 v18, v4, v4
	v_and_b32_e32 v5, 0xffff0000, v5
	v_fmac_f32_e32 v18, v17, v17
	v_fmac_f32_e32 v18, v5, v5
	ds_bpermute_b32 v19, v9, v18
	s_waitcnt lgkmcnt(0)
	v_add_f32_e32 v18, v18, v19
	ds_bpermute_b32 v19, v10, v18
	s_waitcnt lgkmcnt(0)
	v_add_f32_e32 v18, v18, v19
	ds_bpermute_b32 v19, v11, v18
	s_waitcnt lgkmcnt(0)
	v_add_f32_e32 v18, v18, v19
	ds_bpermute_b32 v19, v12, v18
	s_waitcnt lgkmcnt(0)
	v_add_f32_e32 v18, v18, v19
	v_fmamk_f32 v18, v18, 0x3c000000, v229
	v_rsq_f32_e32 v18, v18
	s_nop 0
	v_mul_f32_e32 v2, v18, v2
	v_mul_f32_e32 v14, v18, v14
	v_cvt_pk_bf16_f32 v2, v14, v2
	ds_write_b16 v13, v2 offset:448
	ds_write_b16_d16_hi v13, v2 offset:976
	v_mul_f32_e32 v2, v18, v15
	v_mul_f32_e32 v3, v18, v3
	v_cvt_pk_bf16_f32 v2, v2, v3
	ds_write_b16 v13, v2 offset:1504
	ds_write_b16_d16_hi v13, v2 offset:2032
	v_mul_f32_e32 v2, v18, v16
	v_mul_f32_e32 v3, v18, v4
	v_cvt_pk_bf16_f32 v2, v2, v3
	ds_write_b16 v13, v2 offset:2560
	ds_write_b16_d16_hi v13, v2 offset:3088
	v_mul_f32_e32 v2, v18, v17
	v_mul_f32_e32 v3, v18, v5
	v_cvt_pk_bf16_f32 v2, v2, v3
	ds_write_b16 v13, v2 offset:3616
	ds_write_b16_d16_hi v13, v2 offset:4144
	s_waitcnt lgkmcnt(0)
	s_barrier
	s_and_saveexec_b64 s[6:7], vcc
	s_cbranch_execz .LBB0_294
	s_add_i32 s4, s60, s4
	s_ashr_i32 s5, s4, 31
	s_lshl_b64 s[4:5], s[4:5], 16
	s_add_u32 s22, s56, s4
	s_addc_u32 s23, s57, s5
	s_mov_b64 s[24:25], 0
	v_mov_b32_e32 v2, v8
	v_mov_b32_e32 v3, v6
.LBB0_297:
	s_movk_i32 s0, 0xdff
	v_ashrrev_i32_e32 v4, 5, v3
	v_lshlrev_b32_e32 v5, 1, v2
	v_cmp_lt_i32_e64 s[4:5], s0, v3
	s_movk_i32 s0, 0x210
	v_add_u32_e32 v18, 0x200, v3
	v_mul_lo_u32 v3, v4, s0
	v_and_b32_e32 v188, 0x1f0, v5
	v_add3_u32 v3, 0, v3, v188
	ds_read_b128 v[14:17], v3
	v_ashrrev_i32_e32 v5, 31, v4
	v_lshlrev_b64 v[4:5], 9, v[4:5]
	v_lshl_add_u64 v[4:5], s[22:23], 0, v[4:5]
	v_add_u32_e32 v2, 0x1000, v2
	s_or_b64 s[24:25], s[4:5], s[24:25]
	v_mov_b32_e32 v3, v18
	v_lshl_add_u64 v[4:5], v[4:5], 0, v[188:189]
	s_waitcnt lgkmcnt(0)
	global_store_dwordx4 v[4:5], v[14:17], off
	s_andn2_b64 exec, exec, s[24:25]
	s_cbranch_execnz .LBB0_297
	s_branch .LBB0_294

.LBB0_313:
	s_lshl_b32 s0, s92, 11
	s_ashr_i32 s1, s0, 31
	s_lshl_b32 s10, s92, 5
	s_ashr_i32 s11, s10, 31
	s_lshl_b64 s[0:1], s[0:1], 2
	s_add_u32 s4, s4, s0
	s_addc_u32 s5, s5, s1
	s_add_u32 s6, s6, s0
	s_addc_u32 s7, s7, s1
	s_lshl_b64 s[0:1], s[10:11], 2
	v_readlane_b32 s10, v255, 34
	v_readlane_b32 s11, v255, 35
	s_add_u32 s3, s10, s0
	v_readlane_b32 s0, v255, 36
	s_addc_u32 s10, s11, s1
	s_lshl_b32 s0, s0, 7
	v_readlane_b32 s1, v255, 32
	s_add_i32 s0, s0, 0
	s_lshl_b32 s1, s1, 15
	v_lshlrev_b32_e32 v64, 9, v71
	s_add_i32 s1, s1, s0
	v_add3_u32 v64, s1, v72, v64
	s_barrier
	ds_write_b128 v64, v[60:63]
	ds_write_b128 v64, v[56:59] offset:64
	ds_write_b128 v64, v[52:55] offset:8192
	ds_write_b128 v64, v[48:51] offset:8256
	ds_write_b128 v64, v[44:47] offset:16384
	ds_write_b128 v64, v[40:43] offset:16448
	ds_write_b128 v64, v[36:39] offset:24576
	ds_write_b128 v64, v[32:35] offset:24640
	v_add_u32_e32 v32, 0x10000, v64
	s_ashr_i32 s23, s22, 31
	ds_write_b128 v32, v[28:31]
	ds_write_b128 v32, v[24:27] offset:64
	v_add_u32_e32 v24, 0x12000, v64
	s_lshl_b64 s[0:1], s[22:23], 2
	ds_write_b128 v24, v[20:23]
	ds_write_b128 v24, v[16:19] offset:64
	v_add_u32_e32 v16, 0x14000, v64
	s_add_u32 s0, s3, s0
	ds_write_b128 v16, v[12:15]
	ds_write_b128 v16, v[8:11] offset:64
	v_add_u32_e32 v8, 0x16000, v64
	s_addc_u32 s1, s10, s1
	ds_write_b128 v8, v[4:7]
	ds_write_b128 v8, v[0:3] offset:64
	s_waitcnt vmcnt(0) lgkmcnt(0)
	s_barrier
	global_load_dword v4, v189, s[0:1]
	v_and_b32_e32 v5, 63, v70
	v_lshl_or_b32 v0, s22, 6, v5
	v_ashrrev_i32_e32 v1, 31, v0
	v_lshlrev_b64 v[0:1], 2, v[0:1]
	v_lshl_add_u64 v[2:3], s[6:7], 0, v[0:1]
	global_load_dword v3, v[2:3], off
	v_lshl_add_u64 v[0:1], s[4:5], 0, v[0:1]
	global_load_dword v10, v[0:1], off
	s_lshl_b32 s1, s14, 3
	s_and_b32 s1, s1, 24
	s_add_i32 s1, s1, s2
	s_lshl_b32 s0, s22, 10
	s_lshl_b32 s1, s1, 5
	s_add_i32 s0, s1, s0
	s_mul_hi_i32 s1, s0, 0x900
	s_mulk_i32 s0, 0x900
	s_add_u32 s0, s12, s0
	v_lshlrev_b32_e32 v188, 1, v5
	s_addc_u32 s1, s13, s1
	s_lshl_b32 s3, s2, 14
	v_lshl_add_u64 v[0:1], s[0:1], 0, v[188:189]
	s_add_i32 s0, s3, 0
	v_lshl_add_u32 v2, v5, 2, s0
	v_cvt_pk_bf16_f32 v6, v189, v189
	global_store_short v[0:1], v6, off
	v_cvt_pk_bf16_f32 v11, v189, v189
	global_store_short v[0:1], v11, off offset:128
	s_movk_i32 s0, 0x1000
	v_add_co_u32_e32 v6, vcc, s0, v0
	s_movk_i32 s0, 0x3000
	s_nop 0
	v_addc_co_u32_e32 v7, vcc, 0, v1, vcc
	s_movk_i32 s89, 0x4000
	s_movk_i32 s60, 0x6000
	s_mov_b32 s46, 0x10000
	v_readlane_b32 s90, v255, 15
	v_readlane_b32 s76, v255, 19
	v_readlane_b32 s2, v255, 14
	v_readlane_b32 s91, v255, 16
	v_readlane_b32 s71, v255, 17
	v_readlane_b32 s33, v255, 18
	v_readlane_b32 s77, v255, 20
	s_movk_i32 s43, 0x1040
	s_movk_i32 s69, 0x400
	s_movk_i32 s86, 0x7f
	s_mov_b32 s87, 0xb00000
	v_readlane_b32 s23, v255, 31
	s_waitcnt vmcnt(0)
	v_mul_f32_e32 v4, 0x3fb8aa3b, v4
	v_exp_f32_e32 v8, v4
	v_cvt_f64_f32_e32 v[4:5], v3
	v_mul_f32_e32 v3, 0x42800000, v8
	v_cvt_f64_f32_e32 v[8:9], v8
	v_ldexp_f64 v[8:9], v[8:9], 6
	v_mul_f64 v[4:5], v[8:9], v[4:5]
	v_mul_f64 v[8:9], v[4:5], s[58:59]
	v_rndne_f64_e32 v[8:9], v[8:9]
	v_mul_f32_e32 v3, v10, v3
	v_fma_f64 v[4:5], v[4:5], s[58:59], -v[8:9]
	v_mul_f32_e32 v3, 0x3fb8aa3b, v3
	v_cvt_f32_f64_e32 v4, v[4:5]
	v_exp_f32_e32 v3, v3
	v_cos_f32_e32 v5, v4
	v_sin_f32_e32 v10, v4
	ds_read2st64_b32 v[8:9], v2 offset1:1
	v_mul_f32_e32 v4, v3, v5
	v_mul_f32_e32 v3, v3, v10
	v_mul_f32_e32 v5, 0, v3
	v_fma_f32 v10, v4, 0, -v5
	v_fmac_f32_e32 v5, 0, v4
	s_waitcnt lgkmcnt(0)
	v_add_f32_e32 v10, v8, v10
	v_cvt_pk_bf16_f32 v8, v10, v10
	v_add_f32_e32 v5, v9, v5
	global_store_short v[0:1], v8, off offset:2304
	v_cvt_pk_bf16_f32 v12, v5, v5
	ds_read2st64_b32 v[8:9], v2 offset0:2 offset1:3
	v_mul_f32_e32 v11, v3, v5
	v_mul_f32_e32 v13, v3, v10
	v_fma_f32 v10, v4, v10, -v11
	v_fmac_f32_e32 v13, v4, v5
	global_store_short v[0:1], v12, off offset:2432
	s_waitcnt lgkmcnt(0)
	v_add_f32_e32 v5, v8, v10
	v_cvt_pk_bf16_f32 v8, v5, v5
	v_add_f32_e32 v10, v9, v13
	global_store_short v[6:7], v8, off offset:512
	v_cvt_pk_bf16_f32 v12, v10, v10
	ds_read2st64_b32 v[8:9], v2 offset0:4 offset1:5
	v_mul_f32_e32 v11, v3, v10
	v_mul_f32_e32 v13, v3, v5
	v_fma_f32 v5, v4, v5, -v11
	v_fmac_f32_e32 v13, v4, v10
	global_store_short v[6:7], v12, off offset:640
	s_waitcnt lgkmcnt(0)
	v_add_f32_e32 v5, v5, v8
	v_cvt_pk_bf16_f32 v8, v5, v5
	v_add_f32_e32 v10, v13, v9
	global_store_short v[6:7], v8, off offset:2816
	v_cvt_pk_bf16_f32 v12, v10, v10
	ds_read2st64_b32 v[8:9], v2 offset0:6 offset1:7
	v_mul_f32_e32 v11, v3, v10
	v_mul_f32_e32 v10, v4, v10
	v_fma_f32 v11, v4, v5, -v11
	global_store_short v[6:7], v12, off offset:2944
	v_add_co_u32_e32 v6, vcc, s83, v0
	v_fmac_f32_e32 v10, v3, v5
	s_waitcnt lgkmcnt(0)
	v_add_f32_e32 v5, v11, v8
	v_cvt_pk_bf16_f32 v8, v5, v5
	v_addc_co_u32_e32 v7, vcc, 0, v1, vcc
	v_add_f32_e32 v10, v10, v9
	global_store_short v[6:7], v8, off offset:1024
	v_cvt_pk_bf16_f32 v11, v10, v10
	ds_read2st64_b32 v[8:9], v2 offset0:8 offset1:9
	global_store_short v[6:7], v11, off offset:1152
	v_mul_f32_e32 v11, v3, v10
	v_fma_f32 v11, v4, v5, -v11
	s_waitcnt lgkmcnt(0)
	v_add_f32_e32 v11, v11, v8
	v_mul_f32_e32 v8, v4, v10
	v_fmac_f32_e32 v8, v3, v5
	v_add_f32_e32 v5, v8, v9
	v_cvt_pk_bf16_f32 v8, v11, v11
	global_store_short v[6:7], v8, off offset:3328
	v_cvt_pk_bf16_f32 v10, v5, v5
	ds_read2st64_b32 v[8:9], v2 offset0:10 offset1:11
	global_store_short v[6:7], v10, off offset:3456
	v_mul_f32_e32 v6, v3, v5
	v_fma_f32 v6, v4, v11, -v6
	v_mul_f32_e32 v5, v4, v5
	s_waitcnt lgkmcnt(0)
	v_add_f32_e32 v10, v6, v8
	v_add_co_u32_e32 v6, vcc, s0, v0
	v_fmac_f32_e32 v5, v3, v11
	v_cvt_pk_bf16_f32 v8, v10, v10
	s_nop 0
	v_addc_co_u32_e32 v7, vcc, 0, v1, vcc
	v_add_f32_e32 v5, v5, v9
	global_store_short v[6:7], v8, off offset:1536
	v_cvt_pk_bf16_f32 v11, v5, v5
	ds_read2st64_b32 v[8:9], v2 offset0:12 offset1:13
	global_store_short v[6:7], v11, off offset:1664
	v_mul_f32_e32 v11, v3, v5
	v_fma_f32 v11, v4, v10, -v11
	v_mul_f32_e32 v5, v4, v5
	s_waitcnt lgkmcnt(0)
	v_add_f32_e32 v11, v11, v8
	v_fmac_f32_e32 v5, v3, v10
	v_cvt_pk_bf16_f32 v8, v11, v11
	v_add_f32_e32 v5, v5, v9
	global_store_short v[6:7], v8, off offset:3840
	v_cvt_pk_bf16_f32 v10, v5, v5
	ds_read2st64_b32 v[8:9], v2 offset0:14 offset1:15
	global_store_short v[6:7], v10, off offset:3968
	v_mul_f32_e32 v6, v3, v5
	v_fma_f32 v6, v4, v11, -v6
	v_mul_f32_e32 v5, v4, v5
	s_waitcnt lgkmcnt(0)
	v_add_f32_e32 v10, v6, v8
	v_add_co_u32_e32 v6, vcc, s89, v0
	v_fmac_f32_e32 v5, v3, v11
	v_cvt_pk_bf16_f32 v8, v10, v10
	s_nop 0
	v_addc_co_u32_e32 v7, vcc, 0, v1, vcc
	v_add_f32_e32 v5, v5, v9
	global_store_short v[6:7], v8, off offset:2048
	v_cvt_pk_bf16_f32 v11, v5, v5
	ds_read2st64_b32 v[8:9], v2 offset0:16 offset1:17
	global_store_short v[6:7], v11, off offset:2176
	v_mul_f32_e32 v6, v3, v5
	v_fma_f32 v6, v4, v10, -v6
	s_movk_i32 s0, 0x5000
	s_waitcnt lgkmcnt(0)
	v_add_f32_e32 v11, v6, v8
	v_mul_f32_e32 v5, v4, v5
	v_add_co_u32_e32 v6, vcc, s0, v0
	v_fmac_f32_e32 v5, v3, v10
	v_cvt_pk_bf16_f32 v8, v11, v11
	s_nop 0
	v_addc_co_u32_e32 v7, vcc, 0, v1, vcc
	v_add_f32_e32 v5, v5, v9
	global_store_short v[6:7], v8, off offset:256
	v_cvt_pk_bf16_f32 v10, v5, v5
	ds_read2st64_b32 v[8:9], v2 offset0:18 offset1:19
	global_store_short v[6:7], v10, off offset:384
	v_mul_f32_e32 v10, v3, v5
	v_fma_f32 v10, v4, v11, -v10
	v_mul_f32_e32 v5, v4, v5
	s_waitcnt lgkmcnt(0)
	v_add_f32_e32 v10, v10, v8
	v_fmac_f32_e32 v5, v3, v11
	v_cvt_pk_bf16_f32 v8, v10, v10
	v_add_f32_e32 v5, v5, v9
	global_store_short v[6:7], v8, off offset:2560
	v_cvt_pk_bf16_f32 v11, v5, v5
	ds_read2st64_b32 v[8:9], v2 offset0:20 offset1:21
	global_store_short v[6:7], v11, off offset:2688
	v_mul_f32_e32 v6, v3, v5
	v_fma_f32 v6, v4, v10, -v6
	v_mul_f32_e32 v5, v4, v5
	s_waitcnt lgkmcnt(0)
	v_add_f32_e32 v11, v6, v8
	v_add_co_u32_e32 v6, vcc, s60, v0
	v_fmac_f32_e32 v5, v3, v10
	v_cvt_pk_bf16_f32 v8, v11, v11
	s_nop 0
	v_addc_co_u32_e32 v7, vcc, 0, v1, vcc
	v_add_f32_e32 v5, v5, v9
	global_store_short v[6:7], v8, off offset:768
	v_cvt_pk_bf16_f32 v10, v5, v5
	ds_read2st64_b32 v[8:9], v2 offset0:22 offset1:23
	global_store_short v[6:7], v10, off offset:896
	v_mul_f32_e32 v10, v3, v5
	v_fma_f32 v10, v4, v11, -v10
	v_mul_f32_e32 v5, v4, v5
	s_waitcnt lgkmcnt(0)
	v_add_f32_e32 v10, v10, v8
	v_fmac_f32_e32 v5, v3, v11
	v_cvt_pk_bf16_f32 v8, v10, v10
	v_add_f32_e32 v5, v5, v9
	global_store_short v[6:7], v8, off offset:3072
	v_cvt_pk_bf16_f32 v11, v5, v5
	ds_read2st64_b32 v[8:9], v2 offset0:24 offset1:25
	global_store_short v[6:7], v11, off offset:3200
	v_mul_f32_e32 v6, v3, v5
	v_fma_f32 v6, v4, v10, -v6
	s_movk_i32 s0, 0x7000
	s_waitcnt lgkmcnt(0)
	v_add_f32_e32 v11, v6, v8
	v_mul_f32_e32 v5, v4, v5
	v_add_co_u32_e32 v6, vcc, s0, v0
	v_fmac_f32_e32 v5, v3, v10
	v_cvt_pk_bf16_f32 v8, v11, v11
	s_nop 0
	v_addc_co_u32_e32 v7, vcc, 0, v1, vcc
	v_add_f32_e32 v5, v5, v9
	global_store_short v[6:7], v8, off offset:1280
	v_cvt_pk_bf16_f32 v10, v5, v5
	ds_read2st64_b32 v[8:9], v2 offset0:26 offset1:27
	global_store_short v[6:7], v10, off offset:1408
	v_mul_f32_e32 v10, v3, v5
	v_fma_f32 v10, v4, v11, -v10
	v_mul_f32_e32 v5, v4, v5
	s_waitcnt lgkmcnt(0)
	v_add_f32_e32 v10, v10, v8
	v_fmac_f32_e32 v5, v3, v11
	v_cvt_pk_bf16_f32 v8, v10, v10
	v_add_f32_e32 v5, v5, v9
	global_store_short v[6:7], v8, off offset:3584
	v_cvt_pk_bf16_f32 v11, v5, v5
	ds_read2st64_b32 v[8:9], v2 offset0:28 offset1:29
	global_store_short v[6:7], v11, off offset:3712
	v_mul_f32_e32 v6, v3, v5
	v_fma_f32 v6, v4, v10, -v6
	s_mov_b32 s0, 0x8000
	s_waitcnt lgkmcnt(0)
	v_add_f32_e32 v11, v6, v8
	v_mul_f32_e32 v5, v4, v5
	v_add_co_u32_e32 v6, vcc, s0, v0
	v_fmac_f32_e32 v5, v3, v10
	v_cvt_pk_bf16_f32 v8, v11, v11
	s_nop 0
	v_addc_co_u32_e32 v7, vcc, 0, v1, vcc
	v_add_f32_e32 v5, v5, v9
	global_store_short v[6:7], v8, off offset:1792
	v_cvt_pk_bf16_f32 v10, v5, v5
	ds_read2st64_b32 v[8:9], v2 offset0:30 offset1:31
	global_store_short v[6:7], v10, off offset:1920
	v_mul_f32_e32 v6, v3, v5
	v_fma_f32 v6, v4, v11, -v6
	s_mov_b32 s0, 0x9000
	s_waitcnt lgkmcnt(0)
	v_add_f32_e32 v10, v6, v8
	v_mul_f32_e32 v5, v4, v5
	v_add_co_u32_e32 v6, vcc, s0, v0
	v_fmac_f32_e32 v5, v3, v11
	v_cvt_pk_bf16_f32 v8, v10, v10
	s_nop 0
	v_addc_co_u32_e32 v7, vcc, 0, v1, vcc
	v_add_f32_e32 v5, v5, v9
	global_store_short v[6:7], v8, off
	v_cvt_pk_bf16_f32 v11, v5, v5
	ds_read2st64_b32 v[8:9], v2 offset0:32 offset1:33
	global_store_short v[6:7], v11, off offset:128
	v_mul_f32_e32 v11, v3, v5
	v_fma_f32 v11, v4, v10, -v11
	v_mul_f32_e32 v5, v4, v5
	s_waitcnt lgkmcnt(0)
	v_add_f32_e32 v11, v11, v8
	v_fmac_f32_e32 v5, v3, v10
	v_cvt_pk_bf16_f32 v8, v11, v11
	v_add_f32_e32 v5, v5, v9
	global_store_short v[6:7], v8, off offset:2304
	v_cvt_pk_bf16_f32 v10, v5, v5
	ds_read2st64_b32 v[8:9], v2 offset0:34 offset1:35
	global_store_short v[6:7], v10, off offset:2432
	v_mul_f32_e32 v6, v3, v5
	v_fma_f32 v6, v4, v11, -v6
	s_mov_b32 s0, 0xa000
	s_waitcnt lgkmcnt(0)
	v_add_f32_e32 v10, v6, v8
	v_mul_f32_e32 v5, v4, v5
	v_add_co_u32_e32 v6, vcc, s0, v0
	v_fmac_f32_e32 v5, v3, v11
	v_cvt_pk_bf16_f32 v8, v10, v10
	s_nop 0
	v_addc_co_u32_e32 v7, vcc, 0, v1, vcc
	v_add_f32_e32 v5, v5, v9
	global_store_short v[6:7], v8, off offset:512
	v_cvt_pk_bf16_f32 v11, v5, v5
	ds_read2st64_b32 v[8:9], v2 offset0:36 offset1:37
	global_store_short v[6:7], v11, off offset:640
	v_mul_f32_e32 v11, v3, v5
	v_fma_f32 v11, v4, v10, -v11
	v_mul_f32_e32 v5, v4, v5
	s_waitcnt lgkmcnt(0)
	v_add_f32_e32 v11, v11, v8
	v_fmac_f32_e32 v5, v3, v10
	v_cvt_pk_bf16_f32 v8, v11, v11
	v_add_f32_e32 v5, v5, v9
	global_store_short v[6:7], v8, off offset:2816
	v_cvt_pk_bf16_f32 v10, v5, v5
	ds_read2st64_b32 v[8:9], v2 offset0:38 offset1:39
	global_store_short v[6:7], v10, off offset:2944
	v_mul_f32_e32 v6, v3, v5
	v_fma_f32 v6, v4, v11, -v6
	s_mov_b32 s0, 0xb000
	s_waitcnt lgkmcnt(0)
	v_add_f32_e32 v10, v6, v8
	v_mul_f32_e32 v5, v4, v5
	v_add_co_u32_e32 v6, vcc, s0, v0
	v_fmac_f32_e32 v5, v3, v11
	v_cvt_pk_bf16_f32 v8, v10, v10
	s_nop 0
	v_addc_co_u32_e32 v7, vcc, 0, v1, vcc
	v_add_f32_e32 v5, v5, v9
	global_store_short v[6:7], v8, off offset:1024
	v_cvt_pk_bf16_f32 v11, v5, v5
	ds_read2st64_b32 v[8:9], v2 offset0:40 offset1:41
	global_store_short v[6:7], v11, off offset:1152
	v_mul_f32_e32 v11, v3, v5
	v_fma_f32 v11, v4, v10, -v11
	v_mul_f32_e32 v5, v4, v5
	s_waitcnt lgkmcnt(0)
	v_add_f32_e32 v11, v11, v8
	v_fmac_f32_e32 v5, v3, v10
	v_cvt_pk_bf16_f32 v8, v11, v11
	v_add_f32_e32 v5, v5, v9
	global_store_short v[6:7], v8, off offset:3328
	v_cvt_pk_bf16_f32 v10, v5, v5
	ds_read2st64_b32 v[8:9], v2 offset0:42 offset1:43
	global_store_short v[6:7], v10, off offset:3456
	v_mul_f32_e32 v6, v3, v5
	v_fma_f32 v6, v4, v11, -v6
	s_mov_b32 s0, 0xc000
	s_waitcnt lgkmcnt(0)
	v_add_f32_e32 v10, v6, v8
	v_mul_f32_e32 v5, v4, v5
	v_add_co_u32_e32 v6, vcc, s0, v0
	v_fmac_f32_e32 v5, v3, v11
	v_cvt_pk_bf16_f32 v8, v10, v10
	s_nop 0
	v_addc_co_u32_e32 v7, vcc, 0, v1, vcc
	v_add_f32_e32 v5, v5, v9
	global_store_short v[6:7], v8, off offset:1536
	v_cvt_pk_bf16_f32 v11, v5, v5
	ds_read2st64_b32 v[8:9], v2 offset0:44 offset1:45
	global_store_short v[6:7], v11, off offset:1664
	v_mul_f32_e32 v11, v3, v5
	v_fma_f32 v11, v4, v10, -v11
	v_mul_f32_e32 v5, v4, v5
	s_waitcnt lgkmcnt(0)
	v_add_f32_e32 v11, v11, v8
	v_fmac_f32_e32 v5, v3, v10
	v_cvt_pk_bf16_f32 v8, v11, v11
	v_add_f32_e32 v5, v5, v9
	global_store_short v[6:7], v8, off offset:3840
	v_cvt_pk_bf16_f32 v10, v5, v5
	ds_read2st64_b32 v[8:9], v2 offset0:46 offset1:47
	global_store_short v[6:7], v10, off offset:3968
	v_mul_f32_e32 v6, v3, v5
	v_fma_f32 v6, v4, v11, -v6
	s_mov_b32 s0, 0xd000
	s_waitcnt lgkmcnt(0)
	v_add_f32_e32 v10, v6, v8
	v_mul_f32_e32 v5, v4, v5
	v_add_co_u32_e32 v6, vcc, s0, v0
	v_fmac_f32_e32 v5, v3, v11
	v_cvt_pk_bf16_f32 v8, v10, v10
	s_nop 0
	v_addc_co_u32_e32 v7, vcc, 0, v1, vcc
	v_add_f32_e32 v5, v5, v9
	global_store_short v[6:7], v8, off offset:2048
	v_cvt_pk_bf16_f32 v11, v5, v5
	ds_read2st64_b32 v[8:9], v2 offset0:48 offset1:49
	global_store_short v[6:7], v11, off offset:2176
	v_mul_f32_e32 v6, v3, v5
	v_fma_f32 v6, v4, v10, -v6
	s_mov_b32 s0, 0xe000
	s_waitcnt lgkmcnt(0)
	v_add_f32_e32 v11, v6, v8
	v_mul_f32_e32 v5, v4, v5
	v_add_co_u32_e32 v6, vcc, s0, v0
	v_fmac_f32_e32 v5, v3, v10
	v_cvt_pk_bf16_f32 v8, v11, v11
	s_nop 0
	v_addc_co_u32_e32 v7, vcc, 0, v1, vcc
	v_add_f32_e32 v5, v5, v9
	global_store_short v[6:7], v8, off offset:256
	v_cvt_pk_bf16_f32 v10, v5, v5
	ds_read2st64_b32 v[8:9], v2 offset0:50 offset1:51
	global_store_short v[6:7], v10, off offset:384
	v_mul_f32_e32 v10, v3, v5
	v_fma_f32 v10, v4, v11, -v10
	v_mul_f32_e32 v5, v4, v5
	s_waitcnt lgkmcnt(0)
	v_add_f32_e32 v10, v10, v8
	v_fmac_f32_e32 v5, v3, v11
	v_cvt_pk_bf16_f32 v8, v10, v10
	v_add_f32_e32 v5, v5, v9
	global_store_short v[6:7], v8, off offset:2560
	v_cvt_pk_bf16_f32 v11, v5, v5
	ds_read2st64_b32 v[8:9], v2 offset0:52 offset1:53
	global_store_short v[6:7], v11, off offset:2688
	v_mul_f32_e32 v6, v3, v5
	v_fma_f32 v6, v4, v10, -v6
	s_mov_b32 s0, 0xf000
	s_waitcnt lgkmcnt(0)
	v_add_f32_e32 v11, v6, v8
	v_mul_f32_e32 v5, v4, v5
	v_add_co_u32_e32 v6, vcc, s0, v0
	v_fmac_f32_e32 v5, v3, v10
	v_cvt_pk_bf16_f32 v8, v11, v11
	s_nop 0
	v_addc_co_u32_e32 v7, vcc, 0, v1, vcc
	v_add_f32_e32 v5, v5, v9
	global_store_short v[6:7], v8, off offset:768
	v_cvt_pk_bf16_f32 v10, v5, v5
	ds_read2st64_b32 v[8:9], v2 offset0:54 offset1:55
	global_store_short v[6:7], v10, off offset:896
	v_mul_f32_e32 v10, v3, v5
	v_fma_f32 v10, v4, v11, -v10
	v_mul_f32_e32 v5, v4, v5
	s_waitcnt lgkmcnt(0)
	v_add_f32_e32 v10, v10, v8
	v_fmac_f32_e32 v5, v3, v11
	v_cvt_pk_bf16_f32 v8, v10, v10
	v_add_f32_e32 v5, v5, v9
	global_store_short v[6:7], v8, off offset:3072
	v_cvt_pk_bf16_f32 v11, v5, v5
	ds_read2st64_b32 v[8:9], v2 offset0:56 offset1:57
	global_store_short v[6:7], v11, off offset:3200
	v_mul_f32_e32 v6, v3, v5
	v_fma_f32 v6, v4, v10, -v6
	v_mul_f32_e32 v5, v4, v5
	s_waitcnt lgkmcnt(0)
	v_add_f32_e32 v11, v6, v8
	v_add_co_u32_e32 v6, vcc, s46, v0
	v_fmac_f32_e32 v5, v3, v10
	v_cvt_pk_bf16_f32 v8, v11, v11
	s_nop 0
	v_addc_co_u32_e32 v7, vcc, 0, v1, vcc
	v_add_f32_e32 v5, v5, v9
	global_store_short v[6:7], v8, off offset:1280
	v_cvt_pk_bf16_f32 v10, v5, v5
	ds_read2st64_b32 v[8:9], v2 offset0:58 offset1:59
	global_store_short v[6:7], v10, off offset:1408
	v_mul_f32_e32 v10, v3, v5
	v_fma_f32 v10, v4, v11, -v10
	v_mul_f32_e32 v5, v4, v5
	s_waitcnt lgkmcnt(0)
	v_add_f32_e32 v10, v10, v8
	v_fmac_f32_e32 v5, v3, v11
	v_cvt_pk_bf16_f32 v8, v10, v10
	v_add_f32_e32 v5, v5, v9
	global_store_short v[6:7], v8, off offset:3584
	v_cvt_pk_bf16_f32 v11, v5, v5
	ds_read2st64_b32 v[8:9], v2 offset0:60 offset1:61
	v_mul_f32_e32 v2, v3, v5
	v_fma_f32 v2, v4, v10, -v2
	v_mul_f32_e32 v4, v4, v5
	v_add_co_u32_e32 v0, vcc, 0x11000, v0
	s_waitcnt lgkmcnt(0)
	v_add_f32_e32 v2, v2, v8
	global_store_short v[6:7], v11, off offset:3712
	v_fmac_f32_e32 v4, v3, v10
	v_cvt_pk_bf16_f32 v2, v2, v2
	v_addc_co_u32_e32 v1, vcc, 0, v1, vcc
	v_add_f32_e32 v3, v4, v9
	global_store_short v[0:1], v2, off offset:1792
	v_cvt_pk_bf16_f32 v2, v3, v3
	global_store_short v[0:1], v2, off offset:1920

.LBB0_340:
	v_cvt_pk_bf16_f32 v144, v176, v177
	v_mov_b32_e32 v173, v172
	v_cvt_pk_bf16_f32 v145, v178, v179
	v_cvt_pk_bf16_f32 v146, v180, v181
	v_cvt_pk_bf16_f32 v147, v174, v175
	global_store_dwordx4 v[182:183], v[144:147], off
	v_pk_mul_f32 v[136:137], v[136:137], v[172:173]
	v_pk_mul_f32 v[138:139], v[138:139], v[172:173]
	v_cndmask_b32_e64 v144, 0, 1, s[36:37]
	v_pk_mul_f32 v[132:133], v[132:133], v[172:173]
	v_pk_mul_f32 v[134:135], v[134:135], v[172:173]
	v_cmp_ne_u32_e64 s[6:7], 1, v144
	s_andn2_b64 vcc, exec, s[36:37]
	s_mov_b64 s[36:37], -1
	s_mov_b32 s46, 0x10000
	s_cbranch_vccnz .LBB0_346
	v_pk_mul_f32 v[146:147], v[138:139], v[138:139]
	v_pk_mul_f32 v[144:145], v[136:137], v[136:137]
	v_pk_fma_f32 v[146:147], v[146:147], s[64:65], 1.0 op_sel_hi:[1,0,0]
	v_pk_mul_f32 v[150:151], v[134:135], v[134:135]
	v_pk_mul_f32 v[146:147], v[138:139], v[146:147]
	v_pk_fma_f32 v[144:145], v[144:145], s[64:65], 1.0 op_sel_hi:[1,0,0]
	v_pk_mul_f32 v[146:147], v[146:147], s[66:67] op_sel_hi:[1,0]
	v_pk_fma_f32 v[150:151], v[150:151], s[64:65], 1.0 op_sel_hi:[1,0,0]
	v_pk_mul_f32 v[146:147], v[146:147], s[68:69] op_sel_hi:[1,0]
	v_pk_mul_f32 v[144:145], v[136:137], v[144:145]
	v_exp_f32_e32 v146, v146
	v_exp_f32_e32 v147, v147
	v_pk_mul_f32 v[150:151], v[134:135], v[150:151]
	v_pk_mul_f32 v[144:145], v[144:145], s[66:67] op_sel_hi:[1,0]
	v_pk_mul_f32 v[150:151], v[150:151], s[66:67] op_sel_hi:[1,0]
	v_pk_add_f32 v[146:147], v[146:147], 1.0 op_sel_hi:[1,0]
	v_pk_mul_f32 v[144:145], v[144:145], s[68:69] op_sel_hi:[1,0]
	v_rcp_f32_e32 v148, v146
	v_rcp_f32_e32 v149, v147
	v_pk_mul_f32 v[146:147], v[132:133], v[132:133]
	v_pk_mul_f32 v[150:151], v[150:151], s[68:69] op_sel_hi:[1,0]
	v_pk_fma_f32 v[146:147], v[146:147], s[64:65], 1.0 op_sel_hi:[1,0,0]
	v_exp_f32_e32 v144, v144
	v_pk_mul_f32 v[146:147], v[132:133], v[146:147]
	v_exp_f32_e32 v145, v145
	v_pk_mul_f32 v[146:147], v[146:147], s[66:67] op_sel_hi:[1,0]
	v_exp_f32_e32 v150, v150
	v_pk_mul_f32 v[146:147], v[146:147], s[68:69] op_sel_hi:[1,0]
	v_exp_f32_e32 v151, v151
	v_exp_f32_e32 v146, v146
	v_exp_f32_e32 v147, v147
	v_pk_add_f32 v[144:145], v[144:145], 1.0 op_sel_hi:[1,0]
	v_pk_mul_f32 v[148:149], v[138:139], v[148:149]
	v_rcp_f32_e32 v144, v144
	v_pk_add_f32 v[146:147], v[146:147], 1.0 op_sel_hi:[1,0]
	v_rcp_f32_e32 v145, v145
	v_rcp_f32_e32 v172, v146
	v_rcp_f32_e32 v173, v147
	v_pk_add_f32 v[146:147], v[150:151], 1.0 op_sel_hi:[1,0]
	s_cmp_lt_u32 s22, 4
	v_rcp_f32_e32 v174, v146
	v_rcp_f32_e32 v175, v147
	v_pk_mul_f32 v[146:147], v[136:137], v[144:145]
	v_pk_mul_f32 v[150:151], v[132:133], v[172:173]
	v_pk_mul_f32 v[144:145], v[134:135], v[174:175]
	s_cbranch_scc1 .LBB0_343
	v_lshl_add_u64 v[172:173], s[20:21], 0, v[170:171]
	s_movk_i32 s0, 0xf900
	v_lshl_add_u64 v[172:173], v[188:189], 1, v[172:173]
	s_mov_b32 s1, -1
	v_lshl_add_u64 v[172:173], v[172:173], 0, s[0:1]
	s_mov_b64 s[36:37], 0

.LBB0_348:
	v_add_f32_e32 v132, v152, v153
	v_add_f32_e32 v133, v154, v155
	v_add_f32_e32 v132, v132, v133
	v_fmamk_f32 v132, v132, 0x3a800000, v229
	v_rsq_f32_e32 v134, v132
	v_cvt_pk_bf16_f32 v136, v146, v147
	v_cvt_pk_bf16_f32 v137, v148, v149
	v_cvt_pk_bf16_f32 v138, v150, v151
	v_cvt_pk_bf16_f32 v139, v144, v145
	v_or_b32_e32 v144, 16, v168
	v_ashrrev_i32_e32 v145, 31, v144
	global_store_dwordx4 v[172:173], v[136:139], off
	v_lshlrev_b64 v[132:133], 10, v[144:145]
	v_pk_mul_f32 v[128:129], v[128:129], v[134:135] op_sel_hi:[1,0]
	v_pk_mul_f32 v[136:137], v[130:131], v[134:135] op_sel_hi:[1,0]
	v_pk_mul_f32 v[130:131], v[124:125], v[134:135] op_sel_hi:[1,0]
	v_pk_mul_f32 v[138:139], v[126:127], v[134:135] op_sel_hi:[1,0]
	s_and_b64 vcc, exec, s[6:7]
	s_mov_b64 s[36:37], -1
	s_cbranch_vccnz .LBB0_354
	v_pk_mul_f32 v[124:125], v[128:129], v[128:129]
	v_pk_mul_f32 v[126:127], v[136:137], v[136:137]
	v_pk_mul_f32 v[146:147], v[130:131], v[130:131]
	v_pk_mul_f32 v[148:149], v[138:139], v[138:139]
	v_pk_fma_f32 v[124:125], v[124:125], s[64:65], 1.0 op_sel_hi:[1,0,0]
	v_pk_fma_f32 v[126:127], v[126:127], s[64:65], 1.0 op_sel_hi:[1,0,0]
	v_pk_fma_f32 v[146:147], v[146:147], s[64:65], 1.0 op_sel_hi:[1,0,0]
	v_pk_fma_f32 v[148:149], v[148:149], s[64:65], 1.0 op_sel_hi:[1,0,0]
	v_pk_mul_f32 v[124:125], v[128:129], v[124:125]
	v_pk_mul_f32 v[126:127], v[136:137], v[126:127]
	v_pk_mul_f32 v[146:147], v[130:131], v[146:147]
	v_pk_mul_f32 v[148:149], v[138:139], v[148:149]
	v_pk_mul_f32 v[124:125], v[124:125], s[66:67] op_sel_hi:[1,0]
	v_pk_mul_f32 v[126:127], v[126:127], s[66:67] op_sel_hi:[1,0]
	v_pk_mul_f32 v[146:147], v[146:147], s[66:67] op_sel_hi:[1,0]
	v_pk_mul_f32 v[148:149], v[148:149], s[66:67] op_sel_hi:[1,0]
	v_pk_mul_f32 v[124:125], v[124:125], s[68:69] op_sel_hi:[1,0]
	v_pk_mul_f32 v[126:127], v[126:127], s[68:69] op_sel_hi:[1,0]
	v_pk_mul_f32 v[146:147], v[146:147], s[68:69] op_sel_hi:[1,0]
	v_pk_mul_f32 v[148:149], v[148:149], s[68:69] op_sel_hi:[1,0]
	v_exp_f32_e32 v124, v124
	v_exp_f32_e32 v125, v125
	v_exp_f32_e32 v126, v126
	v_exp_f32_e32 v127, v127
	v_exp_f32_e32 v146, v146
	v_exp_f32_e32 v147, v147
	v_exp_f32_e32 v148, v148
	v_exp_f32_e32 v149, v149
	v_pk_add_f32 v[124:125], v[124:125], 1.0 op_sel_hi:[1,0]
	v_pk_add_f32 v[126:127], v[126:127], 1.0 op_sel_hi:[1,0]
	v_pk_add_f32 v[146:147], v[146:147], 1.0 op_sel_hi:[1,0]
	v_pk_add_f32 v[148:149], v[148:149], 1.0 op_sel_hi:[1,0]
	v_rcp_f32_e32 v124, v124
	v_rcp_f32_e32 v125, v125
	v_rcp_f32_e32 v126, v126
	v_rcp_f32_e32 v127, v127
	v_rcp_f32_e32 v146, v146
	v_rcp_f32_e32 v147, v147
	v_rcp_f32_e32 v154, v148
	v_rcp_f32_e32 v155, v149
	v_pk_mul_f32 v[148:149], v[128:129], v[124:125]
	v_pk_mul_f32 v[150:151], v[136:137], v[126:127]
	v_pk_mul_f32 v[152:153], v[130:131], v[146:147]
	v_pk_mul_f32 v[146:147], v[138:139], v[154:155]
	s_cmp_lt_u32 s22, 4
	s_cbranch_scc1 .LBB0_351
	v_lshl_add_u64 v[124:125], s[20:21], 0, v[132:133]
	s_movk_i32 s0, 0xf800
	v_lshl_add_u64 v[124:125], v[188:189], 1, v[124:125]
	s_mov_b32 s1, -1
	v_lshl_add_u64 v[154:155], v[124:125], 0, s[0:1]
	s_mov_b64 s[36:37], 0

.LBB0_356:
	v_mov_b32_e32 v135, v134
	v_cvt_pk_bf16_f32 v128, v148, v149
	v_cvt_pk_bf16_f32 v129, v150, v151
	v_cvt_pk_bf16_f32 v130, v152, v153
	v_cvt_pk_bf16_f32 v131, v146, v147
	v_pk_mul_f32 v[116:117], v[116:117], v[134:135]
	v_pk_mul_f32 v[118:119], v[118:119], v[134:135]
	v_pk_mul_f32 v[112:113], v[112:113], v[134:135]
	v_pk_mul_f32 v[114:115], v[114:115], v[134:135]
	s_and_b64 vcc, exec, s[6:7]
	s_mov_b64 s[36:37], -1
	global_store_dwordx4 v[154:155], v[128:131], off
	s_cbranch_vccnz .LBB0_362
	s_nop 0
	v_pk_mul_f32 v[130:131], v[118:119], v[118:119]
	v_pk_mul_f32 v[128:129], v[116:117], v[116:117]
	v_pk_fma_f32 v[130:131], v[130:131], s[64:65], 1.0 op_sel_hi:[1,0,0]
	v_pk_mul_f32 v[136:137], v[114:115], v[114:115]
	v_pk_mul_f32 v[130:131], v[118:119], v[130:131]
	v_pk_fma_f32 v[128:129], v[128:129], s[64:65], 1.0 op_sel_hi:[1,0,0]
	v_pk_mul_f32 v[130:131], v[130:131], s[66:67] op_sel_hi:[1,0]
	v_pk_fma_f32 v[136:137], v[136:137], s[64:65], 1.0 op_sel_hi:[1,0,0]
	v_pk_mul_f32 v[130:131], v[130:131], s[68:69] op_sel_hi:[1,0]
	v_pk_mul_f32 v[128:129], v[116:117], v[128:129]
	v_exp_f32_e32 v130, v130
	v_exp_f32_e32 v131, v131
	v_pk_mul_f32 v[136:137], v[114:115], v[136:137]
	v_pk_mul_f32 v[128:129], v[128:129], s[66:67] op_sel_hi:[1,0]
	v_pk_mul_f32 v[136:137], v[136:137], s[66:67] op_sel_hi:[1,0]
	v_pk_add_f32 v[130:131], v[130:131], 1.0 op_sel_hi:[1,0]
	v_pk_mul_f32 v[128:129], v[128:129], s[68:69] op_sel_hi:[1,0]
	v_rcp_f32_e32 v134, v130
	v_rcp_f32_e32 v135, v131
	v_pk_mul_f32 v[130:131], v[112:113], v[112:113]
	v_pk_mul_f32 v[136:137], v[136:137], s[68:69] op_sel_hi:[1,0]
	v_pk_fma_f32 v[130:131], v[130:131], s[64:65], 1.0 op_sel_hi:[1,0,0]
	v_exp_f32_e32 v128, v128
	v_pk_mul_f32 v[130:131], v[112:113], v[130:131]
	v_exp_f32_e32 v129, v129
	v_pk_mul_f32 v[130:131], v[130:131], s[66:67] op_sel_hi:[1,0]
	v_exp_f32_e32 v136, v136
	v_pk_mul_f32 v[130:131], v[130:131], s[68:69] op_sel_hi:[1,0]
	v_exp_f32_e32 v137, v137
	v_exp_f32_e32 v130, v130
	v_exp_f32_e32 v131, v131
	v_pk_add_f32 v[128:129], v[128:129], 1.0 op_sel_hi:[1,0]
	v_pk_mul_f32 v[134:135], v[118:119], v[134:135]
	v_rcp_f32_e32 v128, v128
	v_pk_add_f32 v[130:131], v[130:131], 1.0 op_sel_hi:[1,0]
	v_rcp_f32_e32 v129, v129
	v_rcp_f32_e32 v138, v130
	v_rcp_f32_e32 v139, v131
	v_pk_add_f32 v[130:131], v[136:137], 1.0 op_sel_hi:[1,0]
	s_cmp_lt_u32 s22, 4
	v_rcp_f32_e32 v144, v130
	v_rcp_f32_e32 v145, v131
	v_pk_mul_f32 v[130:131], v[116:117], v[128:129]
	v_pk_mul_f32 v[136:137], v[112:113], v[138:139]
	v_pk_mul_f32 v[128:129], v[114:115], v[144:145]
	s_cbranch_scc1 .LBB0_359
	v_lshl_add_u64 v[138:139], s[20:21], 0, v[132:133]
	s_movk_i32 s0, 0xf900
	v_lshl_add_u64 v[138:139], v[188:189], 1, v[138:139]
	s_mov_b32 s1, -1
	v_lshl_add_u64 v[138:139], v[138:139], 0, s[0:1]
	s_mov_b64 s[36:37], 0

.LBB0_364:
	s_waitcnt lgkmcnt(0)
	v_add_f32_e32 v112, v140, v141
	v_add_f32_e32 v113, v142, v143
	v_add_f32_e32 v112, v112, v113
	v_fmamk_f32 v112, v112, 0x3a800000, v229
	v_rsq_f32_e32 v114, v112
	v_cvt_pk_bf16_f32 v116, v130, v131
	v_cvt_pk_bf16_f32 v117, v134, v135
	v_cvt_pk_bf16_f32 v118, v136, v137
	v_cvt_pk_bf16_f32 v119, v128, v129
	global_store_dwordx4 v[138:139], v[116:119], off
	v_pk_mul_f32 v[108:109], v[108:109], v[114:115] op_sel_hi:[1,0]
	v_pk_mul_f32 v[106:107], v[106:107], v[114:115] op_sel_hi:[1,0]
	v_or_b32_e32 v118, 32, v168
	v_ashrrev_i32_e32 v119, 31, v118
	v_lshlrev_b64 v[112:113], 10, v[118:119]
	v_pk_mul_f32 v[116:117], v[110:111], v[114:115] op_sel_hi:[1,0]
	v_pk_mul_f32 v[110:111], v[104:105], v[114:115] op_sel_hi:[1,0]
	s_and_b64 vcc, exec, s[6:7]
	s_mov_b64 s[36:37], -1
	s_cbranch_vccnz .LBB0_370
	v_pk_mul_f32 v[128:129], v[110:111], v[110:111]
	v_pk_mul_f32 v[104:105], v[108:109], v[108:109]
	v_pk_mul_f32 v[126:127], v[116:117], v[116:117]
	v_pk_fma_f32 v[128:129], v[128:129], s[64:65], 1.0 op_sel_hi:[1,0,0]
	v_pk_mul_f32 v[130:131], v[106:107], v[106:107]
	v_pk_fma_f32 v[104:105], v[104:105], s[64:65], 1.0 op_sel_hi:[1,0,0]
	v_pk_fma_f32 v[126:127], v[126:127], s[64:65], 1.0 op_sel_hi:[1,0,0]
	v_pk_mul_f32 v[128:129], v[110:111], v[128:129]
	v_pk_fma_f32 v[130:131], v[130:131], s[64:65], 1.0 op_sel_hi:[1,0,0]
	v_pk_mul_f32 v[104:105], v[108:109], v[104:105]
	v_pk_mul_f32 v[126:127], v[116:117], v[126:127]
	v_pk_mul_f32 v[128:129], v[128:129], s[66:67] op_sel_hi:[1,0]
	v_pk_mul_f32 v[130:131], v[106:107], v[130:131]
	v_pk_mul_f32 v[104:105], v[104:105], s[66:67] op_sel_hi:[1,0]
	v_pk_mul_f32 v[126:127], v[126:127], s[66:67] op_sel_hi:[1,0]
	v_pk_mul_f32 v[128:129], v[128:129], s[68:69] op_sel_hi:[1,0]
	v_pk_mul_f32 v[130:131], v[130:131], s[66:67] op_sel_hi:[1,0]
	v_pk_mul_f32 v[104:105], v[104:105], s[68:69] op_sel_hi:[1,0]
	v_pk_mul_f32 v[126:127], v[126:127], s[68:69] op_sel_hi:[1,0]
	v_exp_f32_e32 v128, v128
	v_exp_f32_e32 v129, v129
	v_pk_mul_f32 v[130:131], v[130:131], s[68:69] op_sel_hi:[1,0]
	v_exp_f32_e32 v104, v104
	v_exp_f32_e32 v105, v105
	v_exp_f32_e32 v126, v126
	v_exp_f32_e32 v127, v127
	v_exp_f32_e32 v130, v130
	v_exp_f32_e32 v131, v131
	v_pk_add_f32 v[128:129], v[128:129], 1.0 op_sel_hi:[1,0]
	v_pk_add_f32 v[104:105], v[104:105], 1.0 op_sel_hi:[1,0]
	v_pk_add_f32 v[126:127], v[126:127], 1.0 op_sel_hi:[1,0]
	v_rcp_f32_e32 v132, v128
	v_rcp_f32_e32 v133, v129
	v_pk_add_f32 v[128:129], v[130:131], 1.0 op_sel_hi:[1,0]
	v_rcp_f32_e32 v104, v104
	v_rcp_f32_e32 v105, v105
	v_rcp_f32_e32 v126, v126
	v_rcp_f32_e32 v127, v127
	v_rcp_f32_e32 v134, v128
	v_rcp_f32_e32 v135, v129
	v_pk_mul_f32 v[128:129], v[108:109], v[104:105]
	v_pk_mul_f32 v[130:131], v[116:117], v[126:127]
	v_pk_mul_f32 v[132:133], v[110:111], v[132:133]
	v_pk_mul_f32 v[126:127], v[106:107], v[134:135]
	s_cmp_lt_u32 s22, 4
	s_cbranch_scc1 .LBB0_367
	v_lshl_add_u64 v[104:105], s[20:21], 0, v[112:113]
	s_movk_i32 s0, 0xf800
	v_lshl_add_u64 v[104:105], v[188:189], 1, v[104:105]
	s_mov_b32 s1, -1
	v_lshl_add_u64 v[134:135], v[104:105], 0, s[0:1]
	s_mov_b64 s[36:37], 0

.LBB0_372:
	v_mov_b32_e32 v115, v114
	v_cvt_pk_bf16_f32 v106, v128, v129
	v_cvt_pk_bf16_f32 v107, v130, v131
	v_cvt_pk_bf16_f32 v108, v132, v133
	v_cvt_pk_bf16_f32 v109, v126, v127
	v_pk_mul_f32 v[96:97], v[96:97], v[114:115]
	v_pk_mul_f32 v[98:99], v[98:99], v[114:115]
	v_pk_mul_f32 v[92:93], v[92:93], v[114:115]
	v_pk_mul_f32 v[94:95], v[94:95], v[114:115]
	s_and_b64 vcc, exec, s[6:7]
	s_mov_b64 s[36:37], -1
	global_store_dwordx4 v[134:135], v[106:109], off
	s_cbranch_vccnz .LBB0_378
	s_nop 0
	v_pk_mul_f32 v[108:109], v[98:99], v[98:99]
	v_pk_mul_f32 v[106:107], v[96:97], v[96:97]
	v_pk_fma_f32 v[108:109], v[108:109], s[64:65], 1.0 op_sel_hi:[1,0,0]
	v_pk_mul_f32 v[114:115], v[94:95], v[94:95]
	v_pk_mul_f32 v[108:109], v[98:99], v[108:109]
	v_pk_fma_f32 v[106:107], v[106:107], s[64:65], 1.0 op_sel_hi:[1,0,0]
	v_pk_mul_f32 v[108:109], v[108:109], s[66:67] op_sel_hi:[1,0]
	v_pk_fma_f32 v[114:115], v[114:115], s[64:65], 1.0 op_sel_hi:[1,0,0]
	v_pk_mul_f32 v[108:109], v[108:109], s[68:69] op_sel_hi:[1,0]
	v_pk_mul_f32 v[106:107], v[96:97], v[106:107]
	v_exp_f32_e32 v108, v108
	v_exp_f32_e32 v109, v109
	v_pk_mul_f32 v[114:115], v[94:95], v[114:115]
	v_pk_mul_f32 v[106:107], v[106:107], s[66:67] op_sel_hi:[1,0]
	v_pk_mul_f32 v[114:115], v[114:115], s[66:67] op_sel_hi:[1,0]
	v_pk_add_f32 v[108:109], v[108:109], 1.0 op_sel_hi:[1,0]
	v_pk_mul_f32 v[106:107], v[106:107], s[68:69] op_sel_hi:[1,0]
	v_rcp_f32_e32 v110, v108
	v_rcp_f32_e32 v111, v109
	v_pk_mul_f32 v[108:109], v[92:93], v[92:93]
	v_pk_mul_f32 v[114:115], v[114:115], s[68:69] op_sel_hi:[1,0]
	v_pk_fma_f32 v[108:109], v[108:109], s[64:65], 1.0 op_sel_hi:[1,0,0]
	v_exp_f32_e32 v106, v106
	v_pk_mul_f32 v[108:109], v[92:93], v[108:109]
	v_exp_f32_e32 v107, v107
	v_pk_mul_f32 v[108:109], v[108:109], s[66:67] op_sel_hi:[1,0]
	v_exp_f32_e32 v114, v114
	v_pk_mul_f32 v[108:109], v[108:109], s[68:69] op_sel_hi:[1,0]
	v_exp_f32_e32 v115, v115
	v_exp_f32_e32 v108, v108
	v_exp_f32_e32 v109, v109
	v_pk_add_f32 v[106:107], v[106:107], 1.0 op_sel_hi:[1,0]
	v_pk_mul_f32 v[110:111], v[98:99], v[110:111]
	v_rcp_f32_e32 v106, v106
	v_pk_add_f32 v[108:109], v[108:109], 1.0 op_sel_hi:[1,0]
	v_rcp_f32_e32 v107, v107
	v_rcp_f32_e32 v116, v108
	v_rcp_f32_e32 v117, v109
	v_pk_add_f32 v[108:109], v[114:115], 1.0 op_sel_hi:[1,0]
	s_cmp_lt_u32 s22, 4
	v_rcp_f32_e32 v118, v108
	v_rcp_f32_e32 v119, v109
	v_pk_mul_f32 v[108:109], v[96:97], v[106:107]
	v_pk_mul_f32 v[114:115], v[92:93], v[116:117]
	v_pk_mul_f32 v[106:107], v[94:95], v[118:119]
	s_cbranch_scc1 .LBB0_375
	v_lshl_add_u64 v[116:117], s[20:21], 0, v[112:113]
	s_movk_i32 s0, 0xf900
	v_lshl_add_u64 v[116:117], v[188:189], 1, v[116:117]
	s_mov_b32 s1, -1
	v_lshl_add_u64 v[116:117], v[116:117], 0, s[0:1]
	s_mov_b64 s[36:37], 0

.LBB0_380:
	v_add_f32_e32 v92, v120, v121
	v_add_f32_e32 v93, v122, v123
	v_add_f32_e32 v92, v92, v93
	v_fmamk_f32 v92, v92, 0x3a800000, v229
	v_rsq_f32_e32 v94, v92
	v_cvt_pk_bf16_f32 v96, v108, v109
	v_cvt_pk_bf16_f32 v97, v110, v111
	v_cvt_pk_bf16_f32 v98, v114, v115
	v_cvt_pk_bf16_f32 v99, v106, v107
	global_store_dwordx4 v[116:117], v[96:99], off
	v_pk_mul_f32 v[88:89], v[88:89], v[94:95] op_sel_hi:[1,0]
	v_pk_mul_f32 v[86:87], v[86:87], v[94:95] op_sel_hi:[1,0]
	v_or_b32_e32 v98, 48, v168
	v_ashrrev_i32_e32 v99, 31, v98
	v_lshlrev_b64 v[92:93], 10, v[98:99]
	v_pk_mul_f32 v[96:97], v[90:91], v[94:95] op_sel_hi:[1,0]
	v_pk_mul_f32 v[90:91], v[84:85], v[94:95] op_sel_hi:[1,0]
	s_and_b64 vcc, exec, s[6:7]
	s_mov_b64 s[36:37], -1
	s_cbranch_vccnz .LBB0_386
	v_pk_mul_f32 v[106:107], v[90:91], v[90:91]
	v_pk_mul_f32 v[84:85], v[88:89], v[88:89]
	v_pk_mul_f32 v[104:105], v[96:97], v[96:97]
	v_pk_fma_f32 v[106:107], v[106:107], s[64:65], 1.0 op_sel_hi:[1,0,0]
	v_pk_mul_f32 v[108:109], v[86:87], v[86:87]
	v_pk_fma_f32 v[84:85], v[84:85], s[64:65], 1.0 op_sel_hi:[1,0,0]
	v_pk_fma_f32 v[104:105], v[104:105], s[64:65], 1.0 op_sel_hi:[1,0,0]
	v_pk_mul_f32 v[106:107], v[90:91], v[106:107]
	v_pk_fma_f32 v[108:109], v[108:109], s[64:65], 1.0 op_sel_hi:[1,0,0]
	v_pk_mul_f32 v[84:85], v[88:89], v[84:85]
	v_pk_mul_f32 v[104:105], v[96:97], v[104:105]
	v_pk_mul_f32 v[106:107], v[106:107], s[66:67] op_sel_hi:[1,0]
	v_pk_mul_f32 v[108:109], v[86:87], v[108:109]
	v_pk_mul_f32 v[84:85], v[84:85], s[66:67] op_sel_hi:[1,0]
	v_pk_mul_f32 v[104:105], v[104:105], s[66:67] op_sel_hi:[1,0]
	v_pk_mul_f32 v[106:107], v[106:107], s[68:69] op_sel_hi:[1,0]
	v_pk_mul_f32 v[108:109], v[108:109], s[66:67] op_sel_hi:[1,0]
	v_pk_mul_f32 v[84:85], v[84:85], s[68:69] op_sel_hi:[1,0]
	v_pk_mul_f32 v[104:105], v[104:105], s[68:69] op_sel_hi:[1,0]
	v_exp_f32_e32 v106, v106
	v_exp_f32_e32 v107, v107
	v_pk_mul_f32 v[108:109], v[108:109], s[68:69] op_sel_hi:[1,0]
	v_exp_f32_e32 v84, v84
	v_exp_f32_e32 v85, v85
	v_exp_f32_e32 v104, v104
	v_exp_f32_e32 v105, v105
	v_exp_f32_e32 v108, v108
	v_exp_f32_e32 v109, v109
	v_pk_add_f32 v[106:107], v[106:107], 1.0 op_sel_hi:[1,0]
	v_pk_add_f32 v[84:85], v[84:85], 1.0 op_sel_hi:[1,0]
	v_pk_add_f32 v[104:105], v[104:105], 1.0 op_sel_hi:[1,0]
	v_rcp_f32_e32 v110, v106
	v_rcp_f32_e32 v111, v107
	v_pk_add_f32 v[106:107], v[108:109], 1.0 op_sel_hi:[1,0]
	v_rcp_f32_e32 v84, v84
	v_rcp_f32_e32 v85, v85
	v_rcp_f32_e32 v104, v104
	v_rcp_f32_e32 v105, v105
	v_rcp_f32_e32 v112, v106
	v_rcp_f32_e32 v113, v107
	v_pk_mul_f32 v[106:107], v[88:89], v[84:85]
	v_pk_mul_f32 v[108:109], v[96:97], v[104:105]
	v_pk_mul_f32 v[110:111], v[90:91], v[110:111]
	v_pk_mul_f32 v[104:105], v[86:87], v[112:113]
	s_cmp_lt_u32 s22, 4
	s_cbranch_scc1 .LBB0_383
	v_lshl_add_u64 v[84:85], s[20:21], 0, v[92:93]
	s_movk_i32 s0, 0xf800
	v_lshl_add_u64 v[84:85], v[188:189], 1, v[84:85]
	s_mov_b32 s1, -1
	v_lshl_add_u64 v[112:113], v[84:85], 0, s[0:1]
	s_mov_b64 s[36:37], 0

.LBB0_388:
	v_mov_b32_e32 v95, v94
	v_cvt_pk_bf16_f32 v86, v106, v107
	v_cvt_pk_bf16_f32 v87, v108, v109
	v_cvt_pk_bf16_f32 v88, v110, v111
	v_cvt_pk_bf16_f32 v89, v104, v105
	v_pk_mul_f32 v[76:77], v[76:77], v[94:95]
	v_pk_mul_f32 v[78:79], v[78:79], v[94:95]
	v_pk_mul_f32 v[72:73], v[72:73], v[94:95]
	v_pk_mul_f32 v[74:75], v[74:75], v[94:95]
	s_and_b64 vcc, exec, s[6:7]
	s_mov_b64 s[36:37], -1
	global_store_dwordx4 v[112:113], v[86:89], off
	s_cbranch_vccnz .LBB0_394
	s_nop 0
	v_pk_mul_f32 v[88:89], v[78:79], v[78:79]
	v_pk_mul_f32 v[86:87], v[76:77], v[76:77]
	v_pk_fma_f32 v[88:89], v[88:89], s[64:65], 1.0 op_sel_hi:[1,0,0]
	v_pk_mul_f32 v[94:95], v[74:75], v[74:75]
	v_pk_mul_f32 v[88:89], v[78:79], v[88:89]
	v_pk_fma_f32 v[86:87], v[86:87], s[64:65], 1.0 op_sel_hi:[1,0,0]
	v_pk_mul_f32 v[88:89], v[88:89], s[66:67] op_sel_hi:[1,0]
	v_pk_fma_f32 v[94:95], v[94:95], s[64:65], 1.0 op_sel_hi:[1,0,0]
	v_pk_mul_f32 v[88:89], v[88:89], s[68:69] op_sel_hi:[1,0]
	v_pk_mul_f32 v[86:87], v[76:77], v[86:87]
	v_exp_f32_e32 v88, v88
	v_exp_f32_e32 v89, v89
	v_pk_mul_f32 v[94:95], v[74:75], v[94:95]
	v_pk_mul_f32 v[86:87], v[86:87], s[66:67] op_sel_hi:[1,0]
	v_pk_mul_f32 v[94:95], v[94:95], s[66:67] op_sel_hi:[1,0]
	v_pk_add_f32 v[88:89], v[88:89], 1.0 op_sel_hi:[1,0]
	v_pk_mul_f32 v[86:87], v[86:87], s[68:69] op_sel_hi:[1,0]
	v_rcp_f32_e32 v90, v88
	v_rcp_f32_e32 v91, v89
	v_pk_mul_f32 v[88:89], v[72:73], v[72:73]
	v_pk_mul_f32 v[94:95], v[94:95], s[68:69] op_sel_hi:[1,0]
	v_pk_fma_f32 v[88:89], v[88:89], s[64:65], 1.0 op_sel_hi:[1,0,0]
	v_exp_f32_e32 v86, v86
	v_pk_mul_f32 v[88:89], v[72:73], v[88:89]
	v_exp_f32_e32 v87, v87
	v_pk_mul_f32 v[88:89], v[88:89], s[66:67] op_sel_hi:[1,0]
	v_exp_f32_e32 v94, v94
	v_pk_mul_f32 v[88:89], v[88:89], s[68:69] op_sel_hi:[1,0]
	v_exp_f32_e32 v95, v95
	v_exp_f32_e32 v88, v88
	v_exp_f32_e32 v89, v89
	v_pk_add_f32 v[86:87], v[86:87], 1.0 op_sel_hi:[1,0]
	v_pk_mul_f32 v[90:91], v[78:79], v[90:91]
	v_rcp_f32_e32 v86, v86
	v_pk_add_f32 v[88:89], v[88:89], 1.0 op_sel_hi:[1,0]
	v_rcp_f32_e32 v87, v87
	v_rcp_f32_e32 v96, v88
	v_rcp_f32_e32 v97, v89
	v_pk_add_f32 v[88:89], v[94:95], 1.0 op_sel_hi:[1,0]
	s_cmp_lt_u32 s22, 4
	v_rcp_f32_e32 v98, v88
	v_rcp_f32_e32 v99, v89
	v_pk_mul_f32 v[88:89], v[76:77], v[86:87]
	v_pk_mul_f32 v[94:95], v[72:73], v[96:97]
	v_pk_mul_f32 v[86:87], v[74:75], v[98:99]
	s_cbranch_scc1 .LBB0_391
	v_lshl_add_u64 v[96:97], s[20:21], 0, v[92:93]
	s_movk_i32 s0, 0xf900
	v_lshl_add_u64 v[96:97], v[188:189], 1, v[96:97]
	s_mov_b32 s1, -1
	v_lshl_add_u64 v[96:97], v[96:97], 0, s[0:1]
	s_mov_b64 s[36:37], 0

.LBB0_396:
	v_add_f32_e32 v72, v100, v101
	v_add_f32_e32 v73, v102, v103
	v_add_f32_e32 v72, v72, v73
	v_fmamk_f32 v72, v72, 0x3a800000, v229
	v_rsq_f32_e32 v74, v72
	v_cvt_pk_bf16_f32 v76, v88, v89
	v_cvt_pk_bf16_f32 v77, v90, v91
	v_cvt_pk_bf16_f32 v78, v94, v95
	v_cvt_pk_bf16_f32 v79, v86, v87
	global_store_dwordx4 v[96:97], v[76:79], off
	s_nop 1
	v_add_u32_e32 v76, 0x80, v168
	v_ashrrev_i32_e32 v77, 31, v76
	v_lshlrev_b64 v[72:73], 10, v[76:77]
	v_pk_mul_f32 v[68:69], v[68:69], v[74:75] op_sel_hi:[1,0]
	v_pk_mul_f32 v[70:71], v[70:71], v[74:75] op_sel_hi:[1,0]
	v_pk_mul_f32 v[64:65], v[64:65], v[74:75] op_sel_hi:[1,0]
	v_pk_mul_f32 v[66:67], v[66:67], v[74:75] op_sel_hi:[1,0]
	s_and_b64 vcc, exec, s[6:7]
	s_mov_b64 s[36:37], -1
	s_cbranch_vccnz .LBB0_402
	v_pk_mul_f32 v[84:85], v[70:71], v[70:71]
	v_pk_mul_f32 v[78:79], v[68:69], v[68:69]
	v_pk_fma_f32 v[84:85], v[84:85], s[64:65], 1.0 op_sel_hi:[1,0,0]
	v_pk_mul_f32 v[88:89], v[66:67], v[66:67]
	v_pk_mul_f32 v[84:85], v[70:71], v[84:85]
	v_pk_fma_f32 v[78:79], v[78:79], s[64:65], 1.0 op_sel_hi:[1,0,0]
	v_pk_mul_f32 v[84:85], v[84:85], s[66:67] op_sel_hi:[1,0]
	v_pk_fma_f32 v[88:89], v[88:89], s[64:65], 1.0 op_sel_hi:[1,0,0]
	v_pk_mul_f32 v[84:85], v[84:85], s[68:69] op_sel_hi:[1,0]
	v_pk_mul_f32 v[78:79], v[68:69], v[78:79]
	v_exp_f32_e32 v84, v84
	v_exp_f32_e32 v85, v85
	v_pk_mul_f32 v[88:89], v[66:67], v[88:89]
	v_pk_mul_f32 v[78:79], v[78:79], s[66:67] op_sel_hi:[1,0]
	v_pk_mul_f32 v[88:89], v[88:89], s[66:67] op_sel_hi:[1,0]
	v_pk_add_f32 v[84:85], v[84:85], 1.0 op_sel_hi:[1,0]
	v_pk_mul_f32 v[78:79], v[78:79], s[68:69] op_sel_hi:[1,0]
	v_rcp_f32_e32 v86, v84
	v_rcp_f32_e32 v87, v85
	v_pk_mul_f32 v[84:85], v[64:65], v[64:65]
	v_pk_mul_f32 v[88:89], v[88:89], s[68:69] op_sel_hi:[1,0]
	v_pk_fma_f32 v[84:85], v[84:85], s[64:65], 1.0 op_sel_hi:[1,0,0]
	v_exp_f32_e32 v78, v78
	v_pk_mul_f32 v[84:85], v[64:65], v[84:85]
	v_exp_f32_e32 v79, v79
	v_pk_mul_f32 v[84:85], v[84:85], s[66:67] op_sel_hi:[1,0]
	v_exp_f32_e32 v88, v88
	v_pk_mul_f32 v[84:85], v[84:85], s[68:69] op_sel_hi:[1,0]
	v_exp_f32_e32 v89, v89
	v_exp_f32_e32 v84, v84
	v_exp_f32_e32 v85, v85
	v_pk_add_f32 v[78:79], v[78:79], 1.0 op_sel_hi:[1,0]
	v_pk_mul_f32 v[86:87], v[70:71], v[86:87]
	v_rcp_f32_e32 v78, v78
	v_pk_add_f32 v[84:85], v[84:85], 1.0 op_sel_hi:[1,0]
	v_rcp_f32_e32 v79, v79
	v_rcp_f32_e32 v90, v84
	v_rcp_f32_e32 v91, v85
	v_pk_add_f32 v[84:85], v[88:89], 1.0 op_sel_hi:[1,0]
	s_cmp_lt_u32 s22, 4
	v_rcp_f32_e32 v92, v84
	v_rcp_f32_e32 v93, v85
	v_pk_mul_f32 v[84:85], v[68:69], v[78:79]
	v_pk_mul_f32 v[88:89], v[64:65], v[90:91]
	v_pk_mul_f32 v[78:79], v[66:67], v[92:93]
	s_cbranch_scc1 .LBB0_399
	v_lshl_add_u64 v[90:91], s[20:21], 0, v[72:73]
	s_movk_i32 s0, 0xf800
	v_lshl_add_u64 v[90:91], v[188:189], 1, v[90:91]
	s_mov_b32 s1, -1
	v_lshl_add_u64 v[90:91], v[90:91], 0, s[0:1]
	s_mov_b64 s[36:37], 0

.LBB0_404:
	v_mov_b32_e32 v75, v74
	v_cvt_pk_bf16_f32 v64, v84, v85
	v_cvt_pk_bf16_f32 v65, v86, v87
	v_cvt_pk_bf16_f32 v66, v88, v89
	v_cvt_pk_bf16_f32 v67, v78, v79
	v_pk_mul_f32 v[56:57], v[56:57], v[74:75]
	v_pk_mul_f32 v[58:59], v[58:59], v[74:75]
	v_pk_mul_f32 v[52:53], v[52:53], v[74:75]
	v_pk_mul_f32 v[54:55], v[54:55], v[74:75]
	s_and_b64 vcc, exec, s[6:7]
	s_mov_b64 s[36:37], -1
	global_store_dwordx4 v[90:91], v[64:67], off
	s_cbranch_vccnz .LBB0_410
	s_nop 0
	v_pk_mul_f32 v[66:67], v[58:59], v[58:59]
	v_pk_mul_f32 v[64:65], v[56:57], v[56:57]
	v_pk_fma_f32 v[66:67], v[66:67], s[64:65], 1.0 op_sel_hi:[1,0,0]
	v_pk_mul_f32 v[70:71], v[54:55], v[54:55]
	v_pk_mul_f32 v[66:67], v[58:59], v[66:67]
	v_pk_fma_f32 v[64:65], v[64:65], s[64:65], 1.0 op_sel_hi:[1,0,0]
	v_pk_mul_f32 v[66:67], v[66:67], s[66:67] op_sel_hi:[1,0]
	v_pk_fma_f32 v[70:71], v[70:71], s[64:65], 1.0 op_sel_hi:[1,0,0]
	v_pk_mul_f32 v[66:67], v[66:67], s[68:69] op_sel_hi:[1,0]
	v_pk_mul_f32 v[64:65], v[56:57], v[64:65]
	v_exp_f32_e32 v66, v66
	v_exp_f32_e32 v67, v67
	v_pk_mul_f32 v[70:71], v[54:55], v[70:71]
	v_pk_mul_f32 v[64:65], v[64:65], s[66:67] op_sel_hi:[1,0]
	v_pk_mul_f32 v[70:71], v[70:71], s[66:67] op_sel_hi:[1,0]
	v_pk_add_f32 v[66:67], v[66:67], 1.0 op_sel_hi:[1,0]
	v_pk_mul_f32 v[64:65], v[64:65], s[68:69] op_sel_hi:[1,0]
	v_rcp_f32_e32 v68, v66
	v_rcp_f32_e32 v69, v67
	v_pk_mul_f32 v[66:67], v[52:53], v[52:53]
	v_pk_mul_f32 v[70:71], v[70:71], s[68:69] op_sel_hi:[1,0]
	v_pk_fma_f32 v[66:67], v[66:67], s[64:65], 1.0 op_sel_hi:[1,0,0]
	v_exp_f32_e32 v64, v64
	v_pk_mul_f32 v[66:67], v[52:53], v[66:67]
	v_exp_f32_e32 v65, v65
	v_pk_mul_f32 v[66:67], v[66:67], s[66:67] op_sel_hi:[1,0]
	v_exp_f32_e32 v70, v70
	v_pk_mul_f32 v[66:67], v[66:67], s[68:69] op_sel_hi:[1,0]
	v_exp_f32_e32 v71, v71
	v_exp_f32_e32 v66, v66
	v_exp_f32_e32 v67, v67
	v_pk_add_f32 v[64:65], v[64:65], 1.0 op_sel_hi:[1,0]
	v_pk_mul_f32 v[68:69], v[58:59], v[68:69]
	v_rcp_f32_e32 v64, v64
	v_pk_add_f32 v[66:67], v[66:67], 1.0 op_sel_hi:[1,0]
	v_rcp_f32_e32 v65, v65
	v_rcp_f32_e32 v74, v66
	v_rcp_f32_e32 v75, v67
	v_pk_add_f32 v[66:67], v[70:71], 1.0 op_sel_hi:[1,0]
	s_cmp_lt_u32 s22, 4
	v_rcp_f32_e32 v78, v66
	v_rcp_f32_e32 v79, v67
	v_pk_mul_f32 v[66:67], v[56:57], v[64:65]
	v_pk_mul_f32 v[70:71], v[52:53], v[74:75]
	v_pk_mul_f32 v[64:65], v[54:55], v[78:79]
	s_cbranch_scc1 .LBB0_407
	v_lshl_add_u64 v[74:75], s[20:21], 0, v[72:73]
	s_movk_i32 s0, 0xf900
	v_lshl_add_u64 v[74:75], v[188:189], 1, v[74:75]
	s_mov_b32 s1, -1
	v_lshl_add_u64 v[74:75], v[74:75], 0, s[0:1]
	s_mov_b64 s[36:37], 0

.LBB0_412:
	v_add_f32_e32 v52, v80, v81
	v_add_f32_e32 v53, v82, v83
	v_add_f32_e32 v52, v52, v53
	v_fmamk_f32 v52, v52, 0x3a800000, v229
	v_rsq_f32_e32 v54, v52
	v_cvt_pk_bf16_f32 v56, v66, v67
	v_cvt_pk_bf16_f32 v57, v68, v69
	v_cvt_pk_bf16_f32 v58, v70, v71
	v_cvt_pk_bf16_f32 v59, v64, v65
	global_store_dwordx4 v[74:75], v[56:59], off
	v_pk_mul_f32 v[48:49], v[48:49], v[54:55] op_sel_hi:[1,0]
	v_pk_mul_f32 v[46:47], v[46:47], v[54:55] op_sel_hi:[1,0]
	v_add_u32_e32 v58, 0x90, v168
	v_ashrrev_i32_e32 v59, 31, v58
	v_lshlrev_b64 v[52:53], 10, v[58:59]
	v_pk_mul_f32 v[56:57], v[50:51], v[54:55] op_sel_hi:[1,0]
	v_pk_mul_f32 v[50:51], v[44:45], v[54:55] op_sel_hi:[1,0]
	s_and_b64 vcc, exec, s[6:7]
	s_mov_b64 s[36:37], -1
	s_cbranch_vccnz .LBB0_418
	v_pk_mul_f32 v[66:67], v[50:51], v[50:51]
	v_pk_mul_f32 v[44:45], v[48:49], v[48:49]
	v_pk_mul_f32 v[64:65], v[56:57], v[56:57]
	v_pk_fma_f32 v[66:67], v[66:67], s[64:65], 1.0 op_sel_hi:[1,0,0]
	v_pk_mul_f32 v[68:69], v[46:47], v[46:47]
	v_pk_fma_f32 v[44:45], v[44:45], s[64:65], 1.0 op_sel_hi:[1,0,0]
	v_pk_fma_f32 v[64:65], v[64:65], s[64:65], 1.0 op_sel_hi:[1,0,0]
	v_pk_mul_f32 v[66:67], v[50:51], v[66:67]
	v_pk_fma_f32 v[68:69], v[68:69], s[64:65], 1.0 op_sel_hi:[1,0,0]
	v_pk_mul_f32 v[44:45], v[48:49], v[44:45]
	v_pk_mul_f32 v[64:65], v[56:57], v[64:65]
	v_pk_mul_f32 v[66:67], v[66:67], s[66:67] op_sel_hi:[1,0]
	v_pk_mul_f32 v[68:69], v[46:47], v[68:69]
	v_pk_mul_f32 v[44:45], v[44:45], s[66:67] op_sel_hi:[1,0]
	v_pk_mul_f32 v[64:65], v[64:65], s[66:67] op_sel_hi:[1,0]
	v_pk_mul_f32 v[66:67], v[66:67], s[68:69] op_sel_hi:[1,0]
	v_pk_mul_f32 v[68:69], v[68:69], s[66:67] op_sel_hi:[1,0]
	v_pk_mul_f32 v[44:45], v[44:45], s[68:69] op_sel_hi:[1,0]
	v_pk_mul_f32 v[64:65], v[64:65], s[68:69] op_sel_hi:[1,0]
	v_exp_f32_e32 v66, v66
	v_exp_f32_e32 v67, v67
	v_pk_mul_f32 v[68:69], v[68:69], s[68:69] op_sel_hi:[1,0]
	v_exp_f32_e32 v44, v44
	v_exp_f32_e32 v45, v45
	v_exp_f32_e32 v64, v64
	v_exp_f32_e32 v65, v65
	v_exp_f32_e32 v68, v68
	v_exp_f32_e32 v69, v69
	v_pk_add_f32 v[66:67], v[66:67], 1.0 op_sel_hi:[1,0]
	v_pk_add_f32 v[44:45], v[44:45], 1.0 op_sel_hi:[1,0]
	v_pk_add_f32 v[64:65], v[64:65], 1.0 op_sel_hi:[1,0]
	v_rcp_f32_e32 v70, v66
	v_rcp_f32_e32 v71, v67
	v_pk_add_f32 v[66:67], v[68:69], 1.0 op_sel_hi:[1,0]
	v_rcp_f32_e32 v44, v44
	v_rcp_f32_e32 v45, v45
	v_rcp_f32_e32 v64, v64
	v_rcp_f32_e32 v65, v65
	v_rcp_f32_e32 v72, v66
	v_rcp_f32_e32 v73, v67
	v_pk_mul_f32 v[66:67], v[48:49], v[44:45]
	v_pk_mul_f32 v[68:69], v[56:57], v[64:65]
	v_pk_mul_f32 v[70:71], v[50:51], v[70:71]
	v_pk_mul_f32 v[64:65], v[46:47], v[72:73]
	s_cmp_lt_u32 s22, 4
	s_cbranch_scc1 .LBB0_415
	v_lshl_add_u64 v[44:45], s[20:21], 0, v[52:53]
	s_movk_i32 s0, 0xf800
	v_lshl_add_u64 v[44:45], v[188:189], 1, v[44:45]
	s_mov_b32 s1, -1
	v_lshl_add_u64 v[72:73], v[44:45], 0, s[0:1]
	s_mov_b64 s[36:37], 0

.LBB0_420:
	v_mov_b32_e32 v55, v54
	v_cvt_pk_bf16_f32 v46, v66, v67
	v_cvt_pk_bf16_f32 v47, v68, v69
	v_cvt_pk_bf16_f32 v48, v70, v71
	v_cvt_pk_bf16_f32 v49, v64, v65
	v_pk_mul_f32 v[36:37], v[36:37], v[54:55]
	v_pk_mul_f32 v[38:39], v[38:39], v[54:55]
	v_pk_mul_f32 v[32:33], v[32:33], v[54:55]
	v_pk_mul_f32 v[34:35], v[34:35], v[54:55]
	s_and_b64 vcc, exec, s[6:7]
	s_mov_b64 s[36:37], -1
	global_store_dwordx4 v[72:73], v[46:49], off
	s_cbranch_vccnz .LBB0_426
	s_nop 0
	v_pk_mul_f32 v[48:49], v[38:39], v[38:39]
	v_pk_mul_f32 v[46:47], v[36:37], v[36:37]
	v_pk_fma_f32 v[48:49], v[48:49], s[64:65], 1.0 op_sel_hi:[1,0,0]
	v_pk_mul_f32 v[54:55], v[34:35], v[34:35]
	v_pk_mul_f32 v[48:49], v[38:39], v[48:49]
	v_pk_fma_f32 v[46:47], v[46:47], s[64:65], 1.0 op_sel_hi:[1,0,0]
	v_pk_mul_f32 v[48:49], v[48:49], s[66:67] op_sel_hi:[1,0]
	v_pk_fma_f32 v[54:55], v[54:55], s[64:65], 1.0 op_sel_hi:[1,0,0]
	v_pk_mul_f32 v[48:49], v[48:49], s[68:69] op_sel_hi:[1,0]
	v_pk_mul_f32 v[46:47], v[36:37], v[46:47]
	v_exp_f32_e32 v48, v48
	v_exp_f32_e32 v49, v49
	v_pk_mul_f32 v[54:55], v[34:35], v[54:55]
	v_pk_mul_f32 v[46:47], v[46:47], s[66:67] op_sel_hi:[1,0]
	v_pk_mul_f32 v[54:55], v[54:55], s[66:67] op_sel_hi:[1,0]
	v_pk_add_f32 v[48:49], v[48:49], 1.0 op_sel_hi:[1,0]
	v_pk_mul_f32 v[46:47], v[46:47], s[68:69] op_sel_hi:[1,0]
	v_rcp_f32_e32 v50, v48
	v_rcp_f32_e32 v51, v49
	v_pk_mul_f32 v[48:49], v[32:33], v[32:33]
	v_pk_mul_f32 v[54:55], v[54:55], s[68:69] op_sel_hi:[1,0]
	v_pk_fma_f32 v[48:49], v[48:49], s[64:65], 1.0 op_sel_hi:[1,0,0]
	v_exp_f32_e32 v46, v46
	v_pk_mul_f32 v[48:49], v[32:33], v[48:49]
	v_exp_f32_e32 v47, v47
	v_pk_mul_f32 v[48:49], v[48:49], s[66:67] op_sel_hi:[1,0]
	v_exp_f32_e32 v54, v54
	v_pk_mul_f32 v[48:49], v[48:49], s[68:69] op_sel_hi:[1,0]
	v_exp_f32_e32 v55, v55
	v_exp_f32_e32 v48, v48
	v_exp_f32_e32 v49, v49
	v_pk_add_f32 v[46:47], v[46:47], 1.0 op_sel_hi:[1,0]
	v_pk_mul_f32 v[50:51], v[38:39], v[50:51]
	v_rcp_f32_e32 v46, v46
	v_pk_add_f32 v[48:49], v[48:49], 1.0 op_sel_hi:[1,0]
	v_rcp_f32_e32 v47, v47
	v_rcp_f32_e32 v56, v48
	v_rcp_f32_e32 v57, v49
	v_pk_add_f32 v[48:49], v[54:55], 1.0 op_sel_hi:[1,0]
	s_cmp_lt_u32 s22, 4
	v_rcp_f32_e32 v58, v48
	v_rcp_f32_e32 v59, v49
	v_pk_mul_f32 v[48:49], v[36:37], v[46:47]
	v_pk_mul_f32 v[54:55], v[32:33], v[56:57]
	v_pk_mul_f32 v[46:47], v[34:35], v[58:59]
	s_cbranch_scc1 .LBB0_423
	v_lshl_add_u64 v[56:57], s[20:21], 0, v[52:53]
	s_movk_i32 s0, 0xf900
	v_lshl_add_u64 v[56:57], v[188:189], 1, v[56:57]
	s_mov_b32 s1, -1
	v_lshl_add_u64 v[56:57], v[56:57], 0, s[0:1]
	s_mov_b64 s[36:37], 0

.LBB0_428:
	v_add_f32_e32 v32, v60, v61
	v_add_f32_e32 v33, v62, v63
	v_add_f32_e32 v32, v32, v33
	v_fmamk_f32 v32, v32, 0x3a800000, v229
	v_rsq_f32_e32 v34, v32
	v_cvt_pk_bf16_f32 v36, v48, v49
	v_cvt_pk_bf16_f32 v37, v50, v51
	v_cvt_pk_bf16_f32 v38, v54, v55
	v_cvt_pk_bf16_f32 v39, v46, v47
	global_store_dwordx4 v[56:57], v[36:39], off
	v_pk_mul_f32 v[28:29], v[28:29], v[34:35] op_sel_hi:[1,0]
	v_pk_mul_f32 v[26:27], v[26:27], v[34:35] op_sel_hi:[1,0]
	v_add_u32_e32 v38, 0xa0, v168
	v_ashrrev_i32_e32 v39, 31, v38
	v_lshlrev_b64 v[32:33], 10, v[38:39]
	v_pk_mul_f32 v[36:37], v[30:31], v[34:35] op_sel_hi:[1,0]
	v_pk_mul_f32 v[30:31], v[24:25], v[34:35] op_sel_hi:[1,0]
	s_and_b64 vcc, exec, s[6:7]
	s_mov_b64 s[36:37], -1
	s_cbranch_vccnz .LBB0_434
	v_pk_mul_f32 v[46:47], v[30:31], v[30:31]
	v_pk_mul_f32 v[24:25], v[28:29], v[28:29]
	v_pk_mul_f32 v[44:45], v[36:37], v[36:37]
	v_pk_fma_f32 v[46:47], v[46:47], s[64:65], 1.0 op_sel_hi:[1,0,0]
	v_pk_mul_f32 v[48:49], v[26:27], v[26:27]
	v_pk_fma_f32 v[24:25], v[24:25], s[64:65], 1.0 op_sel_hi:[1,0,0]
	v_pk_fma_f32 v[44:45], v[44:45], s[64:65], 1.0 op_sel_hi:[1,0,0]
	v_pk_mul_f32 v[46:47], v[30:31], v[46:47]
	v_pk_fma_f32 v[48:49], v[48:49], s[64:65], 1.0 op_sel_hi:[1,0,0]
	v_pk_mul_f32 v[24:25], v[28:29], v[24:25]
	v_pk_mul_f32 v[44:45], v[36:37], v[44:45]
	v_pk_mul_f32 v[46:47], v[46:47], s[66:67] op_sel_hi:[1,0]
	v_pk_mul_f32 v[48:49], v[26:27], v[48:49]
	v_pk_mul_f32 v[24:25], v[24:25], s[66:67] op_sel_hi:[1,0]
	v_pk_mul_f32 v[44:45], v[44:45], s[66:67] op_sel_hi:[1,0]
	v_pk_mul_f32 v[46:47], v[46:47], s[68:69] op_sel_hi:[1,0]
	v_pk_mul_f32 v[48:49], v[48:49], s[66:67] op_sel_hi:[1,0]
	v_pk_mul_f32 v[24:25], v[24:25], s[68:69] op_sel_hi:[1,0]
	v_pk_mul_f32 v[44:45], v[44:45], s[68:69] op_sel_hi:[1,0]
	v_exp_f32_e32 v46, v46
	v_exp_f32_e32 v47, v47
	v_pk_mul_f32 v[48:49], v[48:49], s[68:69] op_sel_hi:[1,0]
	v_exp_f32_e32 v24, v24
	v_exp_f32_e32 v25, v25
	v_exp_f32_e32 v44, v44
	v_exp_f32_e32 v45, v45
	v_exp_f32_e32 v48, v48
	v_exp_f32_e32 v49, v49
	v_pk_add_f32 v[46:47], v[46:47], 1.0 op_sel_hi:[1,0]
	v_pk_add_f32 v[24:25], v[24:25], 1.0 op_sel_hi:[1,0]
	v_pk_add_f32 v[44:45], v[44:45], 1.0 op_sel_hi:[1,0]
	v_rcp_f32_e32 v50, v46
	v_rcp_f32_e32 v51, v47
	v_pk_add_f32 v[46:47], v[48:49], 1.0 op_sel_hi:[1,0]
	v_rcp_f32_e32 v24, v24
	v_rcp_f32_e32 v25, v25
	v_rcp_f32_e32 v44, v44
	v_rcp_f32_e32 v45, v45
	v_rcp_f32_e32 v52, v46
	v_rcp_f32_e32 v53, v47
	v_pk_mul_f32 v[46:47], v[28:29], v[24:25]
	v_pk_mul_f32 v[48:49], v[36:37], v[44:45]
	v_pk_mul_f32 v[50:51], v[30:31], v[50:51]
	v_pk_mul_f32 v[44:45], v[26:27], v[52:53]
	s_cmp_lt_u32 s22, 4
	s_cbranch_scc1 .LBB0_431
	v_lshl_add_u64 v[24:25], s[20:21], 0, v[32:33]
	s_movk_i32 s0, 0xf800
	v_lshl_add_u64 v[24:25], v[188:189], 1, v[24:25]
	s_mov_b32 s1, -1
	v_lshl_add_u64 v[52:53], v[24:25], 0, s[0:1]
	s_mov_b64 s[36:37], 0

.LBB0_436:
	v_mov_b32_e32 v35, v34
	v_cvt_pk_bf16_f32 v26, v46, v47
	v_cvt_pk_bf16_f32 v27, v48, v49
	v_cvt_pk_bf16_f32 v28, v50, v51
	v_cvt_pk_bf16_f32 v29, v44, v45
	v_pk_mul_f32 v[20:21], v[20:21], v[34:35]
	v_pk_mul_f32 v[22:23], v[22:23], v[34:35]
	v_pk_mul_f32 v[16:17], v[16:17], v[34:35]
	v_pk_mul_f32 v[18:19], v[18:19], v[34:35]
	s_and_b64 vcc, exec, s[6:7]
	s_mov_b64 s[36:37], -1
	global_store_dwordx4 v[52:53], v[26:29], off
	s_cbranch_vccnz .LBB0_442
	s_nop 0
	v_pk_mul_f32 v[28:29], v[22:23], v[22:23]
	v_pk_mul_f32 v[26:27], v[20:21], v[20:21]
	v_pk_fma_f32 v[28:29], v[28:29], s[64:65], 1.0 op_sel_hi:[1,0,0]
	v_pk_mul_f32 v[34:35], v[18:19], v[18:19]
	v_pk_mul_f32 v[28:29], v[22:23], v[28:29]
	v_pk_fma_f32 v[26:27], v[26:27], s[64:65], 1.0 op_sel_hi:[1,0,0]
	v_pk_mul_f32 v[28:29], v[28:29], s[66:67] op_sel_hi:[1,0]
	v_pk_fma_f32 v[34:35], v[34:35], s[64:65], 1.0 op_sel_hi:[1,0,0]
	v_pk_mul_f32 v[28:29], v[28:29], s[68:69] op_sel_hi:[1,0]
	v_pk_mul_f32 v[26:27], v[20:21], v[26:27]
	v_exp_f32_e32 v28, v28
	v_exp_f32_e32 v29, v29
	v_pk_mul_f32 v[34:35], v[18:19], v[34:35]
	v_pk_mul_f32 v[26:27], v[26:27], s[66:67] op_sel_hi:[1,0]
	v_pk_mul_f32 v[34:35], v[34:35], s[66:67] op_sel_hi:[1,0]
	v_pk_add_f32 v[28:29], v[28:29], 1.0 op_sel_hi:[1,0]
	v_pk_mul_f32 v[26:27], v[26:27], s[68:69] op_sel_hi:[1,0]
	v_rcp_f32_e32 v30, v28
	v_rcp_f32_e32 v31, v29
	v_pk_mul_f32 v[28:29], v[16:17], v[16:17]
	v_pk_mul_f32 v[34:35], v[34:35], s[68:69] op_sel_hi:[1,0]
	v_pk_fma_f32 v[28:29], v[28:29], s[64:65], 1.0 op_sel_hi:[1,0,0]
	v_exp_f32_e32 v26, v26
	v_pk_mul_f32 v[28:29], v[16:17], v[28:29]
	v_exp_f32_e32 v27, v27
	v_pk_mul_f32 v[28:29], v[28:29], s[66:67] op_sel_hi:[1,0]
	v_exp_f32_e32 v34, v34
	v_pk_mul_f32 v[28:29], v[28:29], s[68:69] op_sel_hi:[1,0]
	v_exp_f32_e32 v35, v35
	v_exp_f32_e32 v28, v28
	v_exp_f32_e32 v29, v29
	v_pk_add_f32 v[26:27], v[26:27], 1.0 op_sel_hi:[1,0]
	v_pk_mul_f32 v[30:31], v[22:23], v[30:31]
	v_rcp_f32_e32 v26, v26
	v_pk_add_f32 v[28:29], v[28:29], 1.0 op_sel_hi:[1,0]
	v_rcp_f32_e32 v27, v27
	v_rcp_f32_e32 v36, v28
	v_rcp_f32_e32 v37, v29
	v_pk_add_f32 v[28:29], v[34:35], 1.0 op_sel_hi:[1,0]
	s_cmp_lt_u32 s22, 4
	v_rcp_f32_e32 v38, v28
	v_rcp_f32_e32 v39, v29
	v_pk_mul_f32 v[28:29], v[20:21], v[26:27]
	v_pk_mul_f32 v[34:35], v[16:17], v[36:37]
	v_pk_mul_f32 v[26:27], v[18:19], v[38:39]
	s_cbranch_scc1 .LBB0_439
	v_lshl_add_u64 v[36:37], s[20:21], 0, v[32:33]
	s_movk_i32 s0, 0xf900
	v_lshl_add_u64 v[36:37], v[188:189], 1, v[36:37]
	s_mov_b32 s1, -1
	v_lshl_add_u64 v[36:37], v[36:37], 0, s[0:1]
	s_mov_b64 s[36:37], 0

.LBB0_444:
	v_add_f32_e32 v16, v40, v41
	v_add_f32_e32 v17, v42, v43
	v_add_f32_e32 v16, v16, v17
	v_fmamk_f32 v16, v16, 0x3a800000, v229
	v_rsq_f32_e32 v18, v16
	v_cvt_pk_bf16_f32 v20, v28, v29
	v_cvt_pk_bf16_f32 v21, v30, v31
	v_cvt_pk_bf16_f32 v22, v34, v35
	v_cvt_pk_bf16_f32 v23, v26, v27
	global_store_dwordx4 v[36:37], v[20:23], off
	v_pk_mul_f32 v[12:13], v[12:13], v[18:19] op_sel_hi:[1,0]
	v_pk_mul_f32 v[10:11], v[10:11], v[18:19] op_sel_hi:[1,0]
	v_add_u32_e32 v22, 0xb0, v168
	v_ashrrev_i32_e32 v23, 31, v22
	v_lshlrev_b64 v[16:17], 10, v[22:23]
	v_pk_mul_f32 v[20:21], v[14:15], v[18:19] op_sel_hi:[1,0]
	v_pk_mul_f32 v[14:15], v[8:9], v[18:19] op_sel_hi:[1,0]
	s_and_b64 vcc, exec, s[6:7]
	s_mov_b64 s[36:37], -1
	s_cbranch_vccnz .LBB0_450
	v_pk_mul_f32 v[26:27], v[14:15], v[14:15]
	v_pk_mul_f32 v[8:9], v[12:13], v[12:13]
	v_pk_mul_f32 v[24:25], v[20:21], v[20:21]
	v_pk_fma_f32 v[26:27], v[26:27], s[64:65], 1.0 op_sel_hi:[1,0,0]
	v_pk_mul_f32 v[28:29], v[10:11], v[10:11]
	v_pk_fma_f32 v[8:9], v[8:9], s[64:65], 1.0 op_sel_hi:[1,0,0]
	v_pk_fma_f32 v[24:25], v[24:25], s[64:65], 1.0 op_sel_hi:[1,0,0]
	v_pk_mul_f32 v[26:27], v[14:15], v[26:27]
	v_pk_fma_f32 v[28:29], v[28:29], s[64:65], 1.0 op_sel_hi:[1,0,0]
	v_pk_mul_f32 v[8:9], v[12:13], v[8:9]
	v_pk_mul_f32 v[24:25], v[20:21], v[24:25]
	v_pk_mul_f32 v[26:27], v[26:27], s[66:67] op_sel_hi:[1,0]
	v_pk_mul_f32 v[28:29], v[10:11], v[28:29]
	v_pk_mul_f32 v[8:9], v[8:9], s[66:67] op_sel_hi:[1,0]
	v_pk_mul_f32 v[24:25], v[24:25], s[66:67] op_sel_hi:[1,0]
	v_pk_mul_f32 v[26:27], v[26:27], s[68:69] op_sel_hi:[1,0]
	v_pk_mul_f32 v[28:29], v[28:29], s[66:67] op_sel_hi:[1,0]
	v_pk_mul_f32 v[8:9], v[8:9], s[68:69] op_sel_hi:[1,0]
	v_pk_mul_f32 v[24:25], v[24:25], s[68:69] op_sel_hi:[1,0]
	v_exp_f32_e32 v26, v26
	v_exp_f32_e32 v27, v27
	v_pk_mul_f32 v[28:29], v[28:29], s[68:69] op_sel_hi:[1,0]
	v_exp_f32_e32 v8, v8
	v_exp_f32_e32 v9, v9
	v_exp_f32_e32 v24, v24
	v_exp_f32_e32 v25, v25
	v_exp_f32_e32 v28, v28
	v_exp_f32_e32 v29, v29
	v_pk_add_f32 v[26:27], v[26:27], 1.0 op_sel_hi:[1,0]
	v_pk_add_f32 v[8:9], v[8:9], 1.0 op_sel_hi:[1,0]
	v_pk_add_f32 v[24:25], v[24:25], 1.0 op_sel_hi:[1,0]
	v_rcp_f32_e32 v30, v26
	v_rcp_f32_e32 v31, v27
	v_pk_add_f32 v[26:27], v[28:29], 1.0 op_sel_hi:[1,0]
	v_rcp_f32_e32 v8, v8
	v_rcp_f32_e32 v9, v9
	v_rcp_f32_e32 v24, v24
	v_rcp_f32_e32 v25, v25
	v_rcp_f32_e32 v32, v26
	v_rcp_f32_e32 v33, v27
	v_pk_mul_f32 v[26:27], v[12:13], v[8:9]
	v_pk_mul_f32 v[28:29], v[20:21], v[24:25]
	v_pk_mul_f32 v[30:31], v[14:15], v[30:31]
	v_pk_mul_f32 v[24:25], v[10:11], v[32:33]
	s_cmp_lt_u32 s22, 4
	s_cbranch_scc1 .LBB0_447
	v_lshl_add_u64 v[8:9], s[20:21], 0, v[16:17]
	s_movk_i32 s0, 0xf800
	v_lshl_add_u64 v[8:9], v[188:189], 1, v[8:9]
	s_mov_b32 s1, -1
	v_lshl_add_u64 v[32:33], v[8:9], 0, s[0:1]
	s_mov_b64 s[36:37], 0

.LBB0_452:
	v_mov_b32_e32 v19, v18
	v_cvt_pk_bf16_f32 v10, v26, v27
	v_cvt_pk_bf16_f32 v11, v28, v29
	v_cvt_pk_bf16_f32 v12, v30, v31
	v_cvt_pk_bf16_f32 v13, v24, v25
	v_pk_mul_f32 v[4:5], v[4:5], v[18:19]
	v_pk_mul_f32 v[6:7], v[6:7], v[18:19]
	v_pk_mul_f32 v[0:1], v[0:1], v[18:19]
	v_pk_mul_f32 v[2:3], v[2:3], v[18:19]
	s_and_b64 vcc, exec, s[6:7]
	s_mov_b64 s[6:7], -1
	global_store_dwordx4 v[32:33], v[10:13], off
	s_cbranch_vccnz .LBB0_458
	s_nop 0
	v_pk_mul_f32 v[12:13], v[6:7], v[6:7]
	v_pk_mul_f32 v[10:11], v[4:5], v[4:5]
	v_pk_fma_f32 v[12:13], v[12:13], s[64:65], 1.0 op_sel_hi:[1,0,0]
	v_pk_mul_f32 v[18:19], v[2:3], v[2:3]
	v_pk_mul_f32 v[12:13], v[6:7], v[12:13]
	v_pk_fma_f32 v[10:11], v[10:11], s[64:65], 1.0 op_sel_hi:[1,0,0]
	v_pk_mul_f32 v[12:13], v[12:13], s[66:67] op_sel_hi:[1,0]
	v_pk_fma_f32 v[18:19], v[18:19], s[64:65], 1.0 op_sel_hi:[1,0,0]
	v_pk_mul_f32 v[12:13], v[12:13], s[68:69] op_sel_hi:[1,0]
	v_pk_mul_f32 v[10:11], v[4:5], v[10:11]
	v_exp_f32_e32 v12, v12
	v_exp_f32_e32 v13, v13
	v_pk_mul_f32 v[18:19], v[2:3], v[18:19]
	v_pk_mul_f32 v[10:11], v[10:11], s[66:67] op_sel_hi:[1,0]
	v_pk_mul_f32 v[18:19], v[18:19], s[66:67] op_sel_hi:[1,0]
	v_pk_add_f32 v[12:13], v[12:13], 1.0 op_sel_hi:[1,0]
	v_pk_mul_f32 v[10:11], v[10:11], s[68:69] op_sel_hi:[1,0]
	v_rcp_f32_e32 v14, v12
	v_rcp_f32_e32 v15, v13
	v_pk_mul_f32 v[12:13], v[0:1], v[0:1]
	v_pk_mul_f32 v[18:19], v[18:19], s[68:69] op_sel_hi:[1,0]
	v_pk_fma_f32 v[12:13], v[12:13], s[64:65], 1.0 op_sel_hi:[1,0,0]
	v_exp_f32_e32 v10, v10
	v_pk_mul_f32 v[12:13], v[0:1], v[12:13]
	v_exp_f32_e32 v11, v11
	v_pk_mul_f32 v[12:13], v[12:13], s[66:67] op_sel_hi:[1,0]
	v_exp_f32_e32 v18, v18
	v_pk_mul_f32 v[12:13], v[12:13], s[68:69] op_sel_hi:[1,0]
	v_exp_f32_e32 v19, v19
	v_exp_f32_e32 v12, v12
	v_exp_f32_e32 v13, v13
	v_pk_add_f32 v[10:11], v[10:11], 1.0 op_sel_hi:[1,0]
	v_pk_mul_f32 v[14:15], v[6:7], v[14:15]
	v_rcp_f32_e32 v10, v10
	v_pk_add_f32 v[12:13], v[12:13], 1.0 op_sel_hi:[1,0]
	v_rcp_f32_e32 v11, v11
	v_rcp_f32_e32 v20, v12
	v_rcp_f32_e32 v21, v13
	v_pk_add_f32 v[12:13], v[18:19], 1.0 op_sel_hi:[1,0]
	s_cmp_lt_u32 s22, 4
	v_rcp_f32_e32 v22, v12
	v_rcp_f32_e32 v23, v13
	v_pk_mul_f32 v[12:13], v[4:5], v[10:11]
	v_pk_mul_f32 v[18:19], v[0:1], v[20:21]
	v_pk_mul_f32 v[10:11], v[2:3], v[22:23]
	s_cbranch_scc1 .LBB0_455
	v_lshl_add_u64 v[20:21], s[20:21], 0, v[16:17]
	s_movk_i32 s0, 0xf900
	v_lshl_add_u64 v[20:21], v[188:189], 1, v[20:21]
	s_mov_b32 s1, -1
	v_lshl_add_u64 v[20:21], v[20:21], 0, s[0:1]
	s_mov_b64 s[6:7], 0

.LBB0_460:
	s_andn2_b64 vcc, exec, s[4:5]
	s_mov_b64 s[4:5], -1
	v_cvt_pk_bf16_f32 v0, v12, v13
	v_cvt_pk_bf16_f32 v1, v14, v15
	v_cvt_pk_bf16_f32 v2, v18, v19
	v_cvt_pk_bf16_f32 v3, v10, v11
	global_store_dwordx4 v[20:21], v[0:3], off
	s_cbranch_vccnz .LBB0_323
	v_readlane_b32 s0, v255, 32
	v_readlane_b32 s1, v255, 33
	s_andn2_b64 vcc, exec, s[0:1]
	s_cbranch_vccnz .LBB0_322
	s_barrier
	s_branch .LBB0_322

.LBB0_493:
	s_lshl_b32 s17, s17, 8
	v_lshl_or_b32 v208, s16, 8, v236
	v_add_u32_e32 v120, s17, v233
	v_ashrrev_i32_e32 v209, 31, v208
	v_lshlrev_b64 v[224:225], 1, v[208:209]
	v_ashrrev_i32_e32 v121, 31, v120
	v_lshl_add_u64 v[122:123], s[20:21], 0, v[224:225]
	v_lshlrev_b64 v[226:227], 11, v[120:121]
	v_lshl_add_u64 v[124:125], v[122:123], 0, v[226:227]
	global_load_dwordx4 v[250:253], v[124:125], off
	global_load_dwordx4 v[184:187], v[124:125], off offset:256
	v_or_b32_e32 v124, 16, v120
	v_ashrrev_i32_e32 v125, 31, v124
	v_lshlrev_b64 v[222:223], 11, v[124:125]
	v_lshl_add_u64 v[124:125], v[122:123], 0, v[222:223]
	global_load_dwordx4 v[180:183], v[124:125], off
	global_load_dwordx4 v[176:179], v[124:125], off offset:256
	v_or_b32_e32 v124, 32, v120
	v_or_b32_e32 v120, 48, v120
	v_ashrrev_i32_e32 v125, 31, v124
	v_ashrrev_i32_e32 v121, 31, v120
	v_lshlrev_b64 v[220:221], 11, v[124:125]
	v_lshlrev_b64 v[218:219], 11, v[120:121]
	s_mov_b64 s[2:3], 0x40000
	v_lshl_add_u64 v[124:125], v[122:123], 0, v[220:221]
	v_lshl_add_u64 v[120:121], v[122:123], 0, v[218:219]
	v_lshl_add_u64 v[216:217], v[226:227], 0, s[2:3]
	s_mov_b64 s[30:31], 0x48000
	global_load_dwordx4 v[172:175], v[124:125], off
	global_load_dwordx4 v[160:163], v[124:125], off offset:256
	global_load_dwordx4 v[156:159], v[120:121], off
	global_load_dwordx4 v[152:155], v[120:121], off offset:256
	v_lshl_add_u64 v[120:121], v[122:123], 0, v[216:217]
	v_lshl_add_u64 v[214:215], v[226:227], 0, s[30:31]
	s_mov_b64 s[30:31], 0x50000
	global_load_dwordx4 v[148:151], v[120:121], off
	global_load_dwordx4 v[140:143], v[120:121], off offset:256
	v_lshl_add_u64 v[120:121], v[122:123], 0, v[214:215]
	v_lshl_add_u64 v[212:213], v[226:227], 0, s[30:31]
	s_mov_b64 s[30:31], 0x58000
	global_load_dwordx4 v[144:147], v[120:121], off
	global_load_dwordx4 v[136:139], v[120:121], off offset:256
	v_lshl_add_u64 v[120:121], v[122:123], 0, v[212:213]
	v_lshl_add_u64 v[210:211], v[226:227], 0, s[30:31]
	global_load_dwordx4 v[132:135], v[120:121], off
	global_load_dwordx4 v[128:131], v[120:121], off offset:256
	v_lshl_add_u64 v[120:121], v[122:123], 0, v[210:211]
	global_load_dwordx4 v[124:127], v[120:121], off
	s_nop 0
	global_load_dwordx4 v[120:123], v[120:121], off offset:256
	s_waitcnt vmcnt(0) lgkmcnt(0)
	v_lshlrev_b32_e32 v254, 16, v250
	v_fmac_f32_e32 v254, v235, v168
	v_and_b32_e32 v168, 0xffff0000, v250
	v_fmac_f32_e32 v168, v235, v169
	v_lshlrev_b32_e32 v169, 16, v251
	v_fmac_f32_e32 v169, v235, v170
	v_and_b32_e32 v170, 0xffff0000, v251
	v_fmac_f32_e32 v170, v235, v171
	v_cvt_pk_bf16_f32 v168, v254, v168
	v_cvt_pk_bf16_f32 v169, v169, v170
	v_lshlrev_b32_e32 v170, 16, v252
	v_fmac_f32_e32 v170, v235, v164
	v_and_b32_e32 v164, 0xffff0000, v252
	v_fmac_f32_e32 v164, v235, v165
	v_cvt_pk_bf16_f32 v170, v170, v164
	v_lshlrev_b32_e32 v164, 16, v253
	v_and_b32_e32 v165, 0xffff0000, v253
	v_fmac_f32_e32 v164, v235, v166
	v_fmac_f32_e32 v165, v235, v167
	v_cvt_pk_bf16_f32 v171, v164, v165
	v_lshl_add_u64 v[164:165], s[20:21], 0, v[226:227]
	v_lshl_add_u64 v[164:165], v[164:165], 0, v[224:225]
	v_and_b32_e32 v167, 0xffff0000, v168
	global_store_dwordx4 v[164:165], v[168:171], off
	v_lshlrev_b32_e32 v166, 16, v168
	v_mul_f32_e32 v167, v167, v167
	v_and_b32_e32 v168, 0xffff0000, v169
	v_fmac_f32_e32 v167, v166, v166
	v_lshlrev_b32_e32 v166, 16, v169
	v_mul_f32_e32 v168, v168, v168
	v_fmac_f32_e32 v168, v166, v166
	v_add_f32_e32 v166, v167, v168
	v_and_b32_e32 v168, 0xffff0000, v170
	v_lshlrev_b32_e32 v167, 16, v170
	v_mul_f32_e32 v168, v168, v168
	v_fmac_f32_e32 v168, v167, v167
	v_add_f32_e32 v166, v166, v168
	v_and_b32_e32 v168, 0xffff0000, v171
	v_lshlrev_b32_e32 v167, 16, v171
	v_mul_f32_e32 v168, v168, v168
	v_fmac_f32_e32 v168, v167, v167
	v_lshlrev_b32_e32 v167, 16, v184
	v_fmac_f32_e32 v167, v235, v116
	v_and_b32_e32 v116, 0xffff0000, v184
	v_fmac_f32_e32 v116, v235, v117
	v_lshlrev_b32_e32 v117, 16, v185
	v_fmac_f32_e32 v117, v235, v118
	v_and_b32_e32 v118, 0xffff0000, v185
	v_fmac_f32_e32 v118, v235, v119
	v_cvt_pk_bf16_f32 v116, v167, v116
	v_cvt_pk_bf16_f32 v117, v117, v118
	v_lshlrev_b32_e32 v118, 16, v186
	v_fmac_f32_e32 v118, v235, v112
	v_and_b32_e32 v112, 0xffff0000, v186
	v_fmac_f32_e32 v112, v235, v113
	v_and_b32_e32 v113, 0xffff0000, v187
	v_cvt_pk_bf16_f32 v118, v118, v112
	v_lshlrev_b32_e32 v112, 16, v187
	v_fmac_f32_e32 v113, v235, v115
	v_fmac_f32_e32 v112, v235, v114
	v_cvt_pk_bf16_f32 v119, v112, v113
	v_and_b32_e32 v113, 0xffff0000, v116
	v_lshlrev_b32_e32 v112, 16, v116
	v_mul_f32_e32 v113, v113, v113
	v_and_b32_e32 v114, 0xffff0000, v117
	v_fmac_f32_e32 v113, v112, v112
	v_lshlrev_b32_e32 v112, 16, v117
	v_mul_f32_e32 v114, v114, v114
	v_fmac_f32_e32 v114, v112, v112
	v_add_f32_e32 v112, v113, v114
	v_and_b32_e32 v114, 0xffff0000, v118
	v_lshlrev_b32_e32 v113, 16, v118
	v_mul_f32_e32 v114, v114, v114
	v_fmac_f32_e32 v114, v113, v113
	v_add_f32_e32 v112, v112, v114
	v_and_b32_e32 v114, 0xffff0000, v119
	v_lshlrev_b32_e32 v113, 16, v119
	v_mul_f32_e32 v114, v114, v114
	v_fmac_f32_e32 v114, v113, v113
	v_add_f32_e32 v166, v166, v168
	v_add_f32_e32 v112, v112, v114
	v_add_f32_e32 v112, v166, v112
	ds_bpermute_b32 v113, v237, v112
	global_store_dwordx4 v[164:165], v[116:119], off offset:256
	s_waitcnt lgkmcnt(0)
	v_add_f32_e32 v112, v112, v113
	ds_bpermute_b32 v113, v238, v112
	s_and_saveexec_b64 s[30:31], s[4:5]
	s_cbranch_execz .LBB0_495
	s_waitcnt lgkmcnt(0)
	v_add_f32_e32 v112, v112, v113
	ds_write_b32 v240, v112
.LBB0_495:
	s_or_b64 exec, exec, s[30:31]
	v_lshlrev_b32_e32 v112, 16, v180
	v_fmac_f32_e32 v112, v235, v108
	v_and_b32_e32 v108, 0xffff0000, v180
	v_fmac_f32_e32 v108, v235, v109
	v_lshlrev_b32_e32 v109, 16, v181
	v_fmac_f32_e32 v109, v235, v110
	v_and_b32_e32 v110, 0xffff0000, v181
	v_fmac_f32_e32 v110, v235, v111
	v_cvt_pk_bf16_f32 v108, v112, v108
	v_cvt_pk_bf16_f32 v109, v109, v110
	v_lshlrev_b32_e32 v110, 16, v182
	v_fmac_f32_e32 v110, v235, v104
	v_and_b32_e32 v104, 0xffff0000, v182
	v_fmac_f32_e32 v104, v235, v105
	v_cvt_pk_bf16_f32 v110, v110, v104
	v_lshlrev_b32_e32 v104, 16, v183
	v_and_b32_e32 v105, 0xffff0000, v183
	v_fmac_f32_e32 v104, v235, v106
	v_fmac_f32_e32 v105, v235, v107
	v_cvt_pk_bf16_f32 v111, v104, v105
	v_lshl_add_u64 v[104:105], s[20:21], 0, v[222:223]
	v_lshl_add_u64 v[104:105], v[208:209], 1, v[104:105]
	v_and_b32_e32 v107, 0xffff0000, v108
	global_store_dwordx4 v[104:105], v[108:111], off
	v_lshlrev_b32_e32 v106, 16, v108
	v_mul_f32_e32 v107, v107, v107
	v_and_b32_e32 v108, 0xffff0000, v109
	v_fmac_f32_e32 v107, v106, v106
	v_lshlrev_b32_e32 v106, 16, v109
	v_mul_f32_e32 v108, v108, v108
	v_fmac_f32_e32 v108, v106, v106
	v_add_f32_e32 v106, v107, v108
	v_and_b32_e32 v108, 0xffff0000, v110
	v_lshlrev_b32_e32 v107, 16, v110
	v_mul_f32_e32 v108, v108, v108
	v_fmac_f32_e32 v108, v107, v107
	v_add_f32_e32 v106, v106, v108
	v_and_b32_e32 v108, 0xffff0000, v111
	v_lshlrev_b32_e32 v107, 16, v111
	v_mul_f32_e32 v108, v108, v108
	v_fmac_f32_e32 v108, v107, v107
	v_lshlrev_b32_e32 v107, 16, v176
	v_fmac_f32_e32 v107, v235, v100
	v_and_b32_e32 v100, 0xffff0000, v176
	v_fmac_f32_e32 v100, v235, v101
	v_lshlrev_b32_e32 v101, 16, v177
	v_fmac_f32_e32 v101, v235, v102
	v_and_b32_e32 v102, 0xffff0000, v177
	v_fmac_f32_e32 v102, v235, v103
	v_cvt_pk_bf16_f32 v100, v107, v100
	v_cvt_pk_bf16_f32 v101, v101, v102
	v_lshlrev_b32_e32 v102, 16, v178
	v_fmac_f32_e32 v102, v235, v96
	v_and_b32_e32 v96, 0xffff0000, v178
	v_fmac_f32_e32 v96, v235, v97
	v_and_b32_e32 v97, 0xffff0000, v179
	v_cvt_pk_bf16_f32 v102, v102, v96
	v_lshlrev_b32_e32 v96, 16, v179
	v_fmac_f32_e32 v97, v235, v99
	v_fmac_f32_e32 v96, v235, v98
	v_cvt_pk_bf16_f32 v103, v96, v97
	v_and_b32_e32 v97, 0xffff0000, v100
	v_lshlrev_b32_e32 v96, 16, v100
	v_mul_f32_e32 v97, v97, v97
	v_and_b32_e32 v98, 0xffff0000, v101
	v_fmac_f32_e32 v97, v96, v96
	v_lshlrev_b32_e32 v96, 16, v101
	v_mul_f32_e32 v98, v98, v98
	v_fmac_f32_e32 v98, v96, v96
	v_add_f32_e32 v96, v97, v98
	v_and_b32_e32 v98, 0xffff0000, v102
	v_lshlrev_b32_e32 v97, 16, v102
	v_mul_f32_e32 v98, v98, v98
	v_fmac_f32_e32 v98, v97, v97
	v_add_f32_e32 v96, v96, v98
	v_and_b32_e32 v98, 0xffff0000, v103
	v_lshlrev_b32_e32 v97, 16, v103
	v_mul_f32_e32 v98, v98, v98
	v_fmac_f32_e32 v98, v97, v97
	v_add_f32_e32 v106, v106, v108
	v_add_f32_e32 v96, v96, v98
	v_add_f32_e32 v96, v106, v96
	ds_bpermute_b32 v97, v237, v96
	global_store_dwordx4 v[104:105], v[100:103], off offset:256
	s_waitcnt lgkmcnt(0)
	v_add_f32_e32 v96, v96, v97
	ds_bpermute_b32 v97, v238, v96
	s_and_saveexec_b64 s[30:31], s[4:5]
	s_cbranch_execz .LBB0_497
	s_waitcnt lgkmcnt(0)
	v_add_f32_e32 v96, v96, v97
	ds_write_b32 v241, v96
.LBB0_497:
	s_or_b64 exec, exec, s[30:31]
	v_lshlrev_b32_e32 v96, 16, v172
	v_fmac_f32_e32 v96, v235, v92
	v_and_b32_e32 v92, 0xffff0000, v172
	v_fmac_f32_e32 v92, v235, v93
	v_lshlrev_b32_e32 v93, 16, v173
	v_fmac_f32_e32 v93, v235, v94
	v_and_b32_e32 v94, 0xffff0000, v173
	v_fmac_f32_e32 v94, v235, v95
	v_cvt_pk_bf16_f32 v92, v96, v92
	v_cvt_pk_bf16_f32 v93, v93, v94
	v_lshlrev_b32_e32 v94, 16, v174
	v_fmac_f32_e32 v94, v235, v88
	v_and_b32_e32 v88, 0xffff0000, v174
	v_fmac_f32_e32 v88, v235, v89
	v_cvt_pk_bf16_f32 v94, v94, v88
	v_lshlrev_b32_e32 v88, 16, v175
	v_and_b32_e32 v89, 0xffff0000, v175
	v_fmac_f32_e32 v88, v235, v90
	v_fmac_f32_e32 v89, v235, v91
	v_cvt_pk_bf16_f32 v95, v88, v89
	v_lshl_add_u64 v[88:89], s[20:21], 0, v[220:221]
	v_lshl_add_u64 v[88:89], v[208:209], 1, v[88:89]
	v_and_b32_e32 v91, 0xffff0000, v92
	global_store_dwordx4 v[88:89], v[92:95], off
	v_lshlrev_b32_e32 v90, 16, v92
	v_mul_f32_e32 v91, v91, v91
	v_and_b32_e32 v92, 0xffff0000, v93
	v_fmac_f32_e32 v91, v90, v90
	v_lshlrev_b32_e32 v90, 16, v93
	v_mul_f32_e32 v92, v92, v92
	v_fmac_f32_e32 v92, v90, v90
	v_add_f32_e32 v90, v91, v92
	v_and_b32_e32 v92, 0xffff0000, v94
	v_lshlrev_b32_e32 v91, 16, v94
	v_mul_f32_e32 v92, v92, v92
	v_fmac_f32_e32 v92, v91, v91
	v_add_f32_e32 v90, v90, v92
	v_and_b32_e32 v92, 0xffff0000, v95
	v_lshlrev_b32_e32 v91, 16, v95
	v_mul_f32_e32 v92, v92, v92
	v_fmac_f32_e32 v92, v91, v91
	v_lshlrev_b32_e32 v91, 16, v160
	v_fmac_f32_e32 v91, v235, v84
	v_and_b32_e32 v84, 0xffff0000, v160
	v_fmac_f32_e32 v84, v235, v85
	v_lshlrev_b32_e32 v85, 16, v161
	v_fmac_f32_e32 v85, v235, v86
	v_and_b32_e32 v86, 0xffff0000, v161
	v_fmac_f32_e32 v86, v235, v87
	v_cvt_pk_bf16_f32 v84, v91, v84
	v_cvt_pk_bf16_f32 v85, v85, v86
	v_lshlrev_b32_e32 v86, 16, v162
	v_fmac_f32_e32 v86, v235, v80
	v_and_b32_e32 v80, 0xffff0000, v162
	v_fmac_f32_e32 v80, v235, v81
	v_and_b32_e32 v81, 0xffff0000, v163
	v_cvt_pk_bf16_f32 v86, v86, v80
	v_lshlrev_b32_e32 v80, 16, v163
	v_fmac_f32_e32 v81, v235, v83
	v_fmac_f32_e32 v80, v235, v82
	v_cvt_pk_bf16_f32 v87, v80, v81
	v_and_b32_e32 v81, 0xffff0000, v84
	v_lshlrev_b32_e32 v80, 16, v84
	v_mul_f32_e32 v81, v81, v81
	v_and_b32_e32 v82, 0xffff0000, v85
	v_fmac_f32_e32 v81, v80, v80
	v_lshlrev_b32_e32 v80, 16, v85
	v_mul_f32_e32 v82, v82, v82
	v_fmac_f32_e32 v82, v80, v80
	v_add_f32_e32 v80, v81, v82
	v_and_b32_e32 v82, 0xffff0000, v86
	v_lshlrev_b32_e32 v81, 16, v86
	v_mul_f32_e32 v82, v82, v82
	v_fmac_f32_e32 v82, v81, v81
	v_add_f32_e32 v80, v80, v82
	v_and_b32_e32 v82, 0xffff0000, v87
	v_lshlrev_b32_e32 v81, 16, v87
	v_mul_f32_e32 v82, v82, v82
	v_fmac_f32_e32 v82, v81, v81
	v_add_f32_e32 v90, v90, v92
	v_add_f32_e32 v80, v80, v82
	v_add_f32_e32 v80, v90, v80
	ds_bpermute_b32 v81, v237, v80
	global_store_dwordx4 v[88:89], v[84:87], off offset:256
	s_waitcnt lgkmcnt(0)
	v_add_f32_e32 v80, v80, v81
	ds_bpermute_b32 v81, v238, v80
	s_and_saveexec_b64 s[30:31], s[4:5]
	s_cbranch_execz .LBB0_499
	s_waitcnt lgkmcnt(0)
	v_add_f32_e32 v80, v80, v81
	ds_write_b32 v242, v80
.LBB0_499:
	s_or_b64 exec, exec, s[30:31]
	v_lshlrev_b32_e32 v80, 16, v156
	v_fmac_f32_e32 v80, v235, v76
	v_and_b32_e32 v76, 0xffff0000, v156
	v_fmac_f32_e32 v76, v235, v77
	v_lshlrev_b32_e32 v77, 16, v157
	v_fmac_f32_e32 v77, v235, v78
	v_and_b32_e32 v78, 0xffff0000, v157
	v_fmac_f32_e32 v78, v235, v79
	v_cvt_pk_bf16_f32 v76, v80, v76
	v_cvt_pk_bf16_f32 v77, v77, v78
	v_lshlrev_b32_e32 v78, 16, v158
	v_fmac_f32_e32 v78, v235, v72
	v_and_b32_e32 v72, 0xffff0000, v158
	v_fmac_f32_e32 v72, v235, v73
	v_cvt_pk_bf16_f32 v78, v78, v72
	v_lshlrev_b32_e32 v72, 16, v159
	v_and_b32_e32 v73, 0xffff0000, v159
	v_fmac_f32_e32 v72, v235, v74
	v_fmac_f32_e32 v73, v235, v75
	v_cvt_pk_bf16_f32 v79, v72, v73
	v_lshl_add_u64 v[72:73], s[20:21], 0, v[218:219]
	v_lshl_add_u64 v[72:73], v[208:209], 1, v[72:73]
	v_and_b32_e32 v75, 0xffff0000, v76
	global_store_dwordx4 v[72:73], v[76:79], off
	v_lshlrev_b32_e32 v74, 16, v76
	v_mul_f32_e32 v75, v75, v75
	v_and_b32_e32 v76, 0xffff0000, v77
	v_fmac_f32_e32 v75, v74, v74
	v_lshlrev_b32_e32 v74, 16, v77
	v_mul_f32_e32 v76, v76, v76
	v_fmac_f32_e32 v76, v74, v74
	v_add_f32_e32 v74, v75, v76
	v_and_b32_e32 v76, 0xffff0000, v78
	v_lshlrev_b32_e32 v75, 16, v78
	v_mul_f32_e32 v76, v76, v76
	v_fmac_f32_e32 v76, v75, v75
	v_add_f32_e32 v74, v74, v76
	v_and_b32_e32 v76, 0xffff0000, v79
	v_lshlrev_b32_e32 v75, 16, v79
	v_mul_f32_e32 v76, v76, v76
	v_fmac_f32_e32 v76, v75, v75
	v_lshlrev_b32_e32 v75, 16, v152
	v_fmac_f32_e32 v75, v235, v68
	v_and_b32_e32 v68, 0xffff0000, v152
	v_fmac_f32_e32 v68, v235, v69
	v_lshlrev_b32_e32 v69, 16, v153
	v_fmac_f32_e32 v69, v235, v70
	v_and_b32_e32 v70, 0xffff0000, v153
	v_fmac_f32_e32 v70, v235, v71
	v_cvt_pk_bf16_f32 v68, v75, v68
	v_cvt_pk_bf16_f32 v69, v69, v70
	v_lshlrev_b32_e32 v70, 16, v154
	v_fmac_f32_e32 v70, v235, v64
	v_and_b32_e32 v64, 0xffff0000, v154
	v_fmac_f32_e32 v64, v235, v65
	v_and_b32_e32 v65, 0xffff0000, v155
	v_cvt_pk_bf16_f32 v70, v70, v64
	v_lshlrev_b32_e32 v64, 16, v155
	v_fmac_f32_e32 v65, v235, v67
	v_fmac_f32_e32 v64, v235, v66
	v_cvt_pk_bf16_f32 v71, v64, v65
	v_and_b32_e32 v65, 0xffff0000, v68
	v_lshlrev_b32_e32 v64, 16, v68
	v_mul_f32_e32 v65, v65, v65
	v_and_b32_e32 v66, 0xffff0000, v69
	v_fmac_f32_e32 v65, v64, v64
	v_lshlrev_b32_e32 v64, 16, v69
	v_mul_f32_e32 v66, v66, v66
	v_fmac_f32_e32 v66, v64, v64
	v_add_f32_e32 v64, v65, v66
	v_and_b32_e32 v66, 0xffff0000, v70
	v_lshlrev_b32_e32 v65, 16, v70
	v_mul_f32_e32 v66, v66, v66
	v_fmac_f32_e32 v66, v65, v65
	v_add_f32_e32 v64, v64, v66
	v_and_b32_e32 v66, 0xffff0000, v71
	v_lshlrev_b32_e32 v65, 16, v71
	v_mul_f32_e32 v66, v66, v66
	v_fmac_f32_e32 v66, v65, v65
	v_add_f32_e32 v74, v74, v76
	v_add_f32_e32 v64, v64, v66
	v_add_f32_e32 v64, v74, v64
	ds_bpermute_b32 v65, v237, v64
	global_store_dwordx4 v[72:73], v[68:71], off offset:256
	s_waitcnt lgkmcnt(0)
	v_add_f32_e32 v64, v64, v65
	ds_bpermute_b32 v65, v238, v64
	s_and_saveexec_b64 s[30:31], s[4:5]
	s_cbranch_execz .LBB0_501
	s_waitcnt lgkmcnt(0)
	v_add_f32_e32 v64, v64, v65
	ds_write_b32 v243, v64
.LBB0_501:
	s_or_b64 exec, exec, s[30:31]
	v_lshlrev_b32_e32 v64, 16, v148
	v_fmac_f32_e32 v64, v235, v60
	v_and_b32_e32 v60, 0xffff0000, v148
	v_fmac_f32_e32 v60, v235, v61
	v_lshlrev_b32_e32 v61, 16, v149
	v_fmac_f32_e32 v61, v235, v62
	v_and_b32_e32 v62, 0xffff0000, v149
	v_fmac_f32_e32 v62, v235, v63
	v_cvt_pk_bf16_f32 v60, v64, v60
	v_cvt_pk_bf16_f32 v61, v61, v62
	v_lshlrev_b32_e32 v62, 16, v150
	v_fmac_f32_e32 v62, v235, v56
	v_and_b32_e32 v56, 0xffff0000, v150
	v_fmac_f32_e32 v56, v235, v57
	v_cvt_pk_bf16_f32 v62, v62, v56
	v_lshlrev_b32_e32 v56, 16, v151
	v_and_b32_e32 v57, 0xffff0000, v151
	v_fmac_f32_e32 v56, v235, v58
	v_fmac_f32_e32 v57, v235, v59
	v_cvt_pk_bf16_f32 v63, v56, v57
	v_lshl_add_u64 v[56:57], s[20:21], 0, v[216:217]
	v_lshl_add_u64 v[56:57], v[208:209], 1, v[56:57]
	v_and_b32_e32 v59, 0xffff0000, v60
	global_store_dwordx4 v[56:57], v[60:63], off
	v_lshlrev_b32_e32 v58, 16, v60
	v_mul_f32_e32 v59, v59, v59
	v_and_b32_e32 v60, 0xffff0000, v61
	v_fmac_f32_e32 v59, v58, v58
	v_lshlrev_b32_e32 v58, 16, v61
	v_mul_f32_e32 v60, v60, v60
	v_fmac_f32_e32 v60, v58, v58
	v_add_f32_e32 v58, v59, v60
	v_and_b32_e32 v60, 0xffff0000, v62
	v_lshlrev_b32_e32 v59, 16, v62
	v_mul_f32_e32 v60, v60, v60
	v_fmac_f32_e32 v60, v59, v59
	v_add_f32_e32 v58, v58, v60
	v_and_b32_e32 v60, 0xffff0000, v63
	v_lshlrev_b32_e32 v59, 16, v63
	v_mul_f32_e32 v60, v60, v60
	v_fmac_f32_e32 v60, v59, v59
	v_lshlrev_b32_e32 v59, 16, v140
	v_fmac_f32_e32 v59, v235, v52
	v_and_b32_e32 v52, 0xffff0000, v140
	v_fmac_f32_e32 v52, v235, v53
	v_lshlrev_b32_e32 v53, 16, v141
	v_fmac_f32_e32 v53, v235, v54
	v_and_b32_e32 v54, 0xffff0000, v141
	v_fmac_f32_e32 v54, v235, v55
	v_cvt_pk_bf16_f32 v52, v59, v52
	v_cvt_pk_bf16_f32 v53, v53, v54
	v_lshlrev_b32_e32 v54, 16, v142
	v_fmac_f32_e32 v54, v235, v48
	v_and_b32_e32 v48, 0xffff0000, v142
	v_fmac_f32_e32 v48, v235, v49
	v_and_b32_e32 v49, 0xffff0000, v143
	v_cvt_pk_bf16_f32 v54, v54, v48
	v_lshlrev_b32_e32 v48, 16, v143
	v_fmac_f32_e32 v49, v235, v51
	v_fmac_f32_e32 v48, v235, v50
	v_cvt_pk_bf16_f32 v55, v48, v49
	v_and_b32_e32 v49, 0xffff0000, v52
	v_lshlrev_b32_e32 v48, 16, v52
	v_mul_f32_e32 v49, v49, v49
	v_and_b32_e32 v50, 0xffff0000, v53
	v_fmac_f32_e32 v49, v48, v48
	v_lshlrev_b32_e32 v48, 16, v53
	v_mul_f32_e32 v50, v50, v50
	v_fmac_f32_e32 v50, v48, v48
	v_add_f32_e32 v48, v49, v50
	v_and_b32_e32 v50, 0xffff0000, v54
	v_lshlrev_b32_e32 v49, 16, v54
	v_mul_f32_e32 v50, v50, v50
	v_fmac_f32_e32 v50, v49, v49
	v_add_f32_e32 v48, v48, v50
	v_and_b32_e32 v50, 0xffff0000, v55
	v_lshlrev_b32_e32 v49, 16, v55
	v_mul_f32_e32 v50, v50, v50
	v_fmac_f32_e32 v50, v49, v49
	v_add_f32_e32 v58, v58, v60
	v_add_f32_e32 v48, v48, v50
	v_add_f32_e32 v48, v58, v48
	ds_bpermute_b32 v49, v237, v48
	global_store_dwordx4 v[56:57], v[52:55], off offset:256
	s_waitcnt lgkmcnt(0)
	v_add_f32_e32 v48, v48, v49
	ds_bpermute_b32 v49, v238, v48
	s_and_saveexec_b64 s[30:31], s[4:5]
	s_cbranch_execz .LBB0_503
	s_waitcnt lgkmcnt(0)
	v_add_f32_e32 v48, v48, v49
	ds_write_b32 v244, v48
.LBB0_503:
	s_or_b64 exec, exec, s[30:31]
	v_lshlrev_b32_e32 v48, 16, v144
	v_fmac_f32_e32 v48, v235, v44
	v_and_b32_e32 v44, 0xffff0000, v144
	v_fmac_f32_e32 v44, v235, v45
	v_lshlrev_b32_e32 v45, 16, v145
	v_fmac_f32_e32 v45, v235, v46
	v_and_b32_e32 v46, 0xffff0000, v145
	v_fmac_f32_e32 v46, v235, v47
	v_cvt_pk_bf16_f32 v44, v48, v44
	v_cvt_pk_bf16_f32 v45, v45, v46
	v_lshlrev_b32_e32 v46, 16, v146
	v_fmac_f32_e32 v46, v235, v40
	v_and_b32_e32 v40, 0xffff0000, v146
	v_fmac_f32_e32 v40, v235, v41
	v_cvt_pk_bf16_f32 v46, v46, v40
	v_lshlrev_b32_e32 v40, 16, v147
	v_and_b32_e32 v41, 0xffff0000, v147
	v_fmac_f32_e32 v40, v235, v42
	v_fmac_f32_e32 v41, v235, v43
	v_cvt_pk_bf16_f32 v47, v40, v41
	v_lshl_add_u64 v[40:41], s[20:21], 0, v[214:215]
	v_lshl_add_u64 v[40:41], v[208:209], 1, v[40:41]
	v_and_b32_e32 v43, 0xffff0000, v44
	global_store_dwordx4 v[40:41], v[44:47], off
	v_lshlrev_b32_e32 v42, 16, v44
	v_mul_f32_e32 v43, v43, v43
	v_and_b32_e32 v44, 0xffff0000, v45
	v_fmac_f32_e32 v43, v42, v42
	v_lshlrev_b32_e32 v42, 16, v45
	v_mul_f32_e32 v44, v44, v44
	v_fmac_f32_e32 v44, v42, v42
	v_add_f32_e32 v42, v43, v44
	v_and_b32_e32 v44, 0xffff0000, v46
	v_lshlrev_b32_e32 v43, 16, v46
	v_mul_f32_e32 v44, v44, v44
	v_fmac_f32_e32 v44, v43, v43
	v_add_f32_e32 v42, v42, v44
	v_and_b32_e32 v44, 0xffff0000, v47
	v_lshlrev_b32_e32 v43, 16, v47
	v_mul_f32_e32 v44, v44, v44
	v_fmac_f32_e32 v44, v43, v43
	v_lshlrev_b32_e32 v43, 16, v136
	v_fmac_f32_e32 v43, v235, v36
	v_and_b32_e32 v36, 0xffff0000, v136
	v_fmac_f32_e32 v36, v235, v37
	v_lshlrev_b32_e32 v37, 16, v137
	v_fmac_f32_e32 v37, v235, v38
	v_and_b32_e32 v38, 0xffff0000, v137
	v_fmac_f32_e32 v38, v235, v39
	v_cvt_pk_bf16_f32 v36, v43, v36
	v_cvt_pk_bf16_f32 v37, v37, v38
	v_lshlrev_b32_e32 v38, 16, v138
	v_fmac_f32_e32 v38, v235, v32
	v_and_b32_e32 v32, 0xffff0000, v138
	v_fmac_f32_e32 v32, v235, v33
	v_and_b32_e32 v33, 0xffff0000, v139
	v_cvt_pk_bf16_f32 v38, v38, v32
	v_lshlrev_b32_e32 v32, 16, v139
	v_fmac_f32_e32 v33, v235, v35
	v_fmac_f32_e32 v32, v235, v34
	v_cvt_pk_bf16_f32 v39, v32, v33
	v_and_b32_e32 v33, 0xffff0000, v36
	v_lshlrev_b32_e32 v32, 16, v36
	v_mul_f32_e32 v33, v33, v33
	v_and_b32_e32 v34, 0xffff0000, v37
	v_fmac_f32_e32 v33, v32, v32
	v_lshlrev_b32_e32 v32, 16, v37
	v_mul_f32_e32 v34, v34, v34
	v_fmac_f32_e32 v34, v32, v32
	v_add_f32_e32 v32, v33, v34
	v_and_b32_e32 v34, 0xffff0000, v38
	v_lshlrev_b32_e32 v33, 16, v38
	v_mul_f32_e32 v34, v34, v34
	v_fmac_f32_e32 v34, v33, v33
	v_add_f32_e32 v32, v32, v34
	v_and_b32_e32 v34, 0xffff0000, v39
	v_lshlrev_b32_e32 v33, 16, v39
	v_mul_f32_e32 v34, v34, v34
	v_fmac_f32_e32 v34, v33, v33
	v_add_f32_e32 v42, v42, v44
	v_add_f32_e32 v32, v32, v34
	v_add_f32_e32 v32, v42, v32
	ds_bpermute_b32 v33, v237, v32
	global_store_dwordx4 v[40:41], v[36:39], off offset:256
	s_waitcnt lgkmcnt(0)
	v_add_f32_e32 v32, v32, v33
	ds_bpermute_b32 v33, v238, v32
	s_and_saveexec_b64 s[30:31], s[4:5]
	s_cbranch_execz .LBB0_505
	s_waitcnt lgkmcnt(0)
	v_add_f32_e32 v32, v32, v33
	ds_write_b32 v245, v32
.LBB0_505:
	s_or_b64 exec, exec, s[30:31]
	v_lshlrev_b32_e32 v32, 16, v132
	v_fmac_f32_e32 v32, v235, v28
	v_and_b32_e32 v28, 0xffff0000, v132
	v_fmac_f32_e32 v28, v235, v29
	v_lshlrev_b32_e32 v29, 16, v133
	v_fmac_f32_e32 v29, v235, v30
	v_and_b32_e32 v30, 0xffff0000, v133
	v_fmac_f32_e32 v30, v235, v31
	v_cvt_pk_bf16_f32 v28, v32, v28
	v_cvt_pk_bf16_f32 v29, v29, v30
	v_lshlrev_b32_e32 v30, 16, v134
	v_fmac_f32_e32 v30, v235, v24
	v_and_b32_e32 v24, 0xffff0000, v134
	v_fmac_f32_e32 v24, v235, v25
	v_cvt_pk_bf16_f32 v30, v30, v24
	v_lshlrev_b32_e32 v24, 16, v135
	v_and_b32_e32 v25, 0xffff0000, v135
	v_fmac_f32_e32 v24, v235, v26
	v_fmac_f32_e32 v25, v235, v27
	v_cvt_pk_bf16_f32 v31, v24, v25
	v_lshl_add_u64 v[24:25], s[20:21], 0, v[212:213]
	v_lshl_add_u64 v[24:25], v[208:209], 1, v[24:25]
	v_and_b32_e32 v27, 0xffff0000, v28
	global_store_dwordx4 v[24:25], v[28:31], off
	v_lshlrev_b32_e32 v26, 16, v28
	v_mul_f32_e32 v27, v27, v27
	v_and_b32_e32 v28, 0xffff0000, v29
	v_fmac_f32_e32 v27, v26, v26
	v_lshlrev_b32_e32 v26, 16, v29
	v_mul_f32_e32 v28, v28, v28
	v_fmac_f32_e32 v28, v26, v26
	v_add_f32_e32 v26, v27, v28
	v_and_b32_e32 v28, 0xffff0000, v30
	v_lshlrev_b32_e32 v27, 16, v30
	v_mul_f32_e32 v28, v28, v28
	v_fmac_f32_e32 v28, v27, v27
	v_add_f32_e32 v26, v26, v28
	v_and_b32_e32 v28, 0xffff0000, v31
	v_lshlrev_b32_e32 v27, 16, v31
	v_mul_f32_e32 v28, v28, v28
	v_fmac_f32_e32 v28, v27, v27
	v_lshlrev_b32_e32 v27, 16, v128
	v_fmac_f32_e32 v27, v235, v20
	v_and_b32_e32 v20, 0xffff0000, v128
	v_fmac_f32_e32 v20, v235, v21
	v_lshlrev_b32_e32 v21, 16, v129
	v_fmac_f32_e32 v21, v235, v22
	v_and_b32_e32 v22, 0xffff0000, v129
	v_fmac_f32_e32 v22, v235, v23
	v_cvt_pk_bf16_f32 v20, v27, v20
	v_cvt_pk_bf16_f32 v21, v21, v22
	v_lshlrev_b32_e32 v22, 16, v130
	v_fmac_f32_e32 v22, v235, v16
	v_and_b32_e32 v16, 0xffff0000, v130
	v_fmac_f32_e32 v16, v235, v17
	v_and_b32_e32 v17, 0xffff0000, v131
	v_cvt_pk_bf16_f32 v22, v22, v16
	v_lshlrev_b32_e32 v16, 16, v131
	v_fmac_f32_e32 v17, v235, v19
	v_fmac_f32_e32 v16, v235, v18
	v_cvt_pk_bf16_f32 v23, v16, v17
	v_and_b32_e32 v17, 0xffff0000, v20
	v_lshlrev_b32_e32 v16, 16, v20
	v_mul_f32_e32 v17, v17, v17
	v_and_b32_e32 v18, 0xffff0000, v21
	v_fmac_f32_e32 v17, v16, v16
	v_lshlrev_b32_e32 v16, 16, v21
	v_mul_f32_e32 v18, v18, v18
	v_fmac_f32_e32 v18, v16, v16
	v_add_f32_e32 v16, v17, v18
	v_and_b32_e32 v18, 0xffff0000, v22
	v_lshlrev_b32_e32 v17, 16, v22
	v_mul_f32_e32 v18, v18, v18
	v_fmac_f32_e32 v18, v17, v17
	v_add_f32_e32 v16, v16, v18
	v_and_b32_e32 v18, 0xffff0000, v23
	v_lshlrev_b32_e32 v17, 16, v23
	v_mul_f32_e32 v18, v18, v18
	v_fmac_f32_e32 v18, v17, v17
	v_add_f32_e32 v26, v26, v28
	v_add_f32_e32 v16, v16, v18
	v_add_f32_e32 v16, v26, v16
	ds_bpermute_b32 v17, v237, v16
	global_store_dwordx4 v[24:25], v[20:23], off offset:256
	s_waitcnt lgkmcnt(0)
	v_add_f32_e32 v16, v16, v17
	ds_bpermute_b32 v17, v238, v16
	s_and_saveexec_b64 s[30:31], s[4:5]
	s_cbranch_execz .LBB0_507
	s_waitcnt lgkmcnt(0)
	v_add_f32_e32 v16, v16, v17
	ds_write_b32 v246, v16
.LBB0_507:
	s_or_b64 exec, exec, s[30:31]
	v_lshlrev_b32_e32 v16, 16, v124
	v_fmac_f32_e32 v16, v235, v12
	v_and_b32_e32 v12, 0xffff0000, v124
	v_fmac_f32_e32 v12, v235, v13
	v_lshlrev_b32_e32 v13, 16, v125
	v_fmac_f32_e32 v13, v235, v14
	v_and_b32_e32 v14, 0xffff0000, v125
	v_fmac_f32_e32 v14, v235, v15
	v_cvt_pk_bf16_f32 v12, v16, v12
	v_cvt_pk_bf16_f32 v13, v13, v14
	v_lshlrev_b32_e32 v14, 16, v126
	v_fmac_f32_e32 v14, v235, v8
	v_and_b32_e32 v8, 0xffff0000, v126
	v_fmac_f32_e32 v8, v235, v9
	v_cvt_pk_bf16_f32 v14, v14, v8
	v_lshlrev_b32_e32 v8, 16, v127
	v_and_b32_e32 v9, 0xffff0000, v127
	v_fmac_f32_e32 v8, v235, v10
	v_fmac_f32_e32 v9, v235, v11
	v_cvt_pk_bf16_f32 v15, v8, v9
	v_lshl_add_u64 v[8:9], s[20:21], 0, v[210:211]
	v_lshl_add_u64 v[8:9], v[208:209], 1, v[8:9]
	v_and_b32_e32 v11, 0xffff0000, v12
	global_store_dwordx4 v[8:9], v[12:15], off
	v_lshlrev_b32_e32 v10, 16, v12
	v_mul_f32_e32 v11, v11, v11
	v_and_b32_e32 v12, 0xffff0000, v13
	v_fmac_f32_e32 v11, v10, v10
	v_lshlrev_b32_e32 v10, 16, v13
	v_mul_f32_e32 v12, v12, v12
	v_fmac_f32_e32 v12, v10, v10
	v_add_f32_e32 v10, v11, v12
	v_and_b32_e32 v12, 0xffff0000, v14
	v_lshlrev_b32_e32 v11, 16, v14
	v_mul_f32_e32 v12, v12, v12
	v_fmac_f32_e32 v12, v11, v11
	v_add_f32_e32 v10, v10, v12
	v_and_b32_e32 v12, 0xffff0000, v15
	v_lshlrev_b32_e32 v11, 16, v15
	v_mul_f32_e32 v12, v12, v12
	v_fmac_f32_e32 v12, v11, v11
	v_lshlrev_b32_e32 v11, 16, v120
	v_fmac_f32_e32 v11, v235, v4
	v_and_b32_e32 v4, 0xffff0000, v120
	v_fmac_f32_e32 v4, v235, v5
	v_lshlrev_b32_e32 v5, 16, v121
	v_fmac_f32_e32 v5, v235, v6
	v_and_b32_e32 v6, 0xffff0000, v121
	v_fmac_f32_e32 v6, v235, v7
	v_cvt_pk_bf16_f32 v4, v11, v4
	v_cvt_pk_bf16_f32 v5, v5, v6
	v_lshlrev_b32_e32 v6, 16, v122
	v_fmac_f32_e32 v6, v235, v0
	v_and_b32_e32 v0, 0xffff0000, v122
	v_fmac_f32_e32 v0, v235, v1
	v_and_b32_e32 v1, 0xffff0000, v123
	v_cvt_pk_bf16_f32 v6, v6, v0
	v_lshlrev_b32_e32 v0, 16, v123
	v_fmac_f32_e32 v1, v235, v3
	v_fmac_f32_e32 v0, v235, v2
	v_cvt_pk_bf16_f32 v7, v0, v1
	v_and_b32_e32 v1, 0xffff0000, v4
	v_lshlrev_b32_e32 v0, 16, v4
	v_mul_f32_e32 v1, v1, v1
	v_and_b32_e32 v2, 0xffff0000, v5
	v_fmac_f32_e32 v1, v0, v0
	v_lshlrev_b32_e32 v0, 16, v5
	v_mul_f32_e32 v2, v2, v2
	v_fmac_f32_e32 v2, v0, v0
	v_add_f32_e32 v0, v1, v2
	v_and_b32_e32 v2, 0xffff0000, v6
	v_lshlrev_b32_e32 v1, 16, v6
	v_mul_f32_e32 v2, v2, v2
	v_fmac_f32_e32 v2, v1, v1
	v_add_f32_e32 v0, v0, v2
	v_and_b32_e32 v2, 0xffff0000, v7
	v_lshlrev_b32_e32 v1, 16, v7
	v_mul_f32_e32 v2, v2, v2
	v_fmac_f32_e32 v2, v1, v1
	v_add_f32_e32 v10, v10, v12
	v_add_f32_e32 v0, v0, v2
	v_add_f32_e32 v0, v10, v0
	ds_bpermute_b32 v1, v237, v0
	global_store_dwordx4 v[8:9], v[4:7], off offset:256
	s_waitcnt lgkmcnt(0)
	v_add_f32_e32 v0, v0, v1
	ds_bpermute_b32 v1, v238, v0
	s_and_saveexec_b64 s[30:31], s[4:5]
	s_cbranch_execz .LBB0_509
	s_waitcnt lgkmcnt(0)
	v_add_f32_e32 v0, v0, v1
	ds_write_b32 v247, v0
.LBB0_509:
	s_or_b64 exec, exec, s[30:31]
	s_waitcnt lgkmcnt(0)
	s_barrier
	s_and_saveexec_b64 s[30:31], s[6:7]
	s_cbranch_execz .LBB0_511
	s_waitcnt lgkmcnt(0)
	ds_read_b128 v[0:3], v249
	s_waitcnt lgkmcnt(0)
	v_mov_b32_e32 v4, v1
	v_mov_b32_e32 v5, v2
	v_mov_b32_e32 v1, v3
	v_pk_add_f32 v[0:1], v[4:5], v[0:1]
	s_nop 0
	v_add_f32_e32 v2, v0, v1
	v_add_u32_e32 v0, s17, v239
	v_ashrrev_i32_e32 v1, 31, v0
	s_ashr_i32 s17, s16, 31
	v_lshl_add_u64 v[0:1], v[0:1], 4, s[22:23]
	v_lshl_add_u64 v[0:1], s[16:17], 2, v[0:1]
	global_store_dword v[0:1], v2, off

.LBB0_531:
	v_lshl_add_u32 v154, s54, 12, v145
	ds_read_b128 v[96:99], v154
	s_waitcnt lgkmcnt(0)
	v_mov_b32_e32 v150, v97
	v_mov_b32_e32 v151, v98
	v_mov_b32_e32 v97, v99
	v_pk_add_f32 v[96:97], v[150:151], v[96:97]
	v_lshl_add_u32 v151, s24, 8, v139
	v_add_f32_e32 v96, v96, v97
	v_fmamk_f32 v96, v96, 0x3a800000, v229
	v_rsq_f32_e32 v150, v96
	ds_read_b128 v[96:99], v154 offset:256
	v_pk_mul_f32 v[128:129], v[128:129], v[150:151] op_sel_hi:[1,0]
	v_pk_mul_f32 v[124:125], v[124:125], v[150:151] op_sel_hi:[1,0]
	s_waitcnt lgkmcnt(0)
	v_mov_b32_e32 v152, v97
	v_mov_b32_e32 v153, v98
	v_mov_b32_e32 v97, v99
	v_pk_add_f32 v[96:97], v[152:153], v[96:97]
	v_pk_mul_f32 v[124:125], v[124:125], v[128:129]
	v_add_f32_e32 v96, v96, v97
	v_fmamk_f32 v96, v96, 0x3a800000, v229
	v_rsq_f32_e32 v148, v96
	ds_read_b128 v[96:99], v154 offset:512
	v_pk_mul_f32 v[128:129], v[128:129], s[68:69] op_sel_hi:[1,0]
	v_pk_mul_f32 v[126:127], v[126:127], v[150:151] op_sel_hi:[1,0]
	v_exp_f32_e32 v128, v128
	v_exp_f32_e32 v129, v129
	s_waitcnt lgkmcnt(0)
	v_mov_b32_e32 v152, v97
	v_mov_b32_e32 v153, v98
	v_mov_b32_e32 v97, v99
	v_pk_add_f32 v[96:97], v[152:153], v[96:97]
	v_pk_add_f32 v[128:129], v[128:129], 1.0 op_sel_hi:[1,0]
	v_add_f32_e32 v96, v96, v97
	v_fmamk_f32 v96, v96, 0x3a800000, v229
	v_rsq_f32_e32 v146, v96
	ds_read_b128 v[96:99], v154 offset:768
	v_rcp_f32_e32 v128, v128
	v_rcp_f32_e32 v129, v129
	v_pk_mul_f32 v[120:121], v[120:121], v[150:151] op_sel_hi:[1,0]
	v_pk_mul_f32 v[116:117], v[116:117], v[150:151] op_sel_hi:[1,0]
	s_waitcnt lgkmcnt(0)
	v_mov_b32_e32 v152, v97
	v_mov_b32_e32 v153, v98
	v_mov_b32_e32 v97, v99
	v_pk_add_f32 v[96:97], v[152:153], v[96:97]
	v_pk_mul_f32 v[124:125], v[124:125], v[128:129]
	v_add_f32_e32 v96, v96, v97
	v_fmamk_f32 v96, v96, 0x3a800000, v229
	v_rsq_f32_e32 v144, v96
	ds_read_b128 v[96:99], v154 offset:2048
	v_pk_mul_f32 v[128:129], v[130:131], v[150:151] op_sel_hi:[1,0]
	v_pk_mul_f32 v[116:117], v[120:121], v[116:117]
	v_pk_mul_f32 v[126:127], v[128:129], v[126:127]
	v_pk_mul_f32 v[128:129], v[128:129], s[68:69] op_sel_hi:[1,0]
	s_waitcnt lgkmcnt(0)
	v_mov_b32_e32 v152, v97
	v_mov_b32_e32 v153, v98
	v_mov_b32_e32 v97, v99
	v_pk_add_f32 v[96:97], v[152:153], v[96:97]
	v_pk_mul_f32 v[120:121], v[120:121], s[68:69] op_sel_hi:[1,0]
	v_add_f32_e32 v96, v96, v97
	v_fmamk_f32 v96, v96, 0x3a800000, v229
	v_rsq_f32_e32 v142, v96
	ds_read_b128 v[96:99], v154 offset:2304
	v_exp_f32_e32 v128, v128
	v_exp_f32_e32 v129, v129
	v_exp_f32_e32 v120, v120
	v_exp_f32_e32 v121, v121
	s_waitcnt lgkmcnt(0)
	v_mov_b32_e32 v152, v97
	v_mov_b32_e32 v153, v98
	v_mov_b32_e32 v97, v99
	v_pk_add_f32 v[96:97], v[152:153], v[96:97]
	v_pk_mul_f32 v[112:113], v[112:113], v[148:149] op_sel_hi:[1,0]
	v_add_f32_e32 v96, v96, v97
	v_fmamk_f32 v96, v96, 0x3a800000, v229
	v_rsq_f32_e32 v140, v96
	ds_read_b128 v[96:99], v154 offset:2560
	v_pk_mul_f32 v[108:109], v[108:109], v[148:149] op_sel_hi:[1,0]
	v_pk_add_f32 v[128:129], v[128:129], 1.0 op_sel_hi:[1,0]
	v_pk_mul_f32 v[108:109], v[108:109], v[112:113]
	v_pk_mul_f32 v[112:113], v[112:113], s[68:69] op_sel_hi:[1,0]
	v_pk_add_f32 v[120:121], v[120:121], 1.0 op_sel_hi:[1,0]
	v_exp_f32_e32 v112, v112
	v_exp_f32_e32 v113, v113
	v_rcp_f32_e32 v128, v128
	v_rcp_f32_e32 v129, v129
	v_rcp_f32_e32 v120, v120
	v_rcp_f32_e32 v121, v121
	s_waitcnt lgkmcnt(0)
	v_mov_b32_e32 v152, v97
	v_mov_b32_e32 v153, v98
	v_mov_b32_e32 v97, v99
	v_pk_add_f32 v[96:97], v[152:153], v[96:97]
	v_pk_add_f32 v[112:113], v[112:113], 1.0 op_sel_hi:[1,0]
	v_add_f32_e32 v96, v96, v97
	v_fmamk_f32 v96, v96, 0x3a800000, v229
	v_pk_mul_f32 v[126:127], v[126:127], v[128:129]
	v_pk_mul_f32 v[116:117], v[116:117], v[120:121]
	v_rcp_f32_e32 v112, v112
	v_rcp_f32_e32 v113, v113
	v_rsq_f32_e32 v138, v96
	ds_read_b128 v[96:99], v154 offset:2816
	v_cvt_pk_bf16_f32 v124, v124, v125
	v_cvt_pk_bf16_f32 v125, v126, v127
	v_cvt_pk_bf16_f32 v126, v116, v117
	v_pk_mul_f32 v[116:117], v[122:123], v[150:151] op_sel_hi:[1,0]
	v_pk_mul_f32 v[118:119], v[118:119], v[150:151] op_sel_hi:[1,0]
	v_pk_mul_f32 v[108:109], v[108:109], v[112:113]
	v_pk_mul_f32 v[118:119], v[116:117], v[118:119]
	v_pk_mul_f32 v[116:117], v[116:117], s[68:69] op_sel_hi:[1,0]
	v_pk_mul_f32 v[112:113], v[114:115], v[148:149] op_sel_hi:[1,0]
	v_exp_f32_e32 v116, v116
	v_exp_f32_e32 v117, v117
	v_pk_mul_f32 v[110:111], v[110:111], v[148:149] op_sel_hi:[1,0]
	v_pk_mul_f32 v[104:105], v[104:105], v[148:149] op_sel_hi:[1,0]
	v_pk_mul_f32 v[100:101], v[100:101], v[148:149] op_sel_hi:[1,0]
	v_pk_mul_f32 v[110:111], v[112:113], v[110:111]
	v_pk_mul_f32 v[112:113], v[112:113], s[68:69] op_sel_hi:[1,0]
	v_pk_mul_f32 v[100:101], v[104:105], v[100:101]
	v_pk_mul_f32 v[104:105], v[104:105], s[68:69] op_sel_hi:[1,0]
	v_exp_f32_e32 v112, v112
	v_exp_f32_e32 v113, v113
	v_exp_f32_e32 v104, v104
	v_exp_f32_e32 v105, v105
	v_pk_add_f32 v[116:117], v[116:117], 1.0 op_sel_hi:[1,0]
	v_pk_mul_f32 v[92:93], v[92:93], v[146:147] op_sel_hi:[1,0]
	v_rcp_f32_e32 v116, v116
	v_rcp_f32_e32 v117, v117
	v_pk_mul_f32 v[88:89], v[88:89], v[146:147] op_sel_hi:[1,0]
	v_pk_add_f32 v[112:113], v[112:113], 1.0 op_sel_hi:[1,0]
	v_pk_mul_f32 v[88:89], v[88:89], v[92:93]
	v_pk_mul_f32 v[92:93], v[92:93], s[68:69] op_sel_hi:[1,0]
	v_pk_add_f32 v[104:105], v[104:105], 1.0 op_sel_hi:[1,0]
	v_exp_f32_e32 v92, v92
	v_exp_f32_e32 v93, v93
	v_rcp_f32_e32 v112, v112
	v_rcp_f32_e32 v113, v113
	v_rcp_f32_e32 v104, v104
	v_rcp_f32_e32 v105, v105
	v_lshl_or_b32 v152, s1, 7, v147
	v_pk_mul_f32 v[116:117], v[118:119], v[116:117]
	v_ashrrev_i32_e32 v153, 31, v152
	v_cvt_pk_bf16_f32 v127, v116, v117
	v_mov_b64_e32 v[116:117], s[8:9]
	v_mad_i64_i32 v[120:121], s[0:1], v151, s42, v[116:117]
	v_lshlrev_b64 v[118:119], 1, v[152:153]
	v_pk_add_f32 v[92:93], v[92:93], 1.0 op_sel_hi:[1,0]
	v_lshl_add_u64 v[120:121], v[120:121], 0, v[118:119]
	v_pk_mul_f32 v[110:111], v[110:111], v[112:113]
	v_pk_mul_f32 v[100:101], v[100:101], v[104:105]
	v_rcp_f32_e32 v92, v92
	v_rcp_f32_e32 v93, v93
	global_store_dwordx4 v[120:121], v[124:127], off sc1
	v_cvt_pk_bf16_f32 v108, v108, v109
	v_cvt_pk_bf16_f32 v109, v110, v111
	v_cvt_pk_bf16_f32 v110, v100, v101
	v_pk_mul_f32 v[100:101], v[106:107], v[148:149] op_sel_hi:[1,0]
	v_pk_mul_f32 v[102:103], v[102:103], v[148:149] op_sel_hi:[1,0]
	v_pk_mul_f32 v[88:89], v[88:89], v[92:93]
	v_pk_mul_f32 v[102:103], v[100:101], v[102:103]
	v_pk_mul_f32 v[100:101], v[100:101], s[68:69] op_sel_hi:[1,0]
	v_pk_mul_f32 v[92:93], v[94:95], v[146:147] op_sel_hi:[1,0]
	v_exp_f32_e32 v100, v100
	v_exp_f32_e32 v101, v101
	v_pk_mul_f32 v[90:91], v[90:91], v[146:147] op_sel_hi:[1,0]
	v_pk_mul_f32 v[84:85], v[84:85], v[146:147] op_sel_hi:[1,0]
	v_pk_mul_f32 v[80:81], v[80:81], v[146:147] op_sel_hi:[1,0]
	v_pk_mul_f32 v[90:91], v[92:93], v[90:91]
	v_pk_mul_f32 v[92:93], v[92:93], s[68:69] op_sel_hi:[1,0]
	v_pk_mul_f32 v[80:81], v[84:85], v[80:81]
	v_pk_mul_f32 v[84:85], v[84:85], s[68:69] op_sel_hi:[1,0]
	v_exp_f32_e32 v92, v92
	v_exp_f32_e32 v93, v93
	v_exp_f32_e32 v84, v84
	v_exp_f32_e32 v85, v85
	v_pk_add_f32 v[100:101], v[100:101], 1.0 op_sel_hi:[1,0]
	v_pk_mul_f32 v[76:77], v[76:77], v[144:145] op_sel_hi:[1,0]
	v_rcp_f32_e32 v100, v100
	v_rcp_f32_e32 v101, v101
	v_pk_mul_f32 v[72:73], v[72:73], v[144:145] op_sel_hi:[1,0]
	v_pk_add_f32 v[92:93], v[92:93], 1.0 op_sel_hi:[1,0]
	v_pk_mul_f32 v[72:73], v[72:73], v[76:77]
	v_pk_mul_f32 v[76:77], v[76:77], s[68:69] op_sel_hi:[1,0]
	v_pk_add_f32 v[84:85], v[84:85], 1.0 op_sel_hi:[1,0]
	v_exp_f32_e32 v76, v76
	v_exp_f32_e32 v77, v77
	v_rcp_f32_e32 v92, v92
	v_rcp_f32_e32 v93, v93
	v_rcp_f32_e32 v84, v84
	v_rcp_f32_e32 v85, v85
	v_pk_mul_f32 v[100:101], v[102:103], v[100:101]
	v_pk_add_f32 v[76:77], v[76:77], 1.0 op_sel_hi:[1,0]
	v_cvt_pk_bf16_f32 v111, v100, v101
	v_or_b32_e32 v100, 16, v151
	v_mad_i64_i32 v[100:101], s[0:1], v100, s42, v[116:117]
	v_lshl_add_u64 v[100:101], v[100:101], 0, v[118:119]
	v_pk_mul_f32 v[90:91], v[90:91], v[92:93]
	v_pk_mul_f32 v[80:81], v[80:81], v[84:85]
	v_rcp_f32_e32 v76, v76
	v_rcp_f32_e32 v77, v77
	global_store_dwordx4 v[100:101], v[108:111], off sc1
	v_cvt_pk_bf16_f32 v88, v88, v89
	v_cvt_pk_bf16_f32 v89, v90, v91
	v_cvt_pk_bf16_f32 v90, v80, v81
	v_pk_mul_f32 v[80:81], v[86:87], v[146:147] op_sel_hi:[1,0]
	v_pk_mul_f32 v[82:83], v[82:83], v[146:147] op_sel_hi:[1,0]
	v_pk_mul_f32 v[72:73], v[72:73], v[76:77]
	v_pk_mul_f32 v[82:83], v[80:81], v[82:83]
	v_pk_mul_f32 v[80:81], v[80:81], s[68:69] op_sel_hi:[1,0]
	v_pk_mul_f32 v[76:77], v[78:79], v[144:145] op_sel_hi:[1,0]
	v_exp_f32_e32 v80, v80
	v_exp_f32_e32 v81, v81
	v_pk_mul_f32 v[74:75], v[74:75], v[144:145] op_sel_hi:[1,0]
	v_pk_mul_f32 v[68:69], v[68:69], v[144:145] op_sel_hi:[1,0]
	v_pk_mul_f32 v[64:65], v[64:65], v[144:145] op_sel_hi:[1,0]
	v_pk_mul_f32 v[74:75], v[76:77], v[74:75]
	v_pk_mul_f32 v[76:77], v[76:77], s[68:69] op_sel_hi:[1,0]
	v_pk_mul_f32 v[64:65], v[68:69], v[64:65]
	v_pk_mul_f32 v[68:69], v[68:69], s[68:69] op_sel_hi:[1,0]
	v_exp_f32_e32 v76, v76
	v_exp_f32_e32 v77, v77
	v_exp_f32_e32 v68, v68
	v_exp_f32_e32 v69, v69
	v_pk_add_f32 v[80:81], v[80:81], 1.0 op_sel_hi:[1,0]
	v_pk_add_f32 v[76:77], v[76:77], 1.0 op_sel_hi:[1,0]
	v_rcp_f32_e32 v80, v80
	v_rcp_f32_e32 v81, v81
	v_pk_add_f32 v[68:69], v[68:69], 1.0 op_sel_hi:[1,0]
	v_rcp_f32_e32 v76, v76
	v_rcp_f32_e32 v77, v77
	v_rcp_f32_e32 v68, v68
	v_rcp_f32_e32 v69, v69
	v_pk_mul_f32 v[80:81], v[82:83], v[80:81]
	v_pk_mul_f32 v[74:75], v[74:75], v[76:77]
	v_cvt_pk_bf16_f32 v91, v80, v81
	v_or_b32_e32 v80, 32, v151
	v_mad_i64_i32 v[80:81], s[0:1], v80, s42, v[116:117]
	v_lshl_add_u64 v[80:81], v[80:81], 0, v[118:119]
	v_pk_mul_f32 v[64:65], v[64:65], v[68:69]
	global_store_dwordx4 v[80:81], v[88:91], off sc1
	v_cvt_pk_bf16_f32 v72, v72, v73
	v_cvt_pk_bf16_f32 v73, v74, v75
	v_cvt_pk_bf16_f32 v74, v64, v65
	v_pk_mul_f32 v[64:65], v[70:71], v[144:145] op_sel_hi:[1,0]
	v_pk_mul_f32 v[66:67], v[66:67], v[144:145] op_sel_hi:[1,0]
	s_nop 0
	v_pk_mul_f32 v[66:67], v[64:65], v[66:67]
	v_pk_mul_f32 v[64:65], v[64:65], s[68:69] op_sel_hi:[1,0]
	s_nop 0
	v_exp_f32_e32 v64, v64
	v_exp_f32_e32 v65, v65
	s_nop 0
	v_pk_add_f32 v[64:65], v[64:65], 1.0 op_sel_hi:[1,0]
	s_nop 0
	v_rcp_f32_e32 v64, v64
	v_rcp_f32_e32 v65, v65
	s_nop 0
	v_pk_mul_f32 v[64:65], v[66:67], v[64:65]
	s_nop 0
	v_cvt_pk_bf16_f32 v75, v64, v65
	v_or_b32_e32 v64, 48, v151
	v_mad_i64_i32 v[64:65], s[0:1], v64, s42, v[116:117]
	v_lshl_add_u64 v[64:65], v[64:65], 0, v[118:119]
	global_store_dwordx4 v[64:65], v[72:75], off sc1
	v_add_u32_e32 v64, 0x80, v151
	v_pk_mul_f32 v[60:61], v[60:61], v[142:143] op_sel_hi:[1,0]
	v_pk_mul_f32 v[56:57], v[56:57], v[142:143] op_sel_hi:[1,0]
	v_pk_mul_f32 v[58:59], v[58:59], v[142:143] op_sel_hi:[1,0]
	v_pk_mul_f32 v[56:57], v[60:61], v[56:57]
	v_pk_mul_f32 v[60:61], v[60:61], s[68:69] op_sel_hi:[1,0]
	v_pk_mul_f32 v[52:53], v[52:53], v[142:143] op_sel_hi:[1,0]
	v_exp_f32_e32 v60, v60
	v_exp_f32_e32 v61, v61
	v_pk_mul_f32 v[48:49], v[48:49], v[142:143] op_sel_hi:[1,0]
	v_pk_mul_f32 v[44:45], v[44:45], v[140:141] op_sel_hi:[1,0]
	v_pk_mul_f32 v[48:49], v[52:53], v[48:49]
	v_pk_add_f32 v[60:61], v[60:61], 1.0 op_sel_hi:[1,0]
	v_pk_mul_f32 v[52:53], v[52:53], s[68:69] op_sel_hi:[1,0]
	v_rcp_f32_e32 v60, v60
	v_rcp_f32_e32 v61, v61
	v_exp_f32_e32 v52, v52
	v_exp_f32_e32 v53, v53
	v_pk_mul_f32 v[40:41], v[40:41], v[140:141] op_sel_hi:[1,0]
	v_pk_mul_f32 v[56:57], v[56:57], v[60:61]
	v_pk_mul_f32 v[60:61], v[62:63], v[142:143] op_sel_hi:[1,0]
	v_pk_mul_f32 v[40:41], v[40:41], v[44:45]
	v_pk_mul_f32 v[58:59], v[60:61], v[58:59]
	v_pk_mul_f32 v[60:61], v[60:61], s[68:69] op_sel_hi:[1,0]
	v_pk_mul_f32 v[44:45], v[44:45], s[68:69] op_sel_hi:[1,0]
	v_exp_f32_e32 v60, v60
	v_exp_f32_e32 v61, v61
	v_exp_f32_e32 v44, v44
	v_exp_f32_e32 v45, v45
	v_pk_add_f32 v[52:53], v[52:53], 1.0 op_sel_hi:[1,0]
	v_pk_add_f32 v[60:61], v[60:61], 1.0 op_sel_hi:[1,0]
	v_rcp_f32_e32 v52, v52
	v_rcp_f32_e32 v60, v60
	v_rcp_f32_e32 v61, v61
	v_rcp_f32_e32 v53, v53
	v_pk_add_f32 v[44:45], v[44:45], 1.0 op_sel_hi:[1,0]
	v_cvt_pk_bf16_f32 v56, v56, v57
	v_pk_mul_f32 v[58:59], v[58:59], v[60:61]
	v_rcp_f32_e32 v44, v44
	v_rcp_f32_e32 v45, v45
	v_pk_mul_f32 v[48:49], v[48:49], v[52:53]
	v_cvt_pk_bf16_f32 v57, v58, v59
	v_pk_mul_f32 v[50:51], v[50:51], v[142:143] op_sel_hi:[1,0]
	v_cvt_pk_bf16_f32 v58, v48, v49
	v_pk_mul_f32 v[48:49], v[54:55], v[142:143] op_sel_hi:[1,0]
	v_pk_mul_f32 v[40:41], v[40:41], v[44:45]
	v_pk_mul_f32 v[50:51], v[48:49], v[50:51]
	v_pk_mul_f32 v[48:49], v[48:49], s[68:69] op_sel_hi:[1,0]
	v_pk_mul_f32 v[44:45], v[46:47], v[140:141] op_sel_hi:[1,0]
	v_exp_f32_e32 v48, v48
	v_exp_f32_e32 v49, v49
	v_pk_mul_f32 v[42:43], v[42:43], v[140:141] op_sel_hi:[1,0]
	v_pk_mul_f32 v[36:37], v[36:37], v[140:141] op_sel_hi:[1,0]
	v_pk_mul_f32 v[32:33], v[32:33], v[140:141] op_sel_hi:[1,0]
	v_pk_mul_f32 v[42:43], v[44:45], v[42:43]
	v_pk_mul_f32 v[44:45], v[44:45], s[68:69] op_sel_hi:[1,0]
	v_pk_mul_f32 v[32:33], v[36:37], v[32:33]
	v_pk_mul_f32 v[36:37], v[36:37], s[68:69] op_sel_hi:[1,0]
	v_exp_f32_e32 v44, v44
	v_exp_f32_e32 v45, v45
	v_exp_f32_e32 v36, v36
	v_exp_f32_e32 v37, v37
	v_pk_add_f32 v[48:49], v[48:49], 1.0 op_sel_hi:[1,0]
	v_pk_mul_f32 v[28:29], v[28:29], v[138:139] op_sel_hi:[1,0]
	v_pk_mul_f32 v[24:25], v[24:25], v[138:139] op_sel_hi:[1,0]
	v_rcp_f32_e32 v48, v48
	v_rcp_f32_e32 v49, v49
	v_pk_mul_f32 v[24:25], v[24:25], v[28:29]
	v_pk_mul_f32 v[28:29], v[28:29], s[68:69] op_sel_hi:[1,0]
	v_pk_add_f32 v[44:45], v[44:45], 1.0 op_sel_hi:[1,0]
	v_pk_add_f32 v[36:37], v[36:37], 1.0 op_sel_hi:[1,0]
	v_exp_f32_e32 v28, v28
	v_exp_f32_e32 v29, v29
	v_rcp_f32_e32 v44, v44
	v_rcp_f32_e32 v45, v45
	v_rcp_f32_e32 v36, v36
	v_rcp_f32_e32 v37, v37
	v_pk_mul_f32 v[48:49], v[50:51], v[48:49]
	v_pk_add_f32 v[28:29], v[28:29], 1.0 op_sel_hi:[1,0]
	v_cvt_pk_bf16_f32 v59, v48, v49
	v_mad_i64_i32 v[48:49], s[0:1], v64, s42, v[116:117]
	v_lshl_add_u64 v[48:49], v[48:49], 0, v[118:119]
	v_pk_mul_f32 v[42:43], v[42:43], v[44:45]
	v_pk_mul_f32 v[32:33], v[32:33], v[36:37]
	v_rcp_f32_e32 v28, v28
	v_rcp_f32_e32 v29, v29
	global_store_dwordx4 v[48:49], v[56:59], off sc1
	v_cvt_pk_bf16_f32 v40, v40, v41
	v_cvt_pk_bf16_f32 v41, v42, v43
	v_cvt_pk_bf16_f32 v42, v32, v33
	v_pk_mul_f32 v[32:33], v[38:39], v[140:141] op_sel_hi:[1,0]
	v_pk_mul_f32 v[34:35], v[34:35], v[140:141] op_sel_hi:[1,0]
	v_pk_mul_f32 v[24:25], v[24:25], v[28:29]
	v_pk_mul_f32 v[34:35], v[32:33], v[34:35]
	v_pk_mul_f32 v[32:33], v[32:33], s[68:69] op_sel_hi:[1,0]
	v_pk_mul_f32 v[28:29], v[30:31], v[138:139] op_sel_hi:[1,0]
	v_exp_f32_e32 v32, v32
	v_exp_f32_e32 v33, v33
	v_pk_mul_f32 v[26:27], v[26:27], v[138:139] op_sel_hi:[1,0]
	v_pk_mul_f32 v[20:21], v[20:21], v[138:139] op_sel_hi:[1,0]
	v_pk_mul_f32 v[16:17], v[16:17], v[138:139] op_sel_hi:[1,0]
	v_pk_mul_f32 v[26:27], v[28:29], v[26:27]
	v_pk_mul_f32 v[28:29], v[28:29], s[68:69] op_sel_hi:[1,0]
	v_pk_mul_f32 v[16:17], v[20:21], v[16:17]
	v_pk_mul_f32 v[20:21], v[20:21], s[68:69] op_sel_hi:[1,0]
	v_exp_f32_e32 v28, v28
	v_exp_f32_e32 v29, v29
	v_exp_f32_e32 v20, v20
	v_exp_f32_e32 v21, v21
	v_pk_add_f32 v[32:33], v[32:33], 1.0 op_sel_hi:[1,0]
	v_pk_add_f32 v[28:29], v[28:29], 1.0 op_sel_hi:[1,0]
	v_rcp_f32_e32 v32, v32
	v_rcp_f32_e32 v33, v33
	v_pk_add_f32 v[20:21], v[20:21], 1.0 op_sel_hi:[1,0]
	v_rcp_f32_e32 v28, v28
	v_rcp_f32_e32 v29, v29
	v_rcp_f32_e32 v20, v20
	v_rcp_f32_e32 v21, v21
	v_pk_mul_f32 v[32:33], v[34:35], v[32:33]
	v_pk_mul_f32 v[26:27], v[26:27], v[28:29]
	v_cvt_pk_bf16_f32 v43, v32, v33
	v_add_u32_e32 v32, 0x90, v151
	v_mad_i64_i32 v[32:33], s[0:1], v32, s42, v[116:117]
	v_lshl_add_u64 v[32:33], v[32:33], 0, v[118:119]
	v_pk_mul_f32 v[16:17], v[16:17], v[20:21]
	global_store_dwordx4 v[32:33], v[40:43], off sc1
	v_cvt_pk_bf16_f32 v24, v24, v25
	v_cvt_pk_bf16_f32 v25, v26, v27
	v_cvt_pk_bf16_f32 v26, v16, v17
	v_pk_mul_f32 v[16:17], v[22:23], v[138:139] op_sel_hi:[1,0]
	v_pk_mul_f32 v[18:19], v[18:19], v[138:139] op_sel_hi:[1,0]
	s_mov_b64 s[24:25], -1
	v_pk_mul_f32 v[18:19], v[16:17], v[18:19]
	v_pk_mul_f32 v[16:17], v[16:17], s[68:69] op_sel_hi:[1,0]
	s_andn2_b64 vcc, exec, s[4:5]
	v_exp_f32_e32 v16, v16
	v_exp_f32_e32 v17, v17
	s_nop 0
	v_pk_add_f32 v[16:17], v[16:17], 1.0 op_sel_hi:[1,0]
	s_nop 0
	v_rcp_f32_e32 v16, v16
	v_rcp_f32_e32 v17, v17
	s_nop 0
	v_pk_mul_f32 v[16:17], v[18:19], v[16:17]
	s_nop 0
	v_cvt_pk_bf16_f32 v27, v16, v17
	v_add_u32_e32 v16, 0xa0, v151
	v_mad_i64_i32 v[16:17], s[0:1], v16, s42, v[116:117]
	v_lshl_add_u64 v[16:17], v[16:17], 0, v[118:119]
	global_store_dwordx4 v[16:17], v[24:27], off sc1
	s_waitcnt lgkmcnt(0)
	v_mov_b32_e32 v16, v97
	v_mov_b32_e32 v17, v98
	v_mov_b32_e32 v97, v99
	v_pk_add_f32 v[16:17], v[16:17], v[96:97]
	s_nop 0
	v_add_f32_e32 v16, v16, v17
	v_fmamk_f32 v16, v16, 0x3a800000, v229
	v_rsq_f32_e32 v16, v16
	s_nop 0
	v_pk_mul_f32 v[12:13], v[12:13], v[16:17] op_sel_hi:[1,0]
	v_pk_mul_f32 v[8:9], v[8:9], v[16:17] op_sel_hi:[1,0]
	v_pk_mul_f32 v[10:11], v[10:11], v[16:17] op_sel_hi:[1,0]
	v_pk_mul_f32 v[8:9], v[8:9], v[12:13]
	v_pk_mul_f32 v[12:13], v[12:13], s[68:69] op_sel_hi:[1,0]
	v_pk_mul_f32 v[4:5], v[4:5], v[16:17] op_sel_hi:[1,0]
	v_exp_f32_e32 v12, v12
	v_exp_f32_e32 v13, v13
	v_pk_mul_f32 v[0:1], v[0:1], v[16:17] op_sel_hi:[1,0]
	v_pk_mul_f32 v[2:3], v[2:3], v[16:17] op_sel_hi:[1,0]
	v_pk_mul_f32 v[0:1], v[4:5], v[0:1]
	v_pk_add_f32 v[12:13], v[12:13], 1.0 op_sel_hi:[1,0]
	v_pk_mul_f32 v[4:5], v[4:5], s[68:69] op_sel_hi:[1,0]
	v_rcp_f32_e32 v12, v12
	v_rcp_f32_e32 v13, v13
	v_exp_f32_e32 v4, v4
	v_exp_f32_e32 v5, v5
	v_pk_mul_f32 v[8:9], v[8:9], v[12:13]
	v_pk_mul_f32 v[12:13], v[14:15], v[16:17] op_sel_hi:[1,0]
	v_pk_add_f32 v[4:5], v[4:5], 1.0 op_sel_hi:[1,0]
	v_pk_mul_f32 v[10:11], v[12:13], v[10:11]
	v_pk_mul_f32 v[12:13], v[12:13], s[68:69] op_sel_hi:[1,0]
	v_rcp_f32_e32 v4, v4
	v_exp_f32_e32 v12, v12
	v_exp_f32_e32 v13, v13
	v_rcp_f32_e32 v5, v5
	v_cvt_pk_bf16_f32 v8, v8, v9
	v_pk_add_f32 v[12:13], v[12:13], 1.0 op_sel_hi:[1,0]
	s_nop 0
	v_rcp_f32_e32 v12, v12
	v_rcp_f32_e32 v13, v13
	v_pk_mul_f32 v[0:1], v[0:1], v[4:5]
	v_pk_mul_f32 v[10:11], v[10:11], v[12:13]
	s_nop 0
	v_cvt_pk_bf16_f32 v9, v10, v11
	v_cvt_pk_bf16_f32 v10, v0, v1
	v_pk_mul_f32 v[0:1], v[6:7], v[16:17] op_sel_hi:[1,0]
	s_nop 0
	v_pk_mul_f32 v[2:3], v[0:1], v[2:3]
	v_pk_mul_f32 v[0:1], v[0:1], s[68:69] op_sel_hi:[1,0]
	s_nop 0
	v_exp_f32_e32 v0, v0
	v_exp_f32_e32 v1, v1
	s_nop 0
	v_pk_add_f32 v[0:1], v[0:1], 1.0 op_sel_hi:[1,0]
	s_nop 0
	v_rcp_f32_e32 v0, v0
	v_rcp_f32_e32 v1, v1
	s_nop 0
	v_pk_mul_f32 v[0:1], v[2:3], v[0:1]
	s_nop 0
	v_cvt_pk_bf16_f32 v11, v0, v1
	v_add_u32_e32 v0, 0xb0, v151
	v_mad_i64_i32 v[0:1], s[0:1], v0, s42, v[116:117]
	v_lshl_add_u64 v[0:1], v[0:1], 0, v[118:119]
	global_store_dwordx4 v[0:1], v[8:11], off sc1
	s_cbranch_vccnz .LBB0_522
	s_andn2_b64 vcc, exec, s[6:7]
	s_cbranch_vccnz .LBB0_521
	s_barrier
	s_branch .LBB0_521

.LBB0_538:
	v_ashrrev_i32_e32 v27, 31, v26
	v_lshlrev_b64 v[20:21], 11, v[26:27]
	v_lshl_add_u64 v[20:21], v[16:17], 0, v[20:21]
	global_load_dwordx2 v[42:43], v[20:21], off
	global_load_dwordx2 v[44:45], v[20:21], off offset:512
	global_load_dwordx2 v[46:47], v[20:21], off offset:1024
	global_load_dwordx2 v[48:49], v[20:21], off offset:1536
	v_add_u32_e32 v20, s0, v26
	v_ashrrev_i32_e32 v21, 31, v20
	v_lshlrev_b64 v[22:23], 11, v[20:21]
	v_lshl_add_u64 v[22:23], v[16:17], 0, v[22:23]
	global_load_dwordx2 v[50:51], v[22:23], off
	global_load_dwordx2 v[52:53], v[22:23], off offset:512
	global_load_dwordx2 v[54:55], v[22:23], off offset:1024
	global_load_dwordx2 v[66:67], v[22:23], off offset:1536
	v_add_u32_e32 v24, s1, v26
	v_add_u32_e32 v22, s8, v26
	v_ashrrev_i32_e32 v25, 31, v24
	v_ashrrev_i32_e32 v23, 31, v22
	v_lshlrev_b64 v[26:27], 12, v[26:27]
	v_lshlrev_b64 v[28:29], 11, v[24:25]
	v_lshlrev_b64 v[30:31], 11, v[22:23]
	v_lshl_add_u64 v[70:71], v[18:19], 0, v[26:27]
	v_lshl_add_u64 v[26:27], v[16:17], 0, v[28:29]
	v_lshl_add_u64 v[56:57], v[16:17], 0, v[30:31]
	global_load_dwordx2 v[40:41], v[26:27], off
	global_load_dwordx2 v[38:39], v[26:27], off offset:512
	global_load_dwordx2 v[36:37], v[26:27], off offset:1024
	global_load_dwordx2 v[34:35], v[26:27], off offset:1536
	global_load_dwordx2 v[32:33], v[56:57], off
	global_load_dwordx2 v[30:31], v[56:57], off offset:512
	global_load_dwordx2 v[28:29], v[56:57], off offset:1024
	s_nop 0
	global_load_dwordx2 v[26:27], v[56:57], off offset:1536
	v_lshlrev_b64 v[24:25], 12, v[24:25]
	v_lshlrev_b64 v[22:23], 12, v[22:23]
	s_add_i32 s9, s0, s0
	s_add_i32 s9, s9, s0
	s_waitcnt vmcnt(0) lgkmcnt(0)
	v_and_b32_e32 v69, 0xffff0000, v42
	v_and_b32_e32 v73, 0xffff0000, v43
	v_lshlrev_b32_e32 v68, 16, v42
	v_lshlrev_b32_e32 v72, 16, v43
	v_and_b32_e32 v77, 0xffff0000, v45
	v_and_b32_e32 v76, 0xffff0000, v44
	v_and_b32_e32 v79, 0xffff0000, v46
	v_lshlrev_b32_e32 v83, 16, v48
	v_and_b32_e32 v85, 0xffff0000, v48
	v_mul_f32_e32 v82, v73, v73
	v_mul_f32_e32 v84, v69, v69
	v_lshlrev_b32_e32 v75, 16, v45
	v_lshlrev_b32_e32 v74, 16, v44
	v_lshlrev_b32_e32 v78, 16, v46
	v_lshlrev_b32_e32 v80, 16, v47
	v_and_b32_e32 v81, 0xffff0000, v47
	v_lshlrev_b32_e32 v86, 16, v49
	v_and_b32_e32 v87, 0xffff0000, v49
	v_pk_mul_f32 v[88:89], v[76:77], v[76:77]
	v_mov_b32_e32 v91, v83
	v_mul_f32_e32 v90, v79, v79
	v_lshlrev_b32_e32 v43, 16, v53
	v_and_b32_e32 v49, 0xffff0000, v53
	v_lshlrev_b32_e32 v58, 16, v55
	v_and_b32_e32 v59, 0xffff0000, v55
	v_lshlrev_b32_e32 v55, 16, v66
	v_and_b32_e32 v53, 0xffff0000, v66
	v_lshlrev_b32_e32 v46, 16, v67
	v_and_b32_e32 v47, 0xffff0000, v67
	v_pk_fma_f32 v[66:67], v[72:73], v[72:73], v[82:83] op_sel_hi:[1,1,0]
	v_pk_fma_f32 v[94:95], v[68:69], v[68:69], v[84:85] op_sel_hi:[1,1,0]
	v_mul_f32_e32 v92, v81, v81
	v_pk_fma_f32 v[88:89], v[74:75], v[74:75], v[88:89]
	v_pk_fma_f32 v[96:97], v[78:79], v[78:79], v[90:91] op_sel_hi:[1,1,0]
	v_mov_b32_e32 v82, v94
	v_mov_b32_e32 v90, v66
	v_mul_f32_e32 v98, v85, v85
	v_mul_f32_e32 v99, v86, v86
	v_mul_f32_e32 v100, v87, v87
	v_pk_fma_f32 v[92:93], v[80:81], v[80:81], v[92:93] op_sel_hi:[1,1,0]
	v_pk_add_f32 v[66:67], v[94:95], v[66:67]
	v_pk_add_f32 v[88:89], v[88:89], v[88:89] op_sel:[0,1] op_sel_hi:[1,0]
	v_pk_mul_f32 v[90:91], v[82:83], v[90:91]
	v_mov_b32_e32 v97, v99
	v_mov_b32_e32 v93, v100
	v_mov_b32_e32 v89, v98
	v_mov_b32_e32 v67, v91
	v_pk_add_f32 v[92:93], v[96:97], v[92:93]
	v_pk_add_f32 v[66:67], v[66:67], v[88:89]
	v_lshlrev_b32_e32 v44, 16, v50
	v_pk_add_f32 v[66:67], v[66:67], v[92:93]
	v_and_b32_e32 v45, 0xffff0000, v50
	v_lshlrev_b32_e32 v56, 16, v51
	v_and_b32_e32 v57, 0xffff0000, v51
	v_lshlrev_b32_e32 v50, 16, v54
	v_and_b32_e32 v51, 0xffff0000, v54
	v_add_f32_e32 v54, v66, v67
	ds_bpermute_b32 v82, v60, v54
	v_lshlrev_b32_e32 v42, 16, v52
	v_and_b32_e32 v48, 0xffff0000, v52
	v_mul_f32_e32 v52, v57, v57
	v_pk_fma_f32 v[90:91], v[56:57], v[56:57], v[52:53] op_sel_hi:[1,1,0]
	s_waitcnt lgkmcnt(0)
	v_add_f32_e32 v84, v54, v82
	ds_bpermute_b32 v88, v61, v84
	v_mul_f32_e32 v82, v51, v51
	v_mul_f32_e32 v54, v45, v45
	v_pk_mul_f32 v[66:67], v[48:49], v[48:49]
	v_pk_fma_f32 v[92:93], v[44:45], v[44:45], v[54:55] op_sel_hi:[1,1,0]
	s_waitcnt lgkmcnt(0)
	v_add_f32_e32 v88, v84, v88
	ds_bpermute_b32 v94, v62, v88
	v_mov_b32_e32 v89, v55
	v_mul_f32_e32 v84, v59, v59
	v_pk_fma_f32 v[66:67], v[42:43], v[42:43], v[66:67]
	v_mov_b32_e32 v54, v92
	s_waitcnt lgkmcnt(0)
	v_add_f32_e32 v52, v88, v94
	ds_bpermute_b32 v101, v63, v52
	v_pk_fma_f32 v[94:95], v[50:51], v[50:51], v[82:83] op_sel_hi:[1,1,0]
	v_mov_b32_e32 v88, v90
	v_mul_f32_e32 v98, v53, v53
	v_mul_f32_e32 v99, v46, v46
	s_waitcnt lgkmcnt(0)
	v_add_f32_e32 v52, v52, v101
	ds_bpermute_b32 v82, v64, v52
	v_mul_f32_e32 v100, v47, v47
	v_pk_fma_f32 v[96:97], v[58:59], v[58:59], v[84:85] op_sel_hi:[1,1,0]
	v_pk_add_f32 v[90:91], v[92:93], v[90:91]
	v_pk_add_f32 v[66:67], v[66:67], v[66:67] op_sel:[0,1] op_sel_hi:[1,0]
	s_waitcnt lgkmcnt(0)
	v_add_f32_e32 v52, v52, v82
	ds_bpermute_b32 v82, v65, v52
	v_pk_mul_f32 v[88:89], v[54:55], v[88:89]
	v_mov_b32_e32 v95, v99
	v_mov_b32_e32 v97, v100
	v_mov_b32_e32 v67, v98
	v_mov_b32_e32 v91, v89
	v_pk_add_f32 v[66:67], v[90:91], v[66:67]
	v_pk_add_f32 v[88:89], v[94:95], v[96:97]
	s_waitcnt lgkmcnt(0)
	v_add_f32_e32 v52, v52, v82
	v_pk_add_f32 v[66:67], v[66:67], v[88:89]
	v_fmamk_f32 v52, v52, 0x3a800000, v229
	v_add_f32_e32 v54, v66, v67
	ds_bpermute_b32 v82, v60, v54
	v_rsq_f32_e32 v52, v52
	v_mov_b32_e32 v84, v83
	v_and_b32_e32 v83, 0xffff0000, v34
	s_waitcnt lgkmcnt(0)
	v_add_f32_e32 v54, v54, v82
	v_pk_mul_f32 v[66:67], v[52:53], v[68:69] op_sel_hi:[0,1]
	v_pk_mul_f32 v[68:69], v[52:53], v[72:73] op_sel_hi:[0,1]
	ds_bpermute_b32 v72, v61, v54
	v_pk_mul_f32 v[68:69], v[2:3], v[68:69]
	v_pk_mul_f32 v[66:67], v[0:1], v[66:67]
	global_store_dwordx4 v[70:71], v[66:69], off
	v_lshlrev_b32_e32 v73, 16, v39
	s_waitcnt lgkmcnt(0)
	v_add_f32_e32 v54, v54, v72
	ds_bpermute_b32 v72, v62, v54
	v_mov_b32_e32 v66, v74
	v_mov_b32_e32 v67, v76
	v_mov_b32_e32 v76, v75
	v_pk_mul_f32 v[66:67], v[52:53], v[66:67] op_sel_hi:[0,1]
	s_waitcnt lgkmcnt(0)
	v_add_f32_e32 v54, v54, v72
	ds_bpermute_b32 v72, v63, v54
	v_pk_mul_f32 v[68:69], v[52:53], v[76:77] op_sel_hi:[0,1]
	v_pk_mul_f32 v[68:69], v[6:7], v[68:69]
	v_pk_mul_f32 v[66:67], v[4:5], v[66:67]
	global_store_dwordx4 v[70:71], v[66:69], off offset:1024
	s_waitcnt lgkmcnt(0)
	v_add_f32_e32 v54, v54, v72
	ds_bpermute_b32 v72, v64, v54
	v_pk_mul_f32 v[66:67], v[52:53], v[78:79] op_sel_hi:[0,1]
	v_pk_mul_f32 v[68:69], v[52:53], v[80:81] op_sel_hi:[0,1]
	v_pk_mul_f32 v[68:69], v[10:11], v[68:69]
	v_pk_mul_f32 v[66:67], v[8:9], v[66:67]
	s_waitcnt lgkmcnt(0)
	v_add_f32_e32 v54, v54, v72
	ds_bpermute_b32 v72, v65, v54
	global_store_dwordx4 v[70:71], v[66:69], off offset:2048
	v_lshlrev_b32_e32 v81, 16, v34
	v_and_b32_e32 v39, 0xffff0000, v39
	v_pk_mul_f32 v[66:67], v[84:85], v[52:53] op_sel_hi:[1,0]
	v_pk_mul_f32 v[68:69], v[86:87], v[52:53] op_sel_hi:[1,0]
	v_pk_mul_f32 v[66:67], v[12:13], v[66:67]
	v_pk_mul_f32 v[68:69], v[14:15], v[68:69]
	s_waitcnt lgkmcnt(0)
	v_add_f32_e32 v52, v54, v72
	global_store_dwordx4 v[70:71], v[66:69], off offset:3072
	v_fmamk_f32 v52, v52, 0x3a800000, v229
	v_rsq_f32_e32 v54, v52
	v_lshlrev_b32_e32 v68, 16, v40
	v_and_b32_e32 v69, 0xffff0000, v40
	v_lshlrev_b32_e32 v40, 16, v41
	v_and_b32_e32 v41, 0xffff0000, v41
	v_mul_f32_e32 v52, v41, v41
	v_mul_f32_e32 v34, v69, v69
	v_pk_fma_f32 v[70:71], v[40:41], v[40:41], v[52:53] op_sel_hi:[1,1,0]
	v_lshlrev_b32_e32 v72, 16, v38
	v_and_b32_e32 v38, 0xffff0000, v38
	v_lshlrev_b32_e32 v84, 16, v35
	v_and_b32_e32 v85, 0xffff0000, v35
	v_pk_fma_f32 v[34:35], v[68:69], v[68:69], v[34:35] op_sel_hi:[1,1,0]
	v_pk_mul_f32 v[74:75], v[38:39], v[38:39]
	v_lshlrev_b32_e32 v76, 16, v36
	v_and_b32_e32 v77, 0xffff0000, v36
	v_lshlrev_b32_e32 v78, 16, v37
	v_and_b32_e32 v79, 0xffff0000, v37
	v_mov_b32_e32 v80, v34
	v_mov_b32_e32 v36, v70
	v_mov_b32_e32 v37, v81
	v_pk_fma_f32 v[74:75], v[72:73], v[72:73], v[74:75]
	v_pk_add_f32 v[34:35], v[34:35], v[70:71]
	v_pk_mul_f32 v[36:37], v[80:81], v[36:37]
	v_lshlrev_b64 v[66:67], 12, v[20:21]
	v_mul_f32_e32 v21, v83, v83
	v_mov_b32_e32 v35, v37
	v_pk_add_f32 v[36:37], v[74:75], v[74:75] op_sel:[0,1] op_sel_hi:[1,0]
	v_mul_f32_e32 v52, v84, v84
	v_mov_b32_e32 v37, v21
	v_pk_add_f32 v[34:35], v[34:35], v[36:37]
	v_mul_f32_e32 v36, v77, v77
	v_pk_fma_f32 v[36:37], v[76:77], v[76:77], v[36:37] op_sel_hi:[1,1,0]
	v_mul_f32_e32 v82, v85, v85
	v_mov_b32_e32 v37, v52
	v_mul_f32_e32 v52, v79, v79
	v_pk_fma_f32 v[70:71], v[78:79], v[78:79], v[52:53] op_sel_hi:[1,1,0]
	v_lshl_add_u64 v[66:67], v[18:19], 0, v[66:67]
	v_mov_b32_e32 v71, v82
	v_pk_add_f32 v[36:37], v[36:37], v[70:71]
	v_mov_b32_e32 v82, v81
	v_pk_add_f32 v[34:35], v[34:35], v[36:37]
	v_pk_mul_f32 v[36:37], v[54:55], v[56:57] op_sel_hi:[0,1]
	v_add_f32_e32 v21, v34, v35
	ds_bpermute_b32 v52, v60, v21
	v_pk_mul_f32 v[34:35], v[54:55], v[44:45] op_sel_hi:[0,1]
	v_pk_mul_f32 v[36:37], v[2:3], v[36:37]
	v_pk_mul_f32 v[34:35], v[0:1], v[34:35]
	global_store_dwordx4 v[66:67], v[34:37], off
	s_waitcnt lgkmcnt(0)
	v_add_f32_e32 v21, v21, v52
	ds_bpermute_b32 v44, v61, v21
	v_mov_b32_e32 v34, v42
	v_mov_b32_e32 v35, v48
	v_mov_b32_e32 v48, v43
	v_pk_mul_f32 v[34:35], v[54:55], v[34:35] op_sel_hi:[0,1]
	s_waitcnt lgkmcnt(0)
	v_add_f32_e32 v21, v21, v44
	ds_bpermute_b32 v42, v62, v21
	v_pk_mul_f32 v[36:37], v[54:55], v[48:49] op_sel_hi:[0,1]
	v_pk_mul_f32 v[36:37], v[6:7], v[36:37]
	v_pk_mul_f32 v[34:35], v[4:5], v[34:35]
	global_store_dwordx4 v[66:67], v[34:37], off offset:1024
	s_waitcnt lgkmcnt(0)
	v_add_f32_e32 v21, v21, v42
	ds_bpermute_b32 v42, v63, v21
	v_pk_mul_f32 v[34:35], v[54:55], v[50:51] op_sel_hi:[0,1]
	v_pk_mul_f32 v[36:37], v[54:55], v[58:59] op_sel_hi:[0,1]
	v_pk_mul_f32 v[36:37], v[10:11], v[36:37]
	v_pk_mul_f32 v[34:35], v[8:9], v[34:35]
	s_waitcnt lgkmcnt(0)
	v_add_f32_e32 v21, v21, v42
	ds_bpermute_b32 v42, v64, v21
	v_mov_b32_e32 v52, v55
	global_store_dwordx4 v[66:67], v[34:37], off offset:2048
	v_lshlrev_b32_e32 v51, 16, v26
	v_lshlrev_b32_e32 v45, 16, v31
	s_waitcnt lgkmcnt(0)
	v_add_f32_e32 v21, v21, v42
	ds_bpermute_b32 v42, v65, v21
	v_pk_mul_f32 v[34:35], v[52:53], v[54:55] op_sel_hi:[1,0]
	v_pk_mul_f32 v[36:37], v[46:47], v[54:55] op_sel_hi:[1,0]
	v_pk_mul_f32 v[34:35], v[12:13], v[34:35]
	v_pk_mul_f32 v[36:37], v[14:15], v[36:37]
	global_store_dwordx4 v[66:67], v[34:37], off offset:3072
	s_waitcnt lgkmcnt(0)
	v_add_f32_e32 v21, v21, v42
	v_lshlrev_b32_e32 v44, 16, v30
	v_lshlrev_b32_e32 v36, 16, v32
	v_and_b32_e32 v37, 0xffff0000, v32
	v_lshlrev_b32_e32 v32, 16, v33
	v_and_b32_e32 v33, 0xffff0000, v33
	v_mul_f32_e32 v42, v33, v33
	v_and_b32_e32 v35, 0xffff0000, v26
	v_mul_f32_e32 v26, v37, v37
	v_pk_fma_f32 v[42:43], v[32:33], v[32:33], v[42:43] op_sel_hi:[1,1,0]
	v_and_b32_e32 v31, 0xffff0000, v31
	v_and_b32_e32 v30, 0xffff0000, v30
	v_lshlrev_b32_e32 v52, 16, v27
	v_and_b32_e32 v53, 0xffff0000, v27
	v_pk_fma_f32 v[26:27], v[36:37], v[36:37], v[26:27] op_sel_hi:[1,1,0]
	v_pk_mul_f32 v[46:47], v[30:31], v[30:31]
	v_mov_b32_e32 v50, v26
	v_mov_b32_e32 v54, v42
	v_mov_b32_e32 v55, v51
	v_fmamk_f32 v21, v21, 0x3a800000, v229
	v_pk_fma_f32 v[46:47], v[44:45], v[44:45], v[46:47]
	v_pk_add_f32 v[26:27], v[26:27], v[42:43]
	v_pk_mul_f32 v[42:43], v[50:51], v[54:55]
	v_rsq_f32_e32 v34, v21
	v_mul_f32_e32 v21, v35, v35
	v_mov_b32_e32 v27, v43
	v_pk_add_f32 v[42:43], v[46:47], v[46:47] op_sel:[0,1] op_sel_hi:[1,0]
	v_lshlrev_b32_e32 v48, 16, v28
	v_and_b32_e32 v49, 0xffff0000, v28
	v_lshlrev_b32_e32 v28, 16, v29
	v_and_b32_e32 v29, 0xffff0000, v29
	v_mov_b32_e32 v43, v21
	v_pk_add_f32 v[26:27], v[26:27], v[42:43]
	v_mul_f32_e32 v42, v49, v49
	v_mul_f32_e32 v46, v29, v29
	v_mul_f32_e32 v56, v52, v52
	v_mul_f32_e32 v57, v53, v53
	v_pk_fma_f32 v[42:43], v[48:49], v[48:49], v[42:43] op_sel_hi:[1,1,0]
	v_pk_fma_f32 v[46:47], v[28:29], v[28:29], v[46:47] op_sel_hi:[1,1,0]
	v_mov_b32_e32 v43, v56
	v_mov_b32_e32 v47, v57
	v_pk_add_f32 v[42:43], v[42:43], v[46:47]
	s_nop 0
	v_pk_add_f32 v[26:27], v[26:27], v[42:43]
	v_lshl_add_u64 v[42:43], v[18:19], 0, v[24:25]
	v_add_f32_e32 v21, v26, v27
	ds_bpermute_b32 v46, v60, v21
	v_pk_mul_f32 v[26:27], v[34:35], v[40:41] op_sel_hi:[0,1]
	v_pk_mul_f32 v[24:25], v[34:35], v[68:69] op_sel_hi:[0,1]
	v_pk_mul_f32 v[26:27], v[2:3], v[26:27]
	v_pk_mul_f32 v[24:25], v[0:1], v[24:25]
	s_waitcnt lgkmcnt(0)
	v_add_f32_e32 v21, v21, v46
	ds_bpermute_b32 v40, v61, v21
	global_store_dwordx4 v[42:43], v[24:27], off
	s_waitcnt lgkmcnt(0)
	v_add_f32_e32 v21, v21, v40
	ds_bpermute_b32 v40, v62, v21
	v_mov_b32_e32 v25, v38
	v_mov_b32_e32 v38, v73
	v_pk_mul_f32 v[26:27], v[34:35], v[38:39] op_sel_hi:[0,1]
	v_mov_b32_e32 v24, v72
	s_waitcnt lgkmcnt(0)
	v_add_f32_e32 v21, v21, v40
	ds_bpermute_b32 v38, v63, v21
	v_pk_mul_f32 v[24:25], v[34:35], v[24:25] op_sel_hi:[0,1]
	v_pk_mul_f32 v[26:27], v[6:7], v[26:27]
	v_pk_mul_f32 v[24:25], v[4:5], v[24:25]
	global_store_dwordx4 v[42:43], v[24:27], off offset:1024
	s_waitcnt lgkmcnt(0)
	v_add_f32_e32 v21, v21, v38
	ds_bpermute_b32 v38, v64, v21
	v_pk_mul_f32 v[24:25], v[34:35], v[76:77] op_sel_hi:[0,1]
	v_pk_mul_f32 v[26:27], v[34:35], v[78:79] op_sel_hi:[0,1]
	v_pk_mul_f32 v[26:27], v[10:11], v[26:27]
	v_pk_mul_f32 v[24:25], v[8:9], v[24:25]
	s_waitcnt lgkmcnt(0)
	v_add_f32_e32 v21, v21, v38
	ds_bpermute_b32 v38, v65, v21
	global_store_dwordx4 v[42:43], v[24:27], off offset:2048
	v_lshl_add_u64 v[40:41], v[18:19], 0, v[22:23]
	s_waitcnt lgkmcnt(0)
	v_add_f32_e32 v21, v21, v38
	v_fmamk_f32 v21, v21, 0x3a800000, v229
	v_rsq_f32_e32 v38, v21
	v_pk_mul_f32 v[24:25], v[82:83], v[34:35] op_sel_hi:[1,0]
	v_pk_mul_f32 v[26:27], v[84:85], v[34:35] op_sel_hi:[1,0]
	v_pk_mul_f32 v[24:25], v[12:13], v[24:25]
	v_pk_mul_f32 v[26:27], v[14:15], v[26:27]
	global_store_dwordx4 v[42:43], v[24:27], off offset:3072
	v_pk_mul_f32 v[22:23], v[38:39], v[36:37] op_sel_hi:[0,1]
	v_pk_mul_f32 v[22:23], v[0:1], v[22:23]
	v_pk_mul_f32 v[24:25], v[38:39], v[32:33] op_sel_hi:[0,1]
	v_pk_mul_f32 v[24:25], v[2:3], v[24:25]
	global_store_dwordx4 v[40:41], v[22:25], off
	v_mov_b32_e32 v34, v51
	v_add_u32_e32 v26, s9, v20
	v_mov_b32_e32 v22, v44
	v_mov_b32_e32 v23, v30
	v_mov_b32_e32 v30, v45
	v_pk_mul_f32 v[22:23], v[38:39], v[22:23] op_sel_hi:[0,1]
	v_pk_mul_f32 v[24:25], v[38:39], v[30:31] op_sel_hi:[0,1]
	v_pk_mul_f32 v[24:25], v[6:7], v[24:25]
	v_pk_mul_f32 v[22:23], v[4:5], v[22:23]
	global_store_dwordx4 v[40:41], v[22:25], off offset:1024
	v_cmp_lt_i32_e32 vcc, s41, v26
	s_or_b64 s[6:7], vcc, s[6:7]
	v_pk_mul_f32 v[22:23], v[38:39], v[48:49] op_sel_hi:[0,1]
	v_pk_mul_f32 v[24:25], v[38:39], v[28:29] op_sel_hi:[0,1]
	v_pk_mul_f32 v[24:25], v[10:11], v[24:25]
	v_pk_mul_f32 v[22:23], v[8:9], v[22:23]
	global_store_dwordx4 v[40:41], v[22:25], off offset:2048
	s_nop 1
	v_pk_mul_f32 v[22:23], v[34:35], v[38:39] op_sel_hi:[1,0]
	v_pk_mul_f32 v[24:25], v[52:53], v[38:39] op_sel_hi:[1,0]
	v_pk_mul_f32 v[22:23], v[12:13], v[22:23]
	v_pk_mul_f32 v[24:25], v[14:15], v[24:25]
	global_store_dwordx4 v[40:41], v[22:25], off offset:3072
	s_andn2_b64 exec, exec, s[6:7]
	s_cbranch_execnz .LBB0_538

.LBB0_540:
	s_add_i32 s44, s44, 1
	s_cmp_ge_i32 s44, s45
	s_mov_b64 s[4:5], -1
	s_cbranch_scc1 .LBB0_10
	s_add_i32 s4, s44, -1
	s_mov_b32 s5, 0x100a804
	s_bitcmp1_b32 s5, s4
	s_cbranch_scc1 .Lskip_gridbar
	s_mov_b64 s[4:5], -1
	s_and_b64 vcc, exec, s[76:77]
	s_cbranch_vccz .LBB0_589
	v_readlane_b32 s38, v255, 4
	v_readlane_b32 s39, v255, 5
	s_waitcnt vmcnt(0)
	v_mov_b32_e32 v0, v228
	s_waitcnt vmcnt(0) lgkmcnt(0)
	s_barrier
	s_nop 0
	v_cmp_eq_u32_e32 vcc, 0, v0
	s_and_saveexec_b64 s[36:37], vcc
	s_cbranch_execz .LBB0_588
	s_add_i32 s1, 0, 0x22000
	v_mov_b32_e32 v0, s1
	s_waitcnt vmcnt(0) expcnt(0) lgkmcnt(0)
	s_getreg_b32 s0, hwreg(HW_REG_XCC_ID, 0, 4)
	ds_read_b32 v2, v0
	v_readlane_b32 s3, v255, 11
	s_and_b32 s0, s0, 15
	s_waitcnt lgkmcnt(0)
	v_cmp_ne_u32_e32 vcc, 0, v2
	v_mov_b32_e32 v0, s3
	ds_read_b32 v0, v0
	s_cbranch_vccnz .LBB0_558
	v_readlane_b32 s4, v255, 0
	v_readlane_b32 s5, v255, 1
	s_load_dwordx2 s[8:9], s[4:5], 0x0
	s_load_dword s3, s[4:5], 0x8
	s_add_u32 s4, s38, 0x1000
	s_addc_u32 s5, s39, 0
	s_add_u32 s6, s38, 0x1100
	s_addc_u32 s7, s39, 0
	s_waitcnt lgkmcnt(0)
	s_mul_i32 s30, s9, s8
	s_add_u32 s8, s38, 0x1200
	s_addc_u32 s9, s39, 0
	s_add_u32 s10, s38, 0x1300
	s_mul_i32 s30, s30, s3
	s_addc_u32 s11, s39, 0
	s_mov_b32 s31, 1
	s_mov_b64 s[12:13], 0
	s_branch .LBB0_547

.LBB0_547:
	v_mov_b64_e32 v[12:13], s[38:39]
	global_load_dword v1, v[12:13], off offset:1024 sc1
	global_load_dword v0, v[12:13], off offset:1280 sc1
	global_load_dword v2, v[12:13], off offset:1536 sc1
	s_or_b64 s[18:19], s[18:19], exec
	s_or_b64 s[16:17], s[16:17], exec
	s_waitcnt vmcnt(0) lgkmcnt(0)
	v_add_u32_e32 v3, v0, v1
	v_add_u32_e32 v4, v3, v2
	global_load_dword v3, v[12:13], off offset:1792 sc1
	s_waitcnt vmcnt(0) lgkmcnt(0)
	v_add_u32_e32 v5, v4, v3
	global_load_dword v4, v[12:13], off offset:2048 sc1
	s_waitcnt vmcnt(0) lgkmcnt(0)
	v_add_u32_e32 v6, v5, v4
	global_load_dword v5, v[12:13], off offset:2304 sc1
	s_waitcnt vmcnt(0) lgkmcnt(0)
	v_add_u32_e32 v7, v6, v5
	global_load_dword v6, v[12:13], off offset:2560 sc1
	s_waitcnt vmcnt(0) lgkmcnt(0)
	v_add_u32_e32 v8, v7, v6
	global_load_dword v7, v[12:13], off offset:2816 sc1
	s_waitcnt vmcnt(0) lgkmcnt(0)
	v_add_u32_e32 v9, v8, v7
	global_load_dword v8, v[12:13], off offset:3072 sc1
	s_waitcnt vmcnt(0) lgkmcnt(0)
	v_add_u32_e32 v10, v9, v8
	global_load_dword v9, v[12:13], off offset:3328 sc1
	s_waitcnt vmcnt(0) lgkmcnt(0)
	v_add_u32_e32 v11, v10, v9
	global_load_dword v10, v[12:13], off offset:3584 sc1
	s_waitcnt vmcnt(0) lgkmcnt(0)
	v_add_u32_e32 v14, v11, v10
	global_load_dword v11, v[12:13], off offset:3840 sc1
	v_mov_b64_e32 v[12:13], s[4:5]
	global_load_dword v12, v[12:13], off sc1
	s_waitcnt vmcnt(0) lgkmcnt(0)
	v_add_u32_e32 v14, v14, v11
	v_add_u32_e32 v16, v14, v12
	v_mov_b64_e32 v[14:15], s[6:7]
	global_load_dword v13, v[14:15], off sc1
	v_mov_b64_e32 v[14:15], s[8:9]
	global_load_dword v14, v[14:15], off sc1
	s_waitcnt vmcnt(0) lgkmcnt(0)
	v_add_u32_e32 v16, v16, v13
	v_add_u32_e32 v18, v16, v14
	v_mov_b64_e32 v[16:17], s[10:11]
	global_load_dword v15, v[16:17], off sc1
	s_waitcnt vmcnt(0) lgkmcnt(0)
	v_add_u32_e32 v16, v18, v15
	v_cmp_ne_u32_e32 vcc, s30, v16
	s_and_saveexec_b64 s[20:21], vcc
	s_cbranch_execz .LBB0_546
	s_and_b32 s3, s31, 0xff
	s_mov_b64 s[22:23], -1
	s_cmp_eq_u32 s3, 0
	s_mov_b64 s[26:27], -1
	s_mov_b64 s[24:25], -1
	s_sleep 1
	s_cbranch_scc1 .LBB0_550
	s_and_saveexec_b64 s[28:29], s[26:27]
	s_cbranch_execz .LBB0_545
	s_branch .LBB0_553
.LBB0_550:
	v_mov_b64_e32 v[16:17], s[38:39]
	global_load_dword v16, v[16:17], off offset:512 sc1
	s_mov_b64 s[26:27], 0
	s_waitcnt vmcnt(0) lgkmcnt(0)
	v_cmp_eq_u32_e32 vcc, 0, v16
	s_and_saveexec_b64 s[28:29], vcc
	s_cmp_lt_u32 s31, 0x40001
	s_cselect_b64 s[26:27], -1, 0
	s_xor_b64 s[24:25], exec, -1
	s_and_b64 s[26:27], s[26:27], exec
	s_or_b64 exec, exec, s[28:29]
	s_and_saveexec_b64 s[28:29], s[26:27]
	s_cbranch_execz .LBB0_545

.LBB0_558:
	s_lshl_b32 s0, s0, 8
	s_add_u32 s1, s38, s0
	s_addc_u32 s0, s39, 0
	v_mov_b32_e32 v1, s1
	v_add_co_u32_e32 v4, vcc, 0x1000, v1
	v_mov_b32_e32 v1, s0
	s_nop 0
	v_addc_co_u32_e32 v5, vcc, 0, v1, vcc
	flat_atomic_add v3, v[4:5], v230 offset:1024 sc0
	v_cvt_f32_u32_e32 v1, v2
	v_sub_u32_e32 v4, 0, v2
	v_rcp_iflag_f32_e32 v1, v1
	s_nop 0
	v_mul_f32_e32 v1, 0x4f7ffffe, v1
	v_cvt_u32_f32_e32 v1, v1
	v_mul_lo_u32 v4, v4, v1
	v_mul_hi_u32 v4, v1, v4
	v_add_u32_e32 v1, v1, v4
	s_waitcnt vmcnt(0) lgkmcnt(0)
	v_mul_hi_u32 v1, v3, v1
	v_mul_lo_u32 v4, v1, v2
	v_sub_u32_e32 v4, v3, v4
	v_cmp_ge_u32_e32 vcc, v4, v2
	v_add_u32_e32 v5, 1, v1
	s_nop 0
	v_cndmask_b32_e32 v1, v1, v5, vcc
	v_sub_u32_e32 v5, v4, v2
	v_cndmask_b32_e32 v4, v4, v5, vcc
	v_cmp_ge_u32_e32 vcc, v4, v2
	v_add_u32_e32 v4, 1, v1
	s_nop 0
	v_cndmask_b32_e32 v1, v1, v4, vcc
	v_add_u32_e32 v4, 1, v3
	v_mad_u64_u32 v[2:3], s[4:5], v2, v1, v[2:3]
	v_cmp_ne_u32_e32 vcc, v4, v2
	s_and_saveexec_b64 s[4:5], vcc
	s_xor_b64 s[4:5], exec, s[4:5]
	s_cbranch_execz .LBB0_571
	v_mov_b32_e32 v0, s1
	v_add_co_u32_e32 v2, vcc, 0x2000, v0
	v_mov_b32_e32 v0, s0
	s_nop 0
	v_addc_co_u32_e32 v3, vcc, 0, v0, vcc
	global_load_dword v0, v[2:3], off offset:1024 sc1
	s_add_u32 s8, s1, 0x2400
	s_addc_u32 s9, s0, 0
	s_waitcnt vmcnt(0) lgkmcnt(0)
	v_cmp_eq_u32_e32 vcc, v0, v1
	s_and_saveexec_b64 s[6:7], vcc
	s_cbranch_execz .LBB0_570
	s_mov_b32 s24, 1
	s_mov_b64 s[10:11], 0
	s_branch .LBB0_562

.LBB0_562:
	s_and_b32 s3, s24, 0xff
	s_mov_b64 s[16:17], -1
	s_cmp_lg_u32 s3, 0
	s_mov_b64 s[18:19], -1
	s_sleep 1
	s_cbranch_scc1 .LBB0_566
	v_mov_b64_e32 v[2:3], s[38:39]
	global_load_dword v0, v[2:3], off offset:512 sc1
	s_mov_b64 s[18:19], 0
	s_mov_b64 s[20:21], -1
	s_waitcnt vmcnt(0) lgkmcnt(0)
	v_cmp_eq_u32_e32 vcc, 0, v0
	s_and_saveexec_b64 s[22:23], vcc
	s_cmp_lt_u32 s24, 0x40001
	s_cselect_b64 s[18:19], -1, 0
	s_xor_b64 s[20:21], exec, -1
	s_and_b64 s[18:19], s[18:19], exec
	s_or_b64 exec, exec, s[22:23]
.LBB0_566:
	s_andn2_b64 s[14:15], s[14:15], exec
	s_and_b64 s[20:21], s[20:21], exec
	s_or_b64 s[14:15], s[14:15], s[20:21]
	s_and_saveexec_b64 s[20:21], s[18:19]
	s_cbranch_execz .LBB0_561
	v_mov_b64_e32 v[2:3], s[8:9]
	global_load_dword v0, v[2:3], off sc1
	s_add_i32 s24, s24, 1
	s_or_b64 s[14:15], s[14:15], exec
	s_waitcnt vmcnt(0) lgkmcnt(0)
	v_cmp_ne_u32_e32 vcc, v0, v1
	s_orn2_b64 s[16:17], vcc, exec
	s_branch .LBB0_561

.LBB0_571:
	s_andn2_saveexec_b64 s[4:5], s[4:5]
	s_cbranch_execz .LBB0_588
	v_mov_b32_e32 v1, s38
	v_add_co_u32_e32 v2, vcc, 0x3000, v1
	v_mov_b32_e32 v1, s39
	buffer_wbl2 sc1
	s_waitcnt vmcnt(0)
	v_addc_co_u32_e32 v3, vcc, 0, v1, vcc
	flat_atomic_add v1, v[2:3], v230 offset:1024 sc0
	v_cvt_f32_u32_e32 v2, v0
	v_sub_u32_e32 v3, 0, v0
	s_mov_b64 s[8:9], -1
	v_rcp_iflag_f32_e32 v2, v2
	s_nop 0
	v_mul_f32_e32 v2, 0x4f7ffffe, v2
	v_cvt_u32_f32_e32 v2, v2
	v_mul_lo_u32 v3, v3, v2
	v_mul_hi_u32 v3, v2, v3
	v_add_u32_e32 v2, v2, v3
	s_waitcnt vmcnt(0) lgkmcnt(0)
	v_mul_hi_u32 v2, v1, v2
	v_mul_lo_u32 v3, v2, v0
	v_sub_u32_e32 v3, v1, v3
	v_cmp_ge_u32_e32 vcc, v3, v0
	v_add_u32_e32 v4, 1, v2
	s_nop 0
	v_cndmask_b32_e32 v2, v2, v4, vcc
	v_sub_u32_e32 v4, v3, v0
	v_cndmask_b32_e32 v3, v3, v4, vcc
	v_cmp_ge_u32_e32 vcc, v3, v0
	v_add_u32_e32 v3, 1, v2
	s_nop 0
	v_cndmask_b32_e32 v2, v2, v3, vcc
	v_add_u32_e32 v3, 1, v1
	v_mad_u64_u32 v[0:1], s[4:5], v0, v2, v[0:1]
	s_add_u32 s4, s38, 0x3500
	s_addc_u32 s5, s39, 0
	v_cmp_ne_u32_e32 vcc, v3, v0
	v_mov_b64_e32 v[0:1], s[4:5]
	s_and_saveexec_b64 s[6:7], vcc
	s_cbranch_execz .LBB0_585
	v_mov_b64_e32 v[0:1], s[4:5]
	global_load_dword v0, v[0:1], off sc1
	s_mov_b64 s[12:13], 0
	s_waitcnt vmcnt(0) lgkmcnt(0)
	v_cmp_eq_u32_e32 vcc, v0, v2
	s_and_saveexec_b64 s[10:11], vcc
	s_cbranch_execz .LBB0_584
	s_add_u32 s8, s38, 0x200
	s_addc_u32 s9, s39, 0
	s_mov_b32 s24, 1
	s_branch .LBB0_576

.LBB0_578:
	v_mov_b64_e32 v[0:1], s[8:9]
	global_load_dword v0, v[0:1], off sc1
	s_mov_b64 s[20:21], 0
	s_mov_b64 s[18:19], -1
	s_waitcnt vmcnt(0) lgkmcnt(0)
	v_cmp_eq_u32_e32 vcc, 0, v0
	s_and_saveexec_b64 s[22:23], vcc
	s_cmp_lt_u32 s24, 0x40001
	s_cselect_b64 s[20:21], -1, 0
	s_xor_b64 s[18:19], exec, -1
	s_and_b64 s[20:21], s[20:21], exec
	s_or_b64 exec, exec, s[22:23]
	s_and_saveexec_b64 s[22:23], s[20:21]
	s_cbranch_execz .LBB0_575
.LBB0_581:
	v_mov_b64_e32 v[0:1], s[4:5]
	global_load_dword v0, v[0:1], off sc1
	s_add_i32 s24, s24, 1
	s_or_b64 s[18:19], s[18:19], exec
	s_waitcnt vmcnt(0) lgkmcnt(0)
	v_cmp_ne_u32_e32 vcc, v0, v2
	s_orn2_b64 s[16:17], vcc, exec
	s_branch .LBB0_575
